# dead LDS-offset VALU constants removed (112) and adjacent duplicate s_waitcnt lgkmcnt(0) removed (108); on top of v43
# speedup vs baseline: 1.0055x; 1.0055x over previous
; #define BAR8 __builtin_amdgcn_s_barrier()
;     ...
;   if (!pre) {
;     STAGE8(SB8(0, 0), Bt, K, bcol, 0); STAGE8(SA8(0, 0), A, lda, brow, 0);
;     STAGE8(SB8(0, 1), Bt, K, bcol + 128, 0); STAGE8(SA8(0, 1), A, lda, brow + 128, 0);
;   }
;   if (wr == 1) BAR8;
.LBB0_188:
	s_and_b32 s0, s25, 63
	s_lshl_b32 s30, s0, 19
	s_and_b32 s0, s24, 0xffffff00
	s_ashr_i32 s1, s0, 31
	s_lshl_b64 s[56:57], s[0:1], 11
	s_mov_b32 s0, 25
	s_ashr_i32 s1, s0, 31
	s_and_b32 s20, s33, 63
	s_lshl_b64 s[0:1], s[0:1], 3
	s_add_u32 s0, s70, s0
	s_addc_u32 s1, s71, s1
	v_readlane_b32 s0, v255, 60
	v_readlane_b32 s1, v255, 61
	s_nop 4
	v_readlane_b32 s12, v254, 35
	s_mov_b32 s31, s12
	v_readlane_b32 s13, v254, 36
	v_readlane_b32 s14, v254, 37
	s_waitcnt lgkmcnt(0)
	s_add_u32 s54, s0, 0xf640000
	s_mov_b32 s0, 25
	s_addc_u32 s55, s1, 0
	s_ashr_i32 s1, s0, 31
	s_lshl_b64 s[0:1], s[0:1], 3
	s_add_u32 s0, s70, s0
	s_addc_u32 s1, s71, s1
	v_readlane_b32 s0, v255, 60
	v_readlane_b32 s1, v255, 61
	s_nop 4
	v_readlane_b32 s15, v254, 38
	s_waitcnt lgkmcnt(0)
	s_add_u32 s50, s0, 0x2000000
	s_addc_u32 s51, s1, 0
	s_lshl_b32 s0, s33, 2
	s_lshl_b32 s36, s20, 8
	s_and_b32 s52, s0, 0xffffff00
	s_andn2_b64 vcc, exec, s[40:41]
	s_mov_b64 s[0:1], -1
	s_cbranch_vccnz .LBB0_238
	s_mov_b32 s0, 4
	s_ashr_i32 s1, s0, 31
	s_lshl_b64 s[0:1], s[0:1], 3
	s_add_u32 s0, s70, s0
	s_addc_u32 s1, s71, s1
	s_mov_b32 s2, 5
	s_load_dwordx2 s[0:1], s[0:1], 0x0
	s_ashr_i32 s3, s2, 31
	s_lshl_b64 s[2:3], s[2:3], 3
	s_add_u32 s2, s70, s2
	s_addc_u32 s3, s71, s3
	s_mov_b32 s4, 25
	s_load_dwordx2 s[2:3], s[2:3], 0x0
	s_ashr_i32 s5, s4, 31
	s_lshl_b64 s[4:5], s[4:5], 3
	s_add_u32 s4, s70, s4
	s_addc_u32 s5, s71, s5
	v_mov_b32_e32 v3, v224
	v_readlane_b32 s12, v255, 60
	v_readlane_b32 s13, v255, 61
	s_nop 4
	s_ashr_i32 s53, s52, 31
	v_bfe_i32 v1, v3, 27, 1
	s_waitcnt vmcnt(10)
	v_lshlrev_b32_e32 v150, 4, v3
	s_nop 0
	v_readfirstlane_b32 s100, v150
	v_lshrrev_b32_e32 v1, 22, v1
	v_add_u32_e32 v1, v150, v1
	v_and_b32_e32 v1, 0xfffffc00, v1
	v_ashrrev_i32_e32 v0, 31, v3
	v_sub_u32_e32 v1, v150, v1
	v_lshrrev_b32_e32 v0, 26, v0
	v_lshrrev_b32_e32 v5, 4, v1
	v_add_u32_e32 v0, v3, v0
	v_bitop3_b32 v5, v5, v1, 32 bitop3:0x6c
	v_ashrrev_i32_e32 v1, 31, v1
	v_ashrrev_i32_e32 v0, 6, v0
	v_lshrrev_b32_e32 v1, 26, v1
	v_lshlrev_b32_e32 v6, 3, v0
	v_add_u32_e32 v1, v5, v1
	v_and_b32_e32 v6, -16, v6
	v_ashrrev_i32_e32 v1, 6, v1
	v_add_u32_e32 v6, v1, v6
	v_mul_i32_i24_e32 v1, 64, v1
	v_lshlrev_b32_e32 v0, 5, v0
	v_sub_u32_e32 v1, v5, v1
	v_mov_b32_e32 v14, 1
	s_waitcnt vmcnt(9)
	v_add_u32_e32 v155, 0x2000, v150
	s_lshl_b64 s[4:5], s[52:53], 11
	v_readlane_b32 s21, v254, 44
	v_and_b32_e32 v0, 32, v0
	v_ashrrev_i16_sdwa v1, v14, sext(v1) dst_sel:DWORD dst_unused:UNUSED_PAD src0_sel:DWORD src1_sel:BYTE_0
	v_ashrrev_i32_e32 v5, 31, v155
	s_add_u32 s4, s21, s4
	v_readlane_b32 s27, v254, 45
	v_add_u32_sdwa v0, v0, sext(v1) dst_sel:DWORD dst_unused:UNUSED_PAD src0_sel:DWORD src1_sel:WORD_0
	v_ashrrev_i32_e32 v7, 31, v6
	v_lshrrev_b32_e32 v5, 22, v5
	s_addc_u32 s5, s27, s5
	v_lshlrev_b64 v[132:133], 11, v[6:7]
	v_ashrrev_i32_e32 v1, 31, v0
	v_add_u32_e32 v5, v155, v5
	v_lshl_add_u64 v[8:9], s[4:5], 0, v[132:133]
	v_lshlrev_b64 v[6:7], 1, v[0:1]
	v_ashrrev_i32_e32 v5, 10, v5
	v_lshl_add_u64 v[10:11], v[8:9], 0, v[6:7]
	v_mul_i32_i24_e32 v8, 0x400, v5
	v_sub_u32_e32 v8, v155, v8
	v_lshrrev_b32_e32 v9, 4, v8
	v_bitop3_b32 v9, v9, v8, 32 bitop3:0x6c
	v_ashrrev_i32_e32 v12, 31, v9
	v_lshrrev_b32_e32 v12, 26, v12
	v_add_u32_e32 v12, v9, v12
	v_lshlrev_b32_e32 v8, 3, v5
	v_ashrrev_i32_e32 v13, 6, v12
	v_and_b32_e32 v12, 0xc0, v12
	v_and_b32_e32 v8, -16, v8
	v_lshlrev_b32_e32 v5, 5, v5
	v_sub_u32_e32 v9, v9, v12
	v_add_u32_e32 v8, v13, v8
	v_and_b32_e32 v5, 32, v5
	v_ashrrev_i16_sdwa v9, v14, sext(v9) dst_sel:DWORD dst_unused:UNUSED_PAD src0_sel:DWORD src1_sel:BYTE_0
	v_add_u32_sdwa v134, v5, sext(v9) dst_sel:DWORD dst_unused:UNUSED_PAD src0_sel:DWORD src1_sel:WORD_0
	v_ashrrev_i32_e32 v9, 31, v8
	v_lshlrev_b64 v[136:137], 11, v[8:9]
	s_waitcnt vmcnt(8)
	v_mov_b32_e32 v4, v2
	s_or_b32 m0, s100, 0x10000
	v_lshl_add_u64 v[12:13], s[4:5], 0, v[136:137]
	global_load_lds_dwordx4 v[10:11], off
	s_or_b32 m0, s100, 0x12000
	s_lshl_b32 s4, s20, 19
	v_ashrrev_i32_e32 v135, 31, v134
	s_waitcnt lgkmcnt(0)
	s_add_u32 s4, s12, s4
	v_lshlrev_b64 v[8:9], 1, v[134:135]
	s_addc_u32 s5, s13, 0
	v_lshl_add_u64 v[12:13], v[12:13], 0, v[8:9]
	v_lshl_add_u64 v[14:15], s[4:5], 0, v[132:133]
	s_or_b32 s58, s52, 0x80
	global_load_lds_dwordx4 v[12:13], off
	v_lshl_add_u64 v[14:15], v[14:15], 0, v[6:7]
	s_mov_b32 m0, s100
	s_ashr_i32 s59, s58, 31
	global_load_lds_dwordx4 v[14:15], off
	s_or_b32 m0, s100, 0x2000
	s_lshl_b64 s[14:15], s[58:59], 11
	s_add_u32 s14, s21, s14
	v_lshl_add_u64 v[16:17], s[4:5], 0, v[136:137]
	s_addc_u32 s15, s27, s15
	v_lshl_add_u64 v[16:17], v[16:17], 0, v[8:9]
	v_lshl_add_u64 v[18:19], s[14:15], 0, v[132:133]
	global_load_lds_dwordx4 v[16:17], off
	v_lshl_add_u64 v[18:19], v[18:19], 0, v[6:7]
	s_or_b32 m0, s100, 0x14000
	v_lshl_add_u64 v[20:21], s[14:15], 0, v[136:137]
	global_load_lds_dwordx4 v[18:19], off
	s_or_b32 m0, s100, 0x16000
	s_add_u32 s14, s4, 0x40000
	s_addc_u32 s15, s5, 0
	v_lshl_add_u64 v[20:21], v[20:21], 0, v[8:9]
	v_lshl_add_u64 v[22:23], s[14:15], 0, v[132:133]
	global_load_lds_dwordx4 v[20:21], off
	v_lshl_add_u64 v[22:23], v[22:23], 0, v[6:7]
	s_or_b32 m0, s100, 0x4000
	global_load_lds_dwordx4 v[22:23], off
	v_lshl_add_u64 v[22:23], s[14:15], 0, v[136:137]
	v_lshl_add_u64 v[22:23], v[22:23], 0, v[8:9]
	s_or_b32 m0, s100, 0x6000
	v_ashrrev_i32_e32 v5, 8, v3
	global_load_lds_dwordx4 v[22:23], off
	v_cmp_eq_u32_e32 vcc, 1, v5
	s_and_saveexec_b64 s[14:15], vcc
	s_cbranch_execz .LBB0_191
	s_barrier
; #define WAIT_V8(n) asm volatile("s_waitcnt vmcnt(" #n ")" ::: "memory")
; #define BAR8 __builtin_amdgcn_s_barrier()
;     ...
;   {
;     float zinit = 0.f;
;     asm volatile("" : "+v"(zinit));
; #pragma unroll
;     for (int a = 0; a < 2; ++a)
; #pragma unroll
;       for (int b = 0; b < 2; ++b)
; #pragma unroll
;         for (int m = 0; m < 4; ++m)
; #pragma unroll
;           for (int n = 0; n < 2; ++n)
; #pragma unroll
;             for (int j = 0; j < 4; ++j) acc[a][b][m][n][j] = zinit;
;   }
;   bf16x8 At[4][2], B0[2][2], B1[2][2];
;   const int nt = K / 64;
;   if (!pre) {
;     STAGE8(SB8(0, 0), Bt, K, bcol, 0); STAGE8(SA8(0, 0), A, lda, brow, 0);
;     STAGE8(SB8(0, 1), Bt, K, bcol + 128, 0); STAGE8(SA8(0, 1), A, lda, brow + 128, 0);
;   }
;   if (wr == 1) BAR8;
;   WAIT_V8(4); BAR8;
;   STAGE8(SB8(1, 0), Bt, K, bcol, 1); STAGE8(SA8(1, 0), A, lda, brow, 1); STAGE8(SB8(1, 1), Bt, K, bcol + 128, 1);
;   WAIT_V8(6); BAR8;
;   for (int tt = 0; tt < nt - 2; tt += 2) {
.LBB0_191:
	s_or_b64 exec, exec, s[14:15]
	s_mov_b64 s[60:61], 0x80
	v_lshl_add_u64 v[10:11], v[10:11], 0, s[60:61]
	s_or_b32 m0, s100, 0x18000
	s_waitcnt vmcnt(4)
	s_barrier
	global_load_lds_dwordx4 v[10:11], off
	v_lshl_add_u64 v[10:11], v[12:13], 0, s[60:61]
	s_or_b32 m0, s100, 0x1a000
	global_load_lds_dwordx4 v[10:11], off
	v_lshl_add_u64 v[10:11], v[14:15], 0, s[60:61]
	s_or_b32 m0, s100, 0x8000
	global_load_lds_dwordx4 v[10:11], off
	v_lshl_add_u64 v[10:11], v[16:17], 0, s[60:61]
	s_or_b32 m0, s100, 0xa000
	global_load_lds_dwordx4 v[10:11], off
	v_lshl_add_u64 v[10:11], v[18:19], 0, s[60:61]
	s_or_b32 m0, s100, 0x1c000
	s_nop 0
	global_load_lds_dwordx4 v[10:11], off
	v_lshl_add_u64 v[10:11], v[20:21], 0, s[60:61]
	s_or_b32 m0, s100, 0x1e000
	v_and_b32_e32 v147, 15, v3
	global_load_lds_dwordx4 v[10:11], off
	v_bfe_u32 v148, v3, 4, 2
	v_lshlrev_b32_e32 v10, 4, v148
	v_lshlrev_b32_e32 v11, 6, v147
	v_lshlrev_b32_e32 v14, 2, v3
	v_or_b32_e32 v13, v10, v11
	v_and_b32_e32 v14, 32, v14
	s_mov_b32 s14, 0x10000
	v_bitop3_b32 v16, v13, s14, v14 bitop3:0xde
	s_mov_b32 s14, 0x14000
	v_bitop3_b32 v15, v10, v14, v11 bitop3:0x36
	v_bitop3_b32 v17, v13, s14, v14 bitop3:0xde
	s_mov_b32 s14, 0x18000
	v_lshlrev_b32_e32 v11, 6, v3
	v_bitop3_b32 v18, v13, s14, v14 bitop3:0xde
	s_mov_b32 s14, 0x1c000
	v_and_b32_e32 v11, 0x3c0, v11
	v_bitop3_b32 v13, v13, s14, v14 bitop3:0xde
	v_bitop3_b32 v14, v11, v14, v10 bitop3:0x36
	v_lshl_add_u64 v[10:11], s[30:31], 0, v[136:137]
	v_lshl_add_u64 v[10:11], v[10:11], 0, v[8:9]
	v_lshl_add_u64 v[138:139], s[12:13], 0, v[10:11]
	v_lshl_add_u64 v[10:11], s[30:31], 0, v[132:133]
	v_lshl_add_u64 v[10:11], v[10:11], 0, v[6:7]
	v_lshl_add_u64 v[140:141], s[12:13], 0, v[10:11]
	v_lshl_add_u64 v[10:11], s[56:57], 0, v[132:133]
	v_lshl_add_u64 v[6:7], v[10:11], 0, v[6:7]
	v_bfe_u32 v146, v3, 6, 2
	s_waitcnt vmcnt(6)
	v_lshlrev_b32_e32 v149, 6, v5
	v_lshlrev_b32_e32 v5, 13, v5
	v_lshl_add_u64 v[142:143], s[46:47], 0, v[6:7]
	v_lshl_add_u64 v[6:7], s[56:57], 0, v[136:137]
	v_lshlrev_b32_e32 v12, 12, v146
	v_or_b32_e32 v19, 0x800, v5
	v_or_b32_e32 v20, 0x1000, v5
	v_or_b32_e32 v21, 0x1800, v5
	v_lshl_add_u64 v[6:7], v[6:7], 0, v[8:9]
	v_lshl_add_u64 v[144:145], s[46:47], 0, v[6:7]
	s_mov_b32 s14, -2
	s_mov_b64 s[12:13], 0
	v_add_u32_e32 v173, v16, v12
	v_add_u32_e32 v156, v15, v5
	v_add_u32_e32 v154, v14, v19
	v_add_u32_e32 v153, v14, v20
	v_add_u32_e32 v152, v14, v21
	v_add_u32_e32 v169, v17, v12
	v_add_u32_e32 v159, v18, v12
	v_add_u32_e32 v158, v13, v12
	v_mov_b32_e32 v5, v4
	v_mov_b64_e32 v[6:7], v[4:5]
	v_mov_b64_e32 v[8:9], v[4:5]
	v_mov_b64_e32 v[10:11], v[4:5]
	v_mov_b64_e32 v[12:13], v[4:5]
	v_mov_b64_e32 v[14:15], v[4:5]
	v_mov_b64_e32 v[16:17], v[4:5]
	v_mov_b64_e32 v[18:19], v[4:5]
	v_mov_b64_e32 v[20:21], v[4:5]
	v_mov_b64_e32 v[22:23], v[4:5]
	v_mov_b64_e32 v[24:25], v[4:5]
	v_mov_b64_e32 v[26:27], v[4:5]
	v_mov_b64_e32 v[28:29], v[4:5]
	v_mov_b64_e32 v[30:31], v[4:5]
	v_mov_b64_e32 v[32:33], v[4:5]
	v_mov_b64_e32 v[34:35], v[4:5]
	v_mov_b64_e32 v[36:37], v[4:5]
	v_mov_b64_e32 v[38:39], v[4:5]
	v_mov_b64_e32 v[40:41], v[4:5]
	v_mov_b64_e32 v[42:43], v[4:5]
	v_mov_b64_e32 v[44:45], v[4:5]
	v_mov_b64_e32 v[46:47], v[4:5]
	v_mov_b64_e32 v[48:49], v[4:5]
	v_mov_b64_e32 v[50:51], v[4:5]
	v_mov_b64_e32 v[52:53], v[4:5]
	v_mov_b64_e32 v[54:55], v[4:5]
	v_mov_b64_e32 v[56:57], v[4:5]
	v_mov_b64_e32 v[58:59], v[4:5]
	v_mov_b64_e32 v[60:61], v[4:5]
	v_mov_b64_e32 v[62:63], v[4:5]
	v_mov_b64_e32 v[64:65], v[4:5]
	v_mov_b64_e32 v[66:67], v[4:5]
	v_mov_b64_e32 v[68:69], v[4:5]
	v_mov_b64_e32 v[70:71], v[4:5]
	v_mov_b64_e32 v[72:73], v[4:5]
	v_mov_b64_e32 v[74:75], v[4:5]
	v_mov_b64_e32 v[76:77], v[4:5]
	v_mov_b64_e32 v[78:79], v[4:5]
	v_mov_b64_e32 v[80:81], v[4:5]
	v_mov_b64_e32 v[82:83], v[4:5]
	v_mov_b64_e32 v[84:85], v[4:5]
	v_mov_b64_e32 v[86:87], v[4:5]
	v_mov_b64_e32 v[88:89], v[4:5]
	v_mov_b64_e32 v[90:91], v[4:5]
	v_mov_b64_e32 v[92:93], v[4:5]
	v_mov_b64_e32 v[94:95], v[4:5]
	v_mov_b64_e32 v[96:97], v[4:5]
	v_mov_b64_e32 v[98:99], v[4:5]
	v_mov_b64_e32 v[100:101], v[4:5]
	v_mov_b64_e32 v[102:103], v[4:5]
	v_mov_b64_e32 v[104:105], v[4:5]
	v_mov_b64_e32 v[106:107], v[4:5]
	v_mov_b64_e32 v[108:109], v[4:5]
	v_mov_b64_e32 v[110:111], v[4:5]
	v_mov_b64_e32 v[112:113], v[4:5]
	v_mov_b64_e32 v[114:115], v[4:5]
	v_mov_b64_e32 v[116:117], v[4:5]
	v_mov_b64_e32 v[118:119], v[4:5]
	v_mov_b64_e32 v[120:121], v[4:5]
	v_mov_b64_e32 v[122:123], v[4:5]
	v_mov_b64_e32 v[124:125], v[4:5]
	v_mov_b64_e32 v[126:127], v[4:5]
	v_mov_b64_e32 v[128:129], v[4:5]
	v_mov_b64_e32 v[130:131], v[4:5]
	s_mov_b64 s[60:61], 0xc000100
	s_mov_b64 s[62:63], 0xc040100
	s_mov_b64 s[64:65], 0xc000180
	s_mov_b64 s[66:67], 0xc040180
	s_barrier
; #define LDA8(dst, b, h) _Pragma("unroll") for (int m = 0; m < 4; ++m) _Pragma("unroll") for (int k = 0; k < 2; ++k) \
;     dst[m][k] = *(const bf16x8*)((const char*)SA8(b, h) + lds_byte8(wr * 64 + m * 16 + fr, k * 32 + fq * 8))
; #define LDB8(dst, b, h) _Pragma("unroll") for (int n = 0; n < 2; ++n) _Pragma("unroll") for (int k = 0; k < 2; ++k) \
;     dst[n][k] = *(const bf16x8*)((const char*)SB8(b, h) + lds_byte8(wc * 32 + n * 16 + fr, k * 32 + fq * 8))
; #define WAIT_L8(n) asm volatile("s_waitcnt lgkmcnt(" #n ")" ::: "memory")
; #define BAR8 __builtin_amdgcn_s_barrier()
; #define SCHED8 __builtin_amdgcn_sched_barrier(0)
;     ...
;   for (int tt = 0; tt < nt - 2; tt += 2) {
;     LDB8(B0, 0, 0); SCHED8; LDA8(At, 0, 0); STAGE8(SA8(1, 1), A, lda, brow + 128, tt + 1);
;     WAIT_L8(8); BAR8; WAIT_L8(0); MMA8(0, 0, At, B0); BAR8; SCHED8;
;     LDB8(B1, 0, 1); STAGE8(SB8(0, 0), Bt, K, bcol, tt + 2);
;     BAR8; WAIT_L8(0); MMA8(0, 1, At, B1); BAR8;
;     LDA8(At, 0, 1); STAGE8(SA8(0, 0), A, lda, brow, tt + 2);
;     BAR8; WAIT_L8(0); MMA8(1, 0, At, B0); BAR8; SCHED8;
;     STAGE8(SB8(0, 1), Bt, K, bcol + 128, tt + 2);
.LBB0_192:
	ds_read_b128 v[174:177], v173
	ds_read_b128 v[178:181], v173 offset:1024
	ds_read_b128 v[182:185], v173 offset:2048
	ds_read_b128 v[186:189], v173 offset:3072
	v_lshl_add_u64 v[222:223], v[140:141], 0, s[12:13]
	v_lshl_add_u64 v[226:227], v[222:223], 0, s[34:35]
	s_or_b32 m0, s100, 0xc000
	ds_read_b128 v[190:193], v156
	ds_read_b128 v[194:197], v156 offset:1024
	ds_read_b128 v[198:201], v154
	ds_read_b128 v[202:205], v154 offset:1024
	ds_read_b128 v[206:209], v153
	ds_read_b128 v[210:213], v153 offset:1024
	ds_read_b128 v[214:217], v152
	ds_read_b128 v[218:221], v152 offset:1024
	global_load_lds_dwordx4 v[226:227], off
	v_lshl_add_u64 v[226:227], v[138:139], 0, s[12:13]
	v_lshl_add_u64 v[228:229], v[226:227], 0, s[34:35]
	s_or_b32 m0, s100, 0xe000
	s_nop 0
	global_load_lds_dwordx4 v[228:229], off
	s_waitcnt lgkmcnt(8)
	s_barrier
	s_waitcnt lgkmcnt(0)
	v_mfma_f32_16x16x32_f16 v[128:131], v[190:193], v[174:177], v[128:131]
	v_mfma_f32_16x16x32_f16 v[124:127], v[190:193], v[182:185], v[124:127]
	v_mfma_f32_16x16x32_f16 v[120:123], v[198:201], v[174:177], v[120:123]
	v_mfma_f32_16x16x32_f16 v[116:119], v[198:201], v[182:185], v[116:119]
	v_mfma_f32_16x16x32_f16 v[112:115], v[206:209], v[174:177], v[112:115]
	v_mfma_f32_16x16x32_f16 v[108:111], v[206:209], v[182:185], v[108:111]
	v_mfma_f32_16x16x32_f16 v[104:107], v[214:217], v[174:177], v[104:107]
	v_mfma_f32_16x16x32_f16 v[100:103], v[214:217], v[182:185], v[100:103]
	v_mfma_f32_16x16x32_f16 v[128:131], v[194:197], v[178:181], v[128:131]
	v_mfma_f32_16x16x32_f16 v[124:127], v[194:197], v[186:189], v[124:127]
	v_mfma_f32_16x16x32_f16 v[120:123], v[202:205], v[178:181], v[120:123]
	v_mfma_f32_16x16x32_f16 v[116:119], v[202:205], v[186:189], v[116:119]
	v_mfma_f32_16x16x32_f16 v[112:115], v[210:213], v[178:181], v[112:115]
	v_mfma_f32_16x16x32_f16 v[108:111], v[210:213], v[186:189], v[108:111]
	v_mfma_f32_16x16x32_f16 v[104:107], v[218:221], v[178:181], v[104:107]
	v_mfma_f32_16x16x32_f16 v[100:103], v[218:221], v[186:189], v[100:103]
	s_barrier
	v_lshl_add_u64 v[228:229], v[142:143], 0, s[12:13]
	v_lshl_add_u64 v[236:237], v[228:229], 0, s[60:61]
	s_or_b32 m0, s100, 0x10000
	ds_read_b128 v[238:241], v169
	ds_read_b128 v[242:245], v169 offset:1024
	ds_read_b128 v[246:249], v169 offset:2048
	ds_read_b128 v[230:233], v169 offset:3072
	global_load_lds_dwordx4 v[236:237], off
	v_lshl_add_u64 v[236:237], v[144:145], 0, s[12:13]
	v_lshl_add_u64 v[250:251], v[236:237], 0, s[60:61]
	s_or_b32 m0, s100, 0x12000
	s_nop 0
	global_load_lds_dwordx4 v[250:251], off
	s_barrier
	s_waitcnt lgkmcnt(0)
	v_mfma_f32_16x16x32_f16 v[96:99], v[190:193], v[238:241], v[96:99]
	v_mfma_f32_16x16x32_f16 v[92:95], v[190:193], v[246:249], v[92:95]
	v_mfma_f32_16x16x32_f16 v[88:91], v[198:201], v[238:241], v[88:91]
	v_mfma_f32_16x16x32_f16 v[84:87], v[198:201], v[246:249], v[84:87]
	v_mfma_f32_16x16x32_f16 v[80:83], v[206:209], v[238:241], v[80:83]
	v_mfma_f32_16x16x32_f16 v[76:79], v[206:209], v[246:249], v[76:79]
	v_mfma_f32_16x16x32_f16 v[72:75], v[214:217], v[238:241], v[72:75]
	v_mfma_f32_16x16x32_f16 v[68:71], v[214:217], v[246:249], v[68:71]
	v_mfma_f32_16x16x32_f16 v[96:99], v[194:197], v[242:245], v[96:99]
	v_mfma_f32_16x16x32_f16 v[92:95], v[194:197], v[230:233], v[92:95]
	v_mfma_f32_16x16x32_f16 v[88:91], v[202:205], v[242:245], v[88:91]
	v_mfma_f32_16x16x32_f16 v[84:87], v[202:205], v[230:233], v[84:87]
	v_mfma_f32_16x16x32_f16 v[80:83], v[210:213], v[242:245], v[80:83]
	v_mfma_f32_16x16x32_f16 v[76:79], v[210:213], v[230:233], v[76:79]
	v_mfma_f32_16x16x32_f16 v[72:75], v[218:221], v[242:245], v[72:75]
	v_mfma_f32_16x16x32_f16 v[68:71], v[218:221], v[230:233], v[68:71]
	v_lshl_add_u64 v[250:251], v[222:223], 0, s[10:11]
	s_mov_b32 m0, s100
	s_barrier
	ds_read_b128 v[190:193], v156 offset:16384
	ds_read_b128 v[194:197], v156 offset:17408
	ds_read_b128 v[198:201], v154 offset:16384
	ds_read_b128 v[202:205], v154 offset:17408
	ds_read_b128 v[206:209], v153 offset:16384
	ds_read_b128 v[210:213], v153 offset:17408
	ds_read_b128 v[214:217], v152 offset:16384
	ds_read_b128 v[218:221], v152 offset:17408
	global_load_lds_dwordx4 v[250:251], off
	v_lshl_add_u64 v[250:251], v[226:227], 0, s[10:11]
	s_or_b32 m0, s100, 0x2000
	s_nop 0
	global_load_lds_dwordx4 v[250:251], off
	s_barrier
	s_waitcnt lgkmcnt(0)
	v_mfma_f32_16x16x32_f16 v[64:67], v[190:193], v[174:177], v[64:67]
	v_mfma_f32_16x16x32_f16 v[60:63], v[190:193], v[182:185], v[60:63]
	v_mfma_f32_16x16x32_f16 v[56:59], v[198:201], v[174:177], v[56:59]
	v_mfma_f32_16x16x32_f16 v[52:55], v[198:201], v[182:185], v[52:55]
	v_mfma_f32_16x16x32_f16 v[48:51], v[206:209], v[174:177], v[48:51]
	v_mfma_f32_16x16x32_f16 v[44:47], v[206:209], v[182:185], v[44:47]
	v_mfma_f32_16x16x32_f16 v[40:43], v[214:217], v[174:177], v[40:43]
	v_mfma_f32_16x16x32_f16 v[36:39], v[214:217], v[182:185], v[36:39]
	v_mfma_f32_16x16x32_f16 v[64:67], v[194:197], v[178:181], v[64:67]
	v_mfma_f32_16x16x32_f16 v[60:63], v[194:197], v[186:189], v[60:63]
	v_mfma_f32_16x16x32_f16 v[56:59], v[202:205], v[178:181], v[56:59]
	v_mfma_f32_16x16x32_f16 v[52:55], v[202:205], v[186:189], v[52:55]
	v_mfma_f32_16x16x32_f16 v[48:51], v[210:213], v[178:181], v[48:51]
	v_mfma_f32_16x16x32_f16 v[44:47], v[210:213], v[186:189], v[44:47]
	v_mfma_f32_16x16x32_f16 v[40:43], v[218:221], v[178:181], v[40:43]
	v_mfma_f32_16x16x32_f16 v[36:39], v[218:221], v[186:189], v[36:39]
	s_barrier
	v_lshl_add_u64 v[174:175], v[228:229], 0, s[62:63]
	s_or_b32 m0, s100, 0x14000
	s_nop 0
	global_load_lds_dwordx4 v[174:175], off
	v_lshl_add_u64 v[174:175], v[236:237], 0, s[62:63]
	s_or_b32 m0, s100, 0x16000
	s_nop 0
	global_load_lds_dwordx4 v[174:175], off
	s_waitcnt vmcnt(6)
	s_barrier
; #define LDA8(dst, b, h) _Pragma("unroll") for (int m = 0; m < 4; ++m) _Pragma("unroll") for (int k = 0; k < 2; ++k) \
;     dst[m][k] = *(const bf16x8*)((const char*)SA8(b, h) + lds_byte8(wr * 64 + m * 16 + fr, k * 32 + fq * 8))
; #define LDB8(dst, b, h) _Pragma("unroll") for (int n = 0; n < 2; ++n) _Pragma("unroll") for (int k = 0; k < 2; ++k) \
;     dst[n][k] = *(const bf16x8*)((const char*)SB8(b, h) + lds_byte8(wc * 32 + n * 16 + fr, k * 32 + fq * 8))
; #define WAIT_V8(n) asm volatile("s_waitcnt vmcnt(" #n ")" ::: "memory")
; #define WAIT_L8(n) asm volatile("s_waitcnt lgkmcnt(" #n ")" ::: "memory")
; #define BAR8 __builtin_amdgcn_s_barrier()
; #define SCHED8 __builtin_amdgcn_sched_barrier(0)
;     ...
;     WAIT_V8(6); BAR8; MMA8(1, 1, At, B1); BAR8;
;     LDB8(B0, 1, 0); SCHED8; LDA8(At, 1, 0); STAGE8(SA8(0, 1), A, lda, brow + 128, tt + 2);
;     WAIT_L8(8); BAR8; WAIT_L8(0); MMA8(0, 0, At, B0); BAR8; SCHED8;
;     LDB8(B1, 1, 1); STAGE8(SB8(1, 0), Bt, K, bcol, tt + 3);
;     BAR8; WAIT_L8(0); MMA8(0, 1, At, B1); BAR8;
;     LDA8(At, 1, 1); STAGE8(SA8(1, 0), A, lda, brow, tt + 3);
	v_mfma_f32_16x16x32_f16 v[32:35], v[190:193], v[238:241], v[32:35]
	v_mfma_f32_16x16x32_f16 v[28:31], v[190:193], v[246:249], v[28:31]
	v_mfma_f32_16x16x32_f16 v[24:27], v[198:201], v[238:241], v[24:27]
	v_mfma_f32_16x16x32_f16 v[20:23], v[198:201], v[246:249], v[20:23]
	v_mfma_f32_16x16x32_f16 v[16:19], v[206:209], v[238:241], v[16:19]
	v_mfma_f32_16x16x32_f16 v[12:15], v[206:209], v[246:249], v[12:15]
	v_mfma_f32_16x16x32_f16 v[8:11], v[214:217], v[238:241], v[8:11]
	v_mfma_f32_16x16x32_f16 v[4:7], v[214:217], v[246:249], v[4:7]
	v_mfma_f32_16x16x32_f16 v[32:35], v[194:197], v[242:245], v[32:35]
	v_mfma_f32_16x16x32_f16 v[28:31], v[194:197], v[230:233], v[28:31]
	v_mfma_f32_16x16x32_f16 v[24:27], v[202:205], v[242:245], v[24:27]
	v_mfma_f32_16x16x32_f16 v[20:23], v[202:205], v[230:233], v[20:23]
	v_mfma_f32_16x16x32_f16 v[16:19], v[210:213], v[242:245], v[16:19]
	v_mfma_f32_16x16x32_f16 v[12:15], v[210:213], v[230:233], v[12:15]
	v_mfma_f32_16x16x32_f16 v[8:11], v[218:221], v[242:245], v[8:11]
	v_mfma_f32_16x16x32_f16 v[4:7], v[218:221], v[230:233], v[4:7]
	s_barrier
	ds_read_b128 v[174:177], v159
	ds_read_b128 v[178:181], v159 offset:1024
	ds_read_b128 v[182:185], v159 offset:2048
	ds_read_b128 v[186:189], v159 offset:3072
	v_lshl_add_u64 v[230:231], v[222:223], 0, s[18:19]
	s_or_b32 m0, s100, 0x4000
	ds_read_b128 v[190:193], v156 offset:32768
	ds_read_b128 v[194:197], v156 offset:33792
	ds_read_b128 v[198:201], v154 offset:32768
	ds_read_b128 v[202:205], v154 offset:33792
	ds_read_b128 v[206:209], v153 offset:32768
	ds_read_b128 v[210:213], v153 offset:33792
	ds_read_b128 v[214:217], v152 offset:32768
	ds_read_b128 v[218:221], v152 offset:33792
	global_load_lds_dwordx4 v[230:231], off
	v_lshl_add_u64 v[230:231], v[226:227], 0, s[18:19]
	s_or_b32 m0, s100, 0x6000
	s_nop 0
	global_load_lds_dwordx4 v[230:231], off
	s_waitcnt lgkmcnt(8)
	s_barrier
	s_waitcnt lgkmcnt(0)
	v_mfma_f32_16x16x32_f16 v[128:131], v[190:193], v[174:177], v[128:131]
	v_mfma_f32_16x16x32_f16 v[124:127], v[190:193], v[182:185], v[124:127]
	v_mfma_f32_16x16x32_f16 v[120:123], v[198:201], v[174:177], v[120:123]
	v_mfma_f32_16x16x32_f16 v[116:119], v[198:201], v[182:185], v[116:119]
	v_mfma_f32_16x16x32_f16 v[112:115], v[206:209], v[174:177], v[112:115]
	v_mfma_f32_16x16x32_f16 v[108:111], v[206:209], v[182:185], v[108:111]
	v_mfma_f32_16x16x32_f16 v[104:107], v[214:217], v[174:177], v[104:107]
	v_mfma_f32_16x16x32_f16 v[100:103], v[214:217], v[182:185], v[100:103]
	v_mfma_f32_16x16x32_f16 v[128:131], v[194:197], v[178:181], v[128:131]
	v_mfma_f32_16x16x32_f16 v[124:127], v[194:197], v[186:189], v[124:127]
	v_mfma_f32_16x16x32_f16 v[120:123], v[202:205], v[178:181], v[120:123]
	v_mfma_f32_16x16x32_f16 v[116:119], v[202:205], v[186:189], v[116:119]
	v_mfma_f32_16x16x32_f16 v[112:115], v[210:213], v[178:181], v[112:115]
	v_mfma_f32_16x16x32_f16 v[108:111], v[210:213], v[186:189], v[108:111]
	v_mfma_f32_16x16x32_f16 v[104:107], v[218:221], v[178:181], v[104:107]
	v_mfma_f32_16x16x32_f16 v[100:103], v[218:221], v[186:189], v[100:103]
	s_barrier
	v_lshl_add_u64 v[250:251], v[228:229], 0, s[64:65]
	s_or_b32 m0, s100, 0x18000
	ds_read_b128 v[230:233], v158
	ds_read_b128 v[238:241], v158 offset:1024
	ds_read_b128 v[242:245], v158 offset:2048
	ds_read_b128 v[246:249], v158 offset:3072
	global_load_lds_dwordx4 v[250:251], off
	v_lshl_add_u64 v[250:251], v[236:237], 0, s[64:65]
	s_or_b32 m0, s100, 0x1a000
	s_nop 0
	global_load_lds_dwordx4 v[250:251], off
	s_barrier
	s_waitcnt lgkmcnt(0)
	v_mfma_f32_16x16x32_f16 v[96:99], v[190:193], v[230:233], v[96:99]
	v_mfma_f32_16x16x32_f16 v[92:95], v[190:193], v[242:245], v[92:95]
	v_mfma_f32_16x16x32_f16 v[88:91], v[198:201], v[230:233], v[88:91]
	v_mfma_f32_16x16x32_f16 v[84:87], v[198:201], v[242:245], v[84:87]
	v_mfma_f32_16x16x32_f16 v[80:83], v[206:209], v[230:233], v[80:83]
	v_mfma_f32_16x16x32_f16 v[76:79], v[206:209], v[242:245], v[76:79]
	v_mfma_f32_16x16x32_f16 v[72:75], v[214:217], v[230:233], v[72:75]
	v_mfma_f32_16x16x32_f16 v[68:71], v[214:217], v[242:245], v[68:71]
	v_mfma_f32_16x16x32_f16 v[96:99], v[194:197], v[238:241], v[96:99]
	v_mfma_f32_16x16x32_f16 v[92:95], v[194:197], v[246:249], v[92:95]
	v_mfma_f32_16x16x32_f16 v[88:91], v[202:205], v[238:241], v[88:91]
	v_mfma_f32_16x16x32_f16 v[84:87], v[202:205], v[246:249], v[84:87]
	v_mfma_f32_16x16x32_f16 v[80:83], v[210:213], v[238:241], v[80:83]
	v_mfma_f32_16x16x32_f16 v[76:79], v[210:213], v[246:249], v[76:79]
	v_mfma_f32_16x16x32_f16 v[72:75], v[218:221], v[238:241], v[72:75]
	v_mfma_f32_16x16x32_f16 v[68:71], v[218:221], v[246:249], v[68:71]
	v_lshl_add_u64 v[222:223], v[222:223], 0, s[22:23]
	s_or_b32 m0, s100, 0x8000
	s_barrier
	ds_read_b128 v[190:193], v156 offset:49152
	ds_read_b128 v[194:197], v156 offset:50176
	ds_read_b128 v[198:201], v154 offset:49152
	ds_read_b128 v[202:205], v154 offset:50176
	ds_read_b128 v[206:209], v153 offset:49152
	ds_read_b128 v[210:213], v153 offset:50176
	ds_read_b128 v[214:217], v152 offset:49152
	ds_read_b128 v[218:221], v152 offset:50176
	global_load_lds_dwordx4 v[222:223], off
	v_lshl_add_u64 v[222:223], v[226:227], 0, s[22:23]
	s_or_b32 m0, s100, 0xa000
	s_nop 0
	global_load_lds_dwordx4 v[222:223], off
	s_barrier
; #define LDA8(dst, b, h) _Pragma("unroll") for (int m = 0; m < 4; ++m) _Pragma("unroll") for (int k = 0; k < 2; ++k) \
;     dst[m][k] = *(const bf16x8*)((const char*)SA8(b, h) + lds_byte8(wr * 64 + m * 16 + fr, k * 32 + fq * 8))
; #define LDB8(dst, b, h) _Pragma("unroll") for (int n = 0; n < 2; ++n) _Pragma("unroll") for (int k = 0; k < 2; ++k) \
;     dst[n][k] = *(const bf16x8*)((const char*)SB8(b, h) + lds_byte8(wc * 32 + n * 16 + fr, k * 32 + fq * 8))
; #define WAIT_V8(n) asm volatile("s_waitcnt vmcnt(" #n ")" ::: "memory")
; #define WAIT_L8(n) asm volatile("s_waitcnt lgkmcnt(" #n ")" ::: "memory")
; #define BAR8 __builtin_amdgcn_s_barrier()
; #define SCHED8 __builtin_amdgcn_sched_barrier(0)
;     ...
;     BAR8; WAIT_L8(0); MMA8(1, 0, At, B0); BAR8; SCHED8;
;     STAGE8(SB8(1, 1), Bt, K, bcol + 128, tt + 3);
;     WAIT_V8(6); BAR8; MMA8(1, 1, At, B1); BAR8;
;   }
;   { LDB8(B0, 0, 0); LDA8(At, 0, 0); STAGE8(SA8(1, 1), A, lda, brow + 128, nt - 1);
;     BAR8; WAIT_L8(0); MMA8(0, 0, At, B0); BAR8;
;     LDB8(B1, 0, 1); BAR8; WAIT_L8(0); MMA8(0, 1, At, B1); BAR8;
;     LDA8(At, 0, 1); WAIT_V8(4); BAR8; WAIT_L8(0); MMA8(1, 0, At, B0); MMA8(1, 1, At, B1); BAR8; }
	s_waitcnt lgkmcnt(0)
	v_mfma_f32_16x16x32_f16 v[64:67], v[190:193], v[174:177], v[64:67]
	v_mfma_f32_16x16x32_f16 v[60:63], v[190:193], v[182:185], v[60:63]
	v_mfma_f32_16x16x32_f16 v[56:59], v[198:201], v[174:177], v[56:59]
	v_mfma_f32_16x16x32_f16 v[52:55], v[198:201], v[182:185], v[52:55]
	v_mfma_f32_16x16x32_f16 v[48:51], v[206:209], v[174:177], v[48:51]
	v_mfma_f32_16x16x32_f16 v[44:47], v[206:209], v[182:185], v[44:47]
	v_mfma_f32_16x16x32_f16 v[40:43], v[214:217], v[174:177], v[40:43]
	v_mfma_f32_16x16x32_f16 v[36:39], v[214:217], v[182:185], v[36:39]
	v_mfma_f32_16x16x32_f16 v[64:67], v[194:197], v[178:181], v[64:67]
	v_mfma_f32_16x16x32_f16 v[60:63], v[194:197], v[186:189], v[60:63]
	v_mfma_f32_16x16x32_f16 v[56:59], v[202:205], v[178:181], v[56:59]
	v_mfma_f32_16x16x32_f16 v[52:55], v[202:205], v[186:189], v[52:55]
	v_mfma_f32_16x16x32_f16 v[48:51], v[210:213], v[178:181], v[48:51]
	v_mfma_f32_16x16x32_f16 v[44:47], v[210:213], v[186:189], v[44:47]
	v_mfma_f32_16x16x32_f16 v[40:43], v[218:221], v[178:181], v[40:43]
	v_mfma_f32_16x16x32_f16 v[36:39], v[218:221], v[186:189], v[36:39]
	s_barrier
	v_lshl_add_u64 v[174:175], v[228:229], 0, s[66:67]
	s_or_b32 m0, s100, 0x1c000
	s_nop 0
	global_load_lds_dwordx4 v[174:175], off
	v_lshl_add_u64 v[174:175], v[236:237], 0, s[66:67]
	s_or_b32 m0, s100, 0x1e000
	s_nop 0
	global_load_lds_dwordx4 v[174:175], off
	s_waitcnt vmcnt(6)
	s_barrier
	v_mfma_f32_16x16x32_f16 v[32:35], v[190:193], v[230:233], v[32:35]
	v_mfma_f32_16x16x32_f16 v[28:31], v[190:193], v[242:245], v[28:31]
	v_mfma_f32_16x16x32_f16 v[24:27], v[198:201], v[230:233], v[24:27]
	v_mfma_f32_16x16x32_f16 v[20:23], v[198:201], v[242:245], v[20:23]
	v_mfma_f32_16x16x32_f16 v[16:19], v[206:209], v[230:233], v[16:19]
	v_mfma_f32_16x16x32_f16 v[12:15], v[206:209], v[242:245], v[12:15]
	v_mfma_f32_16x16x32_f16 v[8:11], v[214:217], v[230:233], v[8:11]
	v_mfma_f32_16x16x32_f16 v[4:7], v[214:217], v[242:245], v[4:7]
	v_mfma_f32_16x16x32_f16 v[32:35], v[194:197], v[238:241], v[32:35]
	v_mfma_f32_16x16x32_f16 v[28:31], v[194:197], v[246:249], v[28:31]
	v_mfma_f32_16x16x32_f16 v[24:27], v[202:205], v[238:241], v[24:27]
	v_mfma_f32_16x16x32_f16 v[20:23], v[202:205], v[246:249], v[20:23]
	v_mfma_f32_16x16x32_f16 v[16:19], v[210:213], v[238:241], v[16:19]
	v_mfma_f32_16x16x32_f16 v[12:15], v[210:213], v[246:249], v[12:15]
	v_mfma_f32_16x16x32_f16 v[8:11], v[218:221], v[238:241], v[8:11]
	v_mfma_f32_16x16x32_f16 v[4:7], v[218:221], v[246:249], v[4:7]
	s_add_i32 s14, s14, 2
	s_add_u32 s12, s12, 0x100
	s_addc_u32 s13, s13, 0
	s_cmp_lt_u32 s14, 12
	s_barrier
	s_cbranch_scc1 .LBB0_192
	s_add_u32 s4, s4, 0x40780
	s_addc_u32 s5, s5, 0
	v_lshl_add_u64 v[132:133], s[4:5], 0, v[132:133]
	v_lshl_add_u64 v[0:1], v[0:1], 1, v[132:133]
	s_or_b32 m0, s100, 0xc000
	ds_read_b128 v[138:141], v173
	ds_read_b128 v[142:145], v173 offset:1024
	ds_read_b128 v[160:163], v173 offset:2048
	ds_read_b128 v[164:167], v173 offset:3072
	ds_read_b128 v[174:177], v156
	ds_read_b128 v[178:181], v156 offset:1024
	ds_read_b128 v[182:185], v154
	ds_read_b128 v[186:189], v154 offset:1024
	ds_read_b128 v[190:193], v153
	ds_read_b128 v[194:197], v153 offset:1024
	ds_read_b128 v[198:201], v152
	ds_read_b128 v[202:205], v152 offset:1024
	global_load_lds_dwordx4 v[0:1], off
	v_lshl_add_u64 v[0:1], s[4:5], 0, v[136:137]
	v_lshl_add_u64 v[0:1], v[134:135], 1, v[0:1]
	s_or_b32 m0, s100, 0xe000
	s_nop 0
	global_load_lds_dwordx4 v[0:1], off
	s_barrier
	s_waitcnt lgkmcnt(0)
	v_mfma_f32_16x16x32_f16 v[128:131], v[174:177], v[138:141], v[128:131]
	v_mfma_f32_16x16x32_f16 v[124:127], v[174:177], v[160:163], v[124:127]
	v_mfma_f32_16x16x32_f16 v[120:123], v[182:185], v[138:141], v[120:123]
	v_mfma_f32_16x16x32_f16 v[112:115], v[190:193], v[138:141], v[112:115]
	v_mfma_f32_16x16x32_f16 v[128:131], v[178:181], v[142:145], v[128:131]
	v_mfma_f32_16x16x32_f16 v[124:127], v[178:181], v[164:167], v[124:127]
	v_mfma_f32_16x16x32_f16 v[120:123], v[186:189], v[142:145], v[120:123]
	v_mfma_f32_16x16x32_f16 v[116:119], v[182:185], v[160:163], v[116:119]
	v_mfma_f32_16x16x32_f16 v[112:115], v[194:197], v[142:145], v[112:115]
	v_mfma_f32_16x16x32_f16 v[108:111], v[190:193], v[160:163], v[108:111]
	v_mfma_f32_16x16x32_f16 v[104:107], v[198:201], v[138:141], v[104:107]
	v_mfma_f32_16x16x32_f16 v[100:103], v[198:201], v[160:163], v[100:103]
	v_mfma_f32_16x16x32_f16 v[132:135], v[186:189], v[164:167], v[116:119]
	v_mfma_f32_16x16x32_f16 v[170:173], v[194:197], v[164:167], v[108:111]
	v_mfma_f32_16x16x32_f16 v[206:209], v[202:205], v[142:145], v[104:107]
	v_mfma_f32_16x16x32_f16 v[210:213], v[202:205], v[164:167], v[100:103]
	s_barrier
	s_nop 1
	ds_read_b128 v[100:103], v169
	ds_read_b128 v[104:107], v169 offset:1024
	ds_read_b128 v[108:111], v169 offset:2048
	ds_read_b128 v[116:119], v169 offset:3072
	s_barrier
	s_waitcnt lgkmcnt(0)
	v_mfma_f32_16x16x32_f16 v[80:83], v[190:193], v[100:103], v[80:83]
	v_mfma_f32_16x16x32_f16 v[76:79], v[190:193], v[108:111], v[76:79]
	v_mfma_f32_16x16x32_f16 v[72:75], v[198:201], v[100:103], v[72:75]
	v_mfma_f32_16x16x32_f16 v[68:71], v[198:201], v[108:111], v[68:71]
	v_mfma_f32_16x16x32_f16 v[96:99], v[174:177], v[100:103], v[96:99]
	v_mfma_f32_16x16x32_f16 v[92:95], v[174:177], v[108:111], v[92:95]
	v_mfma_f32_16x16x32_f16 v[88:91], v[182:185], v[100:103], v[88:91]
	v_mfma_f32_16x16x32_f16 v[84:87], v[182:185], v[108:111], v[84:87]
	v_mfma_f32_16x16x32_f16 v[80:83], v[194:197], v[104:107], v[80:83]
	v_mfma_f32_16x16x32_f16 v[76:79], v[194:197], v[116:119], v[76:79]
	v_mfma_f32_16x16x32_f16 v[72:75], v[202:205], v[104:107], v[72:75]
	v_mfma_f32_16x16x32_f16 v[68:71], v[202:205], v[116:119], v[68:71]
	v_mfma_f32_16x16x32_f16 v[214:217], v[178:181], v[104:107], v[96:99]
	v_mfma_f32_16x16x32_f16 v[174:177], v[178:181], v[116:119], v[92:95]
	v_mfma_f32_16x16x32_f16 v[178:181], v[186:189], v[104:107], v[88:91]
	v_mfma_f32_16x16x32_f16 v[182:185], v[186:189], v[116:119], v[84:87]
	s_barrier
; #define LDA8(dst, b, h) _Pragma("unroll") for (int m = 0; m < 4; ++m) _Pragma("unroll") for (int k = 0; k < 2; ++k) \
;     dst[m][k] = *(const bf16x8*)((const char*)SA8(b, h) + lds_byte8(wr * 64 + m * 16 + fr, k * 32 + fq * 8))
; #define LDB8(dst, b, h) _Pragma("unroll") for (int n = 0; n < 2; ++n) _Pragma("unroll") for (int k = 0; k < 2; ++k) \
;     dst[n][k] = *(const bf16x8*)((const char*)SB8(b, h) + lds_byte8(wc * 32 + n * 16 + fr, k * 32 + fq * 8))
; #define WAIT_V8(n) asm volatile("s_waitcnt vmcnt(" #n ")" ::: "memory")
; #define WAIT_L8(n) asm volatile("s_waitcnt lgkmcnt(" #n ")" ::: "memory")
; #define BAR8 __builtin_amdgcn_s_barrier()
;     ...
;     LDA8(At, 0, 1); WAIT_V8(4); BAR8; WAIT_L8(0); MMA8(1, 0, At, B0); MMA8(1, 1, At, B1); BAR8; }
;   { LDB8(B0, 1, 0); LDA8(At, 1, 0); WAIT_V8(2); BAR8; WAIT_L8(0); MMA8(0, 0, At, B0); BAR8;
;     LDB8(B1, 1, 1); WAIT_V8(0); BAR8; WAIT_L8(0); MMA8(0, 1, At, B1); BAR8;
	s_nop 0
	ds_read_b128 v[84:87], v156 offset:16384
	ds_read_b128 v[88:91], v156 offset:17408
	ds_read_b128 v[92:95], v154 offset:16384
	ds_read_b128 v[96:99], v154 offset:17408
	ds_read_b128 v[186:189], v153 offset:16384
	ds_read_b128 v[190:193], v153 offset:17408
	ds_read_b128 v[194:197], v152 offset:16384
	ds_read_b128 v[198:201], v152 offset:17408
	s_waitcnt vmcnt(4)
	s_barrier
	s_waitcnt lgkmcnt(0)
	v_mfma_f32_16x16x32_f16 v[64:67], v[84:87], v[138:141], v[64:67]
	v_mfma_f32_16x16x32_f16 v[60:63], v[84:87], v[160:163], v[60:63]
	v_mfma_f32_16x16x32_f16 v[56:59], v[92:95], v[138:141], v[56:59]
	v_mfma_f32_16x16x32_f16 v[52:55], v[92:95], v[160:163], v[52:55]
	v_mfma_f32_16x16x32_f16 v[48:51], v[186:189], v[138:141], v[48:51]
	v_mfma_f32_16x16x32_f16 v[44:47], v[186:189], v[160:163], v[44:47]
	v_mfma_f32_16x16x32_f16 v[64:67], v[88:91], v[142:145], v[64:67]
	v_mfma_f32_16x16x32_f16 v[60:63], v[88:91], v[164:167], v[60:63]
	v_mfma_f32_16x16x32_f16 v[56:59], v[96:99], v[142:145], v[56:59]
	v_mfma_f32_16x16x32_f16 v[52:55], v[96:99], v[164:167], v[52:55]
	v_mfma_f32_16x16x32_f16 v[48:51], v[190:193], v[142:145], v[48:51]
	v_mfma_f32_16x16x32_f16 v[44:47], v[190:193], v[164:167], v[44:47]
	v_mfma_f32_16x16x32_f16 v[40:43], v[194:197], v[138:141], v[40:43]
	v_mfma_f32_16x16x32_f16 v[36:39], v[194:197], v[160:163], v[36:39]
	v_mfma_f32_16x16x32_f16 v[136:139], v[198:201], v[142:145], v[40:43]
	v_mfma_f32_16x16x32_f16 v[140:143], v[198:201], v[164:167], v[36:39]
	v_mfma_f32_16x16x32_f16 v[32:35], v[84:87], v[100:103], v[32:35]
	v_mfma_f32_16x16x32_f16 v[28:31], v[84:87], v[108:111], v[28:31]
	v_mfma_f32_16x16x32_f16 v[24:27], v[92:95], v[100:103], v[24:27]
	v_mfma_f32_16x16x32_f16 v[20:23], v[92:95], v[108:111], v[20:23]
	v_mfma_f32_16x16x32_f16 v[16:19], v[186:189], v[100:103], v[16:19]
	v_mfma_f32_16x16x32_f16 v[12:15], v[186:189], v[108:111], v[12:15]
	v_mfma_f32_16x16x32_f16 v[8:11], v[194:197], v[100:103], v[8:11]
	v_mfma_f32_16x16x32_f16 v[4:7], v[194:197], v[108:111], v[4:7]
	v_mfma_f32_16x16x32_f16 v[160:163], v[88:91], v[104:107], v[32:35]
	v_mfma_f32_16x16x32_f16 v[164:167], v[88:91], v[116:119], v[28:31]
	v_mfma_f32_16x16x32_f16 v[202:205], v[96:99], v[104:107], v[24:27]
	v_mfma_f32_16x16x32_f16 v[218:221], v[96:99], v[116:119], v[20:23]
	v_mfma_f32_16x16x32_f16 v[230:233], v[190:193], v[104:107], v[16:19]
	v_mfma_f32_16x16x32_f16 v[186:189], v[190:193], v[116:119], v[12:15]
	v_mfma_f32_16x16x32_f16 v[190:193], v[198:201], v[104:107], v[8:11]
	v_mfma_f32_16x16x32_f16 v[194:197], v[198:201], v[116:119], v[4:7]
	s_barrier
	s_nop 0
	ds_read_b128 v[4:7], v159
	ds_read_b128 v[8:11], v159 offset:1024
	ds_read_b128 v[198:201], v159 offset:2048
	ds_read_b128 v[238:241], v159 offset:3072
	ds_read_b128 v[16:19], v156 offset:32768
	ds_read_b128 v[20:23], v156 offset:33792
	ds_read_b128 v[24:27], v154 offset:32768
	ds_read_b128 v[32:35], v154 offset:33792
	ds_read_b128 v[36:39], v153 offset:32768
	ds_read_b128 v[40:43], v153 offset:33792
	ds_read_b128 v[242:245], v152 offset:32768
	ds_read_b128 v[246:249], v152 offset:33792
	s_waitcnt vmcnt(2)
	s_barrier
	s_waitcnt lgkmcnt(0)
	v_mfma_f32_16x16x32_f16 v[12:15], v[16:19], v[4:7], v[128:131]
	v_mfma_f32_16x16x32_f16 v[104:107], v[20:23], v[8:11], v[12:15]
	v_mfma_f32_16x16x32_f16 v[12:15], v[16:19], v[198:201], v[124:127]
	v_mfma_f32_16x16x32_f16 v[116:119], v[20:23], v[238:241], v[12:15]
	v_mfma_f32_16x16x32_f16 v[12:15], v[24:27], v[4:7], v[120:123]
	v_mfma_f32_16x16x32_f16 v[100:103], v[32:35], v[8:11], v[12:15]
	v_mfma_f32_16x16x32_f16 v[12:15], v[24:27], v[198:201], v[132:135]
	v_mfma_f32_16x16x32_f16 v[108:111], v[32:35], v[238:241], v[12:15]
	v_mfma_f32_16x16x32_f16 v[12:15], v[36:39], v[4:7], v[112:115]
	v_mfma_f32_16x16x32_f16 v[92:95], v[40:43], v[8:11], v[12:15]
	v_mfma_f32_16x16x32_f16 v[12:15], v[36:39], v[198:201], v[170:173]
	v_mfma_f32_16x16x32_f16 v[96:99], v[40:43], v[238:241], v[12:15]
	v_mfma_f32_16x16x32_f16 v[12:15], v[242:245], v[4:7], v[206:209]
	v_mfma_f32_16x16x32_f16 v[84:87], v[246:249], v[8:11], v[12:15]
	v_mfma_f32_16x16x32_f16 v[12:15], v[242:245], v[198:201], v[210:213]
	v_mfma_f32_16x16x32_f16 v[88:91], v[246:249], v[238:241], v[12:15]
	s_barrier
; #define LDA8(dst, b, h) _Pragma("unroll") for (int m = 0; m < 4; ++m) _Pragma("unroll") for (int k = 0; k < 2; ++k) \
;     dst[m][k] = *(const bf16x8*)((const char*)SA8(b, h) + lds_byte8(wr * 64 + m * 16 + fr, k * 32 + fq * 8))
; #define LDB8(dst, b, h) _Pragma("unroll") for (int n = 0; n < 2; ++n) _Pragma("unroll") for (int k = 0; k < 2; ++k) \
;     dst[n][k] = *(const bf16x8*)((const char*)SB8(b, h) + lds_byte8(wc * 32 + n * 16 + fr, k * 32 + fq * 8))
; #define WAIT_V8(n) asm volatile("s_waitcnt vmcnt(" #n ")" ::: "memory")
; #define WAIT_L8(n) asm volatile("s_waitcnt lgkmcnt(" #n ")" ::: "memory")
; #define BAR8 __builtin_amdgcn_s_barrier()
;     ...
;     LDB8(B1, 1, 1); WAIT_V8(0); BAR8; WAIT_L8(0); MMA8(0, 1, At, B1); BAR8;
;     LDA8(At, 1, 1); BAR8; WAIT_L8(0); MMA8(1, 0, At, B0); MMA8(1, 1, At, B1); BAR8; }
;   if (wr == 0) BAR8;
;   __syncthreads();
	ds_read_b128 v[132:135], v158
	ds_read_b128 v[168:171], v158 offset:1024
	ds_read_b128 v[206:209], v158 offset:2048
	ds_read_b128 v[210:213], v158 offset:3072
	s_waitcnt vmcnt(0)
	s_barrier
	s_waitcnt lgkmcnt(0)
	v_mfma_f32_16x16x32_f16 v[12:15], v[16:19], v[132:135], v[214:217]
	v_mfma_f32_16x16x32_f16 v[16:19], v[16:19], v[206:209], v[174:177]
	v_mfma_f32_16x16x32_f16 v[12:15], v[20:23], v[168:171], v[12:15]
	v_mfma_f32_16x16x32_f16 v[28:31], v[20:23], v[210:213], v[16:19]
	v_mfma_f32_16x16x32_f16 v[16:19], v[24:27], v[132:135], v[178:181]
	v_mfma_f32_16x16x32_f16 v[20:23], v[24:27], v[206:209], v[182:185]
	v_mfma_f32_16x16x32_f16 v[16:19], v[32:35], v[168:171], v[16:19]
	v_mfma_f32_16x16x32_f16 v[32:35], v[32:35], v[210:213], v[20:23]
	v_mfma_f32_16x16x32_f16 v[20:23], v[36:39], v[132:135], v[80:83]
	v_mfma_f32_16x16x32_f16 v[24:27], v[36:39], v[206:209], v[76:79]
	v_mfma_f32_16x16x32_f16 v[20:23], v[40:43], v[168:171], v[20:23]
	v_mfma_f32_16x16x32_f16 v[36:39], v[40:43], v[210:213], v[24:27]
	v_mfma_f32_16x16x32_f16 v[24:27], v[242:245], v[132:135], v[72:75]
	v_mfma_f32_16x16x32_f16 v[40:43], v[242:245], v[206:209], v[68:71]
	v_mfma_f32_16x16x32_f16 v[24:27], v[246:249], v[168:171], v[24:27]
	v_mfma_f32_16x16x32_f16 v[40:43], v[246:249], v[210:213], v[40:43]
	s_barrier
	ds_read_b128 v[68:71], v156 offset:49152
	ds_read_b128 v[72:75], v156 offset:50176
	ds_read_b128 v[156:159], v154 offset:49152
	ds_read_b128 v[172:175], v154 offset:50176
	ds_read_b128 v[176:179], v153 offset:49152
	ds_read_b128 v[180:183], v153 offset:50176
	ds_read_b128 v[214:217], v152 offset:49152
	ds_read_b128 v[150:153], v152 offset:50176
	s_barrier
	s_waitcnt lgkmcnt(0)
	v_mfma_f32_16x16x32_f16 v[64:67], v[68:71], v[4:7], v[64:67]
	v_mfma_f32_16x16x32_f16 v[56:59], v[156:159], v[4:7], v[56:59]
	v_mfma_f32_16x16x32_f16 v[48:51], v[176:179], v[4:7], v[48:51]
	v_mfma_f32_16x16x32_f16 v[4:7], v[214:217], v[4:7], v[136:139]
	v_mfma_f32_16x16x32_f16 v[128:131], v[72:75], v[8:11], v[64:67]
	v_mfma_f32_16x16x32_f16 v[60:63], v[68:71], v[198:201], v[60:63]
	v_mfma_f32_16x16x32_f16 v[120:123], v[172:175], v[8:11], v[56:59]
	v_mfma_f32_16x16x32_f16 v[52:55], v[156:159], v[198:201], v[52:55]
	v_mfma_f32_16x16x32_f16 v[80:83], v[180:183], v[8:11], v[48:51]
	v_mfma_f32_16x16x32_f16 v[44:47], v[176:179], v[198:201], v[44:47]
	v_mfma_f32_16x16x32_f16 v[8:11], v[150:153], v[8:11], v[4:7]
	v_mfma_f32_16x16x32_f16 v[4:7], v[214:217], v[198:201], v[140:143]
	v_mfma_f32_16x16x32_f16 v[124:127], v[72:75], v[238:241], v[60:63]
	v_mfma_f32_16x16x32_f16 v[112:115], v[172:175], v[238:241], v[52:55]
	v_mfma_f32_16x16x32_f16 v[76:79], v[180:183], v[238:241], v[44:47]
	v_mfma_f32_16x16x32_f16 v[4:7], v[150:153], v[238:241], v[4:7]
	v_mfma_f32_16x16x32_f16 v[44:47], v[68:71], v[132:135], v[160:163]
	v_mfma_f32_16x16x32_f16 v[48:51], v[68:71], v[206:209], v[164:167]
	v_mfma_f32_16x16x32_f16 v[52:55], v[156:159], v[206:209], v[218:221]
	v_mfma_f32_16x16x32_f16 v[56:59], v[176:179], v[206:209], v[186:189]
	v_mfma_f32_16x16x32_f16 v[44:47], v[72:75], v[168:171], v[44:47]
	v_mfma_f32_16x16x32_f16 v[60:63], v[72:75], v[210:213], v[48:51]
	v_mfma_f32_16x16x32_f16 v[48:51], v[156:159], v[132:135], v[202:205]
	v_mfma_f32_16x16x32_f16 v[64:67], v[172:175], v[210:213], v[52:55]
	v_mfma_f32_16x16x32_f16 v[52:55], v[176:179], v[132:135], v[230:233]
	v_mfma_f32_16x16x32_f16 v[68:71], v[180:183], v[210:213], v[56:59]
	v_mfma_f32_16x16x32_f16 v[56:59], v[214:217], v[132:135], v[190:193]
	v_mfma_f32_16x16x32_f16 v[72:75], v[214:217], v[206:209], v[194:197]
	v_mfma_f32_16x16x32_f16 v[48:51], v[172:175], v[168:171], v[48:51]
	v_mfma_f32_16x16x32_f16 v[52:55], v[180:183], v[168:171], v[52:55]
	v_mfma_f32_16x16x32_f16 v[56:59], v[150:153], v[168:171], v[56:59]
	v_mfma_f32_16x16x32_f16 v[72:75], v[150:153], v[210:213], v[72:75]
	s_movk_i32 s4, 0x100
	v_cmp_gt_u32_e32 vcc, s4, v3
	s_barrier
	s_and_saveexec_b64 s[4:5], vcc
	s_cbranch_execz .LBB0_195
	s_barrier

; #define BAR8 __builtin_amdgcn_s_barrier()
;     ...
;   const int brow = m0, bcol = n0;
;   const int wid = t >> 6, lane = t & 63, wr = wid >> 2, wc = wid & 3, fr = lane & 15, fq = lane >> 4;
;   f32x4 acc[2][2][4][2];
;   {
;     float zinit = 0.f;
;     asm volatile("" : "+v"(zinit));
; #pragma unroll
;     for (int a = 0; a < 2; ++a)
; #pragma unroll
;       for (int b = 0; b < 2; ++b)
; #pragma unroll
;         for (int m = 0; m < 4; ++m)
; #pragma unroll
;           for (int n = 0; n < 2; ++n)
; #pragma unroll
;             for (int j = 0; j < 4; ++j) acc[a][b][m][n][j] = zinit;
;   }
;   bf16x8 At[4][2], B0[2][2], B1[2][2];
;   const int nt = K / 64;
;   if (!pre) {
;     STAGE8(SB8(0, 0), Bt, K, bcol, 0); STAGE8(SA8(0, 0), A, lda, brow, 0);
;     STAGE8(SB8(0, 1), Bt, K, bcol + 128, 0); STAGE8(SA8(0, 1), A, lda, brow + 128, 0);
;   }
;   if (wr == 1) BAR8;
.LBB0_238:
	s_and_b64 vcc, exec, s[0:1]
	s_cbranch_vccz .LBB0_187
	s_mov_b32 s0, 25
	s_ashr_i32 s1, s0, 31
	s_lshl_b64 s[0:1], s[0:1], 3
	s_add_u32 s0, s70, s0
	s_addc_u32 s1, s71, s1
	v_readlane_b32 s2, v255, 60
	v_readlane_b32 s3, v255, 61
	s_nop 4
	s_mov_b32 s0, 25
	s_ashr_i32 s1, s0, 31
	s_lshl_b64 s[0:1], s[0:1], 3
	s_add_u32 s0, s70, s0
	s_addc_u32 s1, s71, s1
	v_readlane_b32 s4, v255, 60
	v_readlane_b32 s5, v255, 61
	s_nop 4
	s_mov_b32 s0, 25
	s_ashr_i32 s1, s0, 31
	s_lshl_b64 s[0:1], s[0:1], 3
	s_add_u32 s0, s70, s0
	s_addc_u32 s1, s71, s1
	v_mov_b32_e32 v3, v224
	v_readlane_b32 s14, v255, 60
	v_readlane_b32 s15, v255, 61
	s_nop 4
	s_ashr_i32 s53, s52, 31
	v_bfe_i32 v1, v3, 27, 1
	s_waitcnt vmcnt(10)
	v_lshlrev_b32_e32 v150, 4, v3
	s_nop 0
	v_readfirstlane_b32 s100, v150
	v_lshrrev_b32_e32 v1, 22, v1
	v_add_u32_e32 v1, v150, v1
	v_and_b32_e32 v1, 0xfffffc00, v1
	v_ashrrev_i32_e32 v0, 31, v3
	v_sub_u32_e32 v1, v150, v1
	v_lshrrev_b32_e32 v0, 26, v0
	v_lshrrev_b32_e32 v5, 4, v1
	v_add_u32_e32 v0, v3, v0
	v_bitop3_b32 v5, v5, v1, 32 bitop3:0x6c
	v_ashrrev_i32_e32 v1, 31, v1
	v_ashrrev_i32_e32 v0, 6, v0
	v_lshrrev_b32_e32 v1, 26, v1
	v_lshlrev_b32_e32 v6, 3, v0
	v_add_u32_e32 v1, v5, v1
	v_and_b32_e32 v6, -16, v6
	v_ashrrev_i32_e32 v1, 6, v1
	v_add_u32_e32 v6, v1, v6
	v_mul_i32_i24_e32 v1, 64, v1
	v_lshlrev_b32_e32 v0, 5, v0
	v_sub_u32_e32 v1, v5, v1
	v_mov_b32_e32 v14, 1
	s_waitcnt vmcnt(9)
	v_add_u32_e32 v155, 0x2000, v150
	s_lshl_b64 s[0:1], s[52:53], 11
	v_readlane_b32 s27, v254, 44
	v_and_b32_e32 v0, 32, v0
	v_ashrrev_i16_sdwa v1, v14, sext(v1) dst_sel:DWORD dst_unused:UNUSED_PAD src0_sel:DWORD src1_sel:BYTE_0
	v_ashrrev_i32_e32 v5, 31, v155
	s_add_u32 s0, s27, s0
	v_readlane_b32 s29, v254, 45
	v_add_u32_sdwa v0, v0, sext(v1) dst_sel:DWORD dst_unused:UNUSED_PAD src0_sel:DWORD src1_sel:WORD_0
	v_ashrrev_i32_e32 v7, 31, v6
	v_lshrrev_b32_e32 v5, 22, v5
	s_addc_u32 s1, s29, s1
	v_lshlrev_b64 v[132:133], 11, v[6:7]
	v_ashrrev_i32_e32 v1, 31, v0
	v_add_u32_e32 v5, v155, v5
	v_lshl_add_u64 v[8:9], s[0:1], 0, v[132:133]
	v_lshlrev_b64 v[6:7], 1, v[0:1]
	v_ashrrev_i32_e32 v5, 10, v5
	v_lshl_add_u64 v[10:11], v[8:9], 0, v[6:7]
	v_mul_i32_i24_e32 v8, 0x400, v5
	v_sub_u32_e32 v8, v155, v8
	v_lshrrev_b32_e32 v9, 4, v8
	v_bitop3_b32 v9, v9, v8, 32 bitop3:0x6c
	v_ashrrev_i32_e32 v12, 31, v9
	v_lshrrev_b32_e32 v12, 26, v12
	v_add_u32_e32 v12, v9, v12
	v_lshlrev_b32_e32 v8, 3, v5
	v_ashrrev_i32_e32 v13, 6, v12
	v_and_b32_e32 v12, 0xc0, v12
	v_and_b32_e32 v8, -16, v8
	v_lshlrev_b32_e32 v5, 5, v5
	v_sub_u32_e32 v9, v9, v12
	v_add_u32_e32 v8, v13, v8
	v_and_b32_e32 v5, 32, v5
	v_ashrrev_i16_sdwa v9, v14, sext(v9) dst_sel:DWORD dst_unused:UNUSED_PAD src0_sel:DWORD src1_sel:BYTE_0
	v_add_u32_sdwa v134, v5, sext(v9) dst_sel:DWORD dst_unused:UNUSED_PAD src0_sel:DWORD src1_sel:WORD_0
	v_ashrrev_i32_e32 v9, 31, v8
	v_lshlrev_b64 v[136:137], 11, v[8:9]
	s_waitcnt vmcnt(8)
	v_mov_b32_e32 v4, v2
	s_or_b32 m0, s100, 0x10000
	v_lshl_add_u64 v[12:13], s[0:1], 0, v[136:137]
	global_load_lds_dwordx4 v[10:11], off
	s_or_b32 m0, s100, 0x12000
	s_lshl_b32 s0, s20, 19
	v_ashrrev_i32_e32 v135, 31, v134
	s_waitcnt lgkmcnt(0)
	s_add_u32 s12, s14, s0
	v_lshlrev_b64 v[8:9], 1, v[134:135]
	s_addc_u32 s13, s15, 0
	v_lshl_add_u64 v[12:13], v[12:13], 0, v[8:9]
	v_lshl_add_u64 v[14:15], s[12:13], 0, v[132:133]
	global_load_lds_dwordx4 v[12:13], off
	v_lshl_add_u64 v[14:15], v[14:15], 0, v[6:7]
	s_mov_b32 m0, s100
	s_nop 0
	global_load_lds_dwordx4 v[14:15], off
	s_or_b32 m0, s100, 0x2000
	s_or_b32 s0, s52, 0x80
	s_ashr_i32 s1, s0, 31
	s_lshl_b64 s[20:21], s[0:1], 11
	s_add_u32 s20, s27, s20
	v_lshl_add_u64 v[16:17], s[12:13], 0, v[136:137]
	s_addc_u32 s21, s29, s21
	v_lshl_add_u64 v[16:17], v[16:17], 0, v[8:9]
	v_lshl_add_u64 v[18:19], s[20:21], 0, v[132:133]
	v_lshl_add_u64 v[20:21], s[20:21], 0, v[136:137]
	s_add_u32 s20, s12, 0x40000
	global_load_lds_dwordx4 v[16:17], off
	v_lshl_add_u64 v[18:19], v[18:19], 0, v[6:7]
	s_addc_u32 s21, s13, 0
	s_or_b32 m0, s100, 0x14000
	global_load_lds_dwordx4 v[18:19], off
	v_lshl_add_u64 v[20:21], v[20:21], 0, v[8:9]
	s_or_b32 m0, s100, 0x16000
	v_lshl_add_u64 v[22:23], s[20:21], 0, v[132:133]
	global_load_lds_dwordx4 v[20:21], off
	v_lshl_add_u64 v[22:23], v[22:23], 0, v[6:7]
	s_or_b32 m0, s100, 0x4000
	global_load_lds_dwordx4 v[22:23], off
	v_lshl_add_u64 v[22:23], s[20:21], 0, v[136:137]
	v_lshl_add_u64 v[22:23], v[22:23], 0, v[8:9]
	s_or_b32 m0, s100, 0x6000
	v_ashrrev_i32_e32 v5, 8, v3
	global_load_lds_dwordx4 v[22:23], off
	v_cmp_eq_u32_e32 vcc, 1, v5
	s_and_saveexec_b64 s[20:21], vcc
	s_cbranch_execz .LBB0_241
	s_barrier
; #define WAIT_V8(n) asm volatile("s_waitcnt vmcnt(" #n ")" ::: "memory")
; #define BAR8 __builtin_amdgcn_s_barrier()
;     ...
;   const int wid = t >> 6, lane = t & 63, wr = wid >> 2, wc = wid & 3, fr = lane & 15, fq = lane >> 4;
;   f32x4 acc[2][2][4][2];
;   {
;     float zinit = 0.f;
;     asm volatile("" : "+v"(zinit));
; #pragma unroll
;     for (int a = 0; a < 2; ++a)
; #pragma unroll
;       for (int b = 0; b < 2; ++b)
; #pragma unroll
;         for (int m = 0; m < 4; ++m)
; #pragma unroll
;           for (int n = 0; n < 2; ++n)
; #pragma unroll
;             for (int j = 0; j < 4; ++j) acc[a][b][m][n][j] = zinit;
;   }
;   bf16x8 At[4][2], B0[2][2], B1[2][2];
;   const int nt = K / 64;
;   if (!pre) {
;     STAGE8(SB8(0, 0), Bt, K, bcol, 0); STAGE8(SA8(0, 0), A, lda, brow, 0);
;     STAGE8(SB8(0, 1), Bt, K, bcol + 128, 0); STAGE8(SA8(0, 1), A, lda, brow + 128, 0);
;   }
;   if (wr == 1) BAR8;
;   WAIT_V8(4); BAR8;
;   STAGE8(SB8(1, 0), Bt, K, bcol, 1); STAGE8(SA8(1, 0), A, lda, brow, 1); STAGE8(SB8(1, 1), Bt, K, bcol + 128, 1);
;   WAIT_V8(6); BAR8;
.LBB0_241:
	s_or_b64 exec, exec, s[20:21]
	s_mov_b64 s[20:21], 0x80
	v_lshl_add_u64 v[10:11], v[10:11], 0, s[20:21]
	s_or_b32 m0, s100, 0x18000
	s_waitcnt vmcnt(4)
	s_barrier
	global_load_lds_dwordx4 v[10:11], off
	v_lshl_add_u64 v[10:11], v[12:13], 0, s[20:21]
	s_or_b32 m0, s100, 0x1a000
	global_load_lds_dwordx4 v[10:11], off
	v_lshl_add_u64 v[10:11], v[14:15], 0, s[20:21]
	s_or_b32 m0, s100, 0x8000
	global_load_lds_dwordx4 v[10:11], off
	v_lshl_add_u64 v[10:11], v[16:17], 0, s[20:21]
	s_or_b32 m0, s100, 0xa000
	global_load_lds_dwordx4 v[10:11], off
	v_lshl_add_u64 v[10:11], v[18:19], 0, s[20:21]
	s_or_b32 m0, s100, 0x1c000
	s_nop 0
	global_load_lds_dwordx4 v[10:11], off
	v_lshl_add_u64 v[10:11], v[20:21], 0, s[20:21]
	s_or_b32 m0, s100, 0x1e000
	v_and_b32_e32 v147, 15, v3
	global_load_lds_dwordx4 v[10:11], off
	v_bfe_u32 v148, v3, 4, 2
	v_lshlrev_b32_e32 v10, 4, v148
	v_lshlrev_b32_e32 v11, 6, v147
	v_lshlrev_b32_e32 v14, 2, v3
	v_or_b32_e32 v13, v10, v11
	v_and_b32_e32 v14, 32, v14
	s_mov_b32 s1, 0x10000
	v_bitop3_b32 v16, v13, s1, v14 bitop3:0xde
	s_mov_b32 s1, 0x14000
	v_bitop3_b32 v15, v10, v14, v11 bitop3:0x36
	v_bitop3_b32 v17, v13, s1, v14 bitop3:0xde
	s_mov_b32 s1, 0x18000
	v_lshlrev_b32_e32 v11, 6, v3
	v_bitop3_b32 v18, v13, s1, v14 bitop3:0xde
	s_mov_b32 s1, 0x1c000
	v_and_b32_e32 v11, 0x3c0, v11
	v_bitop3_b32 v13, v13, s1, v14 bitop3:0xde
	v_bitop3_b32 v14, v11, v14, v10 bitop3:0x36
	v_lshl_add_u64 v[10:11], s[30:31], 0, v[136:137]
	v_lshl_add_u64 v[10:11], v[10:11], 0, v[8:9]
	v_lshl_add_u64 v[138:139], s[14:15], 0, v[10:11]
	v_lshl_add_u64 v[10:11], s[30:31], 0, v[132:133]
	v_lshl_add_u64 v[10:11], v[10:11], 0, v[6:7]
	v_lshl_add_u64 v[140:141], s[14:15], 0, v[10:11]
	v_lshl_add_u64 v[10:11], s[56:57], 0, v[132:133]
	v_lshl_add_u64 v[6:7], v[10:11], 0, v[6:7]
	v_bfe_u32 v146, v3, 6, 2
	s_waitcnt vmcnt(6)
	v_lshlrev_b32_e32 v149, 6, v5
	v_lshlrev_b32_e32 v5, 13, v5
	v_lshl_add_u64 v[142:143], s[46:47], 0, v[6:7]
	v_lshl_add_u64 v[6:7], s[56:57], 0, v[136:137]
	v_lshlrev_b32_e32 v12, 12, v146
	v_or_b32_e32 v19, 0x800, v5
	v_or_b32_e32 v20, 0x1000, v5
	v_or_b32_e32 v21, 0x1800, v5
	v_lshl_add_u64 v[6:7], v[6:7], 0, v[8:9]
	v_lshl_add_u64 v[144:145], s[46:47], 0, v[6:7]
	s_mov_b32 s1, -2
	s_mov_b64 s[14:15], 0
	v_add_u32_e32 v171, v16, v12
	v_add_u32_e32 v156, v15, v5
	v_add_u32_e32 v154, v14, v19
	v_add_u32_e32 v153, v14, v20
	v_add_u32_e32 v152, v14, v21
	v_add_u32_e32 v168, v17, v12
	v_add_u32_e32 v159, v18, v12
	v_add_u32_e32 v157, v13, v12
	v_mov_b32_e32 v5, v4
	v_mov_b64_e32 v[6:7], v[4:5]
	v_mov_b64_e32 v[8:9], v[4:5]
	v_mov_b64_e32 v[10:11], v[4:5]
	v_mov_b64_e32 v[12:13], v[4:5]
	v_mov_b64_e32 v[14:15], v[4:5]
	v_mov_b64_e32 v[16:17], v[4:5]
	v_mov_b64_e32 v[18:19], v[4:5]
	v_mov_b64_e32 v[20:21], v[4:5]
	v_mov_b64_e32 v[22:23], v[4:5]
	v_mov_b64_e32 v[24:25], v[4:5]
	v_mov_b64_e32 v[26:27], v[4:5]
	v_mov_b64_e32 v[28:29], v[4:5]
	v_mov_b64_e32 v[30:31], v[4:5]
	v_mov_b64_e32 v[32:33], v[4:5]
	v_mov_b64_e32 v[34:35], v[4:5]
	v_mov_b64_e32 v[36:37], v[4:5]
	v_mov_b64_e32 v[38:39], v[4:5]
	v_mov_b64_e32 v[40:41], v[4:5]
	v_mov_b64_e32 v[42:43], v[4:5]
	v_mov_b64_e32 v[44:45], v[4:5]
	v_mov_b64_e32 v[46:47], v[4:5]
	v_mov_b64_e32 v[48:49], v[4:5]
	v_mov_b64_e32 v[50:51], v[4:5]
	v_mov_b64_e32 v[52:53], v[4:5]
	v_mov_b64_e32 v[54:55], v[4:5]
	v_mov_b64_e32 v[56:57], v[4:5]
	v_mov_b64_e32 v[58:59], v[4:5]
	v_mov_b64_e32 v[60:61], v[4:5]
	v_mov_b64_e32 v[62:63], v[4:5]
	v_mov_b64_e32 v[64:65], v[4:5]
	v_mov_b64_e32 v[66:67], v[4:5]
	v_mov_b64_e32 v[68:69], v[4:5]
	v_mov_b64_e32 v[70:71], v[4:5]
	v_mov_b64_e32 v[72:73], v[4:5]
	v_mov_b64_e32 v[74:75], v[4:5]
	v_mov_b64_e32 v[76:77], v[4:5]
	v_mov_b64_e32 v[78:79], v[4:5]
	v_mov_b64_e32 v[80:81], v[4:5]
	v_mov_b64_e32 v[82:83], v[4:5]
	v_mov_b64_e32 v[84:85], v[4:5]
	v_mov_b64_e32 v[86:87], v[4:5]
	v_mov_b64_e32 v[88:89], v[4:5]
	v_mov_b64_e32 v[90:91], v[4:5]
	v_mov_b64_e32 v[92:93], v[4:5]
	v_mov_b64_e32 v[94:95], v[4:5]
	v_mov_b64_e32 v[96:97], v[4:5]
	v_mov_b64_e32 v[98:99], v[4:5]
	v_mov_b64_e32 v[100:101], v[4:5]
	v_mov_b64_e32 v[102:103], v[4:5]
	v_mov_b64_e32 v[104:105], v[4:5]
	v_mov_b64_e32 v[106:107], v[4:5]
	v_mov_b64_e32 v[108:109], v[4:5]
	v_mov_b64_e32 v[110:111], v[4:5]
	v_mov_b64_e32 v[112:113], v[4:5]
	v_mov_b64_e32 v[114:115], v[4:5]
	v_mov_b64_e32 v[116:117], v[4:5]
	v_mov_b64_e32 v[118:119], v[4:5]
	v_mov_b64_e32 v[120:121], v[4:5]
	v_mov_b64_e32 v[122:123], v[4:5]
	v_mov_b64_e32 v[124:125], v[4:5]
	v_mov_b64_e32 v[126:127], v[4:5]
	v_mov_b64_e32 v[128:129], v[4:5]
	v_mov_b64_e32 v[130:131], v[4:5]
	s_mov_b64 s[30:31], 0xc000100
	s_mov_b64 s[56:57], 0xc040100
	s_mov_b64 s[58:59], 0xc000180
	s_mov_b64 s[60:61], 0xc040180
	s_barrier
; #define LDA8(dst, b, h) _Pragma("unroll") for (int m = 0; m < 4; ++m) _Pragma("unroll") for (int k = 0; k < 2; ++k) \
;     dst[m][k] = *(const bf16x8*)((const char*)SA8(b, h) + lds_byte8(wr * 64 + m * 16 + fr, k * 32 + fq * 8))
; #define LDB8(dst, b, h) _Pragma("unroll") for (int n = 0; n < 2; ++n) _Pragma("unroll") for (int k = 0; k < 2; ++k) \
;     dst[n][k] = *(const bf16x8*)((const char*)SB8(b, h) + lds_byte8(wc * 32 + n * 16 + fr, k * 32 + fq * 8))
; #define WAIT_L8(n) asm volatile("s_waitcnt lgkmcnt(" #n ")" ::: "memory")
; #define BAR8 __builtin_amdgcn_s_barrier()
; #define SCHED8 __builtin_amdgcn_sched_barrier(0)
;     ...
;   for (int tt = 0; tt < nt - 2; tt += 2) {
;     LDB8(B0, 0, 0); SCHED8; LDA8(At, 0, 0); STAGE8(SA8(1, 1), A, lda, brow + 128, tt + 1);
;     WAIT_L8(8); BAR8; WAIT_L8(0); MMA8(0, 0, At, B0); BAR8; SCHED8;
;     LDB8(B1, 0, 1); STAGE8(SB8(0, 0), Bt, K, bcol, tt + 2);
;     BAR8; WAIT_L8(0); MMA8(0, 1, At, B1); BAR8;
;     LDA8(At, 0, 1); STAGE8(SA8(0, 0), A, lda, brow, tt + 2);
;     BAR8; WAIT_L8(0); MMA8(1, 0, At, B0); BAR8; SCHED8;
.LBB0_242:
	ds_read_b128 v[174:177], v171
	ds_read_b128 v[178:181], v171 offset:1024
	ds_read_b128 v[182:185], v171 offset:2048
	ds_read_b128 v[186:189], v171 offset:3072
	v_lshl_add_u64 v[222:223], v[140:141], 0, s[14:15]
	v_lshl_add_u64 v[226:227], v[222:223], 0, s[34:35]
	s_or_b32 m0, s100, 0xc000
	ds_read_b128 v[190:193], v156
	ds_read_b128 v[194:197], v156 offset:1024
	ds_read_b128 v[198:201], v154
	ds_read_b128 v[202:205], v154 offset:1024
	ds_read_b128 v[206:209], v153
	ds_read_b128 v[210:213], v153 offset:1024
	ds_read_b128 v[214:217], v152
	ds_read_b128 v[218:221], v152 offset:1024
	global_load_lds_dwordx4 v[226:227], off
	v_lshl_add_u64 v[226:227], v[138:139], 0, s[14:15]
	v_lshl_add_u64 v[228:229], v[226:227], 0, s[34:35]
	s_or_b32 m0, s100, 0xe000
	s_nop 0
	global_load_lds_dwordx4 v[228:229], off
	s_waitcnt lgkmcnt(8)
	s_barrier
	s_waitcnt lgkmcnt(0)
	v_mfma_f32_16x16x32_f16 v[128:131], v[190:193], v[174:177], v[128:131]
	v_mfma_f32_16x16x32_f16 v[124:127], v[190:193], v[182:185], v[124:127]
	v_mfma_f32_16x16x32_f16 v[120:123], v[198:201], v[174:177], v[120:123]
	v_mfma_f32_16x16x32_f16 v[116:119], v[198:201], v[182:185], v[116:119]
	v_mfma_f32_16x16x32_f16 v[112:115], v[206:209], v[174:177], v[112:115]
	v_mfma_f32_16x16x32_f16 v[108:111], v[206:209], v[182:185], v[108:111]
	v_mfma_f32_16x16x32_f16 v[104:107], v[214:217], v[174:177], v[104:107]
	v_mfma_f32_16x16x32_f16 v[100:103], v[214:217], v[182:185], v[100:103]
	v_mfma_f32_16x16x32_f16 v[128:131], v[194:197], v[178:181], v[128:131]
	v_mfma_f32_16x16x32_f16 v[124:127], v[194:197], v[186:189], v[124:127]
	v_mfma_f32_16x16x32_f16 v[120:123], v[202:205], v[178:181], v[120:123]
	v_mfma_f32_16x16x32_f16 v[116:119], v[202:205], v[186:189], v[116:119]
	v_mfma_f32_16x16x32_f16 v[112:115], v[210:213], v[178:181], v[112:115]
	v_mfma_f32_16x16x32_f16 v[108:111], v[210:213], v[186:189], v[108:111]
	v_mfma_f32_16x16x32_f16 v[104:107], v[218:221], v[178:181], v[104:107]
	v_mfma_f32_16x16x32_f16 v[100:103], v[218:221], v[186:189], v[100:103]
	s_barrier
	v_lshl_add_u64 v[228:229], v[142:143], 0, s[14:15]
	v_lshl_add_u64 v[236:237], v[228:229], 0, s[30:31]
	s_or_b32 m0, s100, 0x10000
	ds_read_b128 v[230:233], v168
	ds_read_b128 v[238:241], v168 offset:1024
	ds_read_b128 v[242:245], v168 offset:2048
	ds_read_b128 v[246:249], v168 offset:3072
	global_load_lds_dwordx4 v[236:237], off
	v_lshl_add_u64 v[236:237], v[144:145], 0, s[14:15]
	v_lshl_add_u64 v[250:251], v[236:237], 0, s[30:31]
	s_or_b32 m0, s100, 0x12000
	s_nop 0
	global_load_lds_dwordx4 v[250:251], off
	s_barrier
	s_waitcnt lgkmcnt(0)
	v_mfma_f32_16x16x32_f16 v[96:99], v[190:193], v[230:233], v[96:99]
	v_mfma_f32_16x16x32_f16 v[92:95], v[190:193], v[242:245], v[92:95]
	v_mfma_f32_16x16x32_f16 v[88:91], v[198:201], v[230:233], v[88:91]
	v_mfma_f32_16x16x32_f16 v[84:87], v[198:201], v[242:245], v[84:87]
	v_mfma_f32_16x16x32_f16 v[80:83], v[206:209], v[230:233], v[80:83]
	v_mfma_f32_16x16x32_f16 v[76:79], v[206:209], v[242:245], v[76:79]
	v_mfma_f32_16x16x32_f16 v[72:75], v[214:217], v[230:233], v[72:75]
	v_mfma_f32_16x16x32_f16 v[68:71], v[214:217], v[242:245], v[68:71]
	v_mfma_f32_16x16x32_f16 v[96:99], v[194:197], v[238:241], v[96:99]
	v_mfma_f32_16x16x32_f16 v[92:95], v[194:197], v[246:249], v[92:95]
	v_mfma_f32_16x16x32_f16 v[88:91], v[202:205], v[238:241], v[88:91]
	v_mfma_f32_16x16x32_f16 v[84:87], v[202:205], v[246:249], v[84:87]
	v_mfma_f32_16x16x32_f16 v[80:83], v[210:213], v[238:241], v[80:83]
	v_mfma_f32_16x16x32_f16 v[76:79], v[210:213], v[246:249], v[76:79]
	v_mfma_f32_16x16x32_f16 v[72:75], v[218:221], v[238:241], v[72:75]
	v_mfma_f32_16x16x32_f16 v[68:71], v[218:221], v[246:249], v[68:71]
	v_lshl_add_u64 v[250:251], v[222:223], 0, s[10:11]
	s_mov_b32 m0, s100
	s_barrier
	ds_read_b128 v[190:193], v156 offset:16384
	ds_read_b128 v[194:197], v156 offset:17408
	ds_read_b128 v[198:201], v154 offset:16384
	ds_read_b128 v[202:205], v154 offset:17408
	ds_read_b128 v[206:209], v153 offset:16384
	ds_read_b128 v[210:213], v153 offset:17408
	ds_read_b128 v[214:217], v152 offset:16384
	ds_read_b128 v[218:221], v152 offset:17408
	global_load_lds_dwordx4 v[250:251], off
	v_lshl_add_u64 v[250:251], v[226:227], 0, s[10:11]
	s_or_b32 m0, s100, 0x2000
	s_nop 0
	global_load_lds_dwordx4 v[250:251], off
	s_barrier
	s_waitcnt lgkmcnt(0)
	v_mfma_f32_16x16x32_f16 v[64:67], v[190:193], v[174:177], v[64:67]
	v_mfma_f32_16x16x32_f16 v[60:63], v[190:193], v[182:185], v[60:63]
	v_mfma_f32_16x16x32_f16 v[56:59], v[198:201], v[174:177], v[56:59]
	v_mfma_f32_16x16x32_f16 v[52:55], v[198:201], v[182:185], v[52:55]
	v_mfma_f32_16x16x32_f16 v[48:51], v[206:209], v[174:177], v[48:51]
	v_mfma_f32_16x16x32_f16 v[44:47], v[206:209], v[182:185], v[44:47]
	v_mfma_f32_16x16x32_f16 v[40:43], v[214:217], v[174:177], v[40:43]
	v_mfma_f32_16x16x32_f16 v[36:39], v[214:217], v[182:185], v[36:39]
	v_mfma_f32_16x16x32_f16 v[64:67], v[194:197], v[178:181], v[64:67]
	v_mfma_f32_16x16x32_f16 v[60:63], v[194:197], v[186:189], v[60:63]
	v_mfma_f32_16x16x32_f16 v[56:59], v[202:205], v[178:181], v[56:59]
	v_mfma_f32_16x16x32_f16 v[52:55], v[202:205], v[186:189], v[52:55]
	v_mfma_f32_16x16x32_f16 v[48:51], v[210:213], v[178:181], v[48:51]
	v_mfma_f32_16x16x32_f16 v[44:47], v[210:213], v[186:189], v[44:47]
	v_mfma_f32_16x16x32_f16 v[40:43], v[218:221], v[178:181], v[40:43]
	v_mfma_f32_16x16x32_f16 v[36:39], v[218:221], v[186:189], v[36:39]
	s_barrier
	v_lshl_add_u64 v[174:175], v[228:229], 0, s[56:57]
	s_or_b32 m0, s100, 0x14000
	s_nop 0
	global_load_lds_dwordx4 v[174:175], off
	v_lshl_add_u64 v[174:175], v[236:237], 0, s[56:57]
	s_or_b32 m0, s100, 0x16000
	s_nop 0
	global_load_lds_dwordx4 v[174:175], off
	s_waitcnt vmcnt(6)
	s_barrier
; #define LDA8(dst, b, h) _Pragma("unroll") for (int m = 0; m < 4; ++m) _Pragma("unroll") for (int k = 0; k < 2; ++k) \
;     dst[m][k] = *(const bf16x8*)((const char*)SA8(b, h) + lds_byte8(wr * 64 + m * 16 + fr, k * 32 + fq * 8))
; #define LDB8(dst, b, h) _Pragma("unroll") for (int n = 0; n < 2; ++n) _Pragma("unroll") for (int k = 0; k < 2; ++k) \
;     dst[n][k] = *(const bf16x8*)((const char*)SB8(b, h) + lds_byte8(wc * 32 + n * 16 + fr, k * 32 + fq * 8))
; #define WAIT_V8(n) asm volatile("s_waitcnt vmcnt(" #n ")" ::: "memory")
; #define WAIT_L8(n) asm volatile("s_waitcnt lgkmcnt(" #n ")" ::: "memory")
; #define BAR8 __builtin_amdgcn_s_barrier()
; #define SCHED8 __builtin_amdgcn_sched_barrier(0)
;     ...
;     BAR8; WAIT_L8(0); MMA8(1, 0, At, B0); BAR8; SCHED8;
;     STAGE8(SB8(0, 1), Bt, K, bcol + 128, tt + 2);
;     WAIT_V8(6); BAR8; MMA8(1, 1, At, B1); BAR8;
;     LDB8(B0, 1, 0); SCHED8; LDA8(At, 1, 0); STAGE8(SA8(0, 1), A, lda, brow + 128, tt + 2);
;     WAIT_L8(8); BAR8; WAIT_L8(0); MMA8(0, 0, At, B0); BAR8; SCHED8;
	v_mfma_f32_16x16x32_f16 v[32:35], v[190:193], v[230:233], v[32:35]
	v_mfma_f32_16x16x32_f16 v[28:31], v[190:193], v[242:245], v[28:31]
	v_mfma_f32_16x16x32_f16 v[24:27], v[198:201], v[230:233], v[24:27]
	v_mfma_f32_16x16x32_f16 v[20:23], v[198:201], v[242:245], v[20:23]
	v_mfma_f32_16x16x32_f16 v[16:19], v[206:209], v[230:233], v[16:19]
	v_mfma_f32_16x16x32_f16 v[12:15], v[206:209], v[242:245], v[12:15]
	v_mfma_f32_16x16x32_f16 v[8:11], v[214:217], v[230:233], v[8:11]
	v_mfma_f32_16x16x32_f16 v[4:7], v[214:217], v[242:245], v[4:7]
	v_mfma_f32_16x16x32_f16 v[32:35], v[194:197], v[238:241], v[32:35]
	v_mfma_f32_16x16x32_f16 v[28:31], v[194:197], v[246:249], v[28:31]
	v_mfma_f32_16x16x32_f16 v[24:27], v[202:205], v[238:241], v[24:27]
	v_mfma_f32_16x16x32_f16 v[20:23], v[202:205], v[246:249], v[20:23]
	v_mfma_f32_16x16x32_f16 v[16:19], v[210:213], v[238:241], v[16:19]
	v_mfma_f32_16x16x32_f16 v[12:15], v[210:213], v[246:249], v[12:15]
	v_mfma_f32_16x16x32_f16 v[8:11], v[218:221], v[238:241], v[8:11]
	v_mfma_f32_16x16x32_f16 v[4:7], v[218:221], v[246:249], v[4:7]
	s_barrier
	ds_read_b128 v[174:177], v159
	ds_read_b128 v[178:181], v159 offset:1024
	ds_read_b128 v[182:185], v159 offset:2048
	ds_read_b128 v[186:189], v159 offset:3072
	v_lshl_add_u64 v[230:231], v[222:223], 0, s[18:19]
	s_or_b32 m0, s100, 0x4000
	ds_read_b128 v[190:193], v156 offset:32768
	ds_read_b128 v[194:197], v156 offset:33792
	ds_read_b128 v[198:201], v154 offset:32768
	ds_read_b128 v[202:205], v154 offset:33792
	ds_read_b128 v[206:209], v153 offset:32768
	ds_read_b128 v[210:213], v153 offset:33792
	ds_read_b128 v[214:217], v152 offset:32768
	ds_read_b128 v[218:221], v152 offset:33792
	global_load_lds_dwordx4 v[230:231], off
	v_lshl_add_u64 v[230:231], v[226:227], 0, s[18:19]
	s_or_b32 m0, s100, 0x6000
	s_nop 0
	global_load_lds_dwordx4 v[230:231], off
	s_waitcnt lgkmcnt(8)
	s_barrier
	s_waitcnt lgkmcnt(0)
	v_mfma_f32_16x16x32_f16 v[128:131], v[190:193], v[174:177], v[128:131]
	v_mfma_f32_16x16x32_f16 v[124:127], v[190:193], v[182:185], v[124:127]
	v_mfma_f32_16x16x32_f16 v[120:123], v[198:201], v[174:177], v[120:123]
	v_mfma_f32_16x16x32_f16 v[116:119], v[198:201], v[182:185], v[116:119]
	v_mfma_f32_16x16x32_f16 v[112:115], v[206:209], v[174:177], v[112:115]
	v_mfma_f32_16x16x32_f16 v[108:111], v[206:209], v[182:185], v[108:111]
	v_mfma_f32_16x16x32_f16 v[104:107], v[214:217], v[174:177], v[104:107]
	v_mfma_f32_16x16x32_f16 v[100:103], v[214:217], v[182:185], v[100:103]
	v_mfma_f32_16x16x32_f16 v[128:131], v[194:197], v[178:181], v[128:131]
	v_mfma_f32_16x16x32_f16 v[124:127], v[194:197], v[186:189], v[124:127]
	v_mfma_f32_16x16x32_f16 v[120:123], v[202:205], v[178:181], v[120:123]
	v_mfma_f32_16x16x32_f16 v[116:119], v[202:205], v[186:189], v[116:119]
	v_mfma_f32_16x16x32_f16 v[112:115], v[210:213], v[178:181], v[112:115]
	v_mfma_f32_16x16x32_f16 v[108:111], v[210:213], v[186:189], v[108:111]
	v_mfma_f32_16x16x32_f16 v[104:107], v[218:221], v[178:181], v[104:107]
	v_mfma_f32_16x16x32_f16 v[100:103], v[218:221], v[186:189], v[100:103]
	s_barrier
	v_lshl_add_u64 v[250:251], v[228:229], 0, s[58:59]
	s_or_b32 m0, s100, 0x18000
	ds_read_b128 v[230:233], v157
	ds_read_b128 v[238:241], v157 offset:1024
	ds_read_b128 v[242:245], v157 offset:2048
	ds_read_b128 v[246:249], v157 offset:3072
	global_load_lds_dwordx4 v[250:251], off
	v_lshl_add_u64 v[250:251], v[236:237], 0, s[58:59]
	s_or_b32 m0, s100, 0x1a000
	s_nop 0
	global_load_lds_dwordx4 v[250:251], off
	s_barrier
	s_waitcnt lgkmcnt(0)
	v_mfma_f32_16x16x32_f16 v[96:99], v[190:193], v[230:233], v[96:99]
	v_mfma_f32_16x16x32_f16 v[92:95], v[190:193], v[242:245], v[92:95]
	v_mfma_f32_16x16x32_f16 v[88:91], v[198:201], v[230:233], v[88:91]
	v_mfma_f32_16x16x32_f16 v[84:87], v[198:201], v[242:245], v[84:87]
	v_mfma_f32_16x16x32_f16 v[80:83], v[206:209], v[230:233], v[80:83]
	v_mfma_f32_16x16x32_f16 v[76:79], v[206:209], v[242:245], v[76:79]
	v_mfma_f32_16x16x32_f16 v[72:75], v[214:217], v[230:233], v[72:75]
	v_mfma_f32_16x16x32_f16 v[68:71], v[214:217], v[242:245], v[68:71]
	v_mfma_f32_16x16x32_f16 v[96:99], v[194:197], v[238:241], v[96:99]
	v_mfma_f32_16x16x32_f16 v[92:95], v[194:197], v[246:249], v[92:95]
	v_mfma_f32_16x16x32_f16 v[88:91], v[202:205], v[238:241], v[88:91]
	v_mfma_f32_16x16x32_f16 v[84:87], v[202:205], v[246:249], v[84:87]
	v_mfma_f32_16x16x32_f16 v[80:83], v[210:213], v[238:241], v[80:83]
	v_mfma_f32_16x16x32_f16 v[76:79], v[210:213], v[246:249], v[76:79]
	v_mfma_f32_16x16x32_f16 v[72:75], v[218:221], v[238:241], v[72:75]
	v_mfma_f32_16x16x32_f16 v[68:71], v[218:221], v[246:249], v[68:71]
	v_lshl_add_u64 v[222:223], v[222:223], 0, s[22:23]
	s_or_b32 m0, s100, 0x8000
	s_barrier
	ds_read_b128 v[190:193], v156 offset:49152
	ds_read_b128 v[194:197], v156 offset:50176
	ds_read_b128 v[198:201], v154 offset:49152
	ds_read_b128 v[202:205], v154 offset:50176
	ds_read_b128 v[206:209], v153 offset:49152
	ds_read_b128 v[210:213], v153 offset:50176
	ds_read_b128 v[214:217], v152 offset:49152
	ds_read_b128 v[218:221], v152 offset:50176
	global_load_lds_dwordx4 v[222:223], off
	v_lshl_add_u64 v[222:223], v[226:227], 0, s[22:23]
	s_or_b32 m0, s100, 0xa000
	s_nop 0
	global_load_lds_dwordx4 v[222:223], off
	s_barrier
; #define LDA8(dst, b, h) _Pragma("unroll") for (int m = 0; m < 4; ++m) _Pragma("unroll") for (int k = 0; k < 2; ++k) \
;     dst[m][k] = *(const bf16x8*)((const char*)SA8(b, h) + lds_byte8(wr * 64 + m * 16 + fr, k * 32 + fq * 8))
; #define LDB8(dst, b, h) _Pragma("unroll") for (int n = 0; n < 2; ++n) _Pragma("unroll") for (int k = 0; k < 2; ++k) \
;     dst[n][k] = *(const bf16x8*)((const char*)SB8(b, h) + lds_byte8(wc * 32 + n * 16 + fr, k * 32 + fq * 8))
; #define WAIT_V8(n) asm volatile("s_waitcnt vmcnt(" #n ")" ::: "memory")
; #define WAIT_L8(n) asm volatile("s_waitcnt lgkmcnt(" #n ")" ::: "memory")
; #define BAR8 __builtin_amdgcn_s_barrier()
; #define SCHED8 __builtin_amdgcn_sched_barrier(0)
;     ...
;     WAIT_L8(8); BAR8; WAIT_L8(0); MMA8(0, 0, At, B0); BAR8; SCHED8;
;     LDB8(B1, 1, 1); STAGE8(SB8(1, 0), Bt, K, bcol, tt + 3);
;     BAR8; WAIT_L8(0); MMA8(0, 1, At, B1); BAR8;
;     LDA8(At, 1, 1); STAGE8(SA8(1, 0), A, lda, brow, tt + 3);
;     BAR8; WAIT_L8(0); MMA8(1, 0, At, B0); BAR8; SCHED8;
;     STAGE8(SB8(1, 1), Bt, K, bcol + 128, tt + 3);
;     WAIT_V8(6); BAR8; MMA8(1, 1, At, B1); BAR8;
;   }
;   { LDB8(B0, 0, 0); LDA8(At, 0, 0); STAGE8(SA8(1, 1), A, lda, brow + 128, nt - 1);
;     BAR8; WAIT_L8(0); MMA8(0, 0, At, B0); BAR8;
;     LDB8(B1, 0, 1); BAR8; WAIT_L8(0); MMA8(0, 1, At, B1); BAR8;
	s_waitcnt lgkmcnt(0)
	v_mfma_f32_16x16x32_f16 v[64:67], v[190:193], v[174:177], v[64:67]
	v_mfma_f32_16x16x32_f16 v[60:63], v[190:193], v[182:185], v[60:63]
	v_mfma_f32_16x16x32_f16 v[56:59], v[198:201], v[174:177], v[56:59]
	v_mfma_f32_16x16x32_f16 v[52:55], v[198:201], v[182:185], v[52:55]
	v_mfma_f32_16x16x32_f16 v[48:51], v[206:209], v[174:177], v[48:51]
	v_mfma_f32_16x16x32_f16 v[44:47], v[206:209], v[182:185], v[44:47]
	v_mfma_f32_16x16x32_f16 v[40:43], v[214:217], v[174:177], v[40:43]
	v_mfma_f32_16x16x32_f16 v[36:39], v[214:217], v[182:185], v[36:39]
	v_mfma_f32_16x16x32_f16 v[64:67], v[194:197], v[178:181], v[64:67]
	v_mfma_f32_16x16x32_f16 v[60:63], v[194:197], v[186:189], v[60:63]
	v_mfma_f32_16x16x32_f16 v[56:59], v[202:205], v[178:181], v[56:59]
	v_mfma_f32_16x16x32_f16 v[52:55], v[202:205], v[186:189], v[52:55]
	v_mfma_f32_16x16x32_f16 v[48:51], v[210:213], v[178:181], v[48:51]
	v_mfma_f32_16x16x32_f16 v[44:47], v[210:213], v[186:189], v[44:47]
	v_mfma_f32_16x16x32_f16 v[40:43], v[218:221], v[178:181], v[40:43]
	v_mfma_f32_16x16x32_f16 v[36:39], v[218:221], v[186:189], v[36:39]
	s_barrier
	v_lshl_add_u64 v[174:175], v[228:229], 0, s[60:61]
	s_or_b32 m0, s100, 0x1c000
	s_nop 0
	global_load_lds_dwordx4 v[174:175], off
	v_lshl_add_u64 v[174:175], v[236:237], 0, s[60:61]
	s_or_b32 m0, s100, 0x1e000
	s_nop 0
	global_load_lds_dwordx4 v[174:175], off
	s_waitcnt vmcnt(6)
	s_barrier
	v_mfma_f32_16x16x32_f16 v[32:35], v[190:193], v[230:233], v[32:35]
	v_mfma_f32_16x16x32_f16 v[28:31], v[190:193], v[242:245], v[28:31]
	v_mfma_f32_16x16x32_f16 v[24:27], v[198:201], v[230:233], v[24:27]
	v_mfma_f32_16x16x32_f16 v[20:23], v[198:201], v[242:245], v[20:23]
	v_mfma_f32_16x16x32_f16 v[16:19], v[206:209], v[230:233], v[16:19]
	v_mfma_f32_16x16x32_f16 v[12:15], v[206:209], v[242:245], v[12:15]
	v_mfma_f32_16x16x32_f16 v[8:11], v[214:217], v[230:233], v[8:11]
	v_mfma_f32_16x16x32_f16 v[4:7], v[214:217], v[242:245], v[4:7]
	v_mfma_f32_16x16x32_f16 v[32:35], v[194:197], v[238:241], v[32:35]
	v_mfma_f32_16x16x32_f16 v[28:31], v[194:197], v[246:249], v[28:31]
	v_mfma_f32_16x16x32_f16 v[24:27], v[202:205], v[238:241], v[24:27]
	v_mfma_f32_16x16x32_f16 v[20:23], v[202:205], v[246:249], v[20:23]
	v_mfma_f32_16x16x32_f16 v[16:19], v[210:213], v[238:241], v[16:19]
	v_mfma_f32_16x16x32_f16 v[12:15], v[210:213], v[246:249], v[12:15]
	v_mfma_f32_16x16x32_f16 v[8:11], v[218:221], v[238:241], v[8:11]
	v_mfma_f32_16x16x32_f16 v[4:7], v[218:221], v[246:249], v[4:7]
	s_add_i32 s1, s1, 2
	s_add_u32 s14, s14, 0x100
	s_addc_u32 s15, s15, 0
	s_cmp_lt_u32 s1, 12
	s_barrier
	s_cbranch_scc1 .LBB0_242
	s_add_u32 s12, s12, 0x40780
	s_addc_u32 s13, s13, 0
	v_lshl_add_u64 v[132:133], s[12:13], 0, v[132:133]
	v_lshl_add_u64 v[0:1], v[0:1], 1, v[132:133]
	s_or_b32 m0, s100, 0xc000
	ds_read_b128 v[138:141], v171
	ds_read_b128 v[142:145], v171 offset:1024
	ds_read_b128 v[160:163], v171 offset:2048
	ds_read_b128 v[164:167], v171 offset:3072
	ds_read_b128 v[174:177], v156
	ds_read_b128 v[178:181], v156 offset:1024
	ds_read_b128 v[182:185], v154
	ds_read_b128 v[186:189], v154 offset:1024
	ds_read_b128 v[190:193], v153
	ds_read_b128 v[194:197], v153 offset:1024
	ds_read_b128 v[198:201], v152
	ds_read_b128 v[202:205], v152 offset:1024
	global_load_lds_dwordx4 v[0:1], off
	v_lshl_add_u64 v[0:1], s[12:13], 0, v[136:137]
	v_lshl_add_u64 v[0:1], v[134:135], 1, v[0:1]
	s_or_b32 m0, s100, 0xe000
	s_nop 0
	global_load_lds_dwordx4 v[0:1], off
	s_barrier
	s_waitcnt lgkmcnt(0)
	v_mfma_f32_16x16x32_f16 v[128:131], v[174:177], v[138:141], v[128:131]
	v_mfma_f32_16x16x32_f16 v[124:127], v[174:177], v[160:163], v[124:127]
	v_mfma_f32_16x16x32_f16 v[120:123], v[182:185], v[138:141], v[120:123]
	v_mfma_f32_16x16x32_f16 v[112:115], v[190:193], v[138:141], v[112:115]
	v_mfma_f32_16x16x32_f16 v[128:131], v[178:181], v[142:145], v[128:131]
	v_mfma_f32_16x16x32_f16 v[124:127], v[178:181], v[164:167], v[124:127]
	v_mfma_f32_16x16x32_f16 v[120:123], v[186:189], v[142:145], v[120:123]
	v_mfma_f32_16x16x32_f16 v[116:119], v[182:185], v[160:163], v[116:119]
	v_mfma_f32_16x16x32_f16 v[112:115], v[194:197], v[142:145], v[112:115]
	v_mfma_f32_16x16x32_f16 v[108:111], v[190:193], v[160:163], v[108:111]
	v_mfma_f32_16x16x32_f16 v[104:107], v[198:201], v[138:141], v[104:107]
	v_mfma_f32_16x16x32_f16 v[100:103], v[198:201], v[160:163], v[100:103]
	v_mfma_f32_16x16x32_f16 v[132:135], v[186:189], v[164:167], v[116:119]
	v_mfma_f32_16x16x32_f16 v[170:173], v[194:197], v[164:167], v[108:111]
	v_mfma_f32_16x16x32_f16 v[206:209], v[202:205], v[142:145], v[104:107]
	v_mfma_f32_16x16x32_f16 v[210:213], v[202:205], v[164:167], v[100:103]
	s_barrier
	s_nop 1
	ds_read_b128 v[100:103], v168
	ds_read_b128 v[104:107], v168 offset:1024
	ds_read_b128 v[108:111], v168 offset:2048
	ds_read_b128 v[116:119], v168 offset:3072
	s_barrier
	s_waitcnt lgkmcnt(0)
	v_mfma_f32_16x16x32_f16 v[80:83], v[190:193], v[100:103], v[80:83]
	v_mfma_f32_16x16x32_f16 v[76:79], v[190:193], v[108:111], v[76:79]
	v_mfma_f32_16x16x32_f16 v[72:75], v[198:201], v[100:103], v[72:75]
	v_mfma_f32_16x16x32_f16 v[68:71], v[198:201], v[108:111], v[68:71]
	v_mfma_f32_16x16x32_f16 v[96:99], v[174:177], v[100:103], v[96:99]
	v_mfma_f32_16x16x32_f16 v[92:95], v[174:177], v[108:111], v[92:95]
	v_mfma_f32_16x16x32_f16 v[88:91], v[182:185], v[100:103], v[88:91]
	v_mfma_f32_16x16x32_f16 v[84:87], v[182:185], v[108:111], v[84:87]
	v_mfma_f32_16x16x32_f16 v[80:83], v[194:197], v[104:107], v[80:83]
	v_mfma_f32_16x16x32_f16 v[76:79], v[194:197], v[116:119], v[76:79]
	v_mfma_f32_16x16x32_f16 v[72:75], v[202:205], v[104:107], v[72:75]
	v_mfma_f32_16x16x32_f16 v[68:71], v[202:205], v[116:119], v[68:71]
	v_mfma_f32_16x16x32_f16 v[214:217], v[178:181], v[104:107], v[96:99]
	v_mfma_f32_16x16x32_f16 v[174:177], v[178:181], v[116:119], v[92:95]
	v_mfma_f32_16x16x32_f16 v[178:181], v[186:189], v[104:107], v[88:91]
	v_mfma_f32_16x16x32_f16 v[182:185], v[186:189], v[116:119], v[84:87]
	s_barrier
; #define LDA8(dst, b, h) _Pragma("unroll") for (int m = 0; m < 4; ++m) _Pragma("unroll") for (int k = 0; k < 2; ++k) \
;     dst[m][k] = *(const bf16x8*)((const char*)SA8(b, h) + lds_byte8(wr * 64 + m * 16 + fr, k * 32 + fq * 8))
; #define LDB8(dst, b, h) _Pragma("unroll") for (int n = 0; n < 2; ++n) _Pragma("unroll") for (int k = 0; k < 2; ++k) \
;     dst[n][k] = *(const bf16x8*)((const char*)SB8(b, h) + lds_byte8(wc * 32 + n * 16 + fr, k * 32 + fq * 8))
; #define WAIT_V8(n) asm volatile("s_waitcnt vmcnt(" #n ")" ::: "memory")
; #define WAIT_L8(n) asm volatile("s_waitcnt lgkmcnt(" #n ")" ::: "memory")
; #define BAR8 __builtin_amdgcn_s_barrier()
;     ...
;     LDA8(At, 0, 1); WAIT_V8(4); BAR8; WAIT_L8(0); MMA8(1, 0, At, B0); MMA8(1, 1, At, B1); BAR8; }
;   { LDB8(B0, 1, 0); LDA8(At, 1, 0); WAIT_V8(2); BAR8; WAIT_L8(0); MMA8(0, 0, At, B0); BAR8;
;     LDB8(B1, 1, 1); WAIT_V8(0); BAR8; WAIT_L8(0); MMA8(0, 1, At, B1); BAR8;
	s_nop 0
	ds_read_b128 v[84:87], v156 offset:16384
	ds_read_b128 v[88:91], v156 offset:17408
	ds_read_b128 v[92:95], v154 offset:16384
	ds_read_b128 v[96:99], v154 offset:17408
	ds_read_b128 v[186:189], v153 offset:16384
	ds_read_b128 v[190:193], v153 offset:17408
	ds_read_b128 v[194:197], v152 offset:16384
	ds_read_b128 v[198:201], v152 offset:17408
	s_waitcnt vmcnt(4)
	s_barrier
	s_waitcnt lgkmcnt(0)
	v_mfma_f32_16x16x32_f16 v[64:67], v[84:87], v[138:141], v[64:67]
	v_mfma_f32_16x16x32_f16 v[60:63], v[84:87], v[160:163], v[60:63]
	v_mfma_f32_16x16x32_f16 v[56:59], v[92:95], v[138:141], v[56:59]
	v_mfma_f32_16x16x32_f16 v[52:55], v[92:95], v[160:163], v[52:55]
	v_mfma_f32_16x16x32_f16 v[48:51], v[186:189], v[138:141], v[48:51]
	v_mfma_f32_16x16x32_f16 v[44:47], v[186:189], v[160:163], v[44:47]
	v_mfma_f32_16x16x32_f16 v[40:43], v[194:197], v[138:141], v[40:43]
	v_mfma_f32_16x16x32_f16 v[36:39], v[194:197], v[160:163], v[36:39]
	v_mfma_f32_16x16x32_f16 v[64:67], v[88:91], v[142:145], v[64:67]
	v_mfma_f32_16x16x32_f16 v[60:63], v[88:91], v[164:167], v[60:63]
	v_mfma_f32_16x16x32_f16 v[56:59], v[96:99], v[142:145], v[56:59]
	v_mfma_f32_16x16x32_f16 v[52:55], v[96:99], v[164:167], v[52:55]
	v_mfma_f32_16x16x32_f16 v[48:51], v[190:193], v[142:145], v[48:51]
	v_mfma_f32_16x16x32_f16 v[44:47], v[190:193], v[164:167], v[44:47]
	v_mfma_f32_16x16x32_f16 v[40:43], v[198:201], v[142:145], v[40:43]
	v_mfma_f32_16x16x32_f16 v[36:39], v[198:201], v[164:167], v[36:39]
	v_mfma_f32_16x16x32_f16 v[32:35], v[84:87], v[100:103], v[32:35]
	v_mfma_f32_16x16x32_f16 v[28:31], v[84:87], v[108:111], v[28:31]
	v_mfma_f32_16x16x32_f16 v[24:27], v[92:95], v[100:103], v[24:27]
	v_mfma_f32_16x16x32_f16 v[20:23], v[92:95], v[108:111], v[20:23]
	v_mfma_f32_16x16x32_f16 v[16:19], v[186:189], v[100:103], v[16:19]
	v_mfma_f32_16x16x32_f16 v[12:15], v[186:189], v[108:111], v[12:15]
	v_mfma_f32_16x16x32_f16 v[8:11], v[194:197], v[100:103], v[8:11]
	v_mfma_f32_16x16x32_f16 v[4:7], v[194:197], v[108:111], v[4:7]
	v_mfma_f32_16x16x32_f16 v[136:139], v[88:91], v[104:107], v[32:35]
	v_mfma_f32_16x16x32_f16 v[140:143], v[88:91], v[116:119], v[28:31]
	v_mfma_f32_16x16x32_f16 v[160:163], v[96:99], v[104:107], v[24:27]
	v_mfma_f32_16x16x32_f16 v[164:167], v[96:99], v[116:119], v[20:23]
	v_mfma_f32_16x16x32_f16 v[202:205], v[190:193], v[104:107], v[16:19]
	v_mfma_f32_16x16x32_f16 v[186:189], v[190:193], v[116:119], v[12:15]
	v_mfma_f32_16x16x32_f16 v[190:193], v[198:201], v[104:107], v[8:11]
	v_mfma_f32_16x16x32_f16 v[194:197], v[198:201], v[116:119], v[4:7]
	s_barrier
	ds_read_b128 v[198:201], v159
	ds_read_b128 v[218:221], v159 offset:1024
	ds_read_b128 v[230:233], v159 offset:2048
	ds_read_b128 v[238:241], v159 offset:3072
	ds_read_b128 v[8:11], v156 offset:32768
	ds_read_b128 v[12:15], v156 offset:33792
	ds_read_b128 v[16:19], v154 offset:32768
	ds_read_b128 v[24:27], v154 offset:33792
	ds_read_b128 v[28:31], v153 offset:32768
	ds_read_b128 v[32:35], v153 offset:33792
	ds_read_b128 v[242:245], v152 offset:32768
	ds_read_b128 v[246:249], v152 offset:33792
	s_waitcnt vmcnt(2)
	s_barrier
	s_waitcnt lgkmcnt(0)
	v_mfma_f32_16x16x32_f16 v[4:7], v[8:11], v[198:201], v[128:131]
	v_mfma_f32_16x16x32_f16 v[104:107], v[12:15], v[218:221], v[4:7]
	v_mfma_f32_16x16x32_f16 v[4:7], v[8:11], v[230:233], v[124:127]
	v_mfma_f32_16x16x32_f16 v[116:119], v[12:15], v[238:241], v[4:7]
	v_mfma_f32_16x16x32_f16 v[4:7], v[16:19], v[198:201], v[120:123]
	v_mfma_f32_16x16x32_f16 v[100:103], v[24:27], v[218:221], v[4:7]
	v_mfma_f32_16x16x32_f16 v[4:7], v[16:19], v[230:233], v[132:135]
	v_mfma_f32_16x16x32_f16 v[108:111], v[24:27], v[238:241], v[4:7]
	v_mfma_f32_16x16x32_f16 v[4:7], v[28:31], v[198:201], v[112:115]
	v_mfma_f32_16x16x32_f16 v[92:95], v[32:35], v[218:221], v[4:7]
	v_mfma_f32_16x16x32_f16 v[4:7], v[28:31], v[230:233], v[170:173]
	v_mfma_f32_16x16x32_f16 v[96:99], v[32:35], v[238:241], v[4:7]
	v_mfma_f32_16x16x32_f16 v[4:7], v[242:245], v[198:201], v[206:209]
	v_mfma_f32_16x16x32_f16 v[84:87], v[246:249], v[218:221], v[4:7]
	v_mfma_f32_16x16x32_f16 v[4:7], v[242:245], v[230:233], v[210:213]
	v_mfma_f32_16x16x32_f16 v[88:91], v[246:249], v[238:241], v[4:7]
	s_barrier
; #define LDA8(dst, b, h) _Pragma("unroll") for (int m = 0; m < 4; ++m) _Pragma("unroll") for (int k = 0; k < 2; ++k) \
;     dst[m][k] = *(const bf16x8*)((const char*)SA8(b, h) + lds_byte8(wr * 64 + m * 16 + fr, k * 32 + fq * 8))
; #define LDB8(dst, b, h) _Pragma("unroll") for (int n = 0; n < 2; ++n) _Pragma("unroll") for (int k = 0; k < 2; ++k) \
;     dst[n][k] = *(const bf16x8*)((const char*)SB8(b, h) + lds_byte8(wc * 32 + n * 16 + fr, k * 32 + fq * 8))
; #define WAIT_V8(n) asm volatile("s_waitcnt vmcnt(" #n ")" ::: "memory")
; #define WAIT_L8(n) asm volatile("s_waitcnt lgkmcnt(" #n ")" ::: "memory")
; #define BAR8 __builtin_amdgcn_s_barrier()
;     ...
;     LDB8(B1, 1, 1); WAIT_V8(0); BAR8; WAIT_L8(0); MMA8(0, 1, At, B1); BAR8;
;     LDA8(At, 1, 1); BAR8; WAIT_L8(0); MMA8(1, 0, At, B0); MMA8(1, 1, At, B1); BAR8; }
;   if (wr == 0) BAR8;
;   __syncthreads();
	ds_read_b128 v[132:135], v157
	ds_read_b128 v[168:171], v157 offset:1024
	ds_read_b128 v[206:209], v157 offset:2048
	ds_read_b128 v[210:213], v157 offset:3072
	s_waitcnt vmcnt(0)
	s_barrier
	s_waitcnt lgkmcnt(0)
	v_mfma_f32_16x16x32_f16 v[4:7], v[8:11], v[132:135], v[214:217]
	v_mfma_f32_16x16x32_f16 v[8:11], v[8:11], v[206:209], v[174:177]
	v_mfma_f32_16x16x32_f16 v[4:7], v[12:15], v[168:171], v[4:7]
	v_mfma_f32_16x16x32_f16 v[20:23], v[12:15], v[210:213], v[8:11]
	v_mfma_f32_16x16x32_f16 v[8:11], v[16:19], v[132:135], v[178:181]
	v_mfma_f32_16x16x32_f16 v[12:15], v[16:19], v[206:209], v[182:185]
	v_mfma_f32_16x16x32_f16 v[8:11], v[24:27], v[168:171], v[8:11]
	v_mfma_f32_16x16x32_f16 v[24:27], v[24:27], v[210:213], v[12:15]
	v_mfma_f32_16x16x32_f16 v[12:15], v[28:31], v[132:135], v[80:83]
	v_mfma_f32_16x16x32_f16 v[16:19], v[28:31], v[206:209], v[76:79]
	v_mfma_f32_16x16x32_f16 v[12:15], v[32:35], v[168:171], v[12:15]
	v_mfma_f32_16x16x32_f16 v[28:31], v[32:35], v[210:213], v[16:19]
	v_mfma_f32_16x16x32_f16 v[16:19], v[242:245], v[132:135], v[72:75]
	v_mfma_f32_16x16x32_f16 v[32:35], v[242:245], v[206:209], v[68:71]
	v_mfma_f32_16x16x32_f16 v[16:19], v[246:249], v[168:171], v[16:19]
	v_mfma_f32_16x16x32_f16 v[32:35], v[246:249], v[210:213], v[32:35]
	s_barrier
	ds_read_b128 v[172:175], v156 offset:49152
	ds_read_b128 v[156:159], v156 offset:50176
	ds_read_b128 v[176:179], v154 offset:49152
	ds_read_b128 v[180:183], v154 offset:50176
	ds_read_b128 v[214:217], v153 offset:49152
	ds_read_b128 v[242:245], v153 offset:50176
	ds_read_b128 v[246:249], v152 offset:49152
	ds_read_b128 v[150:153], v152 offset:50176
	s_barrier
	s_waitcnt lgkmcnt(0)
	v_mfma_f32_16x16x32_f16 v[64:67], v[172:175], v[198:201], v[64:67]
	v_mfma_f32_16x16x32_f16 v[60:63], v[172:175], v[230:233], v[60:63]
	v_mfma_f32_16x16x32_f16 v[56:59], v[176:179], v[198:201], v[56:59]
	v_mfma_f32_16x16x32_f16 v[52:55], v[176:179], v[230:233], v[52:55]
	v_mfma_f32_16x16x32_f16 v[48:51], v[214:217], v[198:201], v[48:51]
	v_mfma_f32_16x16x32_f16 v[44:47], v[214:217], v[230:233], v[44:47]
	v_mfma_f32_16x16x32_f16 v[40:43], v[246:249], v[198:201], v[40:43]
	v_mfma_f32_16x16x32_f16 v[36:39], v[246:249], v[230:233], v[36:39]
	v_mfma_f32_16x16x32_f16 v[128:131], v[156:159], v[218:221], v[64:67]
	v_mfma_f32_16x16x32_f16 v[124:127], v[156:159], v[238:241], v[60:63]
	v_mfma_f32_16x16x32_f16 v[120:123], v[180:183], v[218:221], v[56:59]
	v_mfma_f32_16x16x32_f16 v[112:115], v[180:183], v[238:241], v[52:55]
	v_mfma_f32_16x16x32_f16 v[80:83], v[242:245], v[218:221], v[48:51]
	v_mfma_f32_16x16x32_f16 v[76:79], v[242:245], v[238:241], v[44:47]
	v_mfma_f32_16x16x32_f16 v[72:75], v[150:153], v[218:221], v[40:43]
	v_mfma_f32_16x16x32_f16 v[68:71], v[150:153], v[238:241], v[36:39]
	v_mfma_f32_16x16x32_f16 v[40:43], v[172:175], v[206:209], v[140:143]
	v_mfma_f32_16x16x32_f16 v[44:47], v[176:179], v[206:209], v[164:167]
	v_mfma_f32_16x16x32_f16 v[48:51], v[214:217], v[206:209], v[186:189]
	v_mfma_f32_16x16x32_f16 v[36:39], v[172:175], v[132:135], v[136:139]
	v_mfma_f32_16x16x32_f16 v[52:55], v[156:159], v[210:213], v[40:43]
	v_mfma_f32_16x16x32_f16 v[40:43], v[176:179], v[132:135], v[160:163]
	v_mfma_f32_16x16x32_f16 v[56:59], v[180:183], v[210:213], v[44:47]
	v_mfma_f32_16x16x32_f16 v[44:47], v[214:217], v[132:135], v[202:205]
	v_mfma_f32_16x16x32_f16 v[60:63], v[242:245], v[210:213], v[48:51]
	v_mfma_f32_16x16x32_f16 v[48:51], v[246:249], v[132:135], v[190:193]
	v_mfma_f32_16x16x32_f16 v[64:67], v[246:249], v[206:209], v[194:197]
	v_mfma_f32_16x16x32_f16 v[36:39], v[156:159], v[168:171], v[36:39]
	v_mfma_f32_16x16x32_f16 v[40:43], v[180:183], v[168:171], v[40:43]
	v_mfma_f32_16x16x32_f16 v[44:47], v[242:245], v[168:171], v[44:47]
	v_mfma_f32_16x16x32_f16 v[48:51], v[150:153], v[168:171], v[48:51]
	v_mfma_f32_16x16x32_f16 v[64:67], v[150:153], v[210:213], v[64:67]
	s_movk_i32 s1, 0x100
	v_cmp_gt_u32_e32 vcc, s1, v3
	s_barrier
	s_and_saveexec_b64 s[12:13], vcc
	s_cbranch_execz .LBB0_245
	s_barrier

; #define LDA8(dst, b, h) _Pragma("unroll") for (int m = 0; m < 4; ++m) _Pragma("unroll") for (int k = 0; k < 2; ++k) \
;     dst[m][k] = *(const bf16x8*)((const char*)SA8(b, h) + lds_byte8(wr * 64 + m * 16 + fr, k * 32 + fq * 8))
; #define LDB8(dst, b, h) _Pragma("unroll") for (int n = 0; n < 2; ++n) _Pragma("unroll") for (int k = 0; k < 2; ++k) \
;     dst[n][k] = *(const bf16x8*)((const char*)SB8(b, h) + lds_byte8(wc * 32 + n * 16 + fr, k * 32 + fq * 8))
; #define WAIT_V8(n) asm volatile("s_waitcnt vmcnt(" #n ")" ::: "memory")
; #define WAIT_L8(n) asm volatile("s_waitcnt lgkmcnt(" #n ")" ::: "memory")
; #define BAR8 __builtin_amdgcn_s_barrier()
; #define SCHED8 __builtin_amdgcn_sched_barrier(0)
;     ...
;   WAIT_V8(4); BAR8;
;   STAGE8(SB8(1, 0), Bt, K, bcol, 1); STAGE8(SA8(1, 0), A, lda, brow, 1); STAGE8(SB8(1, 1), Bt, K, bcol + 128, 1);
;   WAIT_V8(6); BAR8;
;   for (int tt = 0; tt < nt - 2; tt += 2) {
;     LDB8(B0, 0, 0); SCHED8; LDA8(At, 0, 0); STAGE8(SA8(1, 1), A, lda, brow + 128, tt + 1);
;     WAIT_L8(8); BAR8; WAIT_L8(0); MMA8(0, 0, At, B0); BAR8; SCHED8;
;     LDB8(B1, 0, 1); STAGE8(SB8(0, 0), Bt, K, bcol, tt + 2);
;     BAR8; WAIT_L8(0); MMA8(0, 1, At, B1); BAR8;
;     LDA8(At, 0, 1); STAGE8(SA8(0, 0), A, lda, brow, tt + 2);
;     BAR8; WAIT_L8(0); MMA8(1, 0, At, B0); BAR8; SCHED8;
.LBB0_554:
	s_or_b64 exec, exec, s[14:15]
	v_add_u32_e32 v5, 0x18000, v26
	s_mov_b64 s[14:15], 0x80
	v_readfirstlane_b32 s43, v5
	v_add_u32_e32 v5, 0x1a000, v26
	v_lshl_add_u64 v[6:7], v[14:15], 0, s[14:15]
	s_mov_b32 m0, s43
	v_readfirstlane_b32 s42, v5
	v_add_u32_e32 v5, 0x8000, v26
	s_waitcnt vmcnt(4)
	s_barrier
	global_load_lds_dwordx4 v[6:7], off
	v_lshl_add_u64 v[6:7], v[24:25], 0, s[14:15]
	s_mov_b32 m0, s42
	v_readfirstlane_b32 s40, v5
	v_add_u32_e32 v5, 0xa000, v26
	global_load_lds_dwordx4 v[6:7], off
	v_lshl_add_u64 v[6:7], v[20:21], 0, s[14:15]
	s_mov_b32 m0, s40
	v_readfirstlane_b32 s39, v5
	v_add_u32_e32 v5, 0x1c000, v26
	global_load_lds_dwordx4 v[6:7], off
	v_lshl_add_u64 v[6:7], v[22:23], 0, s[14:15]
	s_mov_b32 m0, s39
	v_readfirstlane_b32 s29, v5
	v_add_u32_e32 v5, 0x1e000, v26
	global_load_lds_dwordx4 v[6:7], off
	v_lshl_add_u64 v[6:7], v[16:17], 0, s[14:15]
	s_mov_b32 m0, s29
	v_readfirstlane_b32 s27, v5
	global_load_lds_dwordx4 v[6:7], off
	v_lshl_add_u64 v[6:7], v[18:19], 0, s[14:15]
	s_mov_b32 m0, s27
	v_bfe_u32 v135, v3, 4, 2
	global_load_lds_dwordx4 v[6:7], off
	v_bfe_u32 v133, v3, 6, 2
	v_and_b32_e32 v134, 15, v3
	v_lshlrev_b32_e32 v58, 4, v135
	v_lshlrev_b32_e32 v35, 2, v3
	v_lshlrev_b32_e32 v34, 12, v133
	v_lshl_or_b32 v50, v134, 6, v58
	v_and_b32_e32 v59, 32, v35
	v_bitop3_b32 v212, v50, v34, v59 bitop3:0xde
	v_or_b32_e32 v220, 0x10000, v212
	v_or_b32_e32 v222, 0x10800, v212
	s_waitcnt vmcnt(6)
	s_barrier
	v_or_b32_e32 v221, 0x10400, v212
	ds_read_b128 v[34:37], v220
	ds_read_b128 v[38:41], v221
	v_or_b32_e32 v223, 0x10c00, v212
	ds_read_b128 v[42:45], v222
	ds_read_b128 v[46:49], v223
	s_add_u32 s44, s12, 0x80080
	s_addc_u32 s45, s13, 0
	v_mov_b32_e32 v5, v4
	v_mov_b32_e32 v6, v4
	v_mov_b32_e32 v7, v4
	s_add_u32 s14, s12, 0x80100
	s_addc_u32 s15, s13, 0
	v_lshlrev_b32_e32 v61, 6, v3
	s_movk_i32 s37, 0x3c0
	v_add_u32_e32 v84, 0xc000, v26
	v_lshlrev_b32_e32 v60, 13, v132
	v_and_or_b32 v58, v61, s37, v58
	v_lshl_add_u64 v[82:83], s[44:45], 0, v[10:11]
	v_readfirstlane_b32 s41, v84
	v_bitop3_b32 v226, v50, v60, v59 bitop3:0xde
	v_bitop3_b32 v227, v60, v58, v59 bitop3:0xf6
	v_lshl_add_u64 v[82:83], v[82:83], 0, v[0:1]
	s_mov_b32 m0, s41
	v_add_u32_e32 v84, 0xe000, v26
	ds_read_b128 v[50:53], v226
	ds_read_b128 v[54:57], v226 offset:1024
	ds_read_b128 v[58:61], v227 offset:2048
	ds_read_b128 v[62:65], v227 offset:3072
	ds_read_b128 v[66:69], v227 offset:4096
	ds_read_b128 v[70:73], v227 offset:5120
	ds_read_b128 v[74:77], v227 offset:6144
	ds_read_b128 v[78:81], v227 offset:7168
	global_load_lds_dwordx4 v[82:83], off
	v_lshl_add_u64 v[82:83], s[44:45], 0, v[12:13]
	v_readfirstlane_b32 s37, v84
	v_lshl_add_u64 v[82:83], v[82:83], 0, v[8:9]
	s_mov_b32 m0, s37
	s_nop 0
	global_load_lds_dwordx4 v[82:83], off
	s_waitcnt lgkmcnt(8)
	s_barrier
	s_waitcnt lgkmcnt(0)
	v_mfma_f32_16x16x32_bf16 v[82:85], v[50:53], v[34:37], v[4:7]
	v_mfma_f32_16x16x32_bf16 v[86:89], v[50:53], v[42:45], v[4:7]
	v_mfma_f32_16x16x32_bf16 v[90:93], v[58:61], v[34:37], v[4:7]
	v_mfma_f32_16x16x32_bf16 v[94:97], v[58:61], v[42:45], v[4:7]
	v_mfma_f32_16x16x32_bf16 v[98:101], v[66:69], v[34:37], v[4:7]
	v_mfma_f32_16x16x32_bf16 v[102:105], v[66:69], v[42:45], v[4:7]
	v_mfma_f32_16x16x32_bf16 v[106:109], v[74:77], v[34:37], v[4:7]
	v_mfma_f32_16x16x32_bf16 v[110:113], v[74:77], v[42:45], v[4:7]
	v_mfma_f32_16x16x32_bf16 v[82:85], v[54:57], v[38:41], v[82:85]
	v_mfma_f32_16x16x32_bf16 v[86:89], v[54:57], v[46:49], v[86:89]
	v_mfma_f32_16x16x32_bf16 v[90:93], v[62:65], v[38:41], v[90:93]
	v_mfma_f32_16x16x32_bf16 v[94:97], v[62:65], v[46:49], v[94:97]
	v_mfma_f32_16x16x32_bf16 v[98:101], v[70:73], v[38:41], v[98:101]
	v_mfma_f32_16x16x32_bf16 v[102:105], v[70:73], v[46:49], v[102:105]
	v_mfma_f32_16x16x32_bf16 v[106:109], v[78:81], v[38:41], v[106:109]
	v_mfma_f32_16x16x32_bf16 v[110:113], v[78:81], v[46:49], v[110:113]
	s_barrier
	v_readfirstlane_b32 s44, v30
	v_or_b32_e32 v228, 0x14000, v212
	v_or_b32_e32 v230, 0x14800, v212
	v_lshl_add_u64 v[130:131], v[14:15], 0, s[10:11]
	s_mov_b32 m0, s44
	v_readfirstlane_b32 s44, v33
	v_or_b32_e32 v229, 0x14400, v212
	ds_read_b128 v[114:117], v228
	ds_read_b128 v[118:121], v229
	v_or_b32_e32 v231, 0x14c00, v212
	ds_read_b128 v[122:125], v230
	ds_read_b128 v[126:129], v231
	global_load_lds_dwordx4 v[130:131], off
	v_lshl_add_u64 v[130:131], v[24:25], 0, s[10:11]
	s_mov_b32 m0, s44
	s_nop 0
	global_load_lds_dwordx4 v[130:131], off
	s_barrier
	s_waitcnt lgkmcnt(0)
	v_mfma_f32_16x16x32_bf16 v[136:139], v[50:53], v[114:117], v[4:7]
	v_mfma_f32_16x16x32_bf16 v[50:53], v[50:53], v[122:125], v[4:7]
	v_mfma_f32_16x16x32_bf16 v[136:139], v[54:57], v[118:121], v[136:139]
	v_mfma_f32_16x16x32_bf16 v[50:53], v[54:57], v[126:129], v[50:53]
	v_mfma_f32_16x16x32_bf16 v[54:57], v[58:61], v[114:117], v[4:7]
	v_mfma_f32_16x16x32_bf16 v[58:61], v[58:61], v[122:125], v[4:7]
	v_mfma_f32_16x16x32_bf16 v[54:57], v[62:65], v[118:121], v[54:57]
	v_mfma_f32_16x16x32_bf16 v[58:61], v[62:65], v[126:129], v[58:61]
	v_mfma_f32_16x16x32_bf16 v[62:65], v[66:69], v[114:117], v[4:7]
	v_mfma_f32_16x16x32_bf16 v[66:69], v[66:69], v[122:125], v[4:7]
	v_mfma_f32_16x16x32_bf16 v[62:65], v[70:73], v[118:121], v[62:65]
	v_mfma_f32_16x16x32_bf16 v[66:69], v[70:73], v[126:129], v[66:69]
	v_mfma_f32_16x16x32_bf16 v[70:73], v[74:77], v[114:117], v[4:7]
	v_mfma_f32_16x16x32_bf16 v[74:77], v[74:77], v[122:125], v[4:7]
	v_mfma_f32_16x16x32_bf16 v[70:73], v[78:81], v[118:121], v[70:73]
	v_mfma_f32_16x16x32_bf16 v[74:77], v[78:81], v[126:129], v[74:77]
	v_readfirstlane_b32 s44, v26
	v_lshl_add_u64 v[130:131], v[20:21], 0, s[10:11]
	s_mov_b32 m0, s44
	v_readfirstlane_b32 s44, v27
	s_barrier
; #define LDA8(dst, b, h) _Pragma("unroll") for (int m = 0; m < 4; ++m) _Pragma("unroll") for (int k = 0; k < 2; ++k) \
;     dst[m][k] = *(const bf16x8*)((const char*)SA8(b, h) + lds_byte8(wr * 64 + m * 16 + fr, k * 32 + fq * 8))
; #define LDB8(dst, b, h) _Pragma("unroll") for (int n = 0; n < 2; ++n) _Pragma("unroll") for (int k = 0; k < 2; ++k) \
;     dst[n][k] = *(const bf16x8*)((const char*)SB8(b, h) + lds_byte8(wc * 32 + n * 16 + fr, k * 32 + fq * 8))
; #define WAIT_V8(n) asm volatile("s_waitcnt vmcnt(" #n ")" ::: "memory")
; #define WAIT_L8(n) asm volatile("s_waitcnt lgkmcnt(" #n ")" ::: "memory")
; #define BAR8 __builtin_amdgcn_s_barrier()
; #define SCHED8 __builtin_amdgcn_sched_barrier(0)
;     ...
;     BAR8; WAIT_L8(0); MMA8(1, 0, At, B0); BAR8; SCHED8;
;     STAGE8(SB8(0, 1), Bt, K, bcol + 128, tt + 2);
;     WAIT_V8(6); BAR8; MMA8(1, 1, At, B1); BAR8;
;     LDB8(B0, 1, 0); SCHED8; LDA8(At, 1, 0); STAGE8(SA8(0, 1), A, lda, brow + 128, tt + 2);
;     WAIT_L8(8); BAR8; WAIT_L8(0); MMA8(0, 0, At, B0); BAR8; SCHED8;
;     LDB8(B1, 1, 1); STAGE8(SB8(1, 0), Bt, K, bcol, tt + 3);
;     BAR8; WAIT_L8(0); MMA8(0, 1, At, B1); BAR8;
;     LDA8(At, 1, 1); STAGE8(SA8(1, 0), A, lda, brow, tt + 3);
;     BAR8; WAIT_L8(0); MMA8(1, 0, At, B0); BAR8; SCHED8;
	ds_read_b128 v[78:81], v226 offset:16384
	ds_read_b128 v[140:143], v226 offset:17408
	s_waitcnt vmcnt(0)
	ds_read_b128 v[144:147], v227 offset:18432
	ds_read_b128 v[148:151], v227 offset:19456
	ds_read_b128 v[152:155], v227 offset:20480
	ds_read_b128 v[156:159], v227 offset:21504
	ds_read_b128 v[160:163], v227 offset:22528
	ds_read_b128 v[164:167], v227 offset:23552
	global_load_lds_dwordx4 v[130:131], off
	v_lshl_add_u64 v[130:131], v[22:23], 0, s[10:11]
	s_mov_b32 m0, s44
	s_nop 0
	global_load_lds_dwordx4 v[130:131], off
	s_barrier
	s_waitcnt lgkmcnt(0)
	v_mfma_f32_16x16x32_bf16 v[168:171], v[78:81], v[34:37], v[4:7]
	v_mfma_f32_16x16x32_bf16 v[176:179], v[144:147], v[34:37], v[4:7]
	v_mfma_f32_16x16x32_bf16 v[184:187], v[152:155], v[34:37], v[4:7]
	v_mfma_f32_16x16x32_bf16 v[34:37], v[160:163], v[34:37], v[4:7]
	v_mfma_f32_16x16x32_bf16 v[168:171], v[140:143], v[38:41], v[168:171]
	v_mfma_f32_16x16x32_bf16 v[176:179], v[148:151], v[38:41], v[176:179]
	v_mfma_f32_16x16x32_bf16 v[184:187], v[156:159], v[38:41], v[184:187]
	v_mfma_f32_16x16x32_bf16 v[34:37], v[164:167], v[38:41], v[34:37]
	v_mfma_f32_16x16x32_bf16 v[38:41], v[160:163], v[42:45], v[4:7]
	v_mfma_f32_16x16x32_bf16 v[172:175], v[78:81], v[42:45], v[4:7]
	v_mfma_f32_16x16x32_bf16 v[180:183], v[144:147], v[42:45], v[4:7]
	v_mfma_f32_16x16x32_bf16 v[188:191], v[152:155], v[42:45], v[4:7]
	v_mfma_f32_16x16x32_bf16 v[38:41], v[164:167], v[46:49], v[38:41]
	v_mfma_f32_16x16x32_bf16 v[172:175], v[140:143], v[46:49], v[172:175]
	v_mfma_f32_16x16x32_bf16 v[180:183], v[148:151], v[46:49], v[180:183]
	v_mfma_f32_16x16x32_bf16 v[188:191], v[156:159], v[46:49], v[188:191]
	s_barrier
	v_readfirstlane_b32 s44, v31
	v_lshl_add_u64 v[26:27], v[16:17], 0, s[10:11]
	s_mov_b32 m0, s44
	v_readfirstlane_b32 s44, v32
	global_load_lds_dwordx4 v[26:27], off
	v_lshl_add_u64 v[26:27], v[18:19], 0, s[10:11]
	s_mov_b32 m0, s44
	s_nop 0
	global_load_lds_dwordx4 v[26:27], off
	s_waitcnt vmcnt(6)
	s_barrier
	v_mfma_f32_16x16x32_bf16 v[30:33], v[78:81], v[114:117], v[4:7]
	v_mfma_f32_16x16x32_bf16 v[42:45], v[78:81], v[122:125], v[4:7]
	v_mfma_f32_16x16x32_bf16 v[30:33], v[140:143], v[118:121], v[30:33]
	v_mfma_f32_16x16x32_bf16 v[42:45], v[140:143], v[126:129], v[42:45]
	v_mfma_f32_16x16x32_bf16 v[46:49], v[144:147], v[114:117], v[4:7]
	v_mfma_f32_16x16x32_bf16 v[78:81], v[144:147], v[122:125], v[4:7]
	v_mfma_f32_16x16x32_bf16 v[140:143], v[152:155], v[114:117], v[4:7]
	v_mfma_f32_16x16x32_bf16 v[144:147], v[152:155], v[122:125], v[4:7]
	v_mfma_f32_16x16x32_bf16 v[114:117], v[160:163], v[114:117], v[4:7]
	v_mfma_f32_16x16x32_bf16 v[4:7], v[160:163], v[122:125], v[4:7]
	v_mfma_f32_16x16x32_bf16 v[46:49], v[148:151], v[118:121], v[46:49]
	v_mfma_f32_16x16x32_bf16 v[78:81], v[148:151], v[126:129], v[78:81]
	v_mfma_f32_16x16x32_bf16 v[114:117], v[164:167], v[118:121], v[114:117]
	v_mfma_f32_16x16x32_bf16 v[4:7], v[164:167], v[126:129], v[4:7]
	v_mfma_f32_16x16x32_bf16 v[140:143], v[156:159], v[118:121], v[140:143]
	v_mfma_f32_16x16x32_bf16 v[144:147], v[156:159], v[126:129], v[144:147]
	v_or_b32_e32 v130, 0x18000, v212
	v_or_b32_e32 v232, 0x18800, v212
	s_barrier
	v_or_b32_e32 v131, 0x18400, v212
	ds_read_b128 v[118:121], v130
	ds_read_b128 v[122:125], v131
	v_or_b32_e32 v233, 0x18c00, v212
	ds_read_b128 v[126:129], v232
	ds_read_b128 v[148:151], v233
	v_lshl_add_u64 v[26:27], s[14:15], 0, v[10:11]
	v_readfirstlane_b32 s44, v28
	v_lshl_add_u64 v[26:27], v[26:27], 0, v[0:1]
	s_mov_b32 m0, s44
	ds_read_b128 v[152:155], v226 offset:32768
	ds_read_b128 v[156:159], v226 offset:33792
	ds_read_b128 v[160:163], v227 offset:34816
	ds_read_b128 v[164:167], v227 offset:35840
	ds_read_b128 v[192:195], v227 offset:36864
	ds_read_b128 v[196:199], v227 offset:37888
	ds_read_b128 v[200:203], v227 offset:38912
	ds_read_b128 v[204:207], v227 offset:39936
	global_load_lds_dwordx4 v[26:27], off
	v_lshl_add_u64 v[26:27], s[14:15], 0, v[12:13]
	v_readfirstlane_b32 s14, v29
	v_lshl_add_u64 v[26:27], v[26:27], 0, v[8:9]
	s_mov_b32 m0, s14
	s_nop 0
	global_load_lds_dwordx4 v[26:27], off
	s_waitcnt lgkmcnt(8)
	s_barrier
	s_waitcnt lgkmcnt(0)
	v_mfma_f32_16x16x32_bf16 v[26:29], v[152:155], v[118:121], v[82:85]
	v_mfma_f32_16x16x32_bf16 v[82:85], v[152:155], v[126:129], v[86:89]
	v_mfma_f32_16x16x32_bf16 v[86:89], v[160:163], v[118:121], v[90:93]
	v_mfma_f32_16x16x32_bf16 v[90:93], v[160:163], v[126:129], v[94:97]
	v_mfma_f32_16x16x32_bf16 v[94:97], v[192:195], v[118:121], v[98:101]
	v_mfma_f32_16x16x32_bf16 v[98:101], v[192:195], v[126:129], v[102:105]
	v_mfma_f32_16x16x32_bf16 v[102:105], v[200:203], v[118:121], v[106:109]
	v_mfma_f32_16x16x32_bf16 v[106:109], v[200:203], v[126:129], v[110:113]
	v_mfma_f32_16x16x32_bf16 v[26:29], v[156:159], v[122:125], v[26:29]
	v_mfma_f32_16x16x32_bf16 v[82:85], v[156:159], v[148:151], v[82:85]
	v_mfma_f32_16x16x32_bf16 v[86:89], v[164:167], v[122:125], v[86:89]
	v_mfma_f32_16x16x32_bf16 v[90:93], v[164:167], v[148:151], v[90:93]
	v_mfma_f32_16x16x32_bf16 v[94:97], v[196:199], v[122:125], v[94:97]
	v_mfma_f32_16x16x32_bf16 v[98:101], v[196:199], v[148:151], v[98:101]
	v_mfma_f32_16x16x32_bf16 v[102:105], v[204:207], v[122:125], v[102:105]
	v_mfma_f32_16x16x32_bf16 v[106:109], v[204:207], v[148:151], v[106:109]
	s_barrier
	s_mov_b32 m0, s43
	v_or_b32_e32 v236, 0x1c000, v212
	v_or_b32_e32 v238, 0x1c800, v212
	v_lshl_add_u64 v[14:15], v[14:15], 0, s[22:23]
	v_or_b32_e32 v237, 0x1c400, v212
	ds_read_b128 v[110:113], v236
	ds_read_b128 v[208:211], v237
	v_or_b32_e32 v239, 0x1cc00, v212
	ds_read_b128 v[212:215], v238
	ds_read_b128 v[216:219], v239
	global_load_lds_dwordx4 v[14:15], off
	v_lshl_add_u64 v[14:15], v[24:25], 0, s[22:23]
	s_mov_b32 m0, s42
	s_nop 0
	global_load_lds_dwordx4 v[14:15], off
	s_barrier
; #define LDA8(dst, b, h) _Pragma("unroll") for (int m = 0; m < 4; ++m) _Pragma("unroll") for (int k = 0; k < 2; ++k) \
;     dst[m][k] = *(const bf16x8*)((const char*)SA8(b, h) + lds_byte8(wr * 64 + m * 16 + fr, k * 32 + fq * 8))
; #define LDB8(dst, b, h) _Pragma("unroll") for (int n = 0; n < 2; ++n) _Pragma("unroll") for (int k = 0; k < 2; ++k) \
;     dst[n][k] = *(const bf16x8*)((const char*)SB8(b, h) + lds_byte8(wc * 32 + n * 16 + fr, k * 32 + fq * 8))
; #define WAIT_V8(n) asm volatile("s_waitcnt vmcnt(" #n ")" ::: "memory")
; #define WAIT_L8(n) asm volatile("s_waitcnt lgkmcnt(" #n ")" ::: "memory")
; #define BAR8 __builtin_amdgcn_s_barrier()
; #define SCHED8 __builtin_amdgcn_sched_barrier(0)
;     ...
;     BAR8; WAIT_L8(0); MMA8(1, 0, At, B0); BAR8; SCHED8;
;     STAGE8(SB8(1, 1), Bt, K, bcol + 128, tt + 3);
;     WAIT_V8(6); BAR8; MMA8(1, 1, At, B1); BAR8;
;   }
;   { LDB8(B0, 0, 0); LDA8(At, 0, 0); STAGE8(SA8(1, 1), A, lda, brow + 128, nt - 1);
;     BAR8; WAIT_L8(0); MMA8(0, 0, At, B0); BAR8;
;     LDB8(B1, 0, 1); BAR8; WAIT_L8(0); MMA8(0, 1, At, B1); BAR8;
;     LDA8(At, 0, 1); WAIT_V8(4); BAR8; WAIT_L8(0); MMA8(1, 0, At, B0); MMA8(1, 1, At, B1); BAR8; }
;   { LDB8(B0, 1, 0); LDA8(At, 1, 0); WAIT_V8(2); BAR8; WAIT_L8(0); MMA8(0, 0, At, B0); BAR8;
	s_waitcnt lgkmcnt(0)
	v_mfma_f32_16x16x32_bf16 v[50:53], v[152:155], v[212:215], v[50:53]
	v_mfma_f32_16x16x32_bf16 v[54:57], v[160:163], v[110:113], v[54:57]
	v_mfma_f32_16x16x32_bf16 v[58:61], v[160:163], v[212:215], v[58:61]
	v_mfma_f32_16x16x32_bf16 v[62:65], v[192:195], v[110:113], v[62:65]
	v_mfma_f32_16x16x32_bf16 v[66:69], v[192:195], v[212:215], v[66:69]
	v_mfma_f32_16x16x32_bf16 v[70:73], v[200:203], v[110:113], v[70:73]
	v_mfma_f32_16x16x32_bf16 v[74:77], v[200:203], v[212:215], v[74:77]
	v_mfma_f32_16x16x32_bf16 v[136:139], v[152:155], v[110:113], v[136:139]
	v_mfma_f32_16x16x32_bf16 v[50:53], v[156:159], v[216:219], v[50:53]
	v_mfma_f32_16x16x32_bf16 v[54:57], v[164:167], v[208:211], v[54:57]
	v_mfma_f32_16x16x32_bf16 v[58:61], v[164:167], v[216:219], v[58:61]
	v_mfma_f32_16x16x32_bf16 v[62:65], v[196:199], v[208:211], v[62:65]
	v_mfma_f32_16x16x32_bf16 v[66:69], v[196:199], v[216:219], v[66:69]
	v_mfma_f32_16x16x32_bf16 v[70:73], v[204:207], v[208:211], v[70:73]
	v_mfma_f32_16x16x32_bf16 v[74:77], v[204:207], v[216:219], v[74:77]
	v_mfma_f32_16x16x32_bf16 v[136:139], v[156:159], v[208:211], v[136:139]
	s_mov_b32 m0, s40
	v_lshl_add_u64 v[14:15], v[20:21], 0, s[22:23]
	s_barrier
	ds_read_b128 v[152:155], v226 offset:49152
	ds_read_b128 v[156:159], v226 offset:50176
	ds_read_b128 v[160:163], v227 offset:51200
	ds_read_b128 v[164:167], v227 offset:52224
	ds_read_b128 v[192:195], v227 offset:53248
	ds_read_b128 v[196:199], v227 offset:54272
	ds_read_b128 v[200:203], v227 offset:55296
	ds_read_b128 v[204:207], v227 offset:56320
	global_load_lds_dwordx4 v[14:15], off
	v_lshl_add_u64 v[14:15], v[22:23], 0, s[22:23]
	s_mov_b32 m0, s39
	s_nop 0
	global_load_lds_dwordx4 v[14:15], off
	s_barrier
	s_waitcnt lgkmcnt(0)
	v_mfma_f32_16x16x32_bf16 v[20:23], v[152:155], v[118:121], v[168:171]
	v_mfma_f32_16x16x32_bf16 v[34:37], v[200:203], v[118:121], v[34:37]
	v_mfma_f32_16x16x32_bf16 v[38:41], v[200:203], v[126:129], v[38:41]
	v_mfma_f32_16x16x32_bf16 v[20:23], v[156:159], v[122:125], v[20:23]
	v_mfma_f32_16x16x32_bf16 v[168:171], v[152:155], v[126:129], v[172:175]
	v_mfma_f32_16x16x32_bf16 v[172:175], v[160:163], v[118:121], v[176:179]
	v_mfma_f32_16x16x32_bf16 v[176:179], v[160:163], v[126:129], v[180:183]
	v_mfma_f32_16x16x32_bf16 v[180:183], v[192:195], v[118:121], v[184:187]
	v_mfma_f32_16x16x32_bf16 v[184:187], v[192:195], v[126:129], v[188:191]
	v_mfma_f32_16x16x32_bf16 v[34:37], v[204:207], v[122:125], v[34:37]
	v_mfma_f32_16x16x32_bf16 v[38:41], v[204:207], v[148:151], v[38:41]
	v_mfma_f32_16x16x32_bf16 v[168:171], v[156:159], v[148:151], v[168:171]
	v_mfma_f32_16x16x32_bf16 v[172:175], v[164:167], v[122:125], v[172:175]
	v_mfma_f32_16x16x32_bf16 v[176:179], v[164:167], v[148:151], v[176:179]
	v_mfma_f32_16x16x32_bf16 v[180:183], v[196:199], v[122:125], v[180:183]
	v_mfma_f32_16x16x32_bf16 v[184:187], v[196:199], v[148:151], v[184:187]
	s_barrier
	s_mov_b32 m0, s29
	v_lshl_add_u64 v[14:15], v[16:17], 0, s[22:23]
	global_load_lds_dwordx4 v[14:15], off
	v_lshl_add_u64 v[14:15], v[18:19], 0, s[22:23]
	s_mov_b32 m0, s27
	s_nop 0
	global_load_lds_dwordx4 v[14:15], off
	s_waitcnt vmcnt(6)
	s_barrier
	v_mfma_f32_16x16x32_bf16 v[14:17], v[152:155], v[110:113], v[30:33]
	v_mfma_f32_16x16x32_bf16 v[30:33], v[152:155], v[212:215], v[42:45]
	v_mfma_f32_16x16x32_bf16 v[42:45], v[160:163], v[110:113], v[46:49]
	v_mfma_f32_16x16x32_bf16 v[46:49], v[160:163], v[212:215], v[78:81]
	v_mfma_f32_16x16x32_bf16 v[78:81], v[192:195], v[110:113], v[140:143]
	v_mfma_f32_16x16x32_bf16 v[118:121], v[192:195], v[212:215], v[144:147]
	v_mfma_f32_16x16x32_bf16 v[110:113], v[200:203], v[110:113], v[114:117]
	v_mfma_f32_16x16x32_bf16 v[4:7], v[200:203], v[212:215], v[4:7]
	v_mfma_f32_16x16x32_bf16 v[14:17], v[156:159], v[208:211], v[14:17]
	v_mfma_f32_16x16x32_bf16 v[30:33], v[156:159], v[216:219], v[30:33]
	v_mfma_f32_16x16x32_bf16 v[42:45], v[164:167], v[208:211], v[42:45]
	v_mfma_f32_16x16x32_bf16 v[46:49], v[164:167], v[216:219], v[46:49]
	v_mfma_f32_16x16x32_bf16 v[78:81], v[196:199], v[208:211], v[78:81]
	v_mfma_f32_16x16x32_bf16 v[118:121], v[196:199], v[216:219], v[118:121]
	v_mfma_f32_16x16x32_bf16 v[110:113], v[204:207], v[208:211], v[110:113]
	v_mfma_f32_16x16x32_bf16 v[4:7], v[204:207], v[216:219], v[4:7]
	s_add_u32 s12, s12, 0x80180
	s_addc_u32 s13, s13, 0
	v_lshl_add_u64 v[10:11], s[12:13], 0, v[10:11]
	s_mov_b32 m0, s41
	v_lshl_add_u64 v[0:1], v[10:11], 0, v[0:1]
	s_barrier
	ds_read_b128 v[114:117], v220
	ds_read_b128 v[122:125], v221
	ds_read_b128 v[126:129], v222
	ds_read_b128 v[140:143], v223
	ds_read_b128 v[144:147], v226
	ds_read_b128 v[148:151], v226 offset:1024
	ds_read_b128 v[152:155], v227 offset:2048
	ds_read_b128 v[156:159], v227 offset:3072
	ds_read_b128 v[160:163], v227 offset:4096
	ds_read_b128 v[164:167], v227 offset:5120
	ds_read_b128 v[188:191], v227 offset:6144
	ds_read_b128 v[192:195], v227 offset:7168
	global_load_lds_dwordx4 v[0:1], off
	v_lshl_add_u64 v[0:1], s[12:13], 0, v[12:13]
	v_lshl_add_u64 v[0:1], v[0:1], 0, v[8:9]
	s_mov_b32 m0, s37
	s_nop 0
	global_load_lds_dwordx4 v[0:1], off
	s_barrier
; #define LDA8(dst, b, h) _Pragma("unroll") for (int m = 0; m < 4; ++m) _Pragma("unroll") for (int k = 0; k < 2; ++k) \
;     dst[m][k] = *(const bf16x8*)((const char*)SA8(b, h) + lds_byte8(wr * 64 + m * 16 + fr, k * 32 + fq * 8))
; #define LDB8(dst, b, h) _Pragma("unroll") for (int n = 0; n < 2; ++n) _Pragma("unroll") for (int k = 0; k < 2; ++k) \
;     dst[n][k] = *(const bf16x8*)((const char*)SB8(b, h) + lds_byte8(wc * 32 + n * 16 + fr, k * 32 + fq * 8))
; #define WAIT_V8(n) asm volatile("s_waitcnt vmcnt(" #n ")" ::: "memory")
; #define WAIT_L8(n) asm volatile("s_waitcnt lgkmcnt(" #n ")" ::: "memory")
; #define BAR8 __builtin_amdgcn_s_barrier()
;     ...
;     LDA8(At, 0, 1); WAIT_V8(4); BAR8; WAIT_L8(0); MMA8(1, 0, At, B0); MMA8(1, 1, At, B1); BAR8; }
;   { LDB8(B0, 1, 0); LDA8(At, 1, 0); WAIT_V8(2); BAR8; WAIT_L8(0); MMA8(0, 0, At, B0); BAR8;
;     LDB8(B1, 1, 1); WAIT_V8(0); BAR8; WAIT_L8(0); MMA8(0, 1, At, B1); BAR8;
	s_waitcnt lgkmcnt(0)
	v_mfma_f32_16x16x32_bf16 v[8:11], v[144:147], v[114:117], v[26:29]
	v_mfma_f32_16x16x32_bf16 v[24:27], v[144:147], v[126:129], v[82:85]
	v_mfma_f32_16x16x32_bf16 v[82:85], v[152:155], v[114:117], v[86:89]
	v_mfma_f32_16x16x32_bf16 v[86:89], v[152:155], v[126:129], v[90:93]
	v_mfma_f32_16x16x32_bf16 v[90:93], v[160:163], v[114:117], v[94:97]
	v_mfma_f32_16x16x32_bf16 v[94:97], v[160:163], v[126:129], v[98:101]
	v_mfma_f32_16x16x32_bf16 v[100:103], v[188:191], v[114:117], v[102:105]
	v_mfma_f32_16x16x32_bf16 v[8:11], v[148:151], v[122:125], v[8:11]
	v_mfma_f32_16x16x32_bf16 v[24:27], v[148:151], v[140:143], v[24:27]
	v_mfma_f32_16x16x32_bf16 v[82:85], v[156:159], v[122:125], v[82:85]
	v_mfma_f32_16x16x32_bf16 v[86:89], v[156:159], v[140:143], v[86:89]
	v_mfma_f32_16x16x32_bf16 v[90:93], v[164:167], v[122:125], v[90:93]
	v_mfma_f32_16x16x32_bf16 v[96:99], v[164:167], v[140:143], v[94:97]
	v_mfma_f32_16x16x32_bf16 v[196:199], v[192:195], v[122:125], v[100:103]
	v_mfma_f32_16x16x32_bf16 v[100:103], v[188:191], v[126:129], v[106:109]
	v_mfma_f32_16x16x32_bf16 v[200:203], v[192:195], v[140:143], v[100:103]
	s_barrier
	s_nop 4
	ds_read_b128 v[100:103], v228
	ds_read_b128 v[104:107], v229
	ds_read_b128 v[204:207], v230
	ds_read_b128 v[208:211], v231
	s_barrier
	s_waitcnt lgkmcnt(0)
	v_mfma_f32_16x16x32_bf16 v[50:53], v[144:147], v[204:207], v[50:53]
	v_mfma_f32_16x16x32_bf16 v[54:57], v[152:155], v[100:103], v[54:57]
	v_mfma_f32_16x16x32_bf16 v[58:61], v[152:155], v[204:207], v[58:61]
	v_mfma_f32_16x16x32_bf16 v[62:65], v[160:163], v[100:103], v[62:65]
	v_mfma_f32_16x16x32_bf16 v[66:69], v[160:163], v[204:207], v[66:69]
	v_mfma_f32_16x16x32_bf16 v[70:73], v[188:191], v[100:103], v[70:73]
	v_mfma_f32_16x16x32_bf16 v[74:77], v[188:191], v[204:207], v[74:77]
	v_mfma_f32_16x16x32_bf16 v[136:139], v[144:147], v[100:103], v[136:139]
	v_mfma_f32_16x16x32_bf16 v[50:53], v[148:151], v[208:211], v[50:53]
	v_mfma_f32_16x16x32_bf16 v[54:57], v[156:159], v[104:107], v[54:57]
	v_mfma_f32_16x16x32_bf16 v[58:61], v[156:159], v[208:211], v[58:61]
	v_mfma_f32_16x16x32_bf16 v[62:65], v[164:167], v[104:107], v[62:65]
	v_mfma_f32_16x16x32_bf16 v[66:69], v[164:167], v[208:211], v[66:69]
	v_mfma_f32_16x16x32_bf16 v[70:73], v[192:195], v[104:107], v[70:73]
	v_mfma_f32_16x16x32_bf16 v[74:77], v[192:195], v[208:211], v[74:77]
	v_mfma_f32_16x16x32_bf16 v[136:139], v[148:151], v[104:107], v[136:139]
	s_barrier
	ds_read_b128 v[144:147], v226 offset:16384
	ds_read_b128 v[148:151], v226 offset:17408
	ds_read_b128 v[152:155], v227 offset:18432
	ds_read_b128 v[156:159], v227 offset:19456
	ds_read_b128 v[160:163], v227 offset:20480
	ds_read_b128 v[164:167], v227 offset:21504
	ds_read_b128 v[188:191], v227 offset:22528
	ds_read_b128 v[192:195], v227 offset:23552
	s_waitcnt vmcnt(4)
	s_barrier
	s_waitcnt lgkmcnt(0)
	v_mfma_f32_16x16x32_bf16 v[18:21], v[144:147], v[114:117], v[20:23]
	v_mfma_f32_16x16x32_bf16 v[212:215], v[148:151], v[122:125], v[18:21]
	v_mfma_f32_16x16x32_bf16 v[18:21], v[144:147], v[126:129], v[168:171]
	v_mfma_f32_16x16x32_bf16 v[168:171], v[148:151], v[140:143], v[18:21]
	v_mfma_f32_16x16x32_bf16 v[18:21], v[152:155], v[114:117], v[172:175]
	v_mfma_f32_16x16x32_bf16 v[172:175], v[156:159], v[122:125], v[18:21]
	v_mfma_f32_16x16x32_bf16 v[18:21], v[152:155], v[126:129], v[176:179]
	v_mfma_f32_16x16x32_bf16 v[176:179], v[156:159], v[140:143], v[18:21]
	v_mfma_f32_16x16x32_bf16 v[18:21], v[160:163], v[114:117], v[180:183]
	v_mfma_f32_16x16x32_bf16 v[180:183], v[164:167], v[122:125], v[18:21]
	v_mfma_f32_16x16x32_bf16 v[18:21], v[160:163], v[126:129], v[184:187]
	v_mfma_f32_16x16x32_bf16 v[184:187], v[164:167], v[140:143], v[18:21]
	v_mfma_f32_16x16x32_bf16 v[18:21], v[188:191], v[114:117], v[34:37]
	v_mfma_f32_16x16x32_bf16 v[216:219], v[192:195], v[122:125], v[18:21]
	v_mfma_f32_16x16x32_bf16 v[18:21], v[188:191], v[126:129], v[38:41]
	v_mfma_f32_16x16x32_bf16 v[36:39], v[192:195], v[140:143], v[18:21]
	v_mfma_f32_16x16x32_bf16 v[12:15], v[144:147], v[100:103], v[14:17]
	v_mfma_f32_16x16x32_bf16 v[140:143], v[148:151], v[104:107], v[12:15]
	v_mfma_f32_16x16x32_bf16 v[12:15], v[144:147], v[204:207], v[30:33]
	v_mfma_f32_16x16x32_bf16 v[144:147], v[148:151], v[208:211], v[12:15]
	v_mfma_f32_16x16x32_bf16 v[12:15], v[152:155], v[100:103], v[42:45]
	v_mfma_f32_16x16x32_bf16 v[40:43], v[156:159], v[104:107], v[12:15]
	v_mfma_f32_16x16x32_bf16 v[12:15], v[152:155], v[204:207], v[46:49]
	v_mfma_f32_16x16x32_bf16 v[44:47], v[156:159], v[208:211], v[12:15]
	v_mfma_f32_16x16x32_bf16 v[12:15], v[160:163], v[100:103], v[78:81]
	v_mfma_f32_16x16x32_bf16 v[148:151], v[164:167], v[104:107], v[12:15]
	v_mfma_f32_16x16x32_bf16 v[12:15], v[160:163], v[204:207], v[118:121]
	v_mfma_f32_16x16x32_bf16 v[152:155], v[164:167], v[208:211], v[12:15]
	v_mfma_f32_16x16x32_bf16 v[12:15], v[188:191], v[100:103], v[110:113]
	v_mfma_f32_16x16x32_bf16 v[4:7], v[188:191], v[204:207], v[4:7]
	v_mfma_f32_16x16x32_bf16 v[156:159], v[192:195], v[104:107], v[12:15]
	v_mfma_f32_16x16x32_bf16 v[160:163], v[192:195], v[208:211], v[4:7]
	s_barrier
; #define LDA8(dst, b, h) _Pragma("unroll") for (int m = 0; m < 4; ++m) _Pragma("unroll") for (int k = 0; k < 2; ++k) \
;     dst[m][k] = *(const bf16x8*)((const char*)SA8(b, h) + lds_byte8(wr * 64 + m * 16 + fr, k * 32 + fq * 8))
; #define LDB8(dst, b, h) _Pragma("unroll") for (int n = 0; n < 2; ++n) _Pragma("unroll") for (int k = 0; k < 2; ++k) \
;     dst[n][k] = *(const bf16x8*)((const char*)SB8(b, h) + lds_byte8(wc * 32 + n * 16 + fr, k * 32 + fq * 8))
; #define WAIT_V8(n) asm volatile("s_waitcnt vmcnt(" #n ")" ::: "memory")
; #define WAIT_L8(n) asm volatile("s_waitcnt lgkmcnt(" #n ")" ::: "memory")
; #define BAR8 __builtin_amdgcn_s_barrier()
;     ...
;   { LDB8(B0, 1, 0); LDA8(At, 1, 0); WAIT_V8(2); BAR8; WAIT_L8(0); MMA8(0, 0, At, B0); BAR8;
;     LDB8(B1, 1, 1); WAIT_V8(0); BAR8; WAIT_L8(0); MMA8(0, 1, At, B1); BAR8;
;     LDA8(At, 1, 1); BAR8; WAIT_L8(0); MMA8(1, 0, At, B0); MMA8(1, 1, At, B1); BAR8; }
;   if (wr == 0) BAR8;
;   __syncthreads();
	ds_read_b128 v[164:167], v130
	ds_read_b128 v[188:191], v131
	ds_read_b128 v[192:195], v232
	ds_read_b128 v[204:207], v233
	ds_read_b128 v[12:15], v226 offset:32768
	ds_read_b128 v[16:19], v226 offset:33792
	ds_read_b128 v[28:31], v227 offset:34816
	ds_read_b128 v[32:35], v227 offset:35840
	ds_read_b128 v[78:81], v227 offset:36864
	ds_read_b128 v[112:115], v227 offset:37888
	ds_read_b128 v[120:123], v227 offset:38912
	ds_read_b128 v[124:127], v227 offset:39936
	s_waitcnt vmcnt(2)
	s_barrier
	s_waitcnt lgkmcnt(0)
	v_mfma_f32_16x16x32_bf16 v[4:7], v[12:15], v[164:167], v[8:11]
	v_mfma_f32_16x16x32_bf16 v[104:107], v[16:19], v[188:191], v[4:7]
	v_mfma_f32_16x16x32_bf16 v[4:7], v[12:15], v[192:195], v[24:27]
	v_mfma_f32_16x16x32_bf16 v[116:119], v[16:19], v[204:207], v[4:7]
	v_mfma_f32_16x16x32_bf16 v[4:7], v[28:31], v[164:167], v[82:85]
	v_mfma_f32_16x16x32_bf16 v[100:103], v[32:35], v[188:191], v[4:7]
	v_mfma_f32_16x16x32_bf16 v[4:7], v[28:31], v[192:195], v[86:89]
	v_mfma_f32_16x16x32_bf16 v[108:111], v[32:35], v[204:207], v[4:7]
	v_mfma_f32_16x16x32_bf16 v[4:7], v[78:81], v[164:167], v[90:93]
	v_mfma_f32_16x16x32_bf16 v[92:95], v[112:115], v[188:191], v[4:7]
	v_mfma_f32_16x16x32_bf16 v[4:7], v[78:81], v[192:195], v[96:99]
	v_mfma_f32_16x16x32_bf16 v[96:99], v[112:115], v[204:207], v[4:7]
	v_mfma_f32_16x16x32_bf16 v[4:7], v[120:123], v[164:167], v[196:199]
	v_mfma_f32_16x16x32_bf16 v[84:87], v[124:127], v[188:191], v[4:7]
	v_mfma_f32_16x16x32_bf16 v[4:7], v[120:123], v[192:195], v[200:203]
	v_mfma_f32_16x16x32_bf16 v[88:91], v[124:127], v[204:207], v[4:7]
	s_barrier
	ds_read_b128 v[196:199], v236
	ds_read_b128 v[200:203], v237
	ds_read_b128 v[208:211], v238
	ds_read_b128 v[220:223], v239
	s_waitcnt vmcnt(0)
	s_barrier
	s_waitcnt lgkmcnt(0)
	v_mfma_f32_16x16x32_bf16 v[4:7], v[12:15], v[196:199], v[136:139]
	v_mfma_f32_16x16x32_bf16 v[8:11], v[12:15], v[208:211], v[50:53]
	v_mfma_f32_16x16x32_bf16 v[4:7], v[16:19], v[200:203], v[4:7]
	v_mfma_f32_16x16x32_bf16 v[20:23], v[16:19], v[220:223], v[8:11]
	v_mfma_f32_16x16x32_bf16 v[8:11], v[28:31], v[196:199], v[54:57]
	v_mfma_f32_16x16x32_bf16 v[12:15], v[28:31], v[208:211], v[58:61]
	v_mfma_f32_16x16x32_bf16 v[16:19], v[78:81], v[208:211], v[66:69]
	v_mfma_f32_16x16x32_bf16 v[8:11], v[32:35], v[200:203], v[8:11]
	v_mfma_f32_16x16x32_bf16 v[24:27], v[32:35], v[220:223], v[12:15]
	v_mfma_f32_16x16x32_bf16 v[12:15], v[78:81], v[196:199], v[62:65]
	v_mfma_f32_16x16x32_bf16 v[28:31], v[112:115], v[220:223], v[16:19]
	v_mfma_f32_16x16x32_bf16 v[16:19], v[120:123], v[196:199], v[70:73]
	v_mfma_f32_16x16x32_bf16 v[32:35], v[120:123], v[208:211], v[74:77]
	v_mfma_f32_16x16x32_bf16 v[12:15], v[112:115], v[200:203], v[12:15]
	v_mfma_f32_16x16x32_bf16 v[16:19], v[124:127], v[200:203], v[16:19]
	v_mfma_f32_16x16x32_bf16 v[32:35], v[124:127], v[220:223], v[32:35]
	s_barrier
	ds_read_b128 v[48:51], v226 offset:49152
	ds_read_b128 v[52:55], v226 offset:50176
	ds_read_b128 v[56:59], v227 offset:51200
	ds_read_b128 v[60:63], v227 offset:52224
	ds_read_b128 v[64:67], v227 offset:53248
	ds_read_b128 v[136:139], v227 offset:54272
	ds_read_b128 v[230:233], v227 offset:55296
	ds_read_b128 v[238:241], v227 offset:56320
	s_barrier
	s_waitcnt lgkmcnt(0)
	v_mfma_f32_16x16x32_bf16 v[68:71], v[48:51], v[164:167], v[212:215]
	v_mfma_f32_16x16x32_bf16 v[128:131], v[52:55], v[188:191], v[68:71]
	v_mfma_f32_16x16x32_bf16 v[68:71], v[48:51], v[192:195], v[168:171]
	v_mfma_f32_16x16x32_bf16 v[124:127], v[52:55], v[204:207], v[68:71]
	v_mfma_f32_16x16x32_bf16 v[68:71], v[56:59], v[164:167], v[172:175]
	v_mfma_f32_16x16x32_bf16 v[120:123], v[60:63], v[188:191], v[68:71]
	v_mfma_f32_16x16x32_bf16 v[68:71], v[56:59], v[192:195], v[176:179]
	v_mfma_f32_16x16x32_bf16 v[112:115], v[60:63], v[204:207], v[68:71]
	v_mfma_f32_16x16x32_bf16 v[68:71], v[64:67], v[164:167], v[180:183]
	v_mfma_f32_16x16x32_bf16 v[80:83], v[136:139], v[188:191], v[68:71]
	v_mfma_f32_16x16x32_bf16 v[68:71], v[64:67], v[192:195], v[184:187]
	v_mfma_f32_16x16x32_bf16 v[76:79], v[136:139], v[204:207], v[68:71]
	v_mfma_f32_16x16x32_bf16 v[68:71], v[230:233], v[164:167], v[216:219]
	v_mfma_f32_16x16x32_bf16 v[36:39], v[230:233], v[192:195], v[36:39]
	v_mfma_f32_16x16x32_bf16 v[72:75], v[238:241], v[188:191], v[68:71]
	v_mfma_f32_16x16x32_bf16 v[68:71], v[238:241], v[204:207], v[36:39]
	v_mfma_f32_16x16x32_bf16 v[36:39], v[48:51], v[196:199], v[140:143]
	v_mfma_f32_16x16x32_bf16 v[48:51], v[48:51], v[208:211], v[144:147]
	v_mfma_f32_16x16x32_bf16 v[36:39], v[52:55], v[200:203], v[36:39]
	v_mfma_f32_16x16x32_bf16 v[52:55], v[52:55], v[220:223], v[48:51]
	v_mfma_f32_16x16x32_bf16 v[40:43], v[56:59], v[196:199], v[40:43]
	v_mfma_f32_16x16x32_bf16 v[44:47], v[56:59], v[208:211], v[44:47]
	v_mfma_f32_16x16x32_bf16 v[48:51], v[64:67], v[208:211], v[152:155]
	v_mfma_f32_16x16x32_bf16 v[40:43], v[60:63], v[200:203], v[40:43]
	v_mfma_f32_16x16x32_bf16 v[56:59], v[60:63], v[220:223], v[44:47]
	v_mfma_f32_16x16x32_bf16 v[44:47], v[64:67], v[196:199], v[148:151]
	v_mfma_f32_16x16x32_bf16 v[60:63], v[136:139], v[220:223], v[48:51]
	v_mfma_f32_16x16x32_bf16 v[48:51], v[230:233], v[196:199], v[156:159]
	v_mfma_f32_16x16x32_bf16 v[64:67], v[230:233], v[208:211], v[160:163]
	v_mfma_f32_16x16x32_bf16 v[44:47], v[136:139], v[200:203], v[44:47]
	v_mfma_f32_16x16x32_bf16 v[48:51], v[238:241], v[200:203], v[48:51]
	v_mfma_f32_16x16x32_bf16 v[64:67], v[238:241], v[220:223], v[64:67]
	s_movk_i32 s12, 0x100
	v_cmp_gt_u32_e32 vcc, s12, v3
	s_barrier
	s_and_saveexec_b64 s[12:13], vcc
	s_cbranch_execz .LBB0_556
	s_barrier

; #define BAR8 __builtin_amdgcn_s_barrier()
;     ...
;   const int brow = m0, bcol = n0;
;   const int wid = t >> 6, lane = t & 63, wr = wid >> 2, wc = wid & 3, fr = lane & 15, fq = lane >> 4;
;   f32x4 acc[2][2][4][2];
;   {
;     float zinit = 0.f;
;     asm volatile("" : "+v"(zinit));
; #pragma unroll
;     for (int a = 0; a < 2; ++a)
; #pragma unroll
;       for (int b = 0; b < 2; ++b)
; #pragma unroll
;         for (int m = 0; m < 4; ++m)
; #pragma unroll
;           for (int n = 0; n < 2; ++n)
; #pragma unroll
;             for (int j = 0; j < 4; ++j) acc[a][b][m][n][j] = zinit;
;   }
;   bf16x8 At[4][2], B0[2][2], B1[2][2];
;   const int nt = K / 64;
;   if (!pre) {
;     STAGE8(SB8(0, 0), Bt, K, bcol, 0); STAGE8(SA8(0, 0), A, lda, brow, 0);
;     STAGE8(SB8(0, 1), Bt, K, bcol + 128, 0); STAGE8(SA8(0, 1), A, lda, brow + 128, 0);
;   }
;   if (wr == 1) BAR8;
.LBB0_905:
	s_mov_b32 s0, 24
	s_mov_b32 s0, 25
	s_ashr_i32 s1, s0, 31
	s_lshl_b64 s[0:1], s[0:1], 3
	s_add_u32 s0, s70, s0
	s_addc_u32 s1, s71, s1
	v_readlane_b32 s6, v255, 60
	v_readlane_b32 s7, v255, 61
	s_nop 4
	s_mov_b32 s0, 25
	s_ashr_i32 s1, s0, 31
	s_lshl_b64 s[0:1], s[0:1], 3
	s_add_u32 s0, s70, s0
	s_addc_u32 s1, s71, s1
	s_mov_b32 s2, 25
	v_readlane_b32 s0, v255, 60
	v_readlane_b32 s1, v255, 61
	s_nop 4
	s_ashr_i32 s3, s2, 31
	s_lshl_b64 s[2:3], s[2:3], 3
	s_add_u32 s2, s70, s2
	s_addc_u32 s3, s71, s3
	v_mov_b32_e32 v3, v224
	v_readlane_b32 s2, v255, 60
	v_readlane_b32 s3, v255, 61
	s_nop 4
	v_mov_b32_e32 v18, 1
	v_bfe_i32 v1, v3, 27, 1
	s_waitcnt vmcnt(10)
	v_lshlrev_b32_e32 v150, 4, v3
	s_nop 0
	v_readfirstlane_b32 s100, v150
	v_lshrrev_b32_e32 v1, 22, v1
	v_add_u32_e32 v1, v150, v1
	v_and_b32_e32 v1, 0xfffffc00, v1
	v_ashrrev_i32_e32 v0, 31, v3
	v_sub_u32_e32 v1, v150, v1
	v_lshrrev_b32_e32 v0, 26, v0
	v_lshrrev_b32_e32 v5, 4, v1
	v_add_u32_e32 v0, v3, v0
	v_bitop3_b32 v5, v5, v1, 32 bitop3:0x6c
	v_ashrrev_i32_e32 v1, 31, v1
	s_waitcnt lgkmcnt(0)
	s_add_u32 s29, s2, 0x6000000
	v_ashrrev_i32_e32 v0, 6, v0
	v_lshrrev_b32_e32 v1, 26, v1
	s_addc_u32 s33, s3, 0
	s_lshl_b32 s8, s24, 8
	v_lshlrev_b32_e32 v6, 3, v0
	v_add_u32_e32 v1, v5, v1
	s_and_b32 s25, s8, 0x3f00
	s_lshl_b32 s8, s24, 2
	v_and_b32_e32 v6, -16, v6
	v_ashrrev_i32_e32 v1, 6, v1
	s_and_b32 s8, s8, 0xffffff00
	v_add_u32_e32 v16, v1, v6
	v_mul_i32_i24_e32 v1, 64, v1
	s_ashr_i32 s9, s8, 31
	v_lshlrev_b32_e32 v0, 5, v0
	v_sub_u32_e32 v1, v5, v1
	s_waitcnt vmcnt(9)
	v_add_u32_e32 v152, 0x2000, v150
	s_lshl_b64 s[12:13], s[8:9], 11
	v_and_b32_e32 v0, 32, v0
	v_ashrrev_i16_sdwa v1, v18, sext(v1) dst_sel:DWORD dst_unused:UNUSED_PAD src0_sel:DWORD src1_sel:BYTE_0
	v_ashrrev_i32_e32 v5, 31, v152
	s_add_u32 s12, s14, s12
	v_add_u32_sdwa v0, v0, sext(v1) dst_sel:DWORD dst_unused:UNUSED_PAD src0_sel:DWORD src1_sel:WORD_0
	v_ashrrev_i32_e32 v17, 31, v16
	v_lshrrev_b32_e32 v5, 22, v5
	s_addc_u32 s13, s15, s13
	v_lshlrev_b64 v[6:7], 11, v[16:17]
	v_ashrrev_i32_e32 v1, 31, v0
	v_add_u32_e32 v5, v152, v5
	v_lshl_add_u64 v[10:11], s[12:13], 0, v[6:7]
	v_lshlrev_b64 v[8:9], 1, v[0:1]
	v_ashrrev_i32_e32 v5, 10, v5
	v_lshl_add_u64 v[14:15], v[10:11], 0, v[8:9]
	v_mul_i32_i24_e32 v10, 0x400, v5
	v_sub_u32_e32 v10, v152, v10
	v_lshrrev_b32_e32 v11, 4, v10
	v_bitop3_b32 v10, v11, v10, 32 bitop3:0x6c
	v_ashrrev_i32_e32 v12, 31, v10
	v_lshrrev_b32_e32 v12, 26, v12
	v_lshlrev_b32_e32 v11, 3, v5
	v_add_u32_e32 v12, v10, v12
	v_and_b32_e32 v11, -16, v11
	v_ashrrev_i32_e32 v13, 6, v12
	v_add_u32_e32 v24, v13, v11
	v_and_b32_e32 v11, 0xc0, v12
	v_lshlrev_b32_e32 v5, 5, v5
	v_sub_u32_e32 v10, v10, v11
	v_and_b32_e32 v5, 32, v5
	v_ashrrev_i16_sdwa v10, v18, sext(v10) dst_sel:DWORD dst_unused:UNUSED_PAD src0_sel:DWORD src1_sel:BYTE_0
	v_ashrrev_i32_e32 v25, 31, v24
	v_add_u32_sdwa v132, v5, sext(v10) dst_sel:DWORD dst_unused:UNUSED_PAD src0_sel:DWORD src1_sel:WORD_0
	v_lshlrev_b64 v[10:11], 11, v[24:25]
	s_waitcnt vmcnt(8)
	v_mov_b32_e32 v4, v2
	s_or_b32 m0, s100, 0x10000
	v_lshl_add_u64 v[18:19], s[12:13], 0, v[10:11]
	global_load_lds_dwordx4 v[14:15], off
	v_ashrrev_i32_e32 v133, 31, v132
	s_or_b32 m0, s100, 0x12000
	s_lshl_b32 s27, s25, 10
	s_lshl_b32 s12, s25, 11
	v_lshlrev_b64 v[12:13], 1, v[132:133]
	s_add_u32 s12, s29, s12
	v_lshl_add_u64 v[18:19], v[18:19], 0, v[12:13]
	s_addc_u32 s13, s33, 0
	global_load_lds_dwordx4 v[18:19], off
	v_lshl_add_u64 v[20:21], s[12:13], 0, v[6:7]
	s_mov_b32 m0, s100
	s_or_b32 s30, s8, 0x80
	v_lshl_add_u64 v[20:21], v[20:21], 0, v[8:9]
	v_lshl_add_u64 v[22:23], s[12:13], 0, v[10:11]
	s_ashr_i32 s31, s30, 31
	global_load_lds_dwordx4 v[20:21], off
	s_or_b32 m0, s100, 0x2000
	s_lshl_b64 s[12:13], s[30:31], 11
	s_add_u32 s12, s14, s12
	s_addc_u32 s13, s15, s13
	v_lshl_add_u64 v[22:23], v[22:23], 0, v[12:13]
	v_lshl_add_u64 v[26:27], s[12:13], 0, v[6:7]
	s_bitset1_b32 s27, 17
	global_load_lds_dwordx4 v[22:23], off
	v_lshl_add_u64 v[26:27], v[26:27], 0, v[8:9]
	s_or_b32 m0, s100, 0x14000
	v_lshl_add_u64 v[28:29], s[12:13], 0, v[10:11]
	s_lshl_b32 s27, s27, 1
	global_load_lds_dwordx4 v[26:27], off
	s_or_b32 m0, s100, 0x16000
	s_add_u32 s12, s29, s27
	s_addc_u32 s13, s33, 0
	v_lshl_add_u64 v[28:29], v[28:29], 0, v[12:13]
	v_lshl_add_u64 v[30:31], s[12:13], 0, v[6:7]
	global_load_lds_dwordx4 v[28:29], off
	v_lshl_add_u64 v[30:31], v[30:31], 0, v[8:9]
	s_or_b32 m0, s100, 0x4000
	global_load_lds_dwordx4 v[30:31], off
	v_lshl_add_u64 v[30:31], s[12:13], 0, v[10:11]
	v_lshl_add_u64 v[30:31], v[30:31], 0, v[12:13]
	s_or_b32 m0, s100, 0x6000
	v_ashrrev_i32_e32 v5, 8, v3
	global_load_lds_dwordx4 v[30:31], off
	v_cmp_eq_u32_e32 vcc, 1, v5
	s_and_saveexec_b64 s[12:13], vcc
	s_cbranch_execz .LBB0_907
	s_barrier
; #define WAIT_V8(n) asm volatile("s_waitcnt vmcnt(" #n ")" ::: "memory")
; #define BAR8 __builtin_amdgcn_s_barrier()
;     ...
;   const int wid = t >> 6, lane = t & 63, wr = wid >> 2, wc = wid & 3, fr = lane & 15, fq = lane >> 4;
;   f32x4 acc[2][2][4][2];
;   {
;     float zinit = 0.f;
;     asm volatile("" : "+v"(zinit));
; #pragma unroll
;     for (int a = 0; a < 2; ++a)
; #pragma unroll
;       for (int b = 0; b < 2; ++b)
; #pragma unroll
;         for (int m = 0; m < 4; ++m)
; #pragma unroll
;           for (int n = 0; n < 2; ++n)
; #pragma unroll
;             for (int j = 0; j < 4; ++j) acc[a][b][m][n][j] = zinit;
;   }
;   bf16x8 At[4][2], B0[2][2], B1[2][2];
;   const int nt = K / 64;
;   if (!pre) {
;     STAGE8(SB8(0, 0), Bt, K, bcol, 0); STAGE8(SA8(0, 0), A, lda, brow, 0);
;     STAGE8(SB8(0, 1), Bt, K, bcol + 128, 0); STAGE8(SA8(0, 1), A, lda, brow + 128, 0);
;   }
;   if (wr == 1) BAR8;
;   WAIT_V8(4); BAR8;
;   STAGE8(SB8(1, 0), Bt, K, bcol, 1); STAGE8(SA8(1, 0), A, lda, brow, 1); STAGE8(SB8(1, 1), Bt, K, bcol + 128, 1);
;   WAIT_V8(6); BAR8;
.LBB0_907:
	s_or_b64 exec, exec, s[12:13]
	s_lshl_b32 s29, s20, 11
	s_waitcnt vmcnt(0)
	s_and_b32 s36, s29, 0x1f80000
	s_mov_b64 s[38:39], 0x80
	v_lshl_add_u64 v[14:15], v[14:15], 0, s[38:39]
	s_or_b32 m0, s100, 0x18000
	s_waitcnt vmcnt(4)
	s_barrier
	global_load_lds_dwordx4 v[14:15], off
	v_lshl_add_u64 v[14:15], v[18:19], 0, s[38:39]
	s_or_b32 m0, s100, 0x1a000
	global_load_lds_dwordx4 v[14:15], off
	v_lshl_add_u64 v[14:15], v[20:21], 0, s[38:39]
	s_or_b32 m0, s100, 0x8000
	global_load_lds_dwordx4 v[14:15], off
	v_lshl_add_u64 v[14:15], v[22:23], 0, s[38:39]
	s_or_b32 m0, s100, 0xa000
	global_load_lds_dwordx4 v[14:15], off
	v_lshl_add_u64 v[14:15], v[26:27], 0, s[38:39]
	s_or_b32 m0, s100, 0x1c000
	s_nop 0
	global_load_lds_dwordx4 v[14:15], off
	v_lshl_add_u64 v[14:15], v[28:29], 0, s[38:39]
	s_or_b32 m0, s100, 0x1e000
	v_and_b32_e32 v147, 15, v3
	global_load_lds_dwordx4 v[14:15], off
	v_bfe_u32 v148, v3, 4, 2
	v_lshlrev_b32_e32 v14, 4, v148
	v_lshlrev_b32_e32 v15, 6, v147
	v_lshlrev_b32_e32 v18, 2, v3
	v_lshlrev_b64 v[136:137], 10, v[16:17]
	v_or_b32_e32 v17, v14, v15
	v_and_b32_e32 v18, 32, v18
	s_mov_b32 s29, 0x10000
	s_and_b32 s12, s21, 0xffffff00
	v_bitop3_b32 v20, v17, s29, v18 bitop3:0xde
	s_mov_b32 s29, 0x14000
	s_ashr_i32 s13, s12, 31
	v_readlane_b32 s40, v254, 35
	v_bitop3_b32 v19, v14, v18, v15 bitop3:0x36
	v_bitop3_b32 v21, v17, s29, v18 bitop3:0xde
	s_mov_b32 s29, 0x18000
	v_lshlrev_b32_e32 v15, 6, v3
	s_lshl_b64 s[12:13], s[12:13], 11
	s_mov_b32 s37, s40
	v_bitop3_b32 v22, v17, s29, v18 bitop3:0xde
	s_mov_b32 s29, 0x1c000
	v_and_b32_e32 v15, 0x3c0, v15
	v_bitop3_b32 v17, v17, s29, v18 bitop3:0xde
	v_bitop3_b32 v18, v15, v18, v14 bitop3:0x36
	v_lshl_add_u64 v[14:15], s[12:13], 0, v[6:7]
	v_lshl_add_u64 v[6:7], s[36:37], 0, v[6:7]
	v_lshl_add_u64 v[14:15], v[14:15], 0, v[8:9]
	v_lshl_add_u64 v[6:7], v[6:7], 0, v[8:9]
	v_bfe_u32 v146, v3, 6, 2
	s_waitcnt vmcnt(6)
	v_lshlrev_b32_e32 v149, 6, v5
	v_lshlrev_b32_e32 v5, 13, v5
	v_lshl_add_u64 v[138:139], s[4:5], 0, v[14:15]
	v_lshl_add_u64 v[14:15], s[12:13], 0, v[10:11]
	v_lshl_add_u64 v[142:143], s[2:3], 0, v[6:7]
	v_lshl_add_u64 v[6:7], s[36:37], 0, v[10:11]
	v_lshlrev_b64 v[134:135], 10, v[24:25]
	v_readlane_b32 s41, v254, 36
	v_readlane_b32 s42, v254, 37
	v_readlane_b32 s43, v254, 38
	v_lshlrev_b32_e32 v16, 12, v146
	v_or_b32_e32 v23, 0x800, v5
	v_or_b32_e32 v24, 0x1000, v5
	v_or_b32_e32 v25, 0x1800, v5
	v_lshl_add_u64 v[14:15], v[14:15], 0, v[12:13]
	v_lshl_add_u64 v[6:7], v[6:7], 0, v[12:13]
	v_lshl_add_u64 v[140:141], s[4:5], 0, v[14:15]
	v_lshl_add_u64 v[144:145], s[2:3], 0, v[6:7]
	s_mov_b32 s29, -2
	s_mov_b64 s[12:13], 0
	v_add_u32_e32 v171, v20, v16
	v_add_u32_e32 v156, v19, v5
	v_add_u32_e32 v155, v18, v23
	v_add_u32_e32 v154, v18, v24
	v_add_u32_e32 v153, v18, v25
	v_add_u32_e32 v167, v21, v16
	v_add_u32_e32 v160, v22, v16
	v_add_u32_e32 v158, v17, v16
	v_mov_b32_e32 v5, v4
	v_mov_b64_e32 v[6:7], v[4:5]
	v_mov_b64_e32 v[8:9], v[4:5]
	v_mov_b64_e32 v[10:11], v[4:5]
	v_mov_b64_e32 v[12:13], v[4:5]
	v_mov_b64_e32 v[14:15], v[4:5]
	v_mov_b64_e32 v[16:17], v[4:5]
	v_mov_b64_e32 v[18:19], v[4:5]
	v_mov_b64_e32 v[20:21], v[4:5]
	v_mov_b64_e32 v[22:23], v[4:5]
	v_mov_b64_e32 v[24:25], v[4:5]
	v_mov_b64_e32 v[26:27], v[4:5]
	v_mov_b64_e32 v[28:29], v[4:5]
	v_mov_b64_e32 v[30:31], v[4:5]
	v_mov_b64_e32 v[32:33], v[4:5]
	v_mov_b64_e32 v[34:35], v[4:5]
	v_mov_b64_e32 v[36:37], v[4:5]
	v_mov_b64_e32 v[38:39], v[4:5]
	v_mov_b64_e32 v[40:41], v[4:5]
	v_mov_b64_e32 v[42:43], v[4:5]
	v_mov_b64_e32 v[44:45], v[4:5]
	v_mov_b64_e32 v[46:47], v[4:5]
	v_mov_b64_e32 v[48:49], v[4:5]
	v_mov_b64_e32 v[50:51], v[4:5]
	v_mov_b64_e32 v[52:53], v[4:5]
	v_mov_b64_e32 v[54:55], v[4:5]
	v_mov_b64_e32 v[56:57], v[4:5]
	v_mov_b64_e32 v[58:59], v[4:5]
	v_mov_b64_e32 v[60:61], v[4:5]
	v_mov_b64_e32 v[62:63], v[4:5]
	v_mov_b64_e32 v[64:65], v[4:5]
	v_mov_b64_e32 v[66:67], v[4:5]
	v_mov_b64_e32 v[68:69], v[4:5]
	v_mov_b64_e32 v[70:71], v[4:5]
	v_mov_b64_e32 v[72:73], v[4:5]
	v_mov_b64_e32 v[74:75], v[4:5]
	v_mov_b64_e32 v[76:77], v[4:5]
	v_mov_b64_e32 v[78:79], v[4:5]
	v_mov_b64_e32 v[80:81], v[4:5]
	v_mov_b64_e32 v[82:83], v[4:5]
	v_mov_b64_e32 v[84:85], v[4:5]
	v_mov_b64_e32 v[86:87], v[4:5]
	v_mov_b64_e32 v[88:89], v[4:5]
	v_mov_b64_e32 v[90:91], v[4:5]
	v_mov_b64_e32 v[92:93], v[4:5]
	v_mov_b64_e32 v[94:95], v[4:5]
	v_mov_b64_e32 v[96:97], v[4:5]
	v_mov_b64_e32 v[98:99], v[4:5]
	v_mov_b64_e32 v[100:101], v[4:5]
	v_mov_b64_e32 v[102:103], v[4:5]
	v_mov_b64_e32 v[104:105], v[4:5]
	v_mov_b64_e32 v[106:107], v[4:5]
	v_mov_b64_e32 v[108:109], v[4:5]
	v_mov_b64_e32 v[110:111], v[4:5]
	v_mov_b64_e32 v[112:113], v[4:5]
	v_mov_b64_e32 v[114:115], v[4:5]
	v_mov_b64_e32 v[116:117], v[4:5]
	v_mov_b64_e32 v[118:119], v[4:5]
	v_mov_b64_e32 v[120:121], v[4:5]
	v_mov_b64_e32 v[122:123], v[4:5]
	v_mov_b64_e32 v[124:125], v[4:5]
	v_mov_b64_e32 v[126:127], v[4:5]
	v_mov_b64_e32 v[128:129], v[4:5]
	v_mov_b64_e32 v[130:131], v[4:5]
	s_mov_b64 s[36:37], 0x6040080
	s_mov_b64 s[38:39], 0xc4a0100
	s_mov_b64 s[40:41], 0x6000100
	s_mov_b64 s[42:43], 0xc4e0100
	s_mov_b64 s[44:45], 0x6040100
	s_mov_b64 s[46:47], 0xc4a0180
	s_mov_b64 s[48:49], 0x6000180
	s_mov_b64 s[50:51], 0xc4e0180
	s_barrier
; #define LDA8(dst, b, h) _Pragma("unroll") for (int m = 0; m < 4; ++m) _Pragma("unroll") for (int k = 0; k < 2; ++k) \
;     dst[m][k] = *(const bf16x8*)((const char*)SA8(b, h) + lds_byte8(wr * 64 + m * 16 + fr, k * 32 + fq * 8))
; #define LDB8(dst, b, h) _Pragma("unroll") for (int n = 0; n < 2; ++n) _Pragma("unroll") for (int k = 0; k < 2; ++k) \
;     dst[n][k] = *(const bf16x8*)((const char*)SB8(b, h) + lds_byte8(wc * 32 + n * 16 + fr, k * 32 + fq * 8))
; #define WAIT_L8(n) asm volatile("s_waitcnt lgkmcnt(" #n ")" ::: "memory")
; #define BAR8 __builtin_amdgcn_s_barrier()
; #define SCHED8 __builtin_amdgcn_sched_barrier(0)
;     ...
;   for (int tt = 0; tt < nt - 2; tt += 2) {
;     LDB8(B0, 0, 0); SCHED8; LDA8(At, 0, 0); STAGE8(SA8(1, 1), A, lda, brow + 128, tt + 1);
;     WAIT_L8(8); BAR8; WAIT_L8(0); MMA8(0, 0, At, B0); BAR8; SCHED8;
;     LDB8(B1, 0, 1); STAGE8(SB8(0, 0), Bt, K, bcol, tt + 2);
;     BAR8; WAIT_L8(0); MMA8(0, 1, At, B1); BAR8;
;     LDA8(At, 0, 1); STAGE8(SA8(0, 0), A, lda, brow, tt + 2);
;     BAR8; WAIT_L8(0); MMA8(1, 0, At, B0); BAR8; SCHED8;
.LBB0_908:
	ds_read_b128 v[174:177], v171
	ds_read_b128 v[178:181], v171 offset:1024
	ds_read_b128 v[182:185], v171 offset:2048
	ds_read_b128 v[186:189], v171 offset:3072
	v_lshl_add_u64 v[222:223], v[142:143], 0, s[12:13]
	v_lshl_add_u64 v[226:227], v[222:223], 0, s[36:37]
	s_or_b32 m0, s100, 0xc000
	ds_read_b128 v[190:193], v156
	ds_read_b128 v[194:197], v156 offset:1024
	ds_read_b128 v[198:201], v155
	ds_read_b128 v[202:205], v155 offset:1024
	ds_read_b128 v[206:209], v154
	ds_read_b128 v[210:213], v154 offset:1024
	ds_read_b128 v[214:217], v153
	ds_read_b128 v[218:221], v153 offset:1024
	global_load_lds_dwordx4 v[226:227], off
	v_lshl_add_u64 v[226:227], v[144:145], 0, s[12:13]
	v_lshl_add_u64 v[228:229], v[226:227], 0, s[36:37]
	s_or_b32 m0, s100, 0xe000
	s_nop 0
	global_load_lds_dwordx4 v[228:229], off
	s_waitcnt lgkmcnt(8)
	s_barrier
	s_waitcnt lgkmcnt(0)
	v_mfma_f32_16x16x32_bf16 v[128:131], v[190:193], v[174:177], v[128:131]
	v_mfma_f32_16x16x32_bf16 v[124:127], v[190:193], v[182:185], v[124:127]
	v_mfma_f32_16x16x32_bf16 v[120:123], v[198:201], v[174:177], v[120:123]
	v_mfma_f32_16x16x32_bf16 v[116:119], v[198:201], v[182:185], v[116:119]
	v_mfma_f32_16x16x32_bf16 v[112:115], v[206:209], v[174:177], v[112:115]
	v_mfma_f32_16x16x32_bf16 v[108:111], v[206:209], v[182:185], v[108:111]
	v_mfma_f32_16x16x32_bf16 v[104:107], v[214:217], v[174:177], v[104:107]
	v_mfma_f32_16x16x32_bf16 v[100:103], v[214:217], v[182:185], v[100:103]
	v_mfma_f32_16x16x32_bf16 v[128:131], v[194:197], v[178:181], v[128:131]
	v_mfma_f32_16x16x32_bf16 v[124:127], v[194:197], v[186:189], v[124:127]
	v_mfma_f32_16x16x32_bf16 v[120:123], v[202:205], v[178:181], v[120:123]
	v_mfma_f32_16x16x32_bf16 v[116:119], v[202:205], v[186:189], v[116:119]
	v_mfma_f32_16x16x32_bf16 v[112:115], v[210:213], v[178:181], v[112:115]
	v_mfma_f32_16x16x32_bf16 v[108:111], v[210:213], v[186:189], v[108:111]
	v_mfma_f32_16x16x32_bf16 v[104:107], v[218:221], v[178:181], v[104:107]
	v_mfma_f32_16x16x32_bf16 v[100:103], v[218:221], v[186:189], v[100:103]
	s_barrier
	v_lshl_add_u64 v[228:229], v[138:139], 0, s[12:13]
	v_lshl_add_u64 v[236:237], v[228:229], 0, s[38:39]
	s_or_b32 m0, s100, 0x10000
	ds_read_b128 v[230:233], v167
	ds_read_b128 v[238:241], v167 offset:1024
	ds_read_b128 v[242:245], v167 offset:2048
	ds_read_b128 v[246:249], v167 offset:3072
	global_load_lds_dwordx4 v[236:237], off
	v_lshl_add_u64 v[236:237], v[140:141], 0, s[12:13]
	v_lshl_add_u64 v[250:251], v[236:237], 0, s[38:39]
	s_or_b32 m0, s100, 0x12000
	s_nop 0
	global_load_lds_dwordx4 v[250:251], off
	s_barrier
	s_waitcnt lgkmcnt(0)
	v_mfma_f32_16x16x32_bf16 v[96:99], v[190:193], v[230:233], v[96:99]
	v_mfma_f32_16x16x32_bf16 v[92:95], v[190:193], v[242:245], v[92:95]
	v_mfma_f32_16x16x32_bf16 v[88:91], v[198:201], v[230:233], v[88:91]
	v_mfma_f32_16x16x32_bf16 v[84:87], v[198:201], v[242:245], v[84:87]
	v_mfma_f32_16x16x32_bf16 v[80:83], v[206:209], v[230:233], v[80:83]
	v_mfma_f32_16x16x32_bf16 v[76:79], v[206:209], v[242:245], v[76:79]
	v_mfma_f32_16x16x32_bf16 v[72:75], v[214:217], v[230:233], v[72:75]
	v_mfma_f32_16x16x32_bf16 v[68:71], v[214:217], v[242:245], v[68:71]
	v_mfma_f32_16x16x32_bf16 v[96:99], v[194:197], v[238:241], v[96:99]
	v_mfma_f32_16x16x32_bf16 v[92:95], v[194:197], v[246:249], v[92:95]
	v_mfma_f32_16x16x32_bf16 v[88:91], v[202:205], v[238:241], v[88:91]
	v_mfma_f32_16x16x32_bf16 v[84:87], v[202:205], v[246:249], v[84:87]
	v_mfma_f32_16x16x32_bf16 v[80:83], v[210:213], v[238:241], v[80:83]
	v_mfma_f32_16x16x32_bf16 v[76:79], v[210:213], v[246:249], v[76:79]
	v_mfma_f32_16x16x32_bf16 v[72:75], v[218:221], v[238:241], v[72:75]
	v_mfma_f32_16x16x32_bf16 v[68:71], v[218:221], v[246:249], v[68:71]
	v_lshl_add_u64 v[250:251], v[222:223], 0, s[40:41]
	s_mov_b32 m0, s100
	s_barrier
	ds_read_b128 v[190:193], v156 offset:16384
	ds_read_b128 v[194:197], v156 offset:17408
	ds_read_b128 v[198:201], v155 offset:16384
	ds_read_b128 v[202:205], v155 offset:17408
	ds_read_b128 v[206:209], v154 offset:16384
	ds_read_b128 v[210:213], v154 offset:17408
	ds_read_b128 v[214:217], v153 offset:16384
	ds_read_b128 v[218:221], v153 offset:17408
	global_load_lds_dwordx4 v[250:251], off
	v_lshl_add_u64 v[250:251], v[226:227], 0, s[40:41]
	s_or_b32 m0, s100, 0x2000
	s_nop 0
	global_load_lds_dwordx4 v[250:251], off
	s_barrier
	s_waitcnt lgkmcnt(0)
	v_mfma_f32_16x16x32_bf16 v[64:67], v[190:193], v[174:177], v[64:67]
	v_mfma_f32_16x16x32_bf16 v[60:63], v[190:193], v[182:185], v[60:63]
	v_mfma_f32_16x16x32_bf16 v[56:59], v[198:201], v[174:177], v[56:59]
	v_mfma_f32_16x16x32_bf16 v[52:55], v[198:201], v[182:185], v[52:55]
	v_mfma_f32_16x16x32_bf16 v[48:51], v[206:209], v[174:177], v[48:51]
	v_mfma_f32_16x16x32_bf16 v[44:47], v[206:209], v[182:185], v[44:47]
	v_mfma_f32_16x16x32_bf16 v[40:43], v[214:217], v[174:177], v[40:43]
	v_mfma_f32_16x16x32_bf16 v[36:39], v[214:217], v[182:185], v[36:39]
	v_mfma_f32_16x16x32_bf16 v[64:67], v[194:197], v[178:181], v[64:67]
	v_mfma_f32_16x16x32_bf16 v[60:63], v[194:197], v[186:189], v[60:63]
	v_mfma_f32_16x16x32_bf16 v[56:59], v[202:205], v[178:181], v[56:59]
	v_mfma_f32_16x16x32_bf16 v[52:55], v[202:205], v[186:189], v[52:55]
	v_mfma_f32_16x16x32_bf16 v[48:51], v[210:213], v[178:181], v[48:51]
	v_mfma_f32_16x16x32_bf16 v[44:47], v[210:213], v[186:189], v[44:47]
	v_mfma_f32_16x16x32_bf16 v[40:43], v[218:221], v[178:181], v[40:43]
	v_mfma_f32_16x16x32_bf16 v[36:39], v[218:221], v[186:189], v[36:39]
	s_barrier
	v_lshl_add_u64 v[174:175], v[228:229], 0, s[42:43]
	s_or_b32 m0, s100, 0x14000
	s_nop 0
	global_load_lds_dwordx4 v[174:175], off
	v_lshl_add_u64 v[174:175], v[236:237], 0, s[42:43]
	s_or_b32 m0, s100, 0x16000
	s_nop 0
	global_load_lds_dwordx4 v[174:175], off
	s_waitcnt vmcnt(6)
	s_barrier
; #define LDA8(dst, b, h) _Pragma("unroll") for (int m = 0; m < 4; ++m) _Pragma("unroll") for (int k = 0; k < 2; ++k) \
;     dst[m][k] = *(const bf16x8*)((const char*)SA8(b, h) + lds_byte8(wr * 64 + m * 16 + fr, k * 32 + fq * 8))
; #define LDB8(dst, b, h) _Pragma("unroll") for (int n = 0; n < 2; ++n) _Pragma("unroll") for (int k = 0; k < 2; ++k) \
;     dst[n][k] = *(const bf16x8*)((const char*)SB8(b, h) + lds_byte8(wc * 32 + n * 16 + fr, k * 32 + fq * 8))
; #define WAIT_V8(n) asm volatile("s_waitcnt vmcnt(" #n ")" ::: "memory")
; #define WAIT_L8(n) asm volatile("s_waitcnt lgkmcnt(" #n ")" ::: "memory")
; #define BAR8 __builtin_amdgcn_s_barrier()
; #define SCHED8 __builtin_amdgcn_sched_barrier(0)
;     ...
;     BAR8; WAIT_L8(0); MMA8(1, 0, At, B0); BAR8; SCHED8;
;     STAGE8(SB8(0, 1), Bt, K, bcol + 128, tt + 2);
;     WAIT_V8(6); BAR8; MMA8(1, 1, At, B1); BAR8;
;     LDB8(B0, 1, 0); SCHED8; LDA8(At, 1, 0); STAGE8(SA8(0, 1), A, lda, brow + 128, tt + 2);
;     WAIT_L8(8); BAR8; WAIT_L8(0); MMA8(0, 0, At, B0); BAR8; SCHED8;
	v_mfma_f32_16x16x32_bf16 v[32:35], v[190:193], v[230:233], v[32:35]
	v_mfma_f32_16x16x32_bf16 v[28:31], v[190:193], v[242:245], v[28:31]
	v_mfma_f32_16x16x32_bf16 v[24:27], v[198:201], v[230:233], v[24:27]
	v_mfma_f32_16x16x32_bf16 v[20:23], v[198:201], v[242:245], v[20:23]
	v_mfma_f32_16x16x32_bf16 v[16:19], v[206:209], v[230:233], v[16:19]
	v_mfma_f32_16x16x32_bf16 v[12:15], v[206:209], v[242:245], v[12:15]
	v_mfma_f32_16x16x32_bf16 v[8:11], v[214:217], v[230:233], v[8:11]
	v_mfma_f32_16x16x32_bf16 v[4:7], v[214:217], v[242:245], v[4:7]
	v_mfma_f32_16x16x32_bf16 v[32:35], v[194:197], v[238:241], v[32:35]
	v_mfma_f32_16x16x32_bf16 v[28:31], v[194:197], v[246:249], v[28:31]
	v_mfma_f32_16x16x32_bf16 v[24:27], v[202:205], v[238:241], v[24:27]
	v_mfma_f32_16x16x32_bf16 v[20:23], v[202:205], v[246:249], v[20:23]
	v_mfma_f32_16x16x32_bf16 v[16:19], v[210:213], v[238:241], v[16:19]
	v_mfma_f32_16x16x32_bf16 v[12:15], v[210:213], v[246:249], v[12:15]
	v_mfma_f32_16x16x32_bf16 v[8:11], v[218:221], v[238:241], v[8:11]
	v_mfma_f32_16x16x32_bf16 v[4:7], v[218:221], v[246:249], v[4:7]
	s_barrier
	ds_read_b128 v[174:177], v160
	ds_read_b128 v[178:181], v160 offset:1024
	ds_read_b128 v[182:185], v160 offset:2048
	ds_read_b128 v[186:189], v160 offset:3072
	v_lshl_add_u64 v[230:231], v[222:223], 0, s[44:45]
	s_or_b32 m0, s100, 0x4000
	ds_read_b128 v[190:193], v156 offset:32768
	ds_read_b128 v[194:197], v156 offset:33792
	ds_read_b128 v[198:201], v155 offset:32768
	ds_read_b128 v[202:205], v155 offset:33792
	ds_read_b128 v[206:209], v154 offset:32768
	ds_read_b128 v[210:213], v154 offset:33792
	ds_read_b128 v[214:217], v153 offset:32768
	ds_read_b128 v[218:221], v153 offset:33792
	global_load_lds_dwordx4 v[230:231], off
	v_lshl_add_u64 v[230:231], v[226:227], 0, s[44:45]
	s_or_b32 m0, s100, 0x6000
	s_nop 0
	global_load_lds_dwordx4 v[230:231], off
	s_waitcnt lgkmcnt(8)
	s_barrier
	s_waitcnt lgkmcnt(0)
	v_mfma_f32_16x16x32_bf16 v[128:131], v[190:193], v[174:177], v[128:131]
	v_mfma_f32_16x16x32_bf16 v[124:127], v[190:193], v[182:185], v[124:127]
	v_mfma_f32_16x16x32_bf16 v[120:123], v[198:201], v[174:177], v[120:123]
	v_mfma_f32_16x16x32_bf16 v[116:119], v[198:201], v[182:185], v[116:119]
	v_mfma_f32_16x16x32_bf16 v[112:115], v[206:209], v[174:177], v[112:115]
	v_mfma_f32_16x16x32_bf16 v[108:111], v[206:209], v[182:185], v[108:111]
	v_mfma_f32_16x16x32_bf16 v[104:107], v[214:217], v[174:177], v[104:107]
	v_mfma_f32_16x16x32_bf16 v[100:103], v[214:217], v[182:185], v[100:103]
	v_mfma_f32_16x16x32_bf16 v[128:131], v[194:197], v[178:181], v[128:131]
	v_mfma_f32_16x16x32_bf16 v[124:127], v[194:197], v[186:189], v[124:127]
	v_mfma_f32_16x16x32_bf16 v[120:123], v[202:205], v[178:181], v[120:123]
	v_mfma_f32_16x16x32_bf16 v[116:119], v[202:205], v[186:189], v[116:119]
	v_mfma_f32_16x16x32_bf16 v[112:115], v[210:213], v[178:181], v[112:115]
	v_mfma_f32_16x16x32_bf16 v[108:111], v[210:213], v[186:189], v[108:111]
	v_mfma_f32_16x16x32_bf16 v[104:107], v[218:221], v[178:181], v[104:107]
	v_mfma_f32_16x16x32_bf16 v[100:103], v[218:221], v[186:189], v[100:103]
	s_barrier
	v_lshl_add_u64 v[250:251], v[228:229], 0, s[46:47]
	s_or_b32 m0, s100, 0x18000
	ds_read_b128 v[230:233], v158
	ds_read_b128 v[238:241], v158 offset:1024
	ds_read_b128 v[242:245], v158 offset:2048
	ds_read_b128 v[246:249], v158 offset:3072
	global_load_lds_dwordx4 v[250:251], off
	v_lshl_add_u64 v[250:251], v[236:237], 0, s[46:47]
	s_or_b32 m0, s100, 0x1a000
	s_nop 0
	global_load_lds_dwordx4 v[250:251], off
	s_barrier
	s_waitcnt lgkmcnt(0)
	v_mfma_f32_16x16x32_bf16 v[96:99], v[190:193], v[230:233], v[96:99]
	v_mfma_f32_16x16x32_bf16 v[92:95], v[190:193], v[242:245], v[92:95]
	v_mfma_f32_16x16x32_bf16 v[88:91], v[198:201], v[230:233], v[88:91]
	v_mfma_f32_16x16x32_bf16 v[84:87], v[198:201], v[242:245], v[84:87]
	v_mfma_f32_16x16x32_bf16 v[80:83], v[206:209], v[230:233], v[80:83]
	v_mfma_f32_16x16x32_bf16 v[76:79], v[206:209], v[242:245], v[76:79]
	v_mfma_f32_16x16x32_bf16 v[72:75], v[214:217], v[230:233], v[72:75]
	v_mfma_f32_16x16x32_bf16 v[68:71], v[214:217], v[242:245], v[68:71]
	v_mfma_f32_16x16x32_bf16 v[96:99], v[194:197], v[238:241], v[96:99]
	v_mfma_f32_16x16x32_bf16 v[92:95], v[194:197], v[246:249], v[92:95]
	v_mfma_f32_16x16x32_bf16 v[88:91], v[202:205], v[238:241], v[88:91]
	v_mfma_f32_16x16x32_bf16 v[84:87], v[202:205], v[246:249], v[84:87]
	v_mfma_f32_16x16x32_bf16 v[80:83], v[210:213], v[238:241], v[80:83]
	v_mfma_f32_16x16x32_bf16 v[76:79], v[210:213], v[246:249], v[76:79]
	v_mfma_f32_16x16x32_bf16 v[72:75], v[218:221], v[238:241], v[72:75]
	v_mfma_f32_16x16x32_bf16 v[68:71], v[218:221], v[246:249], v[68:71]
	v_lshl_add_u64 v[222:223], v[222:223], 0, s[48:49]
	s_or_b32 m0, s100, 0x8000
	s_barrier
	ds_read_b128 v[190:193], v156 offset:49152
	ds_read_b128 v[194:197], v156 offset:50176
	ds_read_b128 v[198:201], v155 offset:49152
	ds_read_b128 v[202:205], v155 offset:50176
	ds_read_b128 v[206:209], v154 offset:49152
	ds_read_b128 v[210:213], v154 offset:50176
	ds_read_b128 v[214:217], v153 offset:49152
	ds_read_b128 v[218:221], v153 offset:50176
	global_load_lds_dwordx4 v[222:223], off
	v_lshl_add_u64 v[222:223], v[226:227], 0, s[48:49]
	s_or_b32 m0, s100, 0xa000
	s_nop 0
	global_load_lds_dwordx4 v[222:223], off
	s_barrier
; #define LDA8(dst, b, h) _Pragma("unroll") for (int m = 0; m < 4; ++m) _Pragma("unroll") for (int k = 0; k < 2; ++k) \
;     dst[m][k] = *(const bf16x8*)((const char*)SA8(b, h) + lds_byte8(wr * 64 + m * 16 + fr, k * 32 + fq * 8))
; #define LDB8(dst, b, h) _Pragma("unroll") for (int n = 0; n < 2; ++n) _Pragma("unroll") for (int k = 0; k < 2; ++k) \
;     dst[n][k] = *(const bf16x8*)((const char*)SB8(b, h) + lds_byte8(wc * 32 + n * 16 + fr, k * 32 + fq * 8))
; #define WAIT_V8(n) asm volatile("s_waitcnt vmcnt(" #n ")" ::: "memory")
; #define WAIT_L8(n) asm volatile("s_waitcnt lgkmcnt(" #n ")" ::: "memory")
; #define BAR8 __builtin_amdgcn_s_barrier()
; #define SCHED8 __builtin_amdgcn_sched_barrier(0)
;     ...
;     WAIT_L8(8); BAR8; WAIT_L8(0); MMA8(0, 0, At, B0); BAR8; SCHED8;
;     LDB8(B1, 1, 1); STAGE8(SB8(1, 0), Bt, K, bcol, tt + 3);
;     BAR8; WAIT_L8(0); MMA8(0, 1, At, B1); BAR8;
;     LDA8(At, 1, 1); STAGE8(SA8(1, 0), A, lda, brow, tt + 3);
;     BAR8; WAIT_L8(0); MMA8(1, 0, At, B0); BAR8; SCHED8;
;     STAGE8(SB8(1, 1), Bt, K, bcol + 128, tt + 3);
;     WAIT_V8(6); BAR8; MMA8(1, 1, At, B1); BAR8;
;   }
;   { LDB8(B0, 0, 0); LDA8(At, 0, 0); STAGE8(SA8(1, 1), A, lda, brow + 128, nt - 1);
;     BAR8; WAIT_L8(0); MMA8(0, 0, At, B0); BAR8;
;     LDB8(B1, 0, 1); BAR8; WAIT_L8(0); MMA8(0, 1, At, B1); BAR8;
	s_waitcnt lgkmcnt(0)
	v_mfma_f32_16x16x32_bf16 v[64:67], v[190:193], v[174:177], v[64:67]
	v_mfma_f32_16x16x32_bf16 v[60:63], v[190:193], v[182:185], v[60:63]
	v_mfma_f32_16x16x32_bf16 v[56:59], v[198:201], v[174:177], v[56:59]
	v_mfma_f32_16x16x32_bf16 v[52:55], v[198:201], v[182:185], v[52:55]
	v_mfma_f32_16x16x32_bf16 v[48:51], v[206:209], v[174:177], v[48:51]
	v_mfma_f32_16x16x32_bf16 v[44:47], v[206:209], v[182:185], v[44:47]
	v_mfma_f32_16x16x32_bf16 v[40:43], v[214:217], v[174:177], v[40:43]
	v_mfma_f32_16x16x32_bf16 v[36:39], v[214:217], v[182:185], v[36:39]
	v_mfma_f32_16x16x32_bf16 v[64:67], v[194:197], v[178:181], v[64:67]
	v_mfma_f32_16x16x32_bf16 v[60:63], v[194:197], v[186:189], v[60:63]
	v_mfma_f32_16x16x32_bf16 v[56:59], v[202:205], v[178:181], v[56:59]
	v_mfma_f32_16x16x32_bf16 v[52:55], v[202:205], v[186:189], v[52:55]
	v_mfma_f32_16x16x32_bf16 v[48:51], v[210:213], v[178:181], v[48:51]
	v_mfma_f32_16x16x32_bf16 v[44:47], v[210:213], v[186:189], v[44:47]
	v_mfma_f32_16x16x32_bf16 v[40:43], v[218:221], v[178:181], v[40:43]
	v_mfma_f32_16x16x32_bf16 v[36:39], v[218:221], v[186:189], v[36:39]
	s_barrier
	v_lshl_add_u64 v[174:175], v[228:229], 0, s[50:51]
	s_or_b32 m0, s100, 0x1c000
	s_nop 0
	global_load_lds_dwordx4 v[174:175], off
	v_lshl_add_u64 v[174:175], v[236:237], 0, s[50:51]
	s_or_b32 m0, s100, 0x1e000
	s_nop 0
	global_load_lds_dwordx4 v[174:175], off
	s_waitcnt vmcnt(6)
	s_barrier
	v_mfma_f32_16x16x32_bf16 v[32:35], v[190:193], v[230:233], v[32:35]
	v_mfma_f32_16x16x32_bf16 v[28:31], v[190:193], v[242:245], v[28:31]
	v_mfma_f32_16x16x32_bf16 v[24:27], v[198:201], v[230:233], v[24:27]
	v_mfma_f32_16x16x32_bf16 v[20:23], v[198:201], v[242:245], v[20:23]
	v_mfma_f32_16x16x32_bf16 v[16:19], v[206:209], v[230:233], v[16:19]
	v_mfma_f32_16x16x32_bf16 v[12:15], v[206:209], v[242:245], v[12:15]
	v_mfma_f32_16x16x32_bf16 v[8:11], v[214:217], v[230:233], v[8:11]
	v_mfma_f32_16x16x32_bf16 v[4:7], v[214:217], v[242:245], v[4:7]
	v_mfma_f32_16x16x32_bf16 v[32:35], v[194:197], v[238:241], v[32:35]
	v_mfma_f32_16x16x32_bf16 v[28:31], v[194:197], v[246:249], v[28:31]
	v_mfma_f32_16x16x32_bf16 v[24:27], v[202:205], v[238:241], v[24:27]
	v_mfma_f32_16x16x32_bf16 v[20:23], v[202:205], v[246:249], v[20:23]
	v_mfma_f32_16x16x32_bf16 v[16:19], v[210:213], v[238:241], v[16:19]
	v_mfma_f32_16x16x32_bf16 v[12:15], v[210:213], v[246:249], v[12:15]
	v_mfma_f32_16x16x32_bf16 v[8:11], v[218:221], v[238:241], v[8:11]
	v_mfma_f32_16x16x32_bf16 v[4:7], v[218:221], v[246:249], v[4:7]
	s_add_i32 s29, s29, 2
	s_add_u32 s12, s12, 0x100
	s_addc_u32 s13, s13, 0
	s_cmp_lt_u32 s29, 12
	s_barrier
	s_cbranch_scc1 .LBB0_908
	s_add_u32 s2, s2, s27
	s_addc_u32 s3, s3, 0
	s_add_u32 s2, s2, 0x6000780
	s_addc_u32 s3, s3, 0
	v_lshl_add_u64 v[136:137], v[136:137], 1, s[2:3]
	v_lshl_add_u64 v[0:1], v[0:1], 1, v[136:137]
	s_or_b32 m0, s100, 0xc000
	ds_read_b128 v[138:141], v171
	ds_read_b128 v[142:145], v171 offset:1024
	ds_read_b128 v[162:165], v171 offset:2048
	ds_read_b128 v[168:171], v171 offset:3072
	ds_read_b128 v[174:177], v156
	ds_read_b128 v[178:181], v156 offset:1024
	ds_read_b128 v[182:185], v155
	ds_read_b128 v[186:189], v155 offset:1024
	ds_read_b128 v[190:193], v154
	ds_read_b128 v[194:197], v154 offset:1024
	ds_read_b128 v[198:201], v153
	ds_read_b128 v[202:205], v153 offset:1024
	global_load_lds_dwordx4 v[0:1], off
	v_lshl_add_u64 v[0:1], v[134:135], 1, s[2:3]
	v_lshl_add_u64 v[0:1], v[132:133], 1, v[0:1]
	s_or_b32 m0, s100, 0xe000
	s_nop 0
	global_load_lds_dwordx4 v[0:1], off
	s_barrier
	s_waitcnt lgkmcnt(0)
	v_mfma_f32_16x16x32_bf16 v[128:131], v[174:177], v[138:141], v[128:131]
	v_mfma_f32_16x16x32_bf16 v[124:127], v[174:177], v[162:165], v[124:127]
	v_mfma_f32_16x16x32_bf16 v[120:123], v[182:185], v[138:141], v[120:123]
	v_mfma_f32_16x16x32_bf16 v[112:115], v[190:193], v[138:141], v[112:115]
	v_mfma_f32_16x16x32_bf16 v[128:131], v[178:181], v[142:145], v[128:131]
	v_mfma_f32_16x16x32_bf16 v[124:127], v[178:181], v[168:171], v[124:127]
	v_mfma_f32_16x16x32_bf16 v[120:123], v[186:189], v[142:145], v[120:123]
	v_mfma_f32_16x16x32_bf16 v[116:119], v[182:185], v[162:165], v[116:119]
	v_mfma_f32_16x16x32_bf16 v[112:115], v[194:197], v[142:145], v[112:115]
	v_mfma_f32_16x16x32_bf16 v[108:111], v[190:193], v[162:165], v[108:111]
	v_mfma_f32_16x16x32_bf16 v[104:107], v[198:201], v[138:141], v[104:107]
	v_mfma_f32_16x16x32_bf16 v[100:103], v[198:201], v[162:165], v[100:103]
	v_mfma_f32_16x16x32_bf16 v[132:135], v[186:189], v[168:171], v[116:119]
	v_mfma_f32_16x16x32_bf16 v[206:209], v[194:197], v[168:171], v[108:111]
	v_mfma_f32_16x16x32_bf16 v[210:213], v[202:205], v[142:145], v[104:107]
	v_mfma_f32_16x16x32_bf16 v[214:217], v[202:205], v[168:171], v[100:103]
	s_barrier
	s_nop 1
	ds_read_b128 v[100:103], v167
	ds_read_b128 v[104:107], v167 offset:1024
	ds_read_b128 v[108:111], v167 offset:2048
	ds_read_b128 v[116:119], v167 offset:3072
	s_barrier
	s_waitcnt lgkmcnt(0)
	v_mfma_f32_16x16x32_bf16 v[80:83], v[190:193], v[100:103], v[80:83]
	v_mfma_f32_16x16x32_bf16 v[76:79], v[190:193], v[108:111], v[76:79]
	v_mfma_f32_16x16x32_bf16 v[72:75], v[198:201], v[100:103], v[72:75]
	v_mfma_f32_16x16x32_bf16 v[68:71], v[198:201], v[108:111], v[68:71]
	v_mfma_f32_16x16x32_bf16 v[96:99], v[174:177], v[100:103], v[96:99]
	v_mfma_f32_16x16x32_bf16 v[92:95], v[174:177], v[108:111], v[92:95]
	v_mfma_f32_16x16x32_bf16 v[88:91], v[182:185], v[100:103], v[88:91]
	v_mfma_f32_16x16x32_bf16 v[84:87], v[182:185], v[108:111], v[84:87]
	v_mfma_f32_16x16x32_bf16 v[80:83], v[194:197], v[104:107], v[80:83]
	v_mfma_f32_16x16x32_bf16 v[76:79], v[194:197], v[116:119], v[76:79]
	v_mfma_f32_16x16x32_bf16 v[72:75], v[202:205], v[104:107], v[72:75]
	v_mfma_f32_16x16x32_bf16 v[68:71], v[202:205], v[116:119], v[68:71]
	v_mfma_f32_16x16x32_bf16 v[218:221], v[178:181], v[104:107], v[96:99]
	v_mfma_f32_16x16x32_bf16 v[172:175], v[178:181], v[116:119], v[92:95]
	v_mfma_f32_16x16x32_bf16 v[176:179], v[186:189], v[104:107], v[88:91]
	v_mfma_f32_16x16x32_bf16 v[180:183], v[186:189], v[116:119], v[84:87]
	s_barrier
; #define LDA8(dst, b, h) _Pragma("unroll") for (int m = 0; m < 4; ++m) _Pragma("unroll") for (int k = 0; k < 2; ++k) \
;     dst[m][k] = *(const bf16x8*)((const char*)SA8(b, h) + lds_byte8(wr * 64 + m * 16 + fr, k * 32 + fq * 8))
; #define LDB8(dst, b, h) _Pragma("unroll") for (int n = 0; n < 2; ++n) _Pragma("unroll") for (int k = 0; k < 2; ++k) \
;     dst[n][k] = *(const bf16x8*)((const char*)SB8(b, h) + lds_byte8(wc * 32 + n * 16 + fr, k * 32 + fq * 8))
; #define WAIT_V8(n) asm volatile("s_waitcnt vmcnt(" #n ")" ::: "memory")
; #define WAIT_L8(n) asm volatile("s_waitcnt lgkmcnt(" #n ")" ::: "memory")
; #define BAR8 __builtin_amdgcn_s_barrier()
;     ...
;     LDA8(At, 0, 1); WAIT_V8(4); BAR8; WAIT_L8(0); MMA8(1, 0, At, B0); MMA8(1, 1, At, B1); BAR8; }
;   { LDB8(B0, 1, 0); LDA8(At, 1, 0); WAIT_V8(2); BAR8; WAIT_L8(0); MMA8(0, 0, At, B0); BAR8;
;     LDB8(B1, 1, 1); WAIT_V8(0); BAR8; WAIT_L8(0); MMA8(0, 1, At, B1); BAR8;
	s_nop 0
	ds_read_b128 v[84:87], v156 offset:16384
	ds_read_b128 v[88:91], v156 offset:17408
	ds_read_b128 v[92:95], v155 offset:16384
	ds_read_b128 v[96:99], v155 offset:17408
	ds_read_b128 v[184:187], v154 offset:16384
	ds_read_b128 v[188:191], v154 offset:17408
	ds_read_b128 v[192:195], v153 offset:16384
	ds_read_b128 v[196:199], v153 offset:17408
	s_waitcnt vmcnt(4)
	s_barrier
	s_waitcnt lgkmcnt(0)
	v_mfma_f32_16x16x32_bf16 v[64:67], v[84:87], v[138:141], v[64:67]
	v_mfma_f32_16x16x32_bf16 v[60:63], v[84:87], v[162:165], v[60:63]
	v_mfma_f32_16x16x32_bf16 v[56:59], v[92:95], v[138:141], v[56:59]
	v_mfma_f32_16x16x32_bf16 v[52:55], v[92:95], v[162:165], v[52:55]
	v_mfma_f32_16x16x32_bf16 v[48:51], v[184:187], v[138:141], v[48:51]
	v_mfma_f32_16x16x32_bf16 v[44:47], v[184:187], v[162:165], v[44:47]
	v_mfma_f32_16x16x32_bf16 v[40:43], v[192:195], v[138:141], v[40:43]
	v_mfma_f32_16x16x32_bf16 v[36:39], v[192:195], v[162:165], v[36:39]
	v_mfma_f32_16x16x32_bf16 v[64:67], v[88:91], v[142:145], v[64:67]
	v_mfma_f32_16x16x32_bf16 v[60:63], v[88:91], v[168:171], v[60:63]
	v_mfma_f32_16x16x32_bf16 v[56:59], v[96:99], v[142:145], v[56:59]
	v_mfma_f32_16x16x32_bf16 v[52:55], v[96:99], v[168:171], v[52:55]
	v_mfma_f32_16x16x32_bf16 v[48:51], v[188:191], v[142:145], v[48:51]
	v_mfma_f32_16x16x32_bf16 v[44:47], v[188:191], v[168:171], v[44:47]
	v_mfma_f32_16x16x32_bf16 v[40:43], v[196:199], v[142:145], v[40:43]
	v_mfma_f32_16x16x32_bf16 v[36:39], v[196:199], v[168:171], v[36:39]
	v_mfma_f32_16x16x32_bf16 v[32:35], v[84:87], v[100:103], v[32:35]
	v_mfma_f32_16x16x32_bf16 v[28:31], v[84:87], v[108:111], v[28:31]
	v_mfma_f32_16x16x32_bf16 v[24:27], v[92:95], v[100:103], v[24:27]
	v_mfma_f32_16x16x32_bf16 v[20:23], v[92:95], v[108:111], v[20:23]
	v_mfma_f32_16x16x32_bf16 v[16:19], v[184:187], v[100:103], v[16:19]
	v_mfma_f32_16x16x32_bf16 v[12:15], v[184:187], v[108:111], v[12:15]
	v_mfma_f32_16x16x32_bf16 v[8:11], v[192:195], v[100:103], v[8:11]
	v_mfma_f32_16x16x32_bf16 v[4:7], v[192:195], v[108:111], v[4:7]
	v_mfma_f32_16x16x32_bf16 v[136:139], v[88:91], v[104:107], v[32:35]
	v_mfma_f32_16x16x32_bf16 v[140:143], v[88:91], v[116:119], v[28:31]
	v_mfma_f32_16x16x32_bf16 v[162:165], v[96:99], v[104:107], v[24:27]
	v_mfma_f32_16x16x32_bf16 v[166:169], v[96:99], v[116:119], v[20:23]
	v_mfma_f32_16x16x32_bf16 v[200:203], v[188:191], v[104:107], v[16:19]
	v_mfma_f32_16x16x32_bf16 v[184:187], v[188:191], v[116:119], v[12:15]
	v_mfma_f32_16x16x32_bf16 v[188:191], v[196:199], v[104:107], v[8:11]
	v_mfma_f32_16x16x32_bf16 v[192:195], v[196:199], v[116:119], v[4:7]
	s_barrier
	ds_read_b128 v[196:199], v160
	ds_read_b128 v[230:233], v160 offset:1024
	ds_read_b128 v[238:241], v160 offset:2048
	ds_read_b128 v[242:245], v160 offset:3072
	ds_read_b128 v[8:11], v156 offset:32768
	ds_read_b128 v[12:15], v156 offset:33792
	ds_read_b128 v[16:19], v155 offset:32768
	ds_read_b128 v[24:27], v155 offset:33792
	ds_read_b128 v[28:31], v154 offset:32768
	ds_read_b128 v[32:35], v154 offset:33792
	ds_read_b128 v[246:249], v153 offset:32768
	ds_read_b128 v[226:229], v153 offset:33792
	s_waitcnt vmcnt(2)
	s_barrier
	s_waitcnt lgkmcnt(0)
	v_mfma_f32_16x16x32_bf16 v[4:7], v[8:11], v[196:199], v[128:131]
	v_mfma_f32_16x16x32_bf16 v[104:107], v[12:15], v[230:233], v[4:7]
	v_mfma_f32_16x16x32_bf16 v[4:7], v[8:11], v[238:241], v[124:127]
	v_mfma_f32_16x16x32_bf16 v[116:119], v[12:15], v[242:245], v[4:7]
	v_mfma_f32_16x16x32_bf16 v[4:7], v[16:19], v[196:199], v[120:123]
	v_mfma_f32_16x16x32_bf16 v[100:103], v[24:27], v[230:233], v[4:7]
	v_mfma_f32_16x16x32_bf16 v[4:7], v[16:19], v[238:241], v[132:135]
	v_mfma_f32_16x16x32_bf16 v[108:111], v[24:27], v[242:245], v[4:7]
	v_mfma_f32_16x16x32_bf16 v[4:7], v[28:31], v[196:199], v[112:115]
	v_mfma_f32_16x16x32_bf16 v[92:95], v[32:35], v[230:233], v[4:7]
	v_mfma_f32_16x16x32_bf16 v[4:7], v[28:31], v[238:241], v[206:209]
	v_mfma_f32_16x16x32_bf16 v[96:99], v[32:35], v[242:245], v[4:7]
	v_mfma_f32_16x16x32_bf16 v[4:7], v[246:249], v[196:199], v[210:213]
	v_mfma_f32_16x16x32_bf16 v[84:87], v[226:229], v[230:233], v[4:7]
	v_mfma_f32_16x16x32_bf16 v[4:7], v[246:249], v[238:241], v[214:217]
	v_mfma_f32_16x16x32_bf16 v[88:91], v[226:229], v[242:245], v[4:7]
	s_barrier
; #define LDA8(dst, b, h) _Pragma("unroll") for (int m = 0; m < 4; ++m) _Pragma("unroll") for (int k = 0; k < 2; ++k) \
;     dst[m][k] = *(const bf16x8*)((const char*)SA8(b, h) + lds_byte8(wr * 64 + m * 16 + fr, k * 32 + fq * 8))
; #define LDB8(dst, b, h) _Pragma("unroll") for (int n = 0; n < 2; ++n) _Pragma("unroll") for (int k = 0; k < 2; ++k) \
;     dst[n][k] = *(const bf16x8*)((const char*)SB8(b, h) + lds_byte8(wc * 32 + n * 16 + fr, k * 32 + fq * 8))
; #define WAIT_V8(n) asm volatile("s_waitcnt vmcnt(" #n ")" ::: "memory")
; #define WAIT_L8(n) asm volatile("s_waitcnt lgkmcnt(" #n ")" ::: "memory")
; #define BAR8 __builtin_amdgcn_s_barrier()
;     ...
;     LDB8(B1, 1, 1); WAIT_V8(0); BAR8; WAIT_L8(0); MMA8(0, 1, At, B1); BAR8;
;     LDA8(At, 1, 1); BAR8; WAIT_L8(0); MMA8(1, 0, At, B0); MMA8(1, 1, At, B1); BAR8; }
;   if (wr == 0) BAR8;
;   __syncthreads();
	ds_read_b128 v[132:135], v158
	ds_read_b128 v[204:207], v158 offset:1024
	ds_read_b128 v[208:211], v158 offset:2048
	ds_read_b128 v[158:161], v158 offset:3072
	s_waitcnt vmcnt(0)
	s_barrier
	s_waitcnt lgkmcnt(0)
	v_mfma_f32_16x16x32_bf16 v[4:7], v[8:11], v[132:135], v[218:221]
	v_mfma_f32_16x16x32_bf16 v[8:11], v[8:11], v[208:211], v[172:175]
	v_mfma_f32_16x16x32_bf16 v[4:7], v[12:15], v[204:207], v[4:7]
	v_mfma_f32_16x16x32_bf16 v[20:23], v[12:15], v[158:161], v[8:11]
	v_mfma_f32_16x16x32_bf16 v[8:11], v[16:19], v[132:135], v[176:179]
	v_mfma_f32_16x16x32_bf16 v[12:15], v[16:19], v[208:211], v[180:183]
	v_mfma_f32_16x16x32_bf16 v[8:11], v[24:27], v[204:207], v[8:11]
	v_mfma_f32_16x16x32_bf16 v[24:27], v[24:27], v[158:161], v[12:15]
	v_mfma_f32_16x16x32_bf16 v[12:15], v[28:31], v[132:135], v[80:83]
	v_mfma_f32_16x16x32_bf16 v[16:19], v[28:31], v[208:211], v[76:79]
	v_mfma_f32_16x16x32_bf16 v[12:15], v[32:35], v[204:207], v[12:15]
	v_mfma_f32_16x16x32_bf16 v[28:31], v[32:35], v[158:161], v[16:19]
	v_mfma_f32_16x16x32_bf16 v[16:19], v[246:249], v[132:135], v[72:75]
	v_mfma_f32_16x16x32_bf16 v[32:35], v[246:249], v[208:211], v[68:71]
	v_mfma_f32_16x16x32_bf16 v[16:19], v[226:229], v[204:207], v[16:19]
	v_mfma_f32_16x16x32_bf16 v[32:35], v[226:229], v[158:161], v[32:35]
	s_barrier
	ds_read_b128 v[170:173], v156 offset:49152
	ds_read_b128 v[174:177], v156 offset:50176
	ds_read_b128 v[178:181], v155 offset:49152
	ds_read_b128 v[212:215], v155 offset:50176
	ds_read_b128 v[216:219], v154 offset:49152
	ds_read_b128 v[154:157], v154 offset:50176
	ds_read_b128 v[220:223], v153 offset:49152
	ds_read_b128 v[150:153], v153 offset:50176
	s_barrier
	s_waitcnt lgkmcnt(0)
	v_mfma_f32_16x16x32_bf16 v[64:67], v[170:173], v[196:199], v[64:67]
	v_mfma_f32_16x16x32_bf16 v[60:63], v[170:173], v[238:241], v[60:63]
	v_mfma_f32_16x16x32_bf16 v[56:59], v[178:181], v[196:199], v[56:59]
	v_mfma_f32_16x16x32_bf16 v[52:55], v[178:181], v[238:241], v[52:55]
	v_mfma_f32_16x16x32_bf16 v[48:51], v[216:219], v[196:199], v[48:51]
	v_mfma_f32_16x16x32_bf16 v[44:47], v[216:219], v[238:241], v[44:47]
	v_mfma_f32_16x16x32_bf16 v[40:43], v[220:223], v[196:199], v[40:43]
	v_mfma_f32_16x16x32_bf16 v[36:39], v[220:223], v[238:241], v[36:39]
	v_mfma_f32_16x16x32_bf16 v[128:131], v[174:177], v[230:233], v[64:67]
	v_mfma_f32_16x16x32_bf16 v[124:127], v[174:177], v[242:245], v[60:63]
	v_mfma_f32_16x16x32_bf16 v[120:123], v[212:215], v[230:233], v[56:59]
	v_mfma_f32_16x16x32_bf16 v[112:115], v[212:215], v[242:245], v[52:55]
	v_mfma_f32_16x16x32_bf16 v[80:83], v[154:157], v[230:233], v[48:51]
	v_mfma_f32_16x16x32_bf16 v[76:79], v[154:157], v[242:245], v[44:47]
	v_mfma_f32_16x16x32_bf16 v[72:75], v[150:153], v[230:233], v[40:43]
	v_mfma_f32_16x16x32_bf16 v[68:71], v[150:153], v[242:245], v[36:39]
	v_mfma_f32_16x16x32_bf16 v[40:43], v[170:173], v[208:211], v[140:143]
	v_mfma_f32_16x16x32_bf16 v[44:47], v[178:181], v[208:211], v[166:169]
	v_mfma_f32_16x16x32_bf16 v[48:51], v[216:219], v[208:211], v[184:187]
	v_mfma_f32_16x16x32_bf16 v[36:39], v[170:173], v[132:135], v[136:139]
	v_mfma_f32_16x16x32_bf16 v[52:55], v[174:177], v[158:161], v[40:43]
	v_mfma_f32_16x16x32_bf16 v[40:43], v[178:181], v[132:135], v[162:165]
	v_mfma_f32_16x16x32_bf16 v[56:59], v[212:215], v[158:161], v[44:47]
	v_mfma_f32_16x16x32_bf16 v[44:47], v[216:219], v[132:135], v[200:203]
	v_mfma_f32_16x16x32_bf16 v[60:63], v[154:157], v[158:161], v[48:51]
	v_mfma_f32_16x16x32_bf16 v[48:51], v[220:223], v[132:135], v[188:191]
	v_mfma_f32_16x16x32_bf16 v[64:67], v[220:223], v[208:211], v[192:195]
	v_mfma_f32_16x16x32_bf16 v[36:39], v[174:177], v[204:207], v[36:39]
	v_mfma_f32_16x16x32_bf16 v[40:43], v[212:215], v[204:207], v[40:43]
	v_mfma_f32_16x16x32_bf16 v[44:47], v[154:157], v[204:207], v[44:47]
	v_mfma_f32_16x16x32_bf16 v[48:51], v[150:153], v[204:207], v[48:51]
	v_mfma_f32_16x16x32_bf16 v[64:67], v[150:153], v[158:161], v[64:67]
	s_movk_i32 s2, 0x100
	v_cmp_gt_u32_e32 vcc, s2, v3
	s_barrier
	s_and_saveexec_b64 s[2:3], vcc
	s_cbranch_execz .LBB0_911
	s_barrier

; #define BAR8 __builtin_amdgcn_s_barrier()
;     ...
;   const int brow = m0, bcol = n0;
;   const int wid = t >> 6, lane = t & 63, wr = wid >> 2, wc = wid & 3, fr = lane & 15, fq = lane >> 4;
;   f32x4 acc[2][2][4][2];
;   {
;     float zinit = 0.f;
;     asm volatile("" : "+v"(zinit));
; #pragma unroll
;     for (int a = 0; a < 2; ++a)
; #pragma unroll
;       for (int b = 0; b < 2; ++b)
; #pragma unroll
;         for (int m = 0; m < 4; ++m)
; #pragma unroll
;           for (int n = 0; n < 2; ++n)
; #pragma unroll
;             for (int j = 0; j < 4; ++j) acc[a][b][m][n][j] = zinit;
;   }
;   bf16x8 At[4][2], B0[2][2], B1[2][2];
;   const int nt = K / 64;
;   if (!pre) {
;     STAGE8(SB8(0, 0), Bt, K, bcol, 0); STAGE8(SA8(0, 0), A, lda, brow, 0);
;     STAGE8(SB8(0, 1), Bt, K, bcol + 128, 0); STAGE8(SA8(0, 1), A, lda, brow + 128, 0);
;   }
;   if (wr == 1) BAR8;
.LBB0_1001:
	s_lshr_b32 s27, s37, 8
	s_cmpk_gt_i32 s38, 0x7f
	s_mov_b64 s[0:1], -1
	s_cbranch_scc0 .LBB0_1011
	s_mov_b32 s0, 25
	s_ashr_i32 s1, s0, 31
	s_lshl_b64 s[0:1], s[0:1], 3
	s_add_u32 s0, s70, s0
	s_addc_u32 s1, s71, s1
	v_readlane_b32 s6, v255, 60
	v_readlane_b32 s7, v255, 61
	s_nop 4
	s_mov_b32 s0, 25
	s_ashr_i32 s1, s0, 31
	s_lshl_b64 s[0:1], s[0:1], 3
	s_add_u32 s0, s70, s0
	s_addc_u32 s1, s71, s1
	v_readlane_b32 s2, v255, 60
	v_readlane_b32 s3, v255, 61
	s_nop 4
	s_mov_b32 s0, 25
	s_ashr_i32 s1, s0, 31
	s_lshl_b64 s[0:1], s[0:1], 3
	s_add_u32 s0, s70, s0
	s_addc_u32 s1, s71, s1
	v_mov_b32_e32 v3, v224
	v_readlane_b32 s12, v255, 60
	v_readlane_b32 s13, v255, 61
	s_nop 4
	s_lshl_b32 s0, s38, 8
	v_bfe_i32 v1, v3, 27, 1
	s_waitcnt vmcnt(10)
	v_lshlrev_b32_e32 v150, 4, v3
	s_nop 0
	v_readfirstlane_b32 s100, v150
	v_lshrrev_b32_e32 v1, 22, v1
	v_add_u32_e32 v1, v150, v1
	v_and_b32_e32 v1, 0xfffffc00, v1
	v_ashrrev_i32_e32 v0, 31, v3
	v_sub_u32_e32 v1, v150, v1
	v_lshrrev_b32_e32 v0, 26, v0
	v_lshrrev_b32_e32 v5, 4, v1
	v_add_u32_e32 v0, v3, v0
	v_bitop3_b32 v5, v5, v1, 32 bitop3:0x6c
	v_ashrrev_i32_e32 v1, 31, v1
	v_ashrrev_i32_e32 v0, 6, v0
	v_lshrrev_b32_e32 v1, 26, v1
	v_lshlrev_b32_e32 v6, 3, v0
	v_add_u32_e32 v1, v5, v1
	s_and_b32 s29, s0, 0x700
	s_lshl_b32 s0, s38, 5
	v_and_b32_e32 v6, -16, v6
	v_ashrrev_i32_e32 v1, 6, v1
	s_and_b32 s39, s0, 0x7fffff00
	v_add_u32_e32 v6, v1, v6
	v_mul_i32_i24_e32 v1, 64, v1
	s_add_i32 s0, s39, 0xfffff000
	v_lshlrev_b32_e32 v0, 5, v0
	v_sub_u32_e32 v1, v5, v1
	v_mov_b32_e32 v14, 1
	s_waitcnt vmcnt(9)
	v_add_u32_e32 v152, 0x2000, v150
	s_lshl_b32 s1, s0, 11
	v_and_b32_e32 v0, 32, v0
	v_ashrrev_i16_sdwa v1, v14, sext(v1) dst_sel:DWORD dst_unused:UNUSED_PAD src0_sel:DWORD src1_sel:BYTE_0
	v_ashrrev_i32_e32 v5, 31, v152
	s_add_u32 s14, s24, s1
	v_add_u32_sdwa v0, v0, sext(v1) dst_sel:DWORD dst_unused:UNUSED_PAD src0_sel:DWORD src1_sel:WORD_0
	v_ashrrev_i32_e32 v7, 31, v6
	v_lshrrev_b32_e32 v5, 22, v5
	s_addc_u32 s15, s25, 0
	v_lshlrev_b64 v[132:133], 11, v[6:7]
	v_ashrrev_i32_e32 v1, 31, v0
	v_add_u32_e32 v5, v152, v5
	v_lshl_add_u64 v[8:9], s[14:15], 0, v[132:133]
	v_lshlrev_b64 v[6:7], 1, v[0:1]
	v_ashrrev_i32_e32 v5, 10, v5
	v_lshl_add_u64 v[10:11], v[8:9], 0, v[6:7]
	v_mul_i32_i24_e32 v8, 0x400, v5
	v_sub_u32_e32 v8, v152, v8
	v_lshrrev_b32_e32 v9, 4, v8
	v_bitop3_b32 v9, v9, v8, 32 bitop3:0x6c
	v_ashrrev_i32_e32 v12, 31, v9
	v_lshrrev_b32_e32 v12, 26, v12
	v_add_u32_e32 v12, v9, v12
	s_waitcnt vmcnt(8)
	v_mov_b32_e32 v4, v2
	s_or_b32 m0, s100, 0x10000
	v_lshlrev_b32_e32 v8, 3, v5
	v_ashrrev_i32_e32 v13, 6, v12
	v_and_b32_e32 v12, 0xc0, v12
	global_load_lds_dwordx4 v[10:11], off
	v_and_b32_e32 v8, -16, v8
	v_lshlrev_b32_e32 v5, 5, v5
	v_sub_u32_e32 v9, v9, v12
	s_or_b32 m0, s100, 0x12000
	s_lshl_b32 s1, s29, 11
	v_add_u32_e32 v8, v13, v8
	v_and_b32_e32 v5, 32, v5
	v_ashrrev_i16_sdwa v9, v14, sext(v9) dst_sel:DWORD dst_unused:UNUSED_PAD src0_sel:DWORD src1_sel:BYTE_0
	s_waitcnt lgkmcnt(0)
	s_add_u32 s1, s12, s1
	v_add_u32_sdwa v134, v5, sext(v9) dst_sel:DWORD dst_unused:UNUSED_PAD src0_sel:DWORD src1_sel:WORD_0
	v_ashrrev_i32_e32 v9, 31, v8
	s_addc_u32 s40, s13, 0
	v_lshlrev_b64 v[136:137], 11, v[8:9]
	v_ashrrev_i32_e32 v135, 31, v134
	s_add_u32 s8, s1, 0xb800000
	v_lshl_add_u64 v[12:13], s[14:15], 0, v[136:137]
	v_lshlrev_b64 v[8:9], 1, v[134:135]
	s_addc_u32 s9, s40, 0
	v_lshl_add_u64 v[12:13], v[12:13], 0, v[8:9]
	v_lshl_add_u64 v[14:15], s[8:9], 0, v[132:133]
	global_load_lds_dwordx4 v[12:13], off
	v_lshl_add_u64 v[16:17], v[14:15], 0, v[6:7]
	s_mov_b32 m0, s100
	s_nop 0
	global_load_lds_dwordx4 v[16:17], off
	s_or_b32 m0, s100, 0x2000
	s_add_u32 s20, s14, 0x40000
	v_lshl_add_u64 v[14:15], s[8:9], 0, v[136:137]
	s_addc_u32 s21, s15, 0
	v_lshl_add_u64 v[14:15], v[14:15], 0, v[8:9]
	v_lshl_add_u64 v[18:19], s[20:21], 0, v[132:133]
	global_load_lds_dwordx4 v[14:15], off
	v_lshl_add_u64 v[18:19], v[18:19], 0, v[6:7]
	s_or_b32 m0, s100, 0x14000
	global_load_lds_dwordx4 v[18:19], off
	v_lshl_add_u64 v[18:19], s[20:21], 0, v[136:137]
	s_or_b32 m0, s100, 0x16000
	s_add_u32 s20, s1, 0xb840000
	v_lshl_add_u64 v[18:19], v[18:19], 0, v[8:9]
	s_addc_u32 s21, s40, 0
	global_load_lds_dwordx4 v[18:19], off
	v_lshl_add_u64 v[18:19], s[20:21], 0, v[132:133]
	v_lshl_add_u64 v[18:19], v[18:19], 0, v[6:7]
	s_or_b32 m0, s100, 0x4000
	global_load_lds_dwordx4 v[18:19], off
	v_lshl_add_u64 v[18:19], s[20:21], 0, v[136:137]
	v_lshl_add_u64 v[18:19], v[18:19], 0, v[8:9]
	s_or_b32 m0, s100, 0x6000
	v_ashrrev_i32_e32 v5, 8, v3
	global_load_lds_dwordx4 v[18:19], off
	v_cmp_eq_u32_e32 vcc, 1, v5
	s_and_saveexec_b64 s[20:21], vcc
	s_cbranch_execz .LBB0_1004
	s_barrier
; #define WAIT_V8(n) asm volatile("s_waitcnt vmcnt(" #n ")" ::: "memory")
; #define BAR8 __builtin_amdgcn_s_barrier()
;     ...
;   const int wid = t >> 6, lane = t & 63, wr = wid >> 2, wc = wid & 3, fr = lane & 15, fq = lane >> 4;
;   f32x4 acc[2][2][4][2];
;   {
;     float zinit = 0.f;
;     asm volatile("" : "+v"(zinit));
; #pragma unroll
;     for (int a = 0; a < 2; ++a)
; #pragma unroll
;       for (int b = 0; b < 2; ++b)
; #pragma unroll
;         for (int m = 0; m < 4; ++m)
; #pragma unroll
;           for (int n = 0; n < 2; ++n)
; #pragma unroll
;             for (int j = 0; j < 4; ++j) acc[a][b][m][n][j] = zinit;
;   }
;   bf16x8 At[4][2], B0[2][2], B1[2][2];
;   const int nt = K / 64;
;   if (!pre) {
;     STAGE8(SB8(0, 0), Bt, K, bcol, 0); STAGE8(SA8(0, 0), A, lda, brow, 0);
;     STAGE8(SB8(0, 1), Bt, K, bcol + 128, 0); STAGE8(SA8(0, 1), A, lda, brow + 128, 0);
;   }
;   if (wr == 1) BAR8;
;   WAIT_V8(4); BAR8;
;   STAGE8(SB8(1, 0), Bt, K, bcol, 1); STAGE8(SA8(1, 0), A, lda, brow, 1); STAGE8(SB8(1, 1), Bt, K, bcol + 128, 1);
;   WAIT_V8(6); BAR8;
.LBB0_1004:
	s_or_b64 exec, exec, s[20:21]
	v_readlane_b32 s40, v254, 35
	s_lshl_b32 s20, s36, 10
	v_readlane_b32 s42, v254, 37
	v_readlane_b32 s43, v254, 38
	s_waitcnt vmcnt(0)
	s_and_b32 s20, s20, 0xfffc0000
	s_mov_b32 s21, s40
	s_mov_b64 s[42:43], 0x80
	s_and_b32 s1, s27, 7
	s_add_i32 s20, s20, 0xffc00000
	v_lshl_add_u64 v[10:11], v[10:11], 0, s[42:43]
	s_or_b32 m0, s100, 0x18000
	s_lshl_b32 s1, s1, 19
	s_lshl_b64 s[20:21], s[20:21], 1
	s_waitcnt vmcnt(4)
	s_barrier
	global_load_lds_dwordx4 v[10:11], off
	v_lshl_add_u64 v[10:11], v[12:13], 0, s[42:43]
	s_or_b32 m0, s100, 0x1a000
	global_load_lds_dwordx4 v[10:11], off
	v_lshl_add_u64 v[10:11], v[16:17], 0, s[42:43]
	s_or_b32 m0, s100, 0x8000
	s_add_u32 s14, s14, 0x40080
	global_load_lds_dwordx4 v[10:11], off
	v_lshl_add_u64 v[10:11], v[14:15], 0, s[42:43]
	s_addc_u32 s15, s15, 0
	s_or_b32 m0, s100, 0xa000
	global_load_lds_dwordx4 v[10:11], off
	v_lshl_add_u64 v[10:11], s[14:15], 0, v[132:133]
	v_lshl_add_u64 v[10:11], v[10:11], 0, v[6:7]
	s_or_b32 m0, s100, 0x1c000
	global_load_lds_dwordx4 v[10:11], off
	v_lshl_add_u64 v[10:11], s[14:15], 0, v[136:137]
	v_lshl_add_u64 v[10:11], v[10:11], 0, v[8:9]
	s_or_b32 m0, s100, 0x1e000
	v_and_b32_e32 v147, 15, v3
	global_load_lds_dwordx4 v[10:11], off
	v_bfe_u32 v148, v3, 4, 2
	v_lshlrev_b32_e32 v11, 4, v148
	v_lshlrev_b32_e32 v12, 6, v147
	v_lshlrev_b32_e32 v14, 2, v3
	v_or_b32_e32 v13, v11, v12
	v_and_b32_e32 v14, 32, v14
	s_mov_b32 s14, 0x10000
	v_bitop3_b32 v15, v13, s14, v14 bitop3:0xde
	s_mov_b32 s14, 0x14000
	s_add_u32 s12, s12, s1
	v_bitop3_b32 v16, v13, s14, v14 bitop3:0xde
	s_mov_b32 s14, 0x18000
	v_lshlrev_b32_e32 v18, 6, v3
	s_addc_u32 s13, s13, 0
	v_lshl_add_u64 v[8:9], v[136:137], 0, v[8:9]
	v_lshl_add_u64 v[6:7], v[132:133], 0, v[6:7]
	v_bfe_u32 v146, v3, 6, 2
	s_waitcnt vmcnt(6)
	v_lshlrev_b32_e32 v149, 6, v5
	v_bitop3_b32 v17, v13, s14, v14 bitop3:0xde
	s_mov_b32 s14, 0x1c000
	v_lshlrev_b32_e32 v5, 13, v5
	v_and_b32_e32 v18, 0x3c0, v18
	v_lshl_add_u64 v[138:139], s[12:13], 0, v[8:9]
	v_lshl_add_u64 v[140:141], s[12:13], 0, v[6:7]
	s_add_u32 s12, s4, s20
	v_readlane_b32 s41, v254, 36
	v_lshlrev_b32_e32 v10, 12, v146
	v_bitop3_b32 v12, v11, v14, v12 bitop3:0x36
	v_bitop3_b32 v13, v13, s14, v14 bitop3:0xde
	v_bitop3_b32 v11, v18, v14, v11 bitop3:0x36
	v_or_b32_e32 v14, 0x800, v5
	v_or_b32_e32 v18, 0x1000, v5
	v_or_b32_e32 v19, 0x1800, v5
	s_addc_u32 s13, s5, s21
	v_lshl_add_u64 v[142:143], s[12:13], 0, v[6:7]
	v_lshl_add_u64 v[144:145], s[12:13], 0, v[8:9]
	s_mov_b32 s1, -2
	s_mov_b64 s[12:13], 0
	v_add_u32_e32 v171, v15, v10
	v_add_u32_e32 v156, v12, v5
	v_add_u32_e32 v155, v11, v14
	v_add_u32_e32 v154, v11, v18
	v_add_u32_e32 v153, v11, v19
	v_add_u32_e32 v168, v16, v10
	v_add_u32_e32 v161, v17, v10
	v_add_u32_e32 v158, v13, v10
	v_mov_b32_e32 v5, v4
	v_mov_b64_e32 v[6:7], v[4:5]
	v_mov_b64_e32 v[8:9], v[4:5]
	v_mov_b64_e32 v[10:11], v[4:5]
	v_mov_b64_e32 v[12:13], v[4:5]
	v_mov_b64_e32 v[14:15], v[4:5]
	v_mov_b64_e32 v[16:17], v[4:5]
	v_mov_b64_e32 v[18:19], v[4:5]
	v_mov_b64_e32 v[20:21], v[4:5]
	v_mov_b64_e32 v[22:23], v[4:5]
	v_mov_b64_e32 v[24:25], v[4:5]
	v_mov_b64_e32 v[26:27], v[4:5]
	v_mov_b64_e32 v[28:29], v[4:5]
	v_mov_b64_e32 v[30:31], v[4:5]
	v_mov_b64_e32 v[32:33], v[4:5]
	v_mov_b64_e32 v[34:35], v[4:5]
	v_mov_b64_e32 v[36:37], v[4:5]
	v_mov_b64_e32 v[38:39], v[4:5]
	v_mov_b64_e32 v[40:41], v[4:5]
	v_mov_b64_e32 v[42:43], v[4:5]
	v_mov_b64_e32 v[44:45], v[4:5]
	v_mov_b64_e32 v[46:47], v[4:5]
	v_mov_b64_e32 v[48:49], v[4:5]
	v_mov_b64_e32 v[50:51], v[4:5]
	v_mov_b64_e32 v[52:53], v[4:5]
	v_mov_b64_e32 v[54:55], v[4:5]
	v_mov_b64_e32 v[56:57], v[4:5]
	v_mov_b64_e32 v[58:59], v[4:5]
	v_mov_b64_e32 v[60:61], v[4:5]
	v_mov_b64_e32 v[62:63], v[4:5]
	v_mov_b64_e32 v[64:65], v[4:5]
	v_mov_b64_e32 v[66:67], v[4:5]
	v_mov_b64_e32 v[68:69], v[4:5]
	v_mov_b64_e32 v[70:71], v[4:5]
	v_mov_b64_e32 v[72:73], v[4:5]
	v_mov_b64_e32 v[74:75], v[4:5]
	v_mov_b64_e32 v[76:77], v[4:5]
	v_mov_b64_e32 v[78:79], v[4:5]
	v_mov_b64_e32 v[80:81], v[4:5]
	v_mov_b64_e32 v[82:83], v[4:5]
	v_mov_b64_e32 v[84:85], v[4:5]
	v_mov_b64_e32 v[86:87], v[4:5]
	v_mov_b64_e32 v[88:89], v[4:5]
	v_mov_b64_e32 v[90:91], v[4:5]
	v_mov_b64_e32 v[92:93], v[4:5]
	v_mov_b64_e32 v[94:95], v[4:5]
	v_mov_b64_e32 v[96:97], v[4:5]
	v_mov_b64_e32 v[98:99], v[4:5]
	v_mov_b64_e32 v[100:101], v[4:5]
	v_mov_b64_e32 v[102:103], v[4:5]
	v_mov_b64_e32 v[104:105], v[4:5]
	v_mov_b64_e32 v[106:107], v[4:5]
	v_mov_b64_e32 v[108:109], v[4:5]
	v_mov_b64_e32 v[110:111], v[4:5]
	v_mov_b64_e32 v[112:113], v[4:5]
	v_mov_b64_e32 v[114:115], v[4:5]
	v_mov_b64_e32 v[116:117], v[4:5]
	v_mov_b64_e32 v[118:119], v[4:5]
	v_mov_b64_e32 v[120:121], v[4:5]
	v_mov_b64_e32 v[122:123], v[4:5]
	v_mov_b64_e32 v[124:125], v[4:5]
	v_mov_b64_e32 v[126:127], v[4:5]
	v_mov_b64_e32 v[128:129], v[4:5]
	v_mov_b64_e32 v[130:131], v[4:5]
	s_mov_b64 s[20:21], 0xb840080
	s_mov_b64 s[40:41], 0xc7a0100
	s_mov_b64 s[42:43], 0xb800100
	s_mov_b64 s[44:45], 0xc7e0100
	s_mov_b64 s[46:47], 0xb840100
	s_mov_b64 s[48:49], 0xc7a0180
	s_mov_b64 s[50:51], 0xb800180
	s_mov_b64 s[52:53], 0xc7e0180
	s_barrier
; #define LDA8(dst, b, h) _Pragma("unroll") for (int m = 0; m < 4; ++m) _Pragma("unroll") for (int k = 0; k < 2; ++k) \
;     dst[m][k] = *(const bf16x8*)((const char*)SA8(b, h) + lds_byte8(wr * 64 + m * 16 + fr, k * 32 + fq * 8))
; #define LDB8(dst, b, h) _Pragma("unroll") for (int n = 0; n < 2; ++n) _Pragma("unroll") for (int k = 0; k < 2; ++k) \
;     dst[n][k] = *(const bf16x8*)((const char*)SB8(b, h) + lds_byte8(wc * 32 + n * 16 + fr, k * 32 + fq * 8))
; #define WAIT_V8(n) asm volatile("s_waitcnt vmcnt(" #n ")" ::: "memory")
; #define WAIT_L8(n) asm volatile("s_waitcnt lgkmcnt(" #n ")" ::: "memory")
; #define BAR8 __builtin_amdgcn_s_barrier()
; #define SCHED8 __builtin_amdgcn_sched_barrier(0)
;     ...
;   for (int tt = 0; tt < nt - 2; tt += 2) {
;     LDB8(B0, 0, 0); SCHED8; LDA8(At, 0, 0); STAGE8(SA8(1, 1), A, lda, brow + 128, tt + 1);
;     WAIT_L8(8); BAR8; WAIT_L8(0); MMA8(0, 0, At, B0); BAR8; SCHED8;
;     LDB8(B1, 0, 1); STAGE8(SB8(0, 0), Bt, K, bcol, tt + 2);
;     BAR8; WAIT_L8(0); MMA8(0, 1, At, B1); BAR8;
;     LDA8(At, 0, 1); STAGE8(SA8(0, 0), A, lda, brow, tt + 2);
;     BAR8; WAIT_L8(0); MMA8(1, 0, At, B0); BAR8; SCHED8;
;     STAGE8(SB8(0, 1), Bt, K, bcol + 128, tt + 2);
;     WAIT_V8(6); BAR8; MMA8(1, 1, At, B1); BAR8;
.LBB0_1005:
	ds_read_b128 v[174:177], v171
	ds_read_b128 v[178:181], v171 offset:1024
	ds_read_b128 v[182:185], v171 offset:2048
	ds_read_b128 v[186:189], v171 offset:3072
	v_lshl_add_u64 v[222:223], v[140:141], 0, s[12:13]
	v_lshl_add_u64 v[226:227], v[222:223], 0, s[20:21]
	s_or_b32 m0, s100, 0xc000
	v_lshl_add_u64 v[236:237], v[138:139], 0, s[12:13]
	ds_read_b128 v[190:193], v156
	ds_read_b128 v[194:197], v156 offset:1024
	ds_read_b128 v[198:201], v155
	ds_read_b128 v[202:205], v155 offset:1024
	ds_read_b128 v[206:209], v154
	ds_read_b128 v[210:213], v154 offset:1024
	ds_read_b128 v[214:217], v153
	ds_read_b128 v[218:221], v153 offset:1024
	global_load_lds_dwordx4 v[226:227], off
	v_lshl_add_u64 v[226:227], v[236:237], 0, s[20:21]
	s_or_b32 m0, s100, 0xe000
	s_nop 0
	global_load_lds_dwordx4 v[226:227], off
	s_waitcnt lgkmcnt(8)
	s_barrier
	s_waitcnt lgkmcnt(0)
	v_mfma_f32_16x16x32_bf16 v[128:131], v[190:193], v[174:177], v[128:131]
	v_mfma_f32_16x16x32_bf16 v[124:127], v[190:193], v[182:185], v[124:127]
	v_mfma_f32_16x16x32_bf16 v[120:123], v[198:201], v[174:177], v[120:123]
	v_mfma_f32_16x16x32_bf16 v[116:119], v[198:201], v[182:185], v[116:119]
	v_mfma_f32_16x16x32_bf16 v[112:115], v[206:209], v[174:177], v[112:115]
	v_mfma_f32_16x16x32_bf16 v[108:111], v[206:209], v[182:185], v[108:111]
	v_mfma_f32_16x16x32_bf16 v[104:107], v[214:217], v[174:177], v[104:107]
	v_mfma_f32_16x16x32_bf16 v[100:103], v[214:217], v[182:185], v[100:103]
	v_mfma_f32_16x16x32_bf16 v[128:131], v[194:197], v[178:181], v[128:131]
	v_mfma_f32_16x16x32_bf16 v[124:127], v[194:197], v[186:189], v[124:127]
	v_mfma_f32_16x16x32_bf16 v[120:123], v[202:205], v[178:181], v[120:123]
	v_mfma_f32_16x16x32_bf16 v[116:119], v[202:205], v[186:189], v[116:119]
	v_mfma_f32_16x16x32_bf16 v[112:115], v[210:213], v[178:181], v[112:115]
	v_mfma_f32_16x16x32_bf16 v[108:111], v[210:213], v[186:189], v[108:111]
	v_mfma_f32_16x16x32_bf16 v[104:107], v[218:221], v[178:181], v[104:107]
	v_mfma_f32_16x16x32_bf16 v[100:103], v[218:221], v[186:189], v[100:103]
	s_barrier
	v_lshl_add_u64 v[246:247], v[142:143], 0, s[12:13]
	v_lshl_add_u64 v[248:249], v[246:247], 0, s[40:41]
	s_or_b32 m0, s100, 0x10000
	ds_read_b128 v[226:229], v168
	ds_read_b128 v[230:233], v168 offset:1024
	ds_read_b128 v[238:241], v168 offset:2048
	ds_read_b128 v[242:245], v168 offset:3072
	global_load_lds_dwordx4 v[248:249], off
	v_lshl_add_u64 v[248:249], v[144:145], 0, s[12:13]
	v_lshl_add_u64 v[250:251], v[248:249], 0, s[40:41]
	s_or_b32 m0, s100, 0x12000
	s_nop 0
	global_load_lds_dwordx4 v[250:251], off
	s_barrier
	s_waitcnt lgkmcnt(0)
	v_mfma_f32_16x16x32_bf16 v[96:99], v[190:193], v[226:229], v[96:99]
	v_mfma_f32_16x16x32_bf16 v[92:95], v[190:193], v[238:241], v[92:95]
	v_mfma_f32_16x16x32_bf16 v[88:91], v[198:201], v[226:229], v[88:91]
	v_mfma_f32_16x16x32_bf16 v[84:87], v[198:201], v[238:241], v[84:87]
	v_mfma_f32_16x16x32_bf16 v[80:83], v[206:209], v[226:229], v[80:83]
	v_mfma_f32_16x16x32_bf16 v[76:79], v[206:209], v[238:241], v[76:79]
	v_mfma_f32_16x16x32_bf16 v[72:75], v[214:217], v[226:229], v[72:75]
	v_mfma_f32_16x16x32_bf16 v[68:71], v[214:217], v[238:241], v[68:71]
	v_mfma_f32_16x16x32_bf16 v[96:99], v[194:197], v[230:233], v[96:99]
	v_mfma_f32_16x16x32_bf16 v[92:95], v[194:197], v[242:245], v[92:95]
	v_mfma_f32_16x16x32_bf16 v[88:91], v[202:205], v[230:233], v[88:91]
	v_mfma_f32_16x16x32_bf16 v[84:87], v[202:205], v[242:245], v[84:87]
	v_mfma_f32_16x16x32_bf16 v[80:83], v[210:213], v[230:233], v[80:83]
	v_mfma_f32_16x16x32_bf16 v[76:79], v[210:213], v[242:245], v[76:79]
	v_mfma_f32_16x16x32_bf16 v[72:75], v[218:221], v[230:233], v[72:75]
	v_mfma_f32_16x16x32_bf16 v[68:71], v[218:221], v[242:245], v[68:71]
	v_lshl_add_u64 v[250:251], v[222:223], 0, s[42:43]
	s_mov_b32 m0, s100
	s_barrier
	ds_read_b128 v[190:193], v156 offset:16384
	ds_read_b128 v[194:197], v156 offset:17408
	ds_read_b128 v[198:201], v155 offset:16384
	ds_read_b128 v[202:205], v155 offset:17408
	ds_read_b128 v[206:209], v154 offset:16384
	ds_read_b128 v[210:213], v154 offset:17408
	ds_read_b128 v[214:217], v153 offset:16384
	ds_read_b128 v[218:221], v153 offset:17408
	global_load_lds_dwordx4 v[250:251], off
	v_lshl_add_u64 v[250:251], v[236:237], 0, s[42:43]
	s_or_b32 m0, s100, 0x2000
	s_nop 0
	global_load_lds_dwordx4 v[250:251], off
	s_barrier
	s_waitcnt lgkmcnt(0)
	v_mfma_f32_16x16x32_bf16 v[64:67], v[190:193], v[174:177], v[64:67]
	v_mfma_f32_16x16x32_bf16 v[60:63], v[190:193], v[182:185], v[60:63]
	v_mfma_f32_16x16x32_bf16 v[56:59], v[198:201], v[174:177], v[56:59]
	v_mfma_f32_16x16x32_bf16 v[52:55], v[198:201], v[182:185], v[52:55]
	v_mfma_f32_16x16x32_bf16 v[48:51], v[206:209], v[174:177], v[48:51]
	v_mfma_f32_16x16x32_bf16 v[44:47], v[206:209], v[182:185], v[44:47]
	v_mfma_f32_16x16x32_bf16 v[40:43], v[214:217], v[174:177], v[40:43]
	v_mfma_f32_16x16x32_bf16 v[36:39], v[214:217], v[182:185], v[36:39]
	v_mfma_f32_16x16x32_bf16 v[64:67], v[194:197], v[178:181], v[64:67]
	v_mfma_f32_16x16x32_bf16 v[60:63], v[194:197], v[186:189], v[60:63]
	v_mfma_f32_16x16x32_bf16 v[56:59], v[202:205], v[178:181], v[56:59]
	v_mfma_f32_16x16x32_bf16 v[52:55], v[202:205], v[186:189], v[52:55]
	v_mfma_f32_16x16x32_bf16 v[48:51], v[210:213], v[178:181], v[48:51]
	v_mfma_f32_16x16x32_bf16 v[44:47], v[210:213], v[186:189], v[44:47]
	v_mfma_f32_16x16x32_bf16 v[40:43], v[218:221], v[178:181], v[40:43]
	v_mfma_f32_16x16x32_bf16 v[36:39], v[218:221], v[186:189], v[36:39]
	s_barrier
	v_lshl_add_u64 v[174:175], v[246:247], 0, s[44:45]
	s_or_b32 m0, s100, 0x14000
	s_nop 0
	global_load_lds_dwordx4 v[174:175], off
	v_lshl_add_u64 v[174:175], v[248:249], 0, s[44:45]
	s_or_b32 m0, s100, 0x16000
	s_nop 0
	global_load_lds_dwordx4 v[174:175], off
	s_waitcnt vmcnt(6)
	s_barrier
; #define LDA8(dst, b, h) _Pragma("unroll") for (int m = 0; m < 4; ++m) _Pragma("unroll") for (int k = 0; k < 2; ++k) \
;     dst[m][k] = *(const bf16x8*)((const char*)SA8(b, h) + lds_byte8(wr * 64 + m * 16 + fr, k * 32 + fq * 8))
; #define LDB8(dst, b, h) _Pragma("unroll") for (int n = 0; n < 2; ++n) _Pragma("unroll") for (int k = 0; k < 2; ++k) \
;     dst[n][k] = *(const bf16x8*)((const char*)SB8(b, h) + lds_byte8(wc * 32 + n * 16 + fr, k * 32 + fq * 8))
; #define WAIT_V8(n) asm volatile("s_waitcnt vmcnt(" #n ")" ::: "memory")
; #define WAIT_L8(n) asm volatile("s_waitcnt lgkmcnt(" #n ")" ::: "memory")
; #define BAR8 __builtin_amdgcn_s_barrier()
; #define SCHED8 __builtin_amdgcn_sched_barrier(0)
;     ...
;     WAIT_V8(6); BAR8; MMA8(1, 1, At, B1); BAR8;
;     LDB8(B0, 1, 0); SCHED8; LDA8(At, 1, 0); STAGE8(SA8(0, 1), A, lda, brow + 128, tt + 2);
;     WAIT_L8(8); BAR8; WAIT_L8(0); MMA8(0, 0, At, B0); BAR8; SCHED8;
;     LDB8(B1, 1, 1); STAGE8(SB8(1, 0), Bt, K, bcol, tt + 3);
;     BAR8; WAIT_L8(0); MMA8(0, 1, At, B1); BAR8;
;     LDA8(At, 1, 1); STAGE8(SA8(1, 0), A, lda, brow, tt + 3);
;     BAR8; WAIT_L8(0); MMA8(1, 0, At, B0); BAR8; SCHED8;
	v_mfma_f32_16x16x32_bf16 v[32:35], v[190:193], v[226:229], v[32:35]
	v_mfma_f32_16x16x32_bf16 v[28:31], v[190:193], v[238:241], v[28:31]
	v_mfma_f32_16x16x32_bf16 v[24:27], v[198:201], v[226:229], v[24:27]
	v_mfma_f32_16x16x32_bf16 v[20:23], v[198:201], v[238:241], v[20:23]
	v_mfma_f32_16x16x32_bf16 v[16:19], v[206:209], v[226:229], v[16:19]
	v_mfma_f32_16x16x32_bf16 v[12:15], v[206:209], v[238:241], v[12:15]
	v_mfma_f32_16x16x32_bf16 v[8:11], v[214:217], v[226:229], v[8:11]
	v_mfma_f32_16x16x32_bf16 v[4:7], v[214:217], v[238:241], v[4:7]
	v_mfma_f32_16x16x32_bf16 v[32:35], v[194:197], v[230:233], v[32:35]
	v_mfma_f32_16x16x32_bf16 v[28:31], v[194:197], v[242:245], v[28:31]
	v_mfma_f32_16x16x32_bf16 v[24:27], v[202:205], v[230:233], v[24:27]
	v_mfma_f32_16x16x32_bf16 v[20:23], v[202:205], v[242:245], v[20:23]
	v_mfma_f32_16x16x32_bf16 v[16:19], v[210:213], v[230:233], v[16:19]
	v_mfma_f32_16x16x32_bf16 v[12:15], v[210:213], v[242:245], v[12:15]
	v_mfma_f32_16x16x32_bf16 v[8:11], v[218:221], v[230:233], v[8:11]
	v_mfma_f32_16x16x32_bf16 v[4:7], v[218:221], v[242:245], v[4:7]
	s_barrier
	ds_read_b128 v[174:177], v161
	ds_read_b128 v[178:181], v161 offset:1024
	ds_read_b128 v[182:185], v161 offset:2048
	ds_read_b128 v[186:189], v161 offset:3072
	v_lshl_add_u64 v[226:227], v[222:223], 0, s[46:47]
	s_or_b32 m0, s100, 0x4000
	ds_read_b128 v[190:193], v156 offset:32768
	ds_read_b128 v[194:197], v156 offset:33792
	ds_read_b128 v[198:201], v155 offset:32768
	ds_read_b128 v[202:205], v155 offset:33792
	ds_read_b128 v[206:209], v154 offset:32768
	ds_read_b128 v[210:213], v154 offset:33792
	ds_read_b128 v[214:217], v153 offset:32768
	ds_read_b128 v[218:221], v153 offset:33792
	global_load_lds_dwordx4 v[226:227], off
	v_lshl_add_u64 v[226:227], v[236:237], 0, s[46:47]
	s_or_b32 m0, s100, 0x6000
	s_nop 0
	global_load_lds_dwordx4 v[226:227], off
	s_waitcnt lgkmcnt(8)
	s_barrier
	s_waitcnt lgkmcnt(0)
	v_mfma_f32_16x16x32_bf16 v[128:131], v[190:193], v[174:177], v[128:131]
	v_mfma_f32_16x16x32_bf16 v[124:127], v[190:193], v[182:185], v[124:127]
	v_mfma_f32_16x16x32_bf16 v[120:123], v[198:201], v[174:177], v[120:123]
	v_mfma_f32_16x16x32_bf16 v[116:119], v[198:201], v[182:185], v[116:119]
	v_mfma_f32_16x16x32_bf16 v[112:115], v[206:209], v[174:177], v[112:115]
	v_mfma_f32_16x16x32_bf16 v[108:111], v[206:209], v[182:185], v[108:111]
	v_mfma_f32_16x16x32_bf16 v[104:107], v[214:217], v[174:177], v[104:107]
	v_mfma_f32_16x16x32_bf16 v[100:103], v[214:217], v[182:185], v[100:103]
	v_mfma_f32_16x16x32_bf16 v[128:131], v[194:197], v[178:181], v[128:131]
	v_mfma_f32_16x16x32_bf16 v[124:127], v[194:197], v[186:189], v[124:127]
	v_mfma_f32_16x16x32_bf16 v[120:123], v[202:205], v[178:181], v[120:123]
	v_mfma_f32_16x16x32_bf16 v[116:119], v[202:205], v[186:189], v[116:119]
	v_mfma_f32_16x16x32_bf16 v[112:115], v[210:213], v[178:181], v[112:115]
	v_mfma_f32_16x16x32_bf16 v[108:111], v[210:213], v[186:189], v[108:111]
	v_mfma_f32_16x16x32_bf16 v[104:107], v[218:221], v[178:181], v[104:107]
	v_mfma_f32_16x16x32_bf16 v[100:103], v[218:221], v[186:189], v[100:103]
	s_barrier
	v_lshl_add_u64 v[250:251], v[246:247], 0, s[48:49]
	s_or_b32 m0, s100, 0x18000
	ds_read_b128 v[226:229], v158
	ds_read_b128 v[230:233], v158 offset:1024
	ds_read_b128 v[238:241], v158 offset:2048
	ds_read_b128 v[242:245], v158 offset:3072
	global_load_lds_dwordx4 v[250:251], off
	v_lshl_add_u64 v[250:251], v[248:249], 0, s[48:49]
	s_or_b32 m0, s100, 0x1a000
	s_nop 0
	global_load_lds_dwordx4 v[250:251], off
	s_barrier
	s_waitcnt lgkmcnt(0)
	v_mfma_f32_16x16x32_bf16 v[96:99], v[190:193], v[226:229], v[96:99]
	v_mfma_f32_16x16x32_bf16 v[92:95], v[190:193], v[238:241], v[92:95]
	v_mfma_f32_16x16x32_bf16 v[88:91], v[198:201], v[226:229], v[88:91]
	v_mfma_f32_16x16x32_bf16 v[84:87], v[198:201], v[238:241], v[84:87]
	v_mfma_f32_16x16x32_bf16 v[80:83], v[206:209], v[226:229], v[80:83]
	v_mfma_f32_16x16x32_bf16 v[76:79], v[206:209], v[238:241], v[76:79]
	v_mfma_f32_16x16x32_bf16 v[72:75], v[214:217], v[226:229], v[72:75]
	v_mfma_f32_16x16x32_bf16 v[68:71], v[214:217], v[238:241], v[68:71]
	v_mfma_f32_16x16x32_bf16 v[96:99], v[194:197], v[230:233], v[96:99]
	v_mfma_f32_16x16x32_bf16 v[92:95], v[194:197], v[242:245], v[92:95]
	v_mfma_f32_16x16x32_bf16 v[88:91], v[202:205], v[230:233], v[88:91]
	v_mfma_f32_16x16x32_bf16 v[84:87], v[202:205], v[242:245], v[84:87]
	v_mfma_f32_16x16x32_bf16 v[80:83], v[210:213], v[230:233], v[80:83]
	v_mfma_f32_16x16x32_bf16 v[76:79], v[210:213], v[242:245], v[76:79]
	v_mfma_f32_16x16x32_bf16 v[72:75], v[218:221], v[230:233], v[72:75]
	v_mfma_f32_16x16x32_bf16 v[68:71], v[218:221], v[242:245], v[68:71]
	v_lshl_add_u64 v[222:223], v[222:223], 0, s[50:51]
	s_or_b32 m0, s100, 0x8000
	s_barrier
	ds_read_b128 v[190:193], v156 offset:49152
	ds_read_b128 v[194:197], v156 offset:50176
	ds_read_b128 v[198:201], v155 offset:49152
	ds_read_b128 v[202:205], v155 offset:50176
	ds_read_b128 v[206:209], v154 offset:49152
	ds_read_b128 v[210:213], v154 offset:50176
	ds_read_b128 v[214:217], v153 offset:49152
	ds_read_b128 v[218:221], v153 offset:50176
	global_load_lds_dwordx4 v[222:223], off
	v_lshl_add_u64 v[222:223], v[236:237], 0, s[50:51]
	s_or_b32 m0, s100, 0xa000
	s_nop 0
	global_load_lds_dwordx4 v[222:223], off
	s_barrier
; #define LDA8(dst, b, h) _Pragma("unroll") for (int m = 0; m < 4; ++m) _Pragma("unroll") for (int k = 0; k < 2; ++k) \
;     dst[m][k] = *(const bf16x8*)((const char*)SA8(b, h) + lds_byte8(wr * 64 + m * 16 + fr, k * 32 + fq * 8))
; #define LDB8(dst, b, h) _Pragma("unroll") for (int n = 0; n < 2; ++n) _Pragma("unroll") for (int k = 0; k < 2; ++k) \
;     dst[n][k] = *(const bf16x8*)((const char*)SB8(b, h) + lds_byte8(wc * 32 + n * 16 + fr, k * 32 + fq * 8))
; #define WAIT_V8(n) asm volatile("s_waitcnt vmcnt(" #n ")" ::: "memory")
; #define WAIT_L8(n) asm volatile("s_waitcnt lgkmcnt(" #n ")" ::: "memory")
; #define BAR8 __builtin_amdgcn_s_barrier()
; #define SCHED8 __builtin_amdgcn_sched_barrier(0)
;     ...
;     BAR8; WAIT_L8(0); MMA8(1, 0, At, B0); BAR8; SCHED8;
;     STAGE8(SB8(1, 1), Bt, K, bcol + 128, tt + 3);
;     WAIT_V8(6); BAR8; MMA8(1, 1, At, B1); BAR8;
;   }
;   { LDB8(B0, 0, 0); LDA8(At, 0, 0); STAGE8(SA8(1, 1), A, lda, brow + 128, nt - 1);
;     BAR8; WAIT_L8(0); MMA8(0, 0, At, B0); BAR8;
;     LDB8(B1, 0, 1); BAR8; WAIT_L8(0); MMA8(0, 1, At, B1); BAR8;
;     LDA8(At, 0, 1); WAIT_V8(4); BAR8; WAIT_L8(0); MMA8(1, 0, At, B0); MMA8(1, 1, At, B1); BAR8; }
	s_waitcnt lgkmcnt(0)
	v_mfma_f32_16x16x32_bf16 v[64:67], v[190:193], v[174:177], v[64:67]
	v_mfma_f32_16x16x32_bf16 v[60:63], v[190:193], v[182:185], v[60:63]
	v_mfma_f32_16x16x32_bf16 v[56:59], v[198:201], v[174:177], v[56:59]
	v_mfma_f32_16x16x32_bf16 v[52:55], v[198:201], v[182:185], v[52:55]
	v_mfma_f32_16x16x32_bf16 v[48:51], v[206:209], v[174:177], v[48:51]
	v_mfma_f32_16x16x32_bf16 v[44:47], v[206:209], v[182:185], v[44:47]
	v_mfma_f32_16x16x32_bf16 v[40:43], v[214:217], v[174:177], v[40:43]
	v_mfma_f32_16x16x32_bf16 v[36:39], v[214:217], v[182:185], v[36:39]
	v_mfma_f32_16x16x32_bf16 v[64:67], v[194:197], v[178:181], v[64:67]
	v_mfma_f32_16x16x32_bf16 v[60:63], v[194:197], v[186:189], v[60:63]
	v_mfma_f32_16x16x32_bf16 v[56:59], v[202:205], v[178:181], v[56:59]
	v_mfma_f32_16x16x32_bf16 v[52:55], v[202:205], v[186:189], v[52:55]
	v_mfma_f32_16x16x32_bf16 v[48:51], v[210:213], v[178:181], v[48:51]
	v_mfma_f32_16x16x32_bf16 v[44:47], v[210:213], v[186:189], v[44:47]
	v_mfma_f32_16x16x32_bf16 v[40:43], v[218:221], v[178:181], v[40:43]
	v_mfma_f32_16x16x32_bf16 v[36:39], v[218:221], v[186:189], v[36:39]
	s_barrier
	v_lshl_add_u64 v[174:175], v[246:247], 0, s[52:53]
	s_or_b32 m0, s100, 0x1c000
	s_nop 0
	global_load_lds_dwordx4 v[174:175], off
	v_lshl_add_u64 v[174:175], v[248:249], 0, s[52:53]
	s_or_b32 m0, s100, 0x1e000
	s_nop 0
	global_load_lds_dwordx4 v[174:175], off
	s_waitcnt vmcnt(6)
	s_barrier
	v_mfma_f32_16x16x32_bf16 v[32:35], v[190:193], v[226:229], v[32:35]
	v_mfma_f32_16x16x32_bf16 v[28:31], v[190:193], v[238:241], v[28:31]
	v_mfma_f32_16x16x32_bf16 v[24:27], v[198:201], v[226:229], v[24:27]
	v_mfma_f32_16x16x32_bf16 v[20:23], v[198:201], v[238:241], v[20:23]
	v_mfma_f32_16x16x32_bf16 v[16:19], v[206:209], v[226:229], v[16:19]
	v_mfma_f32_16x16x32_bf16 v[12:15], v[206:209], v[238:241], v[12:15]
	v_mfma_f32_16x16x32_bf16 v[8:11], v[214:217], v[226:229], v[8:11]
	v_mfma_f32_16x16x32_bf16 v[4:7], v[214:217], v[238:241], v[4:7]
	v_mfma_f32_16x16x32_bf16 v[32:35], v[194:197], v[230:233], v[32:35]
	v_mfma_f32_16x16x32_bf16 v[28:31], v[194:197], v[242:245], v[28:31]
	v_mfma_f32_16x16x32_bf16 v[24:27], v[202:205], v[230:233], v[24:27]
	v_mfma_f32_16x16x32_bf16 v[20:23], v[202:205], v[242:245], v[20:23]
	v_mfma_f32_16x16x32_bf16 v[16:19], v[210:213], v[230:233], v[16:19]
	v_mfma_f32_16x16x32_bf16 v[12:15], v[210:213], v[242:245], v[12:15]
	v_mfma_f32_16x16x32_bf16 v[8:11], v[218:221], v[230:233], v[8:11]
	v_mfma_f32_16x16x32_bf16 v[4:7], v[218:221], v[242:245], v[4:7]
	s_add_i32 s1, s1, 2
	s_add_u32 s12, s12, 0x100
	s_addc_u32 s13, s13, 0
	s_cmp_lt_u32 s1, 12
	s_barrier
	s_cbranch_scc1 .LBB0_1005
	s_add_u32 s8, s8, 0x40780
	s_addc_u32 s9, s9, 0
	v_lshl_add_u64 v[132:133], s[8:9], 0, v[132:133]
	v_lshl_add_u64 v[0:1], v[0:1], 1, v[132:133]
	s_or_b32 m0, s100, 0xc000
	ds_read_b128 v[138:141], v171
	ds_read_b128 v[142:145], v171 offset:1024
	ds_read_b128 v[162:165], v171 offset:2048
	ds_read_b128 v[174:177], v171 offset:3072
	ds_read_b128 v[178:181], v156
	ds_read_b128 v[182:185], v156 offset:1024
	ds_read_b128 v[186:189], v155
	ds_read_b128 v[190:193], v155 offset:1024
	ds_read_b128 v[194:197], v154
	ds_read_b128 v[198:201], v154 offset:1024
	ds_read_b128 v[202:205], v153
	ds_read_b128 v[206:209], v153 offset:1024
	global_load_lds_dwordx4 v[0:1], off
	v_lshl_add_u64 v[0:1], s[8:9], 0, v[136:137]
	v_lshl_add_u64 v[0:1], v[134:135], 1, v[0:1]
	s_or_b32 m0, s100, 0xe000
	s_nop 0
	global_load_lds_dwordx4 v[0:1], off
	s_barrier
	s_waitcnt lgkmcnt(0)
	v_mfma_f32_16x16x32_bf16 v[128:131], v[178:181], v[138:141], v[128:131]
	v_mfma_f32_16x16x32_bf16 v[124:127], v[178:181], v[162:165], v[124:127]
	v_mfma_f32_16x16x32_bf16 v[120:123], v[186:189], v[138:141], v[120:123]
	v_mfma_f32_16x16x32_bf16 v[112:115], v[194:197], v[138:141], v[112:115]
	v_mfma_f32_16x16x32_bf16 v[128:131], v[182:185], v[142:145], v[128:131]
	v_mfma_f32_16x16x32_bf16 v[124:127], v[182:185], v[174:177], v[124:127]
	v_mfma_f32_16x16x32_bf16 v[120:123], v[190:193], v[142:145], v[120:123]
	v_mfma_f32_16x16x32_bf16 v[116:119], v[186:189], v[162:165], v[116:119]
	v_mfma_f32_16x16x32_bf16 v[112:115], v[198:201], v[142:145], v[112:115]
	v_mfma_f32_16x16x32_bf16 v[108:111], v[194:197], v[162:165], v[108:111]
	v_mfma_f32_16x16x32_bf16 v[104:107], v[202:205], v[138:141], v[104:107]
	v_mfma_f32_16x16x32_bf16 v[100:103], v[202:205], v[162:165], v[100:103]
	v_mfma_f32_16x16x32_bf16 v[132:135], v[190:193], v[174:177], v[116:119]
	v_mfma_f32_16x16x32_bf16 v[170:173], v[198:201], v[174:177], v[108:111]
	v_mfma_f32_16x16x32_bf16 v[210:213], v[206:209], v[142:145], v[104:107]
	v_mfma_f32_16x16x32_bf16 v[214:217], v[206:209], v[174:177], v[100:103]
	s_barrier
	s_nop 1
	ds_read_b128 v[100:103], v168
	ds_read_b128 v[104:107], v168 offset:1024
	ds_read_b128 v[108:111], v168 offset:2048
	ds_read_b128 v[116:119], v168 offset:3072
	s_barrier
	s_waitcnt lgkmcnt(0)
	v_mfma_f32_16x16x32_bf16 v[80:83], v[194:197], v[100:103], v[80:83]
	v_mfma_f32_16x16x32_bf16 v[76:79], v[194:197], v[108:111], v[76:79]
	v_mfma_f32_16x16x32_bf16 v[72:75], v[202:205], v[100:103], v[72:75]
	v_mfma_f32_16x16x32_bf16 v[68:71], v[202:205], v[108:111], v[68:71]
	v_mfma_f32_16x16x32_bf16 v[96:99], v[178:181], v[100:103], v[96:99]
	v_mfma_f32_16x16x32_bf16 v[92:95], v[178:181], v[108:111], v[92:95]
	v_mfma_f32_16x16x32_bf16 v[88:91], v[186:189], v[100:103], v[88:91]
	v_mfma_f32_16x16x32_bf16 v[84:87], v[186:189], v[108:111], v[84:87]
	v_mfma_f32_16x16x32_bf16 v[80:83], v[198:201], v[104:107], v[80:83]
	v_mfma_f32_16x16x32_bf16 v[76:79], v[198:201], v[116:119], v[76:79]
	v_mfma_f32_16x16x32_bf16 v[72:75], v[206:209], v[104:107], v[72:75]
	v_mfma_f32_16x16x32_bf16 v[68:71], v[206:209], v[116:119], v[68:71]
	v_mfma_f32_16x16x32_bf16 v[166:169], v[182:185], v[104:107], v[96:99]
	v_mfma_f32_16x16x32_bf16 v[178:181], v[182:185], v[116:119], v[92:95]
	v_mfma_f32_16x16x32_bf16 v[182:185], v[190:193], v[104:107], v[88:91]
	v_mfma_f32_16x16x32_bf16 v[186:189], v[190:193], v[116:119], v[84:87]
	s_barrier
; #define LDA8(dst, b, h) _Pragma("unroll") for (int m = 0; m < 4; ++m) _Pragma("unroll") for (int k = 0; k < 2; ++k) \
;     dst[m][k] = *(const bf16x8*)((const char*)SA8(b, h) + lds_byte8(wr * 64 + m * 16 + fr, k * 32 + fq * 8))
; #define LDB8(dst, b, h) _Pragma("unroll") for (int n = 0; n < 2; ++n) _Pragma("unroll") for (int k = 0; k < 2; ++k) \
;     dst[n][k] = *(const bf16x8*)((const char*)SB8(b, h) + lds_byte8(wc * 32 + n * 16 + fr, k * 32 + fq * 8))
; #define WAIT_V8(n) asm volatile("s_waitcnt vmcnt(" #n ")" ::: "memory")
; #define WAIT_L8(n) asm volatile("s_waitcnt lgkmcnt(" #n ")" ::: "memory")
; #define BAR8 __builtin_amdgcn_s_barrier()
;     ...
;     LDA8(At, 0, 1); WAIT_V8(4); BAR8; WAIT_L8(0); MMA8(1, 0, At, B0); MMA8(1, 1, At, B1); BAR8; }
;   { LDB8(B0, 1, 0); LDA8(At, 1, 0); WAIT_V8(2); BAR8; WAIT_L8(0); MMA8(0, 0, At, B0); BAR8;
	s_nop 0
	ds_read_b128 v[84:87], v156 offset:16384
	ds_read_b128 v[88:91], v156 offset:17408
	ds_read_b128 v[92:95], v155 offset:16384
	ds_read_b128 v[96:99], v155 offset:17408
	ds_read_b128 v[190:193], v154 offset:16384
	ds_read_b128 v[194:197], v154 offset:17408
	ds_read_b128 v[198:201], v153 offset:16384
	ds_read_b128 v[202:205], v153 offset:17408
	s_waitcnt vmcnt(4)
	s_barrier
	s_waitcnt lgkmcnt(0)
	v_mfma_f32_16x16x32_bf16 v[64:67], v[84:87], v[138:141], v[64:67]
	v_mfma_f32_16x16x32_bf16 v[60:63], v[84:87], v[162:165], v[60:63]
	v_mfma_f32_16x16x32_bf16 v[56:59], v[92:95], v[138:141], v[56:59]
	v_mfma_f32_16x16x32_bf16 v[52:55], v[92:95], v[162:165], v[52:55]
	v_mfma_f32_16x16x32_bf16 v[48:51], v[190:193], v[138:141], v[48:51]
	v_mfma_f32_16x16x32_bf16 v[44:47], v[190:193], v[162:165], v[44:47]
	v_mfma_f32_16x16x32_bf16 v[40:43], v[198:201], v[138:141], v[40:43]
	v_mfma_f32_16x16x32_bf16 v[36:39], v[198:201], v[162:165], v[36:39]
	v_mfma_f32_16x16x32_bf16 v[64:67], v[88:91], v[142:145], v[64:67]
	v_mfma_f32_16x16x32_bf16 v[60:63], v[88:91], v[174:177], v[60:63]
	v_mfma_f32_16x16x32_bf16 v[56:59], v[96:99], v[142:145], v[56:59]
	v_mfma_f32_16x16x32_bf16 v[52:55], v[96:99], v[174:177], v[52:55]
	v_mfma_f32_16x16x32_bf16 v[48:51], v[194:197], v[142:145], v[48:51]
	v_mfma_f32_16x16x32_bf16 v[44:47], v[194:197], v[174:177], v[44:47]
	v_mfma_f32_16x16x32_bf16 v[40:43], v[202:205], v[142:145], v[40:43]
	v_mfma_f32_16x16x32_bf16 v[36:39], v[202:205], v[174:177], v[36:39]
	v_mfma_f32_16x16x32_bf16 v[32:35], v[84:87], v[100:103], v[32:35]
	v_mfma_f32_16x16x32_bf16 v[28:31], v[84:87], v[108:111], v[28:31]
	v_mfma_f32_16x16x32_bf16 v[24:27], v[92:95], v[100:103], v[24:27]
	v_mfma_f32_16x16x32_bf16 v[20:23], v[92:95], v[108:111], v[20:23]
	v_mfma_f32_16x16x32_bf16 v[16:19], v[190:193], v[100:103], v[16:19]
	v_mfma_f32_16x16x32_bf16 v[12:15], v[190:193], v[108:111], v[12:15]
	v_mfma_f32_16x16x32_bf16 v[8:11], v[198:201], v[100:103], v[8:11]
	v_mfma_f32_16x16x32_bf16 v[4:7], v[198:201], v[108:111], v[4:7]
	v_mfma_f32_16x16x32_bf16 v[136:139], v[88:91], v[104:107], v[32:35]
	v_mfma_f32_16x16x32_bf16 v[140:143], v[88:91], v[116:119], v[28:31]
	v_mfma_f32_16x16x32_bf16 v[162:165], v[96:99], v[104:107], v[24:27]
	v_mfma_f32_16x16x32_bf16 v[174:177], v[96:99], v[116:119], v[20:23]
	v_mfma_f32_16x16x32_bf16 v[206:209], v[194:197], v[104:107], v[16:19]
	v_mfma_f32_16x16x32_bf16 v[190:193], v[194:197], v[116:119], v[12:15]
	v_mfma_f32_16x16x32_bf16 v[194:197], v[202:205], v[104:107], v[8:11]
	v_mfma_f32_16x16x32_bf16 v[198:201], v[202:205], v[116:119], v[4:7]
	s_barrier
	ds_read_b128 v[202:205], v161
	ds_read_b128 v[218:221], v161 offset:1024
	ds_read_b128 v[226:229], v161 offset:2048
	ds_read_b128 v[230:233], v161 offset:3072
	ds_read_b128 v[8:11], v156 offset:32768
	ds_read_b128 v[12:15], v156 offset:33792
	ds_read_b128 v[16:19], v155 offset:32768
	ds_read_b128 v[24:27], v155 offset:33792
	ds_read_b128 v[28:31], v154 offset:32768
	ds_read_b128 v[32:35], v154 offset:33792
	ds_read_b128 v[238:241], v153 offset:32768
	ds_read_b128 v[242:245], v153 offset:33792
	s_waitcnt vmcnt(2)
	s_barrier
	s_waitcnt lgkmcnt(0)
	v_mfma_f32_16x16x32_bf16 v[4:7], v[8:11], v[202:205], v[128:131]
	v_mfma_f32_16x16x32_bf16 v[104:107], v[12:15], v[218:221], v[4:7]
	v_mfma_f32_16x16x32_bf16 v[4:7], v[8:11], v[226:229], v[124:127]
	v_mfma_f32_16x16x32_bf16 v[116:119], v[12:15], v[230:233], v[4:7]
	v_mfma_f32_16x16x32_bf16 v[4:7], v[16:19], v[202:205], v[120:123]
	v_mfma_f32_16x16x32_bf16 v[100:103], v[24:27], v[218:221], v[4:7]
	v_mfma_f32_16x16x32_bf16 v[4:7], v[16:19], v[226:229], v[132:135]
	v_mfma_f32_16x16x32_bf16 v[108:111], v[24:27], v[230:233], v[4:7]
	v_mfma_f32_16x16x32_bf16 v[4:7], v[28:31], v[202:205], v[112:115]
	v_mfma_f32_16x16x32_bf16 v[92:95], v[32:35], v[218:221], v[4:7]
	v_mfma_f32_16x16x32_bf16 v[4:7], v[28:31], v[226:229], v[170:173]
	v_mfma_f32_16x16x32_bf16 v[96:99], v[32:35], v[230:233], v[4:7]
	v_mfma_f32_16x16x32_bf16 v[4:7], v[238:241], v[202:205], v[210:213]
	v_mfma_f32_16x16x32_bf16 v[84:87], v[242:245], v[218:221], v[4:7]
	v_mfma_f32_16x16x32_bf16 v[4:7], v[238:241], v[226:229], v[214:217]
	v_mfma_f32_16x16x32_bf16 v[88:91], v[242:245], v[230:233], v[4:7]
	s_barrier
; #define LDA8(dst, b, h) _Pragma("unroll") for (int m = 0; m < 4; ++m) _Pragma("unroll") for (int k = 0; k < 2; ++k) \
;     dst[m][k] = *(const bf16x8*)((const char*)SA8(b, h) + lds_byte8(wr * 64 + m * 16 + fr, k * 32 + fq * 8))
; #define LDB8(dst, b, h) _Pragma("unroll") for (int n = 0; n < 2; ++n) _Pragma("unroll") for (int k = 0; k < 2; ++k) \
;     dst[n][k] = *(const bf16x8*)((const char*)SB8(b, h) + lds_byte8(wc * 32 + n * 16 + fr, k * 32 + fq * 8))
; #define WAIT_V8(n) asm volatile("s_waitcnt vmcnt(" #n ")" ::: "memory")
; #define WAIT_L8(n) asm volatile("s_waitcnt lgkmcnt(" #n ")" ::: "memory")
; #define BAR8 __builtin_amdgcn_s_barrier()
;     ...
;   { LDB8(B0, 1, 0); LDA8(At, 1, 0); WAIT_V8(2); BAR8; WAIT_L8(0); MMA8(0, 0, At, B0); BAR8;
;     LDB8(B1, 1, 1); WAIT_V8(0); BAR8; WAIT_L8(0); MMA8(0, 1, At, B1); BAR8;
;     LDA8(At, 1, 1); BAR8; WAIT_L8(0); MMA8(1, 0, At, B0); MMA8(1, 1, At, B1); BAR8; }
;   if (wr == 0) BAR8;
;   __syncthreads();
;     ...
;   if (t < 256) {
	ds_read_b128 v[132:135], v158
	ds_read_b128 v[170:173], v158 offset:1024
	ds_read_b128 v[210:213], v158 offset:2048
	ds_read_b128 v[158:161], v158 offset:3072
	s_waitcnt vmcnt(0)
	s_barrier
	s_waitcnt lgkmcnt(0)
	v_mfma_f32_16x16x32_bf16 v[4:7], v[8:11], v[132:135], v[166:169]
	v_mfma_f32_16x16x32_bf16 v[8:11], v[8:11], v[210:213], v[178:181]
	v_mfma_f32_16x16x32_bf16 v[4:7], v[12:15], v[170:173], v[4:7]
	v_mfma_f32_16x16x32_bf16 v[20:23], v[12:15], v[158:161], v[8:11]
	v_mfma_f32_16x16x32_bf16 v[8:11], v[16:19], v[132:135], v[182:185]
	v_mfma_f32_16x16x32_bf16 v[12:15], v[16:19], v[210:213], v[186:189]
	v_mfma_f32_16x16x32_bf16 v[8:11], v[24:27], v[170:173], v[8:11]
	v_mfma_f32_16x16x32_bf16 v[24:27], v[24:27], v[158:161], v[12:15]
	v_mfma_f32_16x16x32_bf16 v[12:15], v[28:31], v[132:135], v[80:83]
	v_mfma_f32_16x16x32_bf16 v[16:19], v[28:31], v[210:213], v[76:79]
	v_mfma_f32_16x16x32_bf16 v[12:15], v[32:35], v[170:173], v[12:15]
	v_mfma_f32_16x16x32_bf16 v[28:31], v[32:35], v[158:161], v[16:19]
	v_mfma_f32_16x16x32_bf16 v[16:19], v[238:241], v[132:135], v[72:75]
	v_mfma_f32_16x16x32_bf16 v[32:35], v[238:241], v[210:213], v[68:71]
	v_mfma_f32_16x16x32_bf16 v[16:19], v[242:245], v[170:173], v[16:19]
	v_mfma_f32_16x16x32_bf16 v[32:35], v[242:245], v[158:161], v[32:35]
	s_barrier
	ds_read_b128 v[166:169], v156 offset:49152
	ds_read_b128 v[178:181], v156 offset:50176
	ds_read_b128 v[182:185], v155 offset:49152
	ds_read_b128 v[186:189], v155 offset:50176
	ds_read_b128 v[214:217], v154 offset:49152
	ds_read_b128 v[154:157], v154 offset:50176
	ds_read_b128 v[238:241], v153 offset:49152
	ds_read_b128 v[150:153], v153 offset:50176
	s_barrier
	s_waitcnt lgkmcnt(0)
	v_mfma_f32_16x16x32_bf16 v[64:67], v[166:169], v[202:205], v[64:67]
	v_mfma_f32_16x16x32_bf16 v[60:63], v[166:169], v[226:229], v[60:63]
	v_mfma_f32_16x16x32_bf16 v[56:59], v[182:185], v[202:205], v[56:59]
	v_mfma_f32_16x16x32_bf16 v[52:55], v[182:185], v[226:229], v[52:55]
	v_mfma_f32_16x16x32_bf16 v[48:51], v[214:217], v[202:205], v[48:51]
	v_mfma_f32_16x16x32_bf16 v[44:47], v[214:217], v[226:229], v[44:47]
	v_mfma_f32_16x16x32_bf16 v[40:43], v[238:241], v[202:205], v[40:43]
	v_mfma_f32_16x16x32_bf16 v[36:39], v[238:241], v[226:229], v[36:39]
	v_mfma_f32_16x16x32_bf16 v[128:131], v[178:181], v[218:221], v[64:67]
	v_mfma_f32_16x16x32_bf16 v[124:127], v[178:181], v[230:233], v[60:63]
	v_mfma_f32_16x16x32_bf16 v[120:123], v[186:189], v[218:221], v[56:59]
	v_mfma_f32_16x16x32_bf16 v[112:115], v[186:189], v[230:233], v[52:55]
	v_mfma_f32_16x16x32_bf16 v[80:83], v[154:157], v[218:221], v[48:51]
	v_mfma_f32_16x16x32_bf16 v[76:79], v[154:157], v[230:233], v[44:47]
	v_mfma_f32_16x16x32_bf16 v[72:75], v[150:153], v[218:221], v[40:43]
	v_mfma_f32_16x16x32_bf16 v[68:71], v[150:153], v[230:233], v[36:39]
	v_mfma_f32_16x16x32_bf16 v[36:39], v[166:169], v[132:135], v[136:139]
	v_mfma_f32_16x16x32_bf16 v[64:67], v[178:181], v[170:173], v[36:39]
	v_mfma_f32_16x16x32_bf16 v[36:39], v[166:169], v[210:213], v[140:143]
	v_mfma_f32_16x16x32_bf16 v[60:63], v[178:181], v[158:161], v[36:39]
	v_mfma_f32_16x16x32_bf16 v[36:39], v[182:185], v[132:135], v[162:165]
	v_mfma_f32_16x16x32_bf16 v[56:59], v[186:189], v[170:173], v[36:39]
	v_mfma_f32_16x16x32_bf16 v[36:39], v[182:185], v[210:213], v[174:177]
	v_mfma_f32_16x16x32_bf16 v[52:55], v[186:189], v[158:161], v[36:39]
	v_mfma_f32_16x16x32_bf16 v[36:39], v[214:217], v[132:135], v[206:209]
	v_mfma_f32_16x16x32_bf16 v[48:51], v[154:157], v[170:173], v[36:39]
	v_mfma_f32_16x16x32_bf16 v[36:39], v[214:217], v[210:213], v[190:193]
	v_mfma_f32_16x16x32_bf16 v[44:47], v[154:157], v[158:161], v[36:39]
	v_mfma_f32_16x16x32_bf16 v[36:39], v[238:241], v[132:135], v[194:197]
	v_mfma_f32_16x16x32_bf16 v[40:43], v[150:153], v[170:173], v[36:39]
	v_mfma_f32_16x16x32_bf16 v[36:39], v[238:241], v[210:213], v[198:201]
	v_mfma_f32_16x16x32_bf16 v[36:39], v[150:153], v[158:161], v[36:39]
	s_movk_i32 s1, 0x100
	v_cmp_gt_u32_e32 vcc, s1, v3
	s_barrier
	s_and_saveexec_b64 s[8:9], vcc
	s_cbranch_execz .LBB0_1008
	s_barrier

;     ...
;   const int brow = m0, bcol = n0;
;   const int wid = t >> 6, lane = t & 63, wr = wid >> 2, wc = wid & 3, fr = lane & 15, fq = lane >> 4;
;   f32x4 acc[2][2][4][2];
;   {
;     float zinit = 0.f;
;     asm volatile("" : "+v"(zinit));
; #pragma unroll
;     for (int a = 0; a < 2; ++a)
; #pragma unroll
;       for (int b = 0; b < 2; ++b)
; #pragma unroll
;         for (int m = 0; m < 4; ++m)
; #pragma unroll
;           for (int n = 0; n < 2; ++n)
; #pragma unroll
;             for (int j = 0; j < 4; ++j) acc[a][b][m][n][j] = zinit;
;   }
;   bf16x8 At[4][2], B0[2][2], B1[2][2];
;   const int nt = K / 64;
;   if (!pre) {
;     STAGE8(SB8(0, 0), Bt, K, bcol, 0); STAGE8(SA8(0, 0), A, lda, brow, 0);
;     STAGE8(SB8(0, 1), Bt, K, bcol + 128, 0); STAGE8(SA8(0, 1), A, lda, brow + 128, 0);
;   }
.LBB0_1011:
	s_and_b64 vcc, exec, s[0:1]
	s_cbranch_vccz .LBB0_1000
	s_mov_b32 s0, 25
	s_ashr_i32 s1, s0, 31
	s_lshl_b64 s[0:1], s[0:1], 3
	s_add_u32 s0, s70, s0
	s_addc_u32 s1, s71, s1
	v_readlane_b32 s6, v255, 60
	v_readlane_b32 s7, v255, 61
	s_nop 4
	s_mov_b32 s0, 25
	s_ashr_i32 s1, s0, 31
	s_lshl_b64 s[0:1], s[0:1], 3
	s_add_u32 s0, s70, s0
	s_addc_u32 s1, s71, s1
	v_readlane_b32 s2, v255, 60
	v_readlane_b32 s3, v255, 61
	s_nop 4
	s_mov_b32 s0, 25
	s_ashr_i32 s1, s0, 31
	s_lshl_b64 s[0:1], s[0:1], 3
	s_add_u32 s0, s70, s0
	s_addc_u32 s1, s71, s1
	v_mov_b32_e32 v3, v224
	v_readlane_b32 s12, v255, 60
	v_readlane_b32 s13, v255, 61
	s_nop 4
	s_lshl_b32 s0, s38, 8
	v_bfe_i32 v1, v3, 27, 1
	s_waitcnt vmcnt(10)
	v_lshlrev_b32_e32 v150, 4, v3
	s_nop 0
	v_readfirstlane_b32 s100, v150
	v_lshrrev_b32_e32 v1, 22, v1
	v_add_u32_e32 v1, v150, v1
	v_and_b32_e32 v1, 0xfffffc00, v1
	v_ashrrev_i32_e32 v0, 31, v3
	v_sub_u32_e32 v1, v150, v1
	v_lshrrev_b32_e32 v0, 26, v0
	v_lshrrev_b32_e32 v5, 4, v1
	v_add_u32_e32 v0, v3, v0
	v_bitop3_b32 v5, v5, v1, 32 bitop3:0x6c
	v_ashrrev_i32_e32 v1, 31, v1
	v_ashrrev_i32_e32 v0, 6, v0
	v_lshrrev_b32_e32 v1, 26, v1
	v_lshlrev_b32_e32 v6, 3, v0
	v_add_u32_e32 v1, v5, v1
	s_and_b32 s20, s0, 0x3f00
	s_lshl_b32 s0, s38, 2
	v_and_b32_e32 v6, -16, v6
	v_ashrrev_i32_e32 v1, 6, v1
	s_and_b32 s0, s0, 0xffffff00
	v_add_u32_e32 v6, v1, v6
	v_mul_i32_i24_e32 v1, 64, v1
	s_ashr_i32 s1, s0, 31
	v_lshlrev_b32_e32 v0, 5, v0
	v_sub_u32_e32 v1, v5, v1
	v_mov_b32_e32 v14, 1
	s_waitcnt vmcnt(9)
	v_add_u32_e32 v152, 0x2000, v150
	s_lshl_b64 s[8:9], s[0:1], 11
	v_and_b32_e32 v0, 32, v0
	v_ashrrev_i16_sdwa v1, v14, sext(v1) dst_sel:DWORD dst_unused:UNUSED_PAD src0_sel:DWORD src1_sel:BYTE_0
	v_ashrrev_i32_e32 v5, 31, v152
	s_add_u32 s8, s30, s8
	v_add_u32_sdwa v0, v0, sext(v1) dst_sel:DWORD dst_unused:UNUSED_PAD src0_sel:DWORD src1_sel:WORD_0
	v_ashrrev_i32_e32 v7, 31, v6
	v_lshrrev_b32_e32 v5, 22, v5
	s_addc_u32 s9, s31, s9
	v_lshlrev_b64 v[132:133], 11, v[6:7]
	v_ashrrev_i32_e32 v1, 31, v0
	v_add_u32_e32 v5, v152, v5
	v_lshl_add_u64 v[8:9], s[8:9], 0, v[132:133]
	v_lshlrev_b64 v[6:7], 1, v[0:1]
	v_ashrrev_i32_e32 v5, 10, v5
	v_lshl_add_u64 v[10:11], v[8:9], 0, v[6:7]
	v_mul_i32_i24_e32 v8, 0x400, v5
	v_sub_u32_e32 v8, v152, v8
	v_lshrrev_b32_e32 v9, 4, v8
	v_bitop3_b32 v9, v9, v8, 32 bitop3:0x6c
	v_ashrrev_i32_e32 v12, 31, v9
	v_lshrrev_b32_e32 v12, 26, v12
	v_add_u32_e32 v12, v9, v12
	v_lshlrev_b32_e32 v8, 3, v5
	v_ashrrev_i32_e32 v13, 6, v12
	v_and_b32_e32 v12, 0xc0, v12
	v_and_b32_e32 v8, -16, v8
	v_lshlrev_b32_e32 v5, 5, v5
	v_sub_u32_e32 v9, v9, v12
	v_add_u32_e32 v8, v13, v8
	v_and_b32_e32 v5, 32, v5
	v_ashrrev_i16_sdwa v9, v14, sext(v9) dst_sel:DWORD dst_unused:UNUSED_PAD src0_sel:DWORD src1_sel:BYTE_0
	v_add_u32_sdwa v134, v5, sext(v9) dst_sel:DWORD dst_unused:UNUSED_PAD src0_sel:DWORD src1_sel:WORD_0
	v_ashrrev_i32_e32 v9, 31, v8
	v_lshlrev_b64 v[136:137], 11, v[8:9]
	s_waitcnt vmcnt(8)
	v_mov_b32_e32 v4, v2
	s_or_b32 m0, s100, 0x10000
	v_lshl_add_u64 v[12:13], s[8:9], 0, v[136:137]
	global_load_lds_dwordx4 v[10:11], off
	s_or_b32 m0, s100, 0x12000
	s_lshl_b32 s8, s20, 11
	v_ashrrev_i32_e32 v135, 31, v134
	s_waitcnt lgkmcnt(0)
	s_add_u32 s8, s12, s8
	v_lshlrev_b64 v[8:9], 1, v[134:135]
	s_addc_u32 s9, s13, 0
	v_lshl_add_u64 v[12:13], v[12:13], 0, v[8:9]
	v_lshl_add_u64 v[14:15], s[8:9], 0, v[132:133]
	global_load_lds_dwordx4 v[12:13], off
	v_lshl_add_u64 v[14:15], v[14:15], 0, v[6:7]
	s_mov_b32 m0, s100
	s_nop 0
	global_load_lds_dwordx4 v[14:15], off
	s_or_b32 m0, s100, 0x2000
	s_or_b32 s14, s0, 0x80
	s_ashr_i32 s15, s14, 31
	s_lshl_b64 s[14:15], s[14:15], 11
	s_add_u32 s14, s30, s14
	v_lshl_add_u64 v[16:17], s[8:9], 0, v[136:137]
	s_addc_u32 s15, s31, s15
	v_lshl_add_u64 v[16:17], v[16:17], 0, v[8:9]
	v_lshl_add_u64 v[18:19], s[14:15], 0, v[132:133]
	global_load_lds_dwordx4 v[16:17], off
	v_lshl_add_u64 v[18:19], v[18:19], 0, v[6:7]
	s_or_b32 m0, s100, 0x14000
	v_lshl_add_u64 v[20:21], s[14:15], 0, v[136:137]
	global_load_lds_dwordx4 v[18:19], off
	s_or_b32 m0, s100, 0x16000
	s_add_u32 s14, s8, 0x40000
	s_addc_u32 s15, s9, 0
	v_lshl_add_u64 v[20:21], v[20:21], 0, v[8:9]
	v_lshl_add_u64 v[22:23], s[14:15], 0, v[132:133]
	global_load_lds_dwordx4 v[20:21], off
	v_lshl_add_u64 v[22:23], v[22:23], 0, v[6:7]
	s_or_b32 m0, s100, 0x4000
	global_load_lds_dwordx4 v[22:23], off
	v_lshl_add_u64 v[22:23], s[14:15], 0, v[136:137]
	v_lshl_add_u64 v[22:23], v[22:23], 0, v[8:9]
	s_or_b32 m0, s100, 0x6000
	v_ashrrev_i32_e32 v5, 8, v3
	global_load_lds_dwordx4 v[22:23], off
	v_cmp_eq_u32_e32 vcc, 1, v5
	s_and_saveexec_b64 s[14:15], vcc
	s_cbranch_execz .LBB0_1014
	s_barrier
; #define WAIT_V8(n) asm volatile("s_waitcnt vmcnt(" #n ")" ::: "memory")
; #define BAR8 __builtin_amdgcn_s_barrier()
;     ...
;   const int wid = t >> 6, lane = t & 63, wr = wid >> 2, wc = wid & 3, fr = lane & 15, fq = lane >> 4;
;   f32x4 acc[2][2][4][2];
;   {
;     float zinit = 0.f;
;     asm volatile("" : "+v"(zinit));
; #pragma unroll
;     for (int a = 0; a < 2; ++a)
; #pragma unroll
;       for (int b = 0; b < 2; ++b)
; #pragma unroll
;         for (int m = 0; m < 4; ++m)
; #pragma unroll
;           for (int n = 0; n < 2; ++n)
; #pragma unroll
;             for (int j = 0; j < 4; ++j) acc[a][b][m][n][j] = zinit;
;   }
;   bf16x8 At[4][2], B0[2][2], B1[2][2];
;     ...
;   if (wr == 1) BAR8;
;   WAIT_V8(4); BAR8;
;   STAGE8(SB8(1, 0), Bt, K, bcol, 1); STAGE8(SA8(1, 0), A, lda, brow, 1); STAGE8(SB8(1, 1), Bt, K, bcol + 128, 1);
;   WAIT_V8(6); BAR8;
.LBB0_1014:
	s_or_b64 exec, exec, s[14:15]
	v_readlane_b32 s40, v254, 35
	v_readlane_b32 s42, v254, 37
	v_readlane_b32 s43, v254, 38
	s_waitcnt vmcnt(0)
	s_mov_b64 s[42:43], 0x80
	v_lshl_add_u64 v[10:11], v[10:11], 0, s[42:43]
	s_or_b32 m0, s100, 0x18000
	s_waitcnt vmcnt(4)
	s_barrier
	global_load_lds_dwordx4 v[10:11], off
	v_lshl_add_u64 v[10:11], v[12:13], 0, s[42:43]
	s_or_b32 m0, s100, 0x1a000
	global_load_lds_dwordx4 v[10:11], off
	v_lshl_add_u64 v[10:11], v[14:15], 0, s[42:43]
	s_or_b32 m0, s100, 0x8000
	global_load_lds_dwordx4 v[10:11], off
	v_lshl_add_u64 v[10:11], v[16:17], 0, s[42:43]
	s_or_b32 m0, s100, 0xa000
	global_load_lds_dwordx4 v[10:11], off
	v_lshl_add_u64 v[10:11], v[18:19], 0, s[42:43]
	s_or_b32 m0, s100, 0x1c000
	s_nop 0
	global_load_lds_dwordx4 v[10:11], off
	v_lshl_add_u64 v[10:11], v[20:21], 0, s[42:43]
	s_or_b32 m0, s100, 0x1e000
	v_and_b32_e32 v147, 15, v3
	global_load_lds_dwordx4 v[10:11], off
	v_bfe_u32 v148, v3, 4, 2
	v_lshlrev_b32_e32 v10, 4, v148
	v_lshlrev_b32_e32 v11, 6, v147
	v_lshlrev_b32_e32 v14, 2, v3
	v_or_b32_e32 v13, v10, v11
	v_and_b32_e32 v14, 32, v14
	s_mov_b32 s21, 0x10000
	v_bitop3_b32 v16, v13, s21, v14 bitop3:0xde
	s_mov_b32 s21, 0x14000
	s_and_b32 s14, s27, 63
	v_bitop3_b32 v15, v10, v14, v11 bitop3:0x36
	v_bitop3_b32 v17, v13, s21, v14 bitop3:0xde
	s_mov_b32 s21, 0x18000
	v_lshlrev_b32_e32 v11, 6, v3
	s_lshl_b32 s14, s14, 19
	s_mov_b32 s15, s40
	v_bitop3_b32 v18, v13, s21, v14 bitop3:0xde
	s_mov_b32 s21, 0x1c000
	v_and_b32_e32 v11, 0x3c0, v11
	v_bitop3_b32 v13, v13, s21, v14 bitop3:0xde
	v_bitop3_b32 v14, v11, v14, v10 bitop3:0x36
	v_lshl_add_u64 v[10:11], s[14:15], 0, v[136:137]
	v_readlane_b32 s41, v254, 36
	s_and_b32 s40, s33, 0xffffff00
	v_lshl_add_u64 v[10:11], v[10:11], 0, v[8:9]
	s_ashr_i32 s41, s40, 31
	v_lshl_add_u64 v[138:139], s[12:13], 0, v[10:11]
	v_lshl_add_u64 v[10:11], s[14:15], 0, v[132:133]
	s_lshl_b64 s[40:41], s[40:41], 11
	v_lshl_add_u64 v[10:11], v[10:11], 0, v[6:7]
	v_lshl_add_u64 v[140:141], s[12:13], 0, v[10:11]
	v_lshl_add_u64 v[10:11], s[40:41], 0, v[132:133]
	v_lshl_add_u64 v[6:7], v[10:11], 0, v[6:7]
	v_bfe_u32 v146, v3, 6, 2
	s_waitcnt vmcnt(6)
	v_lshlrev_b32_e32 v149, 6, v5
	v_lshlrev_b32_e32 v5, 13, v5
	v_lshl_add_u64 v[142:143], s[4:5], 0, v[6:7]
	v_lshl_add_u64 v[6:7], s[40:41], 0, v[136:137]
	v_lshlrev_b32_e32 v12, 12, v146
	v_or_b32_e32 v19, 0x800, v5
	v_or_b32_e32 v20, 0x1000, v5
	v_or_b32_e32 v21, 0x1800, v5
	v_lshl_add_u64 v[6:7], v[6:7], 0, v[8:9]
	v_lshl_add_u64 v[144:145], s[4:5], 0, v[6:7]
	s_mov_b32 s14, -2
	s_mov_b64 s[12:13], 0
	v_add_u32_e32 v171, v16, v12
	v_add_u32_e32 v156, v15, v5
	v_add_u32_e32 v155, v14, v19
	v_add_u32_e32 v154, v14, v20
	v_add_u32_e32 v153, v14, v21
	v_add_u32_e32 v168, v17, v12
	v_add_u32_e32 v161, v18, v12
	v_add_u32_e32 v158, v13, v12
	v_mov_b32_e32 v5, v4
	v_mov_b64_e32 v[6:7], v[4:5]
	v_mov_b64_e32 v[8:9], v[4:5]
	v_mov_b64_e32 v[10:11], v[4:5]
	v_mov_b64_e32 v[12:13], v[4:5]
	v_mov_b64_e32 v[14:15], v[4:5]
	v_mov_b64_e32 v[16:17], v[4:5]
	v_mov_b64_e32 v[18:19], v[4:5]
	v_mov_b64_e32 v[20:21], v[4:5]
	v_mov_b64_e32 v[22:23], v[4:5]
	v_mov_b64_e32 v[24:25], v[4:5]
	v_mov_b64_e32 v[26:27], v[4:5]
	v_mov_b64_e32 v[28:29], v[4:5]
	v_mov_b64_e32 v[30:31], v[4:5]
	v_mov_b64_e32 v[32:33], v[4:5]
	v_mov_b64_e32 v[34:35], v[4:5]
	v_mov_b64_e32 v[36:37], v[4:5]
	v_mov_b64_e32 v[38:39], v[4:5]
	v_mov_b64_e32 v[40:41], v[4:5]
	v_mov_b64_e32 v[42:43], v[4:5]
	v_mov_b64_e32 v[44:45], v[4:5]
	v_mov_b64_e32 v[46:47], v[4:5]
	v_mov_b64_e32 v[48:49], v[4:5]
	v_mov_b64_e32 v[50:51], v[4:5]
	v_mov_b64_e32 v[52:53], v[4:5]
	v_mov_b64_e32 v[54:55], v[4:5]
	v_mov_b64_e32 v[56:57], v[4:5]
	v_mov_b64_e32 v[58:59], v[4:5]
	v_mov_b64_e32 v[60:61], v[4:5]
	v_mov_b64_e32 v[62:63], v[4:5]
	v_mov_b64_e32 v[64:65], v[4:5]
	v_mov_b64_e32 v[66:67], v[4:5]
	v_mov_b64_e32 v[68:69], v[4:5]
	v_mov_b64_e32 v[70:71], v[4:5]
	v_mov_b64_e32 v[72:73], v[4:5]
	v_mov_b64_e32 v[74:75], v[4:5]
	v_mov_b64_e32 v[76:77], v[4:5]
	v_mov_b64_e32 v[78:79], v[4:5]
	v_mov_b64_e32 v[80:81], v[4:5]
	v_mov_b64_e32 v[82:83], v[4:5]
	v_mov_b64_e32 v[84:85], v[4:5]
	v_mov_b64_e32 v[86:87], v[4:5]
	v_mov_b64_e32 v[88:89], v[4:5]
	v_mov_b64_e32 v[90:91], v[4:5]
	v_mov_b64_e32 v[92:93], v[4:5]
	v_mov_b64_e32 v[94:95], v[4:5]
	v_mov_b64_e32 v[96:97], v[4:5]
	v_mov_b64_e32 v[98:99], v[4:5]
	v_mov_b64_e32 v[100:101], v[4:5]
	v_mov_b64_e32 v[102:103], v[4:5]
	v_mov_b64_e32 v[104:105], v[4:5]
	v_mov_b64_e32 v[106:107], v[4:5]
	v_mov_b64_e32 v[108:109], v[4:5]
	v_mov_b64_e32 v[110:111], v[4:5]
	v_mov_b64_e32 v[112:113], v[4:5]
	v_mov_b64_e32 v[114:115], v[4:5]
	v_mov_b64_e32 v[116:117], v[4:5]
	v_mov_b64_e32 v[118:119], v[4:5]
	v_mov_b64_e32 v[120:121], v[4:5]
	v_mov_b64_e32 v[122:123], v[4:5]
	v_mov_b64_e32 v[124:125], v[4:5]
	v_mov_b64_e32 v[126:127], v[4:5]
	v_mov_b64_e32 v[128:129], v[4:5]
	v_mov_b64_e32 v[130:131], v[4:5]
	s_mov_b64 s[40:41], 0xc6a0100
	s_mov_b64 s[42:43], 0xc6e0100
	s_mov_b64 s[44:45], 0xc6a0180
	s_mov_b64 s[46:47], 0xc6e0180
	s_barrier
; #define LDA8(dst, b, h) _Pragma("unroll") for (int m = 0; m < 4; ++m) _Pragma("unroll") for (int k = 0; k < 2; ++k) \
;     dst[m][k] = *(const bf16x8*)((const char*)SA8(b, h) + lds_byte8(wr * 64 + m * 16 + fr, k * 32 + fq * 8))
; #define LDB8(dst, b, h) _Pragma("unroll") for (int n = 0; n < 2; ++n) _Pragma("unroll") for (int k = 0; k < 2; ++k) \
;     dst[n][k] = *(const bf16x8*)((const char*)SB8(b, h) + lds_byte8(wc * 32 + n * 16 + fr, k * 32 + fq * 8))
; #define WAIT_V8(n) asm volatile("s_waitcnt vmcnt(" #n ")" ::: "memory")
; #define WAIT_L8(n) asm volatile("s_waitcnt lgkmcnt(" #n ")" ::: "memory")
; #define BAR8 __builtin_amdgcn_s_barrier()
; #define SCHED8 __builtin_amdgcn_sched_barrier(0)
;     ...
;   for (int tt = 0; tt < nt - 2; tt += 2) {
;     LDB8(B0, 0, 0); SCHED8; LDA8(At, 0, 0); STAGE8(SA8(1, 1), A, lda, brow + 128, tt + 1);
;     WAIT_L8(8); BAR8; WAIT_L8(0); MMA8(0, 0, At, B0); BAR8; SCHED8;
;     LDB8(B1, 0, 1); STAGE8(SB8(0, 0), Bt, K, bcol, tt + 2);
;     BAR8; WAIT_L8(0); MMA8(0, 1, At, B1); BAR8;
;     LDA8(At, 0, 1); STAGE8(SA8(0, 0), A, lda, brow, tt + 2);
;     BAR8; WAIT_L8(0); MMA8(1, 0, At, B0); BAR8; SCHED8;
;     STAGE8(SB8(0, 1), Bt, K, bcol + 128, tt + 2);
;     WAIT_V8(6); BAR8; MMA8(1, 1, At, B1); BAR8;
.LBB0_1015:
	ds_read_b128 v[174:177], v171
	ds_read_b128 v[178:181], v171 offset:1024
	ds_read_b128 v[182:185], v171 offset:2048
	ds_read_b128 v[186:189], v171 offset:3072
	v_lshl_add_u64 v[222:223], v[140:141], 0, s[12:13]
	v_lshl_add_u64 v[226:227], v[222:223], 0, s[34:35]
	s_or_b32 m0, s100, 0xc000
	v_lshl_add_u64 v[236:237], v[138:139], 0, s[12:13]
	ds_read_b128 v[190:193], v156
	ds_read_b128 v[194:197], v156 offset:1024
	ds_read_b128 v[198:201], v155
	ds_read_b128 v[202:205], v155 offset:1024
	ds_read_b128 v[206:209], v154
	ds_read_b128 v[210:213], v154 offset:1024
	ds_read_b128 v[214:217], v153
	ds_read_b128 v[218:221], v153 offset:1024
	global_load_lds_dwordx4 v[226:227], off
	v_lshl_add_u64 v[226:227], v[236:237], 0, s[34:35]
	s_or_b32 m0, s100, 0xe000
	s_nop 0
	global_load_lds_dwordx4 v[226:227], off
	s_waitcnt lgkmcnt(8)
	s_barrier
	s_waitcnt lgkmcnt(0)
	v_mfma_f32_16x16x32_f16 v[128:131], v[190:193], v[174:177], v[128:131]
	v_mfma_f32_16x16x32_f16 v[124:127], v[190:193], v[182:185], v[124:127]
	v_mfma_f32_16x16x32_f16 v[120:123], v[198:201], v[174:177], v[120:123]
	v_mfma_f32_16x16x32_f16 v[116:119], v[198:201], v[182:185], v[116:119]
	v_mfma_f32_16x16x32_f16 v[112:115], v[206:209], v[174:177], v[112:115]
	v_mfma_f32_16x16x32_f16 v[108:111], v[206:209], v[182:185], v[108:111]
	v_mfma_f32_16x16x32_f16 v[104:107], v[214:217], v[174:177], v[104:107]
	v_mfma_f32_16x16x32_f16 v[100:103], v[214:217], v[182:185], v[100:103]
	v_mfma_f32_16x16x32_f16 v[128:131], v[194:197], v[178:181], v[128:131]
	v_mfma_f32_16x16x32_f16 v[124:127], v[194:197], v[186:189], v[124:127]
	v_mfma_f32_16x16x32_f16 v[120:123], v[202:205], v[178:181], v[120:123]
	v_mfma_f32_16x16x32_f16 v[116:119], v[202:205], v[186:189], v[116:119]
	v_mfma_f32_16x16x32_f16 v[112:115], v[210:213], v[178:181], v[112:115]
	v_mfma_f32_16x16x32_f16 v[108:111], v[210:213], v[186:189], v[108:111]
	v_mfma_f32_16x16x32_f16 v[104:107], v[218:221], v[178:181], v[104:107]
	v_mfma_f32_16x16x32_f16 v[100:103], v[218:221], v[186:189], v[100:103]
	s_barrier
	v_lshl_add_u64 v[246:247], v[142:143], 0, s[12:13]
	v_lshl_add_u64 v[248:249], v[246:247], 0, s[40:41]
	s_or_b32 m0, s100, 0x10000
	ds_read_b128 v[226:229], v168
	ds_read_b128 v[230:233], v168 offset:1024
	ds_read_b128 v[238:241], v168 offset:2048
	ds_read_b128 v[242:245], v168 offset:3072
	global_load_lds_dwordx4 v[248:249], off
	v_lshl_add_u64 v[248:249], v[144:145], 0, s[12:13]
	v_lshl_add_u64 v[250:251], v[248:249], 0, s[40:41]
	s_or_b32 m0, s100, 0x12000
	s_nop 0
	global_load_lds_dwordx4 v[250:251], off
	s_barrier
	s_waitcnt lgkmcnt(0)
	v_mfma_f32_16x16x32_f16 v[96:99], v[190:193], v[226:229], v[96:99]
	v_mfma_f32_16x16x32_f16 v[92:95], v[190:193], v[238:241], v[92:95]
	v_mfma_f32_16x16x32_f16 v[88:91], v[198:201], v[226:229], v[88:91]
	v_mfma_f32_16x16x32_f16 v[84:87], v[198:201], v[238:241], v[84:87]
	v_mfma_f32_16x16x32_f16 v[80:83], v[206:209], v[226:229], v[80:83]
	v_mfma_f32_16x16x32_f16 v[76:79], v[206:209], v[238:241], v[76:79]
	v_mfma_f32_16x16x32_f16 v[72:75], v[214:217], v[226:229], v[72:75]
	v_mfma_f32_16x16x32_f16 v[68:71], v[214:217], v[238:241], v[68:71]
	v_mfma_f32_16x16x32_f16 v[96:99], v[194:197], v[230:233], v[96:99]
	v_mfma_f32_16x16x32_f16 v[92:95], v[194:197], v[242:245], v[92:95]
	v_mfma_f32_16x16x32_f16 v[88:91], v[202:205], v[230:233], v[88:91]
	v_mfma_f32_16x16x32_f16 v[84:87], v[202:205], v[242:245], v[84:87]
	v_mfma_f32_16x16x32_f16 v[80:83], v[210:213], v[230:233], v[80:83]
	v_mfma_f32_16x16x32_f16 v[76:79], v[210:213], v[242:245], v[76:79]
	v_mfma_f32_16x16x32_f16 v[72:75], v[218:221], v[230:233], v[72:75]
	v_mfma_f32_16x16x32_f16 v[68:71], v[218:221], v[242:245], v[68:71]
	v_lshl_add_u64 v[250:251], v[222:223], 0, s[10:11]
	s_mov_b32 m0, s100
	s_barrier
	ds_read_b128 v[190:193], v156 offset:16384
	ds_read_b128 v[194:197], v156 offset:17408
	ds_read_b128 v[198:201], v155 offset:16384
	ds_read_b128 v[202:205], v155 offset:17408
	ds_read_b128 v[206:209], v154 offset:16384
	ds_read_b128 v[210:213], v154 offset:17408
	ds_read_b128 v[214:217], v153 offset:16384
	ds_read_b128 v[218:221], v153 offset:17408
	global_load_lds_dwordx4 v[250:251], off
	v_lshl_add_u64 v[250:251], v[236:237], 0, s[10:11]
	s_or_b32 m0, s100, 0x2000
	s_nop 0
	global_load_lds_dwordx4 v[250:251], off
	s_barrier
	s_waitcnt lgkmcnt(0)
	v_mfma_f32_16x16x32_f16 v[64:67], v[190:193], v[174:177], v[64:67]
	v_mfma_f32_16x16x32_f16 v[60:63], v[190:193], v[182:185], v[60:63]
	v_mfma_f32_16x16x32_f16 v[56:59], v[198:201], v[174:177], v[56:59]
	v_mfma_f32_16x16x32_f16 v[52:55], v[198:201], v[182:185], v[52:55]
	v_mfma_f32_16x16x32_f16 v[48:51], v[206:209], v[174:177], v[48:51]
	v_mfma_f32_16x16x32_f16 v[44:47], v[206:209], v[182:185], v[44:47]
	v_mfma_f32_16x16x32_f16 v[40:43], v[214:217], v[174:177], v[40:43]
	v_mfma_f32_16x16x32_f16 v[36:39], v[214:217], v[182:185], v[36:39]
	v_mfma_f32_16x16x32_f16 v[64:67], v[194:197], v[178:181], v[64:67]
	v_mfma_f32_16x16x32_f16 v[60:63], v[194:197], v[186:189], v[60:63]
	v_mfma_f32_16x16x32_f16 v[56:59], v[202:205], v[178:181], v[56:59]
	v_mfma_f32_16x16x32_f16 v[52:55], v[202:205], v[186:189], v[52:55]
	v_mfma_f32_16x16x32_f16 v[48:51], v[210:213], v[178:181], v[48:51]
	v_mfma_f32_16x16x32_f16 v[44:47], v[210:213], v[186:189], v[44:47]
	v_mfma_f32_16x16x32_f16 v[40:43], v[218:221], v[178:181], v[40:43]
	v_mfma_f32_16x16x32_f16 v[36:39], v[218:221], v[186:189], v[36:39]
	s_barrier
	v_lshl_add_u64 v[174:175], v[246:247], 0, s[42:43]
	s_or_b32 m0, s100, 0x14000
	s_nop 0
	global_load_lds_dwordx4 v[174:175], off
	v_lshl_add_u64 v[174:175], v[248:249], 0, s[42:43]
	s_or_b32 m0, s100, 0x16000
	s_nop 0
	global_load_lds_dwordx4 v[174:175], off
	s_waitcnt vmcnt(6)
	s_barrier
; #define LDA8(dst, b, h) _Pragma("unroll") for (int m = 0; m < 4; ++m) _Pragma("unroll") for (int k = 0; k < 2; ++k) \
;     dst[m][k] = *(const bf16x8*)((const char*)SA8(b, h) + lds_byte8(wr * 64 + m * 16 + fr, k * 32 + fq * 8))
; #define LDB8(dst, b, h) _Pragma("unroll") for (int n = 0; n < 2; ++n) _Pragma("unroll") for (int k = 0; k < 2; ++k) \
;     dst[n][k] = *(const bf16x8*)((const char*)SB8(b, h) + lds_byte8(wc * 32 + n * 16 + fr, k * 32 + fq * 8))
; #define WAIT_V8(n) asm volatile("s_waitcnt vmcnt(" #n ")" ::: "memory")
; #define WAIT_L8(n) asm volatile("s_waitcnt lgkmcnt(" #n ")" ::: "memory")
; #define BAR8 __builtin_amdgcn_s_barrier()
; #define SCHED8 __builtin_amdgcn_sched_barrier(0)
;     ...
;     WAIT_V8(6); BAR8; MMA8(1, 1, At, B1); BAR8;
;     LDB8(B0, 1, 0); SCHED8; LDA8(At, 1, 0); STAGE8(SA8(0, 1), A, lda, brow + 128, tt + 2);
;     WAIT_L8(8); BAR8; WAIT_L8(0); MMA8(0, 0, At, B0); BAR8; SCHED8;
;     LDB8(B1, 1, 1); STAGE8(SB8(1, 0), Bt, K, bcol, tt + 3);
;     BAR8; WAIT_L8(0); MMA8(0, 1, At, B1); BAR8;
;     LDA8(At, 1, 1); STAGE8(SA8(1, 0), A, lda, brow, tt + 3);
;     BAR8; WAIT_L8(0); MMA8(1, 0, At, B0); BAR8; SCHED8;
	v_mfma_f32_16x16x32_f16 v[32:35], v[190:193], v[226:229], v[32:35]
	v_mfma_f32_16x16x32_f16 v[28:31], v[190:193], v[238:241], v[28:31]
	v_mfma_f32_16x16x32_f16 v[24:27], v[198:201], v[226:229], v[24:27]
	v_mfma_f32_16x16x32_f16 v[20:23], v[198:201], v[238:241], v[20:23]
	v_mfma_f32_16x16x32_f16 v[16:19], v[206:209], v[226:229], v[16:19]
	v_mfma_f32_16x16x32_f16 v[12:15], v[206:209], v[238:241], v[12:15]
	v_mfma_f32_16x16x32_f16 v[8:11], v[214:217], v[226:229], v[8:11]
	v_mfma_f32_16x16x32_f16 v[4:7], v[214:217], v[238:241], v[4:7]
	v_mfma_f32_16x16x32_f16 v[32:35], v[194:197], v[230:233], v[32:35]
	v_mfma_f32_16x16x32_f16 v[28:31], v[194:197], v[242:245], v[28:31]
	v_mfma_f32_16x16x32_f16 v[24:27], v[202:205], v[230:233], v[24:27]
	v_mfma_f32_16x16x32_f16 v[20:23], v[202:205], v[242:245], v[20:23]
	v_mfma_f32_16x16x32_f16 v[16:19], v[210:213], v[230:233], v[16:19]
	v_mfma_f32_16x16x32_f16 v[12:15], v[210:213], v[242:245], v[12:15]
	v_mfma_f32_16x16x32_f16 v[8:11], v[218:221], v[230:233], v[8:11]
	v_mfma_f32_16x16x32_f16 v[4:7], v[218:221], v[242:245], v[4:7]
	s_barrier
	ds_read_b128 v[174:177], v161
	ds_read_b128 v[178:181], v161 offset:1024
	ds_read_b128 v[182:185], v161 offset:2048
	ds_read_b128 v[186:189], v161 offset:3072
	v_lshl_add_u64 v[226:227], v[222:223], 0, s[18:19]
	s_or_b32 m0, s100, 0x4000
	ds_read_b128 v[190:193], v156 offset:32768
	ds_read_b128 v[194:197], v156 offset:33792
	ds_read_b128 v[198:201], v155 offset:32768
	ds_read_b128 v[202:205], v155 offset:33792
	ds_read_b128 v[206:209], v154 offset:32768
	ds_read_b128 v[210:213], v154 offset:33792
	ds_read_b128 v[214:217], v153 offset:32768
	ds_read_b128 v[218:221], v153 offset:33792
	global_load_lds_dwordx4 v[226:227], off
	v_lshl_add_u64 v[226:227], v[236:237], 0, s[18:19]
	s_or_b32 m0, s100, 0x6000
	s_nop 0
	global_load_lds_dwordx4 v[226:227], off
	s_waitcnt lgkmcnt(8)
	s_barrier
	s_waitcnt lgkmcnt(0)
	v_mfma_f32_16x16x32_f16 v[128:131], v[190:193], v[174:177], v[128:131]
	v_mfma_f32_16x16x32_f16 v[124:127], v[190:193], v[182:185], v[124:127]
	v_mfma_f32_16x16x32_f16 v[120:123], v[198:201], v[174:177], v[120:123]
	v_mfma_f32_16x16x32_f16 v[116:119], v[198:201], v[182:185], v[116:119]
	v_mfma_f32_16x16x32_f16 v[112:115], v[206:209], v[174:177], v[112:115]
	v_mfma_f32_16x16x32_f16 v[108:111], v[206:209], v[182:185], v[108:111]
	v_mfma_f32_16x16x32_f16 v[104:107], v[214:217], v[174:177], v[104:107]
	v_mfma_f32_16x16x32_f16 v[100:103], v[214:217], v[182:185], v[100:103]
	v_mfma_f32_16x16x32_f16 v[128:131], v[194:197], v[178:181], v[128:131]
	v_mfma_f32_16x16x32_f16 v[124:127], v[194:197], v[186:189], v[124:127]
	v_mfma_f32_16x16x32_f16 v[120:123], v[202:205], v[178:181], v[120:123]
	v_mfma_f32_16x16x32_f16 v[116:119], v[202:205], v[186:189], v[116:119]
	v_mfma_f32_16x16x32_f16 v[112:115], v[210:213], v[178:181], v[112:115]
	v_mfma_f32_16x16x32_f16 v[108:111], v[210:213], v[186:189], v[108:111]
	v_mfma_f32_16x16x32_f16 v[104:107], v[218:221], v[178:181], v[104:107]
	v_mfma_f32_16x16x32_f16 v[100:103], v[218:221], v[186:189], v[100:103]
	s_barrier
	v_lshl_add_u64 v[250:251], v[246:247], 0, s[44:45]
	s_or_b32 m0, s100, 0x18000
	ds_read_b128 v[226:229], v158
	ds_read_b128 v[230:233], v158 offset:1024
	ds_read_b128 v[238:241], v158 offset:2048
	ds_read_b128 v[242:245], v158 offset:3072
	global_load_lds_dwordx4 v[250:251], off
	v_lshl_add_u64 v[250:251], v[248:249], 0, s[44:45]
	s_or_b32 m0, s100, 0x1a000
	s_nop 0
	global_load_lds_dwordx4 v[250:251], off
	s_barrier
	s_waitcnt lgkmcnt(0)
	v_mfma_f32_16x16x32_f16 v[96:99], v[190:193], v[226:229], v[96:99]
	v_mfma_f32_16x16x32_f16 v[92:95], v[190:193], v[238:241], v[92:95]
	v_mfma_f32_16x16x32_f16 v[88:91], v[198:201], v[226:229], v[88:91]
	v_mfma_f32_16x16x32_f16 v[84:87], v[198:201], v[238:241], v[84:87]
	v_mfma_f32_16x16x32_f16 v[80:83], v[206:209], v[226:229], v[80:83]
	v_mfma_f32_16x16x32_f16 v[76:79], v[206:209], v[238:241], v[76:79]
	v_mfma_f32_16x16x32_f16 v[72:75], v[214:217], v[226:229], v[72:75]
	v_mfma_f32_16x16x32_f16 v[68:71], v[214:217], v[238:241], v[68:71]
	v_mfma_f32_16x16x32_f16 v[96:99], v[194:197], v[230:233], v[96:99]
	v_mfma_f32_16x16x32_f16 v[92:95], v[194:197], v[242:245], v[92:95]
	v_mfma_f32_16x16x32_f16 v[88:91], v[202:205], v[230:233], v[88:91]
	v_mfma_f32_16x16x32_f16 v[84:87], v[202:205], v[242:245], v[84:87]
	v_mfma_f32_16x16x32_f16 v[80:83], v[210:213], v[230:233], v[80:83]
	v_mfma_f32_16x16x32_f16 v[76:79], v[210:213], v[242:245], v[76:79]
	v_mfma_f32_16x16x32_f16 v[72:75], v[218:221], v[230:233], v[72:75]
	v_mfma_f32_16x16x32_f16 v[68:71], v[218:221], v[242:245], v[68:71]
	v_lshl_add_u64 v[222:223], v[222:223], 0, s[22:23]
	s_or_b32 m0, s100, 0x8000
	s_barrier
	ds_read_b128 v[190:193], v156 offset:49152
	ds_read_b128 v[194:197], v156 offset:50176
	ds_read_b128 v[198:201], v155 offset:49152
	ds_read_b128 v[202:205], v155 offset:50176
	ds_read_b128 v[206:209], v154 offset:49152
	ds_read_b128 v[210:213], v154 offset:50176
	ds_read_b128 v[214:217], v153 offset:49152
	ds_read_b128 v[218:221], v153 offset:50176
	global_load_lds_dwordx4 v[222:223], off
	v_lshl_add_u64 v[222:223], v[236:237], 0, s[22:23]
	s_or_b32 m0, s100, 0xa000
	s_nop 0
	global_load_lds_dwordx4 v[222:223], off
	s_barrier
; #define LDA8(dst, b, h) _Pragma("unroll") for (int m = 0; m < 4; ++m) _Pragma("unroll") for (int k = 0; k < 2; ++k) \
;     dst[m][k] = *(const bf16x8*)((const char*)SA8(b, h) + lds_byte8(wr * 64 + m * 16 + fr, k * 32 + fq * 8))
; #define LDB8(dst, b, h) _Pragma("unroll") for (int n = 0; n < 2; ++n) _Pragma("unroll") for (int k = 0; k < 2; ++k) \
;     dst[n][k] = *(const bf16x8*)((const char*)SB8(b, h) + lds_byte8(wc * 32 + n * 16 + fr, k * 32 + fq * 8))
; #define WAIT_V8(n) asm volatile("s_waitcnt vmcnt(" #n ")" ::: "memory")
; #define WAIT_L8(n) asm volatile("s_waitcnt lgkmcnt(" #n ")" ::: "memory")
; #define BAR8 __builtin_amdgcn_s_barrier()
; #define SCHED8 __builtin_amdgcn_sched_barrier(0)
;     ...
;     BAR8; WAIT_L8(0); MMA8(1, 0, At, B0); BAR8; SCHED8;
;     STAGE8(SB8(1, 1), Bt, K, bcol + 128, tt + 3);
;     WAIT_V8(6); BAR8; MMA8(1, 1, At, B1); BAR8;
;   }
;   { LDB8(B0, 0, 0); LDA8(At, 0, 0); STAGE8(SA8(1, 1), A, lda, brow + 128, nt - 1);
;     BAR8; WAIT_L8(0); MMA8(0, 0, At, B0); BAR8;
;     LDB8(B1, 0, 1); BAR8; WAIT_L8(0); MMA8(0, 1, At, B1); BAR8;
;     LDA8(At, 0, 1); WAIT_V8(4); BAR8; WAIT_L8(0); MMA8(1, 0, At, B0); MMA8(1, 1, At, B1); BAR8; }
	s_waitcnt lgkmcnt(0)
	v_mfma_f32_16x16x32_f16 v[64:67], v[190:193], v[174:177], v[64:67]
	v_mfma_f32_16x16x32_f16 v[60:63], v[190:193], v[182:185], v[60:63]
	v_mfma_f32_16x16x32_f16 v[56:59], v[198:201], v[174:177], v[56:59]
	v_mfma_f32_16x16x32_f16 v[52:55], v[198:201], v[182:185], v[52:55]
	v_mfma_f32_16x16x32_f16 v[48:51], v[206:209], v[174:177], v[48:51]
	v_mfma_f32_16x16x32_f16 v[44:47], v[206:209], v[182:185], v[44:47]
	v_mfma_f32_16x16x32_f16 v[40:43], v[214:217], v[174:177], v[40:43]
	v_mfma_f32_16x16x32_f16 v[36:39], v[214:217], v[182:185], v[36:39]
	v_mfma_f32_16x16x32_f16 v[64:67], v[194:197], v[178:181], v[64:67]
	v_mfma_f32_16x16x32_f16 v[60:63], v[194:197], v[186:189], v[60:63]
	v_mfma_f32_16x16x32_f16 v[56:59], v[202:205], v[178:181], v[56:59]
	v_mfma_f32_16x16x32_f16 v[52:55], v[202:205], v[186:189], v[52:55]
	v_mfma_f32_16x16x32_f16 v[48:51], v[210:213], v[178:181], v[48:51]
	v_mfma_f32_16x16x32_f16 v[44:47], v[210:213], v[186:189], v[44:47]
	v_mfma_f32_16x16x32_f16 v[40:43], v[218:221], v[178:181], v[40:43]
	v_mfma_f32_16x16x32_f16 v[36:39], v[218:221], v[186:189], v[36:39]
	s_barrier
	v_lshl_add_u64 v[174:175], v[246:247], 0, s[46:47]
	s_or_b32 m0, s100, 0x1c000
	s_nop 0
	global_load_lds_dwordx4 v[174:175], off
	v_lshl_add_u64 v[174:175], v[248:249], 0, s[46:47]
	s_or_b32 m0, s100, 0x1e000
	s_nop 0
	global_load_lds_dwordx4 v[174:175], off
	s_waitcnt vmcnt(6)
	s_barrier
	v_mfma_f32_16x16x32_f16 v[32:35], v[190:193], v[226:229], v[32:35]
	v_mfma_f32_16x16x32_f16 v[28:31], v[190:193], v[238:241], v[28:31]
	v_mfma_f32_16x16x32_f16 v[24:27], v[198:201], v[226:229], v[24:27]
	v_mfma_f32_16x16x32_f16 v[20:23], v[198:201], v[238:241], v[20:23]
	v_mfma_f32_16x16x32_f16 v[16:19], v[206:209], v[226:229], v[16:19]
	v_mfma_f32_16x16x32_f16 v[12:15], v[206:209], v[238:241], v[12:15]
	v_mfma_f32_16x16x32_f16 v[8:11], v[214:217], v[226:229], v[8:11]
	v_mfma_f32_16x16x32_f16 v[4:7], v[214:217], v[238:241], v[4:7]
	v_mfma_f32_16x16x32_f16 v[32:35], v[194:197], v[230:233], v[32:35]
	v_mfma_f32_16x16x32_f16 v[28:31], v[194:197], v[242:245], v[28:31]
	v_mfma_f32_16x16x32_f16 v[24:27], v[202:205], v[230:233], v[24:27]
	v_mfma_f32_16x16x32_f16 v[20:23], v[202:205], v[242:245], v[20:23]
	v_mfma_f32_16x16x32_f16 v[16:19], v[210:213], v[230:233], v[16:19]
	v_mfma_f32_16x16x32_f16 v[12:15], v[210:213], v[242:245], v[12:15]
	v_mfma_f32_16x16x32_f16 v[8:11], v[218:221], v[230:233], v[8:11]
	v_mfma_f32_16x16x32_f16 v[4:7], v[218:221], v[242:245], v[4:7]
	s_add_i32 s14, s14, 2
	s_add_u32 s12, s12, 0x100
	s_addc_u32 s13, s13, 0
	s_cmp_lt_u32 s14, 12
	s_barrier
	s_cbranch_scc1 .LBB0_1015
	s_add_u32 s8, s8, 0x40780
	s_addc_u32 s9, s9, 0
	v_lshl_add_u64 v[132:133], s[8:9], 0, v[132:133]
	v_lshl_add_u64 v[0:1], v[0:1], 1, v[132:133]
	s_or_b32 m0, s100, 0xc000
	ds_read_b128 v[138:141], v171
	ds_read_b128 v[142:145], v171 offset:1024
	ds_read_b128 v[162:165], v171 offset:2048
	ds_read_b128 v[174:177], v171 offset:3072
	ds_read_b128 v[178:181], v156
	ds_read_b128 v[182:185], v156 offset:1024
	ds_read_b128 v[186:189], v155
	ds_read_b128 v[190:193], v155 offset:1024
	ds_read_b128 v[194:197], v154
	ds_read_b128 v[198:201], v154 offset:1024
	ds_read_b128 v[202:205], v153
	ds_read_b128 v[206:209], v153 offset:1024
	global_load_lds_dwordx4 v[0:1], off
	v_lshl_add_u64 v[0:1], s[8:9], 0, v[136:137]
	v_lshl_add_u64 v[0:1], v[134:135], 1, v[0:1]
	s_or_b32 m0, s100, 0xe000
	s_nop 0
	global_load_lds_dwordx4 v[0:1], off
	s_barrier
	s_waitcnt lgkmcnt(0)
	v_mfma_f32_16x16x32_f16 v[128:131], v[178:181], v[138:141], v[128:131]
	v_mfma_f32_16x16x32_f16 v[124:127], v[178:181], v[162:165], v[124:127]
	v_mfma_f32_16x16x32_f16 v[120:123], v[186:189], v[138:141], v[120:123]
	v_mfma_f32_16x16x32_f16 v[112:115], v[194:197], v[138:141], v[112:115]
	v_mfma_f32_16x16x32_f16 v[128:131], v[182:185], v[142:145], v[128:131]
	v_mfma_f32_16x16x32_f16 v[124:127], v[182:185], v[174:177], v[124:127]
	v_mfma_f32_16x16x32_f16 v[120:123], v[190:193], v[142:145], v[120:123]
	v_mfma_f32_16x16x32_f16 v[116:119], v[186:189], v[162:165], v[116:119]
	v_mfma_f32_16x16x32_f16 v[112:115], v[198:201], v[142:145], v[112:115]
	v_mfma_f32_16x16x32_f16 v[108:111], v[194:197], v[162:165], v[108:111]
	v_mfma_f32_16x16x32_f16 v[104:107], v[202:205], v[138:141], v[104:107]
	v_mfma_f32_16x16x32_f16 v[100:103], v[202:205], v[162:165], v[100:103]
	v_mfma_f32_16x16x32_f16 v[132:135], v[190:193], v[174:177], v[116:119]
	v_mfma_f32_16x16x32_f16 v[170:173], v[198:201], v[174:177], v[108:111]
	v_mfma_f32_16x16x32_f16 v[210:213], v[206:209], v[142:145], v[104:107]
	v_mfma_f32_16x16x32_f16 v[214:217], v[206:209], v[174:177], v[100:103]
	s_barrier
	s_nop 1
	ds_read_b128 v[100:103], v168
	ds_read_b128 v[104:107], v168 offset:1024
	ds_read_b128 v[108:111], v168 offset:2048
	ds_read_b128 v[116:119], v168 offset:3072
	s_barrier
	s_waitcnt lgkmcnt(0)
	v_mfma_f32_16x16x32_f16 v[80:83], v[194:197], v[100:103], v[80:83]
	v_mfma_f32_16x16x32_f16 v[76:79], v[194:197], v[108:111], v[76:79]
	v_mfma_f32_16x16x32_f16 v[72:75], v[202:205], v[100:103], v[72:75]
	v_mfma_f32_16x16x32_f16 v[68:71], v[202:205], v[108:111], v[68:71]
	v_mfma_f32_16x16x32_f16 v[96:99], v[178:181], v[100:103], v[96:99]
	v_mfma_f32_16x16x32_f16 v[92:95], v[178:181], v[108:111], v[92:95]
	v_mfma_f32_16x16x32_f16 v[88:91], v[186:189], v[100:103], v[88:91]
	v_mfma_f32_16x16x32_f16 v[84:87], v[186:189], v[108:111], v[84:87]
	v_mfma_f32_16x16x32_f16 v[80:83], v[198:201], v[104:107], v[80:83]
	v_mfma_f32_16x16x32_f16 v[76:79], v[198:201], v[116:119], v[76:79]
	v_mfma_f32_16x16x32_f16 v[72:75], v[206:209], v[104:107], v[72:75]
	v_mfma_f32_16x16x32_f16 v[68:71], v[206:209], v[116:119], v[68:71]
	v_mfma_f32_16x16x32_f16 v[166:169], v[182:185], v[104:107], v[96:99]
	v_mfma_f32_16x16x32_f16 v[178:181], v[182:185], v[116:119], v[92:95]
	v_mfma_f32_16x16x32_f16 v[182:185], v[190:193], v[104:107], v[88:91]
	v_mfma_f32_16x16x32_f16 v[186:189], v[190:193], v[116:119], v[84:87]
	s_barrier
; #define LDA8(dst, b, h) _Pragma("unroll") for (int m = 0; m < 4; ++m) _Pragma("unroll") for (int k = 0; k < 2; ++k) \
;     dst[m][k] = *(const bf16x8*)((const char*)SA8(b, h) + lds_byte8(wr * 64 + m * 16 + fr, k * 32 + fq * 8))
; #define LDB8(dst, b, h) _Pragma("unroll") for (int n = 0; n < 2; ++n) _Pragma("unroll") for (int k = 0; k < 2; ++k) \
;     dst[n][k] = *(const bf16x8*)((const char*)SB8(b, h) + lds_byte8(wc * 32 + n * 16 + fr, k * 32 + fq * 8))
; #define WAIT_V8(n) asm volatile("s_waitcnt vmcnt(" #n ")" ::: "memory")
; #define WAIT_L8(n) asm volatile("s_waitcnt lgkmcnt(" #n ")" ::: "memory")
; #define BAR8 __builtin_amdgcn_s_barrier()
;     ...
;     LDA8(At, 0, 1); WAIT_V8(4); BAR8; WAIT_L8(0); MMA8(1, 0, At, B0); MMA8(1, 1, At, B1); BAR8; }
;   { LDB8(B0, 1, 0); LDA8(At, 1, 0); WAIT_V8(2); BAR8; WAIT_L8(0); MMA8(0, 0, At, B0); BAR8;
	s_nop 0
	ds_read_b128 v[84:87], v156 offset:16384
	ds_read_b128 v[88:91], v156 offset:17408
	ds_read_b128 v[92:95], v155 offset:16384
	ds_read_b128 v[96:99], v155 offset:17408
	ds_read_b128 v[190:193], v154 offset:16384
	ds_read_b128 v[194:197], v154 offset:17408
	ds_read_b128 v[198:201], v153 offset:16384
	ds_read_b128 v[202:205], v153 offset:17408
	s_waitcnt vmcnt(4)
	s_barrier
	s_waitcnt lgkmcnt(0)
	v_mfma_f32_16x16x32_f16 v[64:67], v[84:87], v[138:141], v[64:67]
	v_mfma_f32_16x16x32_f16 v[60:63], v[84:87], v[162:165], v[60:63]
	v_mfma_f32_16x16x32_f16 v[56:59], v[92:95], v[138:141], v[56:59]
	v_mfma_f32_16x16x32_f16 v[52:55], v[92:95], v[162:165], v[52:55]
	v_mfma_f32_16x16x32_f16 v[48:51], v[190:193], v[138:141], v[48:51]
	v_mfma_f32_16x16x32_f16 v[44:47], v[190:193], v[162:165], v[44:47]
	v_mfma_f32_16x16x32_f16 v[40:43], v[198:201], v[138:141], v[40:43]
	v_mfma_f32_16x16x32_f16 v[36:39], v[198:201], v[162:165], v[36:39]
	v_mfma_f32_16x16x32_f16 v[64:67], v[88:91], v[142:145], v[64:67]
	v_mfma_f32_16x16x32_f16 v[60:63], v[88:91], v[174:177], v[60:63]
	v_mfma_f32_16x16x32_f16 v[56:59], v[96:99], v[142:145], v[56:59]
	v_mfma_f32_16x16x32_f16 v[52:55], v[96:99], v[174:177], v[52:55]
	v_mfma_f32_16x16x32_f16 v[48:51], v[194:197], v[142:145], v[48:51]
	v_mfma_f32_16x16x32_f16 v[44:47], v[194:197], v[174:177], v[44:47]
	v_mfma_f32_16x16x32_f16 v[40:43], v[202:205], v[142:145], v[40:43]
	v_mfma_f32_16x16x32_f16 v[36:39], v[202:205], v[174:177], v[36:39]
	v_mfma_f32_16x16x32_f16 v[32:35], v[84:87], v[100:103], v[32:35]
	v_mfma_f32_16x16x32_f16 v[28:31], v[84:87], v[108:111], v[28:31]
	v_mfma_f32_16x16x32_f16 v[24:27], v[92:95], v[100:103], v[24:27]
	v_mfma_f32_16x16x32_f16 v[20:23], v[92:95], v[108:111], v[20:23]
	v_mfma_f32_16x16x32_f16 v[16:19], v[190:193], v[100:103], v[16:19]
	v_mfma_f32_16x16x32_f16 v[12:15], v[190:193], v[108:111], v[12:15]
	v_mfma_f32_16x16x32_f16 v[8:11], v[198:201], v[100:103], v[8:11]
	v_mfma_f32_16x16x32_f16 v[4:7], v[198:201], v[108:111], v[4:7]
	v_mfma_f32_16x16x32_f16 v[136:139], v[88:91], v[104:107], v[32:35]
	v_mfma_f32_16x16x32_f16 v[140:143], v[88:91], v[116:119], v[28:31]
	v_mfma_f32_16x16x32_f16 v[162:165], v[96:99], v[104:107], v[24:27]
	v_mfma_f32_16x16x32_f16 v[174:177], v[96:99], v[116:119], v[20:23]
	v_mfma_f32_16x16x32_f16 v[206:209], v[194:197], v[104:107], v[16:19]
	v_mfma_f32_16x16x32_f16 v[190:193], v[194:197], v[116:119], v[12:15]
	v_mfma_f32_16x16x32_f16 v[194:197], v[202:205], v[104:107], v[8:11]
	v_mfma_f32_16x16x32_f16 v[198:201], v[202:205], v[116:119], v[4:7]
	s_barrier
	ds_read_b128 v[202:205], v161
	ds_read_b128 v[218:221], v161 offset:1024
	ds_read_b128 v[226:229], v161 offset:2048
	ds_read_b128 v[230:233], v161 offset:3072
	ds_read_b128 v[8:11], v156 offset:32768
	ds_read_b128 v[12:15], v156 offset:33792
	ds_read_b128 v[16:19], v155 offset:32768
	ds_read_b128 v[24:27], v155 offset:33792
	ds_read_b128 v[28:31], v154 offset:32768
	ds_read_b128 v[32:35], v154 offset:33792
	ds_read_b128 v[238:241], v153 offset:32768
	ds_read_b128 v[242:245], v153 offset:33792
	s_waitcnt vmcnt(2)
	s_barrier
	s_waitcnt lgkmcnt(0)
	v_mfma_f32_16x16x32_f16 v[4:7], v[8:11], v[202:205], v[128:131]
	v_mfma_f32_16x16x32_f16 v[104:107], v[12:15], v[218:221], v[4:7]
	v_mfma_f32_16x16x32_f16 v[4:7], v[8:11], v[226:229], v[124:127]
	v_mfma_f32_16x16x32_f16 v[116:119], v[12:15], v[230:233], v[4:7]
	v_mfma_f32_16x16x32_f16 v[4:7], v[16:19], v[202:205], v[120:123]
	v_mfma_f32_16x16x32_f16 v[100:103], v[24:27], v[218:221], v[4:7]
	v_mfma_f32_16x16x32_f16 v[4:7], v[16:19], v[226:229], v[132:135]
	v_mfma_f32_16x16x32_f16 v[108:111], v[24:27], v[230:233], v[4:7]
	v_mfma_f32_16x16x32_f16 v[4:7], v[28:31], v[202:205], v[112:115]
	v_mfma_f32_16x16x32_f16 v[92:95], v[32:35], v[218:221], v[4:7]
	v_mfma_f32_16x16x32_f16 v[4:7], v[28:31], v[226:229], v[170:173]
	v_mfma_f32_16x16x32_f16 v[96:99], v[32:35], v[230:233], v[4:7]
	v_mfma_f32_16x16x32_f16 v[4:7], v[238:241], v[202:205], v[210:213]
	v_mfma_f32_16x16x32_f16 v[84:87], v[242:245], v[218:221], v[4:7]
	v_mfma_f32_16x16x32_f16 v[4:7], v[238:241], v[226:229], v[214:217]
	v_mfma_f32_16x16x32_f16 v[88:91], v[242:245], v[230:233], v[4:7]
	s_barrier
; #define LDA8(dst, b, h) _Pragma("unroll") for (int m = 0; m < 4; ++m) _Pragma("unroll") for (int k = 0; k < 2; ++k) \
;     dst[m][k] = *(const bf16x8*)((const char*)SA8(b, h) + lds_byte8(wr * 64 + m * 16 + fr, k * 32 + fq * 8))
; #define LDB8(dst, b, h) _Pragma("unroll") for (int n = 0; n < 2; ++n) _Pragma("unroll") for (int k = 0; k < 2; ++k) \
;     dst[n][k] = *(const bf16x8*)((const char*)SB8(b, h) + lds_byte8(wc * 32 + n * 16 + fr, k * 32 + fq * 8))
; #define WAIT_V8(n) asm volatile("s_waitcnt vmcnt(" #n ")" ::: "memory")
; #define WAIT_L8(n) asm volatile("s_waitcnt lgkmcnt(" #n ")" ::: "memory")
; #define BAR8 __builtin_amdgcn_s_barrier()
;     ...
;   { LDB8(B0, 1, 0); LDA8(At, 1, 0); WAIT_V8(2); BAR8; WAIT_L8(0); MMA8(0, 0, At, B0); BAR8;
;     LDB8(B1, 1, 1); WAIT_V8(0); BAR8; WAIT_L8(0); MMA8(0, 1, At, B1); BAR8;
;     LDA8(At, 1, 1); BAR8; WAIT_L8(0); MMA8(1, 0, At, B0); MMA8(1, 1, At, B1); BAR8; }
;   if (wr == 0) BAR8;
;   __syncthreads();
;     ...
;   if (t < 256) {
	ds_read_b128 v[132:135], v158
	ds_read_b128 v[170:173], v158 offset:1024
	ds_read_b128 v[210:213], v158 offset:2048
	ds_read_b128 v[158:161], v158 offset:3072
	s_waitcnt vmcnt(0)
	s_barrier
	s_waitcnt lgkmcnt(0)
	v_mfma_f32_16x16x32_f16 v[4:7], v[8:11], v[132:135], v[166:169]
	v_mfma_f32_16x16x32_f16 v[8:11], v[8:11], v[210:213], v[178:181]
	v_mfma_f32_16x16x32_f16 v[4:7], v[12:15], v[170:173], v[4:7]
	v_mfma_f32_16x16x32_f16 v[20:23], v[12:15], v[158:161], v[8:11]
	v_mfma_f32_16x16x32_f16 v[8:11], v[16:19], v[132:135], v[182:185]
	v_mfma_f32_16x16x32_f16 v[12:15], v[16:19], v[210:213], v[186:189]
	v_mfma_f32_16x16x32_f16 v[8:11], v[24:27], v[170:173], v[8:11]
	v_mfma_f32_16x16x32_f16 v[24:27], v[24:27], v[158:161], v[12:15]
	v_mfma_f32_16x16x32_f16 v[12:15], v[28:31], v[132:135], v[80:83]
	v_mfma_f32_16x16x32_f16 v[16:19], v[28:31], v[210:213], v[76:79]
	v_mfma_f32_16x16x32_f16 v[12:15], v[32:35], v[170:173], v[12:15]
	v_mfma_f32_16x16x32_f16 v[28:31], v[32:35], v[158:161], v[16:19]
	v_mfma_f32_16x16x32_f16 v[16:19], v[238:241], v[132:135], v[72:75]
	v_mfma_f32_16x16x32_f16 v[32:35], v[238:241], v[210:213], v[68:71]
	v_mfma_f32_16x16x32_f16 v[16:19], v[242:245], v[170:173], v[16:19]
	v_mfma_f32_16x16x32_f16 v[32:35], v[242:245], v[158:161], v[32:35]
	s_barrier
	ds_read_b128 v[166:169], v156 offset:49152
	ds_read_b128 v[178:181], v156 offset:50176
	ds_read_b128 v[182:185], v155 offset:49152
	ds_read_b128 v[186:189], v155 offset:50176
	ds_read_b128 v[214:217], v154 offset:49152
	ds_read_b128 v[154:157], v154 offset:50176
	ds_read_b128 v[238:241], v153 offset:49152
	ds_read_b128 v[150:153], v153 offset:50176
	s_barrier
	s_waitcnt lgkmcnt(0)
	v_mfma_f32_16x16x32_f16 v[64:67], v[166:169], v[202:205], v[64:67]
	v_mfma_f32_16x16x32_f16 v[60:63], v[166:169], v[226:229], v[60:63]
	v_mfma_f32_16x16x32_f16 v[56:59], v[182:185], v[202:205], v[56:59]
	v_mfma_f32_16x16x32_f16 v[52:55], v[182:185], v[226:229], v[52:55]
	v_mfma_f32_16x16x32_f16 v[48:51], v[214:217], v[202:205], v[48:51]
	v_mfma_f32_16x16x32_f16 v[44:47], v[214:217], v[226:229], v[44:47]
	v_mfma_f32_16x16x32_f16 v[40:43], v[238:241], v[202:205], v[40:43]
	v_mfma_f32_16x16x32_f16 v[36:39], v[238:241], v[226:229], v[36:39]
	v_mfma_f32_16x16x32_f16 v[128:131], v[178:181], v[218:221], v[64:67]
	v_mfma_f32_16x16x32_f16 v[124:127], v[178:181], v[230:233], v[60:63]
	v_mfma_f32_16x16x32_f16 v[120:123], v[186:189], v[218:221], v[56:59]
	v_mfma_f32_16x16x32_f16 v[112:115], v[186:189], v[230:233], v[52:55]
	v_mfma_f32_16x16x32_f16 v[80:83], v[154:157], v[218:221], v[48:51]
	v_mfma_f32_16x16x32_f16 v[76:79], v[154:157], v[230:233], v[44:47]
	v_mfma_f32_16x16x32_f16 v[72:75], v[150:153], v[218:221], v[40:43]
	v_mfma_f32_16x16x32_f16 v[68:71], v[150:153], v[230:233], v[36:39]
	v_mfma_f32_16x16x32_f16 v[36:39], v[166:169], v[132:135], v[136:139]
	v_mfma_f32_16x16x32_f16 v[64:67], v[178:181], v[170:173], v[36:39]
	v_mfma_f32_16x16x32_f16 v[36:39], v[166:169], v[210:213], v[140:143]
	v_mfma_f32_16x16x32_f16 v[60:63], v[178:181], v[158:161], v[36:39]
	v_mfma_f32_16x16x32_f16 v[36:39], v[182:185], v[132:135], v[162:165]
	v_mfma_f32_16x16x32_f16 v[56:59], v[186:189], v[170:173], v[36:39]
	v_mfma_f32_16x16x32_f16 v[36:39], v[182:185], v[210:213], v[174:177]
	v_mfma_f32_16x16x32_f16 v[52:55], v[186:189], v[158:161], v[36:39]
	v_mfma_f32_16x16x32_f16 v[36:39], v[214:217], v[132:135], v[206:209]
	v_mfma_f32_16x16x32_f16 v[48:51], v[154:157], v[170:173], v[36:39]
	v_mfma_f32_16x16x32_f16 v[36:39], v[214:217], v[210:213], v[190:193]
	v_mfma_f32_16x16x32_f16 v[44:47], v[154:157], v[158:161], v[36:39]
	v_mfma_f32_16x16x32_f16 v[36:39], v[238:241], v[132:135], v[194:197]
	v_mfma_f32_16x16x32_f16 v[40:43], v[150:153], v[170:173], v[36:39]
	v_mfma_f32_16x16x32_f16 v[36:39], v[238:241], v[210:213], v[198:201]
	v_mfma_f32_16x16x32_f16 v[36:39], v[150:153], v[158:161], v[36:39]
	s_movk_i32 s8, 0x100
	v_cmp_gt_u32_e32 vcc, s8, v3
	s_barrier
	s_and_saveexec_b64 s[8:9], vcc
	s_cbranch_execz .LBB0_1018
	s_barrier

;     ...
;   const int brow = m0, bcol = n0;
;   const int wid = t >> 6, lane = t & 63, wr = wid >> 2, wc = wid & 3, fr = lane & 15, fq = lane >> 4;
;   f32x4 acc[2][2][4][2];
;   {
;     float zinit = 0.f;
;     asm volatile("" : "+v"(zinit));
; #pragma unroll
;     for (int a = 0; a < 2; ++a)
; #pragma unroll
;       for (int b = 0; b < 2; ++b)
; #pragma unroll
;         for (int m = 0; m < 4; ++m)
; #pragma unroll
;           for (int n = 0; n < 2; ++n)
; #pragma unroll
;             for (int j = 0; j < 4; ++j) acc[a][b][m][n][j] = zinit;
;   }
;   bf16x8 At[4][2], B0[2][2], B1[2][2];
;   const int nt = K / 64;
;   if (!pre) {
;     STAGE8(SB8(0, 0), Bt, K, bcol, 0); STAGE8(SA8(0, 0), A, lda, brow, 0);
;     STAGE8(SB8(0, 1), Bt, K, bcol + 128, 0); STAGE8(SA8(0, 1), A, lda, brow + 128, 0);
;   }
.LBB0_1149:
	s_mov_b32 s0, 24
	s_mov_b32 s0, 25
	s_ashr_i32 s1, s0, 31
	s_lshl_b64 s[0:1], s[0:1], 3
	s_add_u32 s0, s70, s0
	s_addc_u32 s1, s71, s1
	v_readlane_b32 s6, v255, 60
	v_readlane_b32 s7, v255, 61
	s_nop 4
	s_mov_b32 s0, 25
	s_ashr_i32 s1, s0, 31
	s_lshl_b64 s[0:1], s[0:1], 3
	s_add_u32 s0, s70, s0
	s_addc_u32 s1, s71, s1
	s_mov_b32 s2, 25
	v_readlane_b32 s0, v255, 60
	v_readlane_b32 s1, v255, 61
	s_nop 4
	s_ashr_i32 s3, s2, 31
	s_lshl_b64 s[2:3], s[2:3], 3
	s_add_u32 s2, s70, s2
	s_addc_u32 s3, s71, s3
	v_mov_b32_e32 v3, v224
	v_readlane_b32 s2, v255, 60
	v_readlane_b32 s3, v255, 61
	s_nop 4
	v_mov_b32_e32 v18, 1
	v_bfe_i32 v1, v3, 27, 1
	s_waitcnt vmcnt(10)
	v_lshlrev_b32_e32 v150, 4, v3
	s_nop 0
	v_readfirstlane_b32 s100, v150
	v_lshrrev_b32_e32 v1, 22, v1
	v_add_u32_e32 v1, v150, v1
	v_and_b32_e32 v1, 0xfffffc00, v1
	v_ashrrev_i32_e32 v0, 31, v3
	v_sub_u32_e32 v1, v150, v1
	v_lshrrev_b32_e32 v0, 26, v0
	v_lshrrev_b32_e32 v5, 4, v1
	v_add_u32_e32 v0, v3, v0
	v_bitop3_b32 v5, v5, v1, 32 bitop3:0x6c
	v_ashrrev_i32_e32 v1, 31, v1
	s_waitcnt lgkmcnt(0)
	s_add_u32 s29, s2, 0x3000000
	v_ashrrev_i32_e32 v0, 6, v0
	v_lshrrev_b32_e32 v1, 26, v1
	s_addc_u32 s33, s3, 0
	s_lshl_b32 s8, s24, 8
	v_lshlrev_b32_e32 v6, 3, v0
	v_add_u32_e32 v1, v5, v1
	s_and_b32 s25, s8, 0x3f00
	s_lshl_b32 s8, s24, 2
	v_and_b32_e32 v6, -16, v6
	v_ashrrev_i32_e32 v1, 6, v1
	s_and_b32 s8, s8, 0xffffff00
	v_add_u32_e32 v16, v1, v6
	v_mul_i32_i24_e32 v1, 64, v1
	s_ashr_i32 s9, s8, 31
	v_lshlrev_b32_e32 v0, 5, v0
	v_sub_u32_e32 v1, v5, v1
	s_waitcnt vmcnt(9)
	v_add_u32_e32 v152, 0x2000, v150
	s_lshl_b64 s[12:13], s[8:9], 10
	v_and_b32_e32 v0, 32, v0
	v_ashrrev_i16_sdwa v1, v18, sext(v1) dst_sel:DWORD dst_unused:UNUSED_PAD src0_sel:DWORD src1_sel:BYTE_0
	v_ashrrev_i32_e32 v5, 31, v152
	s_add_u32 s12, s14, s12
	v_add_u32_sdwa v0, v0, sext(v1) dst_sel:DWORD dst_unused:UNUSED_PAD src0_sel:DWORD src1_sel:WORD_0
	v_ashrrev_i32_e32 v17, 31, v16
	v_lshrrev_b32_e32 v5, 22, v5
	s_addc_u32 s13, s15, s13
	v_lshlrev_b64 v[6:7], 10, v[16:17]
	v_ashrrev_i32_e32 v1, 31, v0
	v_add_u32_e32 v5, v152, v5
	v_lshl_add_u64 v[10:11], s[12:13], 0, v[6:7]
	v_lshlrev_b64 v[8:9], 1, v[0:1]
	v_ashrrev_i32_e32 v5, 10, v5
	v_lshl_add_u64 v[14:15], v[10:11], 0, v[8:9]
	v_mul_i32_i24_e32 v10, 0x400, v5
	v_sub_u32_e32 v10, v152, v10
	v_lshrrev_b32_e32 v11, 4, v10
	v_bitop3_b32 v10, v11, v10, 32 bitop3:0x6c
	v_ashrrev_i32_e32 v12, 31, v10
	v_lshrrev_b32_e32 v12, 26, v12
	v_lshlrev_b32_e32 v11, 3, v5
	v_add_u32_e32 v12, v10, v12
	v_and_b32_e32 v11, -16, v11
	v_ashrrev_i32_e32 v13, 6, v12
	v_add_u32_e32 v24, v13, v11
	v_and_b32_e32 v11, 0xc0, v12
	v_lshlrev_b32_e32 v5, 5, v5
	v_sub_u32_e32 v10, v10, v11
	v_and_b32_e32 v5, 32, v5
	v_ashrrev_i16_sdwa v10, v18, sext(v10) dst_sel:DWORD dst_unused:UNUSED_PAD src0_sel:DWORD src1_sel:BYTE_0
	v_ashrrev_i32_e32 v25, 31, v24
	v_add_u32_sdwa v132, v5, sext(v10) dst_sel:DWORD dst_unused:UNUSED_PAD src0_sel:DWORD src1_sel:WORD_0
	v_lshlrev_b64 v[10:11], 10, v[24:25]
	s_waitcnt vmcnt(8)
	v_mov_b32_e32 v4, v2
	s_or_b32 m0, s100, 0x10000
	v_lshl_add_u64 v[18:19], s[12:13], 0, v[10:11]
	global_load_lds_dwordx4 v[14:15], off
	v_ashrrev_i32_e32 v133, 31, v132
	s_or_b32 m0, s100, 0x12000
	s_lshl_b32 s27, s25, 9
	s_lshl_b32 s12, s25, 10
	v_lshlrev_b64 v[12:13], 1, v[132:133]
	s_add_u32 s12, s29, s12
	v_lshl_add_u64 v[18:19], v[18:19], 0, v[12:13]
	s_addc_u32 s13, s33, 0
	global_load_lds_dwordx4 v[18:19], off
	v_lshl_add_u64 v[20:21], s[12:13], 0, v[6:7]
	s_mov_b32 m0, s100
	s_or_b32 s30, s8, 0x80
	v_lshl_add_u64 v[20:21], v[20:21], 0, v[8:9]
	v_lshl_add_u64 v[22:23], s[12:13], 0, v[10:11]
	s_ashr_i32 s31, s30, 31
	global_load_lds_dwordx4 v[20:21], off
	s_or_b32 m0, s100, 0x2000
	s_lshl_b64 s[12:13], s[30:31], 10
	s_add_u32 s12, s14, s12
	s_addc_u32 s13, s15, s13
	v_lshl_add_u64 v[22:23], v[22:23], 0, v[12:13]
	v_lshl_add_u64 v[26:27], s[12:13], 0, v[6:7]
	s_bitset1_b32 s27, 16
	global_load_lds_dwordx4 v[22:23], off
	v_lshl_add_u64 v[26:27], v[26:27], 0, v[8:9]
	s_or_b32 m0, s100, 0x14000
	v_lshl_add_u64 v[28:29], s[12:13], 0, v[10:11]
	s_lshl_b32 s27, s27, 1
	global_load_lds_dwordx4 v[26:27], off
	s_or_b32 m0, s100, 0x16000
	s_add_u32 s12, s29, s27
	s_addc_u32 s13, s33, 0
	v_lshl_add_u64 v[28:29], v[28:29], 0, v[12:13]
	v_lshl_add_u64 v[30:31], s[12:13], 0, v[6:7]
	global_load_lds_dwordx4 v[28:29], off
	v_lshl_add_u64 v[30:31], v[30:31], 0, v[8:9]
	s_or_b32 m0, s100, 0x4000
	global_load_lds_dwordx4 v[30:31], off
	v_lshl_add_u64 v[30:31], s[12:13], 0, v[10:11]
	v_lshl_add_u64 v[30:31], v[30:31], 0, v[12:13]
	s_or_b32 m0, s100, 0x6000
	v_ashrrev_i32_e32 v5, 8, v3
	global_load_lds_dwordx4 v[30:31], off
	v_cmp_eq_u32_e32 vcc, 1, v5
	s_and_saveexec_b64 s[12:13], vcc
	s_cbranch_execz .LBB0_1151
	s_barrier
; #define WAIT_V8(n) asm volatile("s_waitcnt vmcnt(" #n ")" ::: "memory")
; #define BAR8 __builtin_amdgcn_s_barrier()
;     ...
;   const int wid = t >> 6, lane = t & 63, wr = wid >> 2, wc = wid & 3, fr = lane & 15, fq = lane >> 4;
;   f32x4 acc[2][2][4][2];
;   {
;     float zinit = 0.f;
;     asm volatile("" : "+v"(zinit));
; #pragma unroll
;     for (int a = 0; a < 2; ++a)
; #pragma unroll
;       for (int b = 0; b < 2; ++b)
; #pragma unroll
;         for (int m = 0; m < 4; ++m)
; #pragma unroll
;           for (int n = 0; n < 2; ++n)
; #pragma unroll
;             for (int j = 0; j < 4; ++j) acc[a][b][m][n][j] = zinit;
;   }
;   bf16x8 At[4][2], B0[2][2], B1[2][2];
;     ...
;   if (wr == 1) BAR8;
;   WAIT_V8(4); BAR8;
;   STAGE8(SB8(1, 0), Bt, K, bcol, 1); STAGE8(SA8(1, 0), A, lda, brow, 1); STAGE8(SB8(1, 1), Bt, K, bcol + 128, 1);
;   WAIT_V8(6); BAR8;
.LBB0_1151:
	s_or_b64 exec, exec, s[12:13]
	s_lshl_b32 s29, s20, 10
	s_and_b32 s36, s29, 0xfc0000
	s_mov_b64 s[38:39], 0x80
	v_lshl_add_u64 v[14:15], v[14:15], 0, s[38:39]
	s_or_b32 m0, s100, 0x18000
	s_waitcnt vmcnt(4)
	s_barrier
	global_load_lds_dwordx4 v[14:15], off
	v_lshl_add_u64 v[14:15], v[18:19], 0, s[38:39]
	s_or_b32 m0, s100, 0x1a000
	global_load_lds_dwordx4 v[14:15], off
	v_lshl_add_u64 v[14:15], v[20:21], 0, s[38:39]
	s_or_b32 m0, s100, 0x8000
	global_load_lds_dwordx4 v[14:15], off
	v_lshl_add_u64 v[14:15], v[22:23], 0, s[38:39]
	s_or_b32 m0, s100, 0xa000
	global_load_lds_dwordx4 v[14:15], off
	v_lshl_add_u64 v[14:15], v[26:27], 0, s[38:39]
	s_or_b32 m0, s100, 0x1c000
	s_nop 0
	global_load_lds_dwordx4 v[14:15], off
	v_lshl_add_u64 v[14:15], v[28:29], 0, s[38:39]
	s_or_b32 m0, s100, 0x1e000
	v_and_b32_e32 v147, 15, v3
	global_load_lds_dwordx4 v[14:15], off
	v_bfe_u32 v148, v3, 4, 2
	v_lshlrev_b32_e32 v14, 4, v148
	v_lshlrev_b32_e32 v15, 6, v147
	v_lshlrev_b32_e32 v18, 2, v3
	v_lshlrev_b64 v[136:137], 9, v[16:17]
	v_or_b32_e32 v17, v14, v15
	v_and_b32_e32 v18, 32, v18
	s_mov_b32 s29, 0x10000
	s_and_b32 s12, s21, 0xffffff00
	v_bitop3_b32 v20, v17, s29, v18 bitop3:0xde
	s_mov_b32 s29, 0x14000
	s_ashr_i32 s13, s12, 31
	v_readlane_b32 s40, v254, 35
	v_bitop3_b32 v19, v14, v18, v15 bitop3:0x36
	v_bitop3_b32 v21, v17, s29, v18 bitop3:0xde
	s_mov_b32 s29, 0x18000
	v_lshlrev_b32_e32 v15, 6, v3
	s_lshl_b64 s[12:13], s[12:13], 10
	s_mov_b32 s37, s40
	v_bitop3_b32 v22, v17, s29, v18 bitop3:0xde
	s_mov_b32 s29, 0x1c000
	v_and_b32_e32 v15, 0x3c0, v15
	v_bitop3_b32 v17, v17, s29, v18 bitop3:0xde
	v_bitop3_b32 v18, v15, v18, v14 bitop3:0x36
	v_lshl_add_u64 v[14:15], s[12:13], 0, v[6:7]
	v_lshl_add_u64 v[6:7], s[36:37], 0, v[6:7]
	v_lshl_add_u64 v[14:15], v[14:15], 0, v[8:9]
	v_lshl_add_u64 v[6:7], v[6:7], 0, v[8:9]
	v_bfe_u32 v146, v3, 6, 2
	s_waitcnt vmcnt(6)
	v_lshlrev_b32_e32 v149, 6, v5
	v_lshlrev_b32_e32 v5, 13, v5
	v_lshl_add_u64 v[138:139], s[4:5], 0, v[14:15]
	v_lshl_add_u64 v[14:15], s[12:13], 0, v[10:11]
	v_lshl_add_u64 v[142:143], s[2:3], 0, v[6:7]
	v_lshl_add_u64 v[6:7], s[36:37], 0, v[10:11]
	v_lshlrev_b64 v[134:135], 9, v[24:25]
	v_readlane_b32 s41, v254, 36
	v_readlane_b32 s42, v254, 37
	v_readlane_b32 s43, v254, 38
	v_lshlrev_b32_e32 v16, 12, v146
	v_or_b32_e32 v23, 0x800, v5
	v_or_b32_e32 v24, 0x1000, v5
	v_or_b32_e32 v25, 0x1800, v5
	v_lshl_add_u64 v[14:15], v[14:15], 0, v[12:13]
	v_lshl_add_u64 v[6:7], v[6:7], 0, v[12:13]
	v_lshl_add_u64 v[140:141], s[4:5], 0, v[14:15]
	v_lshl_add_u64 v[144:145], s[2:3], 0, v[6:7]
	s_mov_b32 s29, -2
	s_mov_b64 s[12:13], 0
	v_add_u32_e32 v171, v20, v16
	v_add_u32_e32 v156, v19, v5
	v_add_u32_e32 v155, v18, v23
	v_add_u32_e32 v154, v18, v24
	v_add_u32_e32 v153, v18, v25
	v_add_u32_e32 v167, v21, v16
	v_add_u32_e32 v160, v22, v16
	v_add_u32_e32 v158, v17, v16
	v_mov_b32_e32 v5, v4
	v_mov_b64_e32 v[6:7], v[4:5]
	v_mov_b64_e32 v[8:9], v[4:5]
	v_mov_b64_e32 v[10:11], v[4:5]
	v_mov_b64_e32 v[12:13], v[4:5]
	v_mov_b64_e32 v[14:15], v[4:5]
	v_mov_b64_e32 v[16:17], v[4:5]
	v_mov_b64_e32 v[18:19], v[4:5]
	v_mov_b64_e32 v[20:21], v[4:5]
	v_mov_b64_e32 v[22:23], v[4:5]
	v_mov_b64_e32 v[24:25], v[4:5]
	v_mov_b64_e32 v[26:27], v[4:5]
	v_mov_b64_e32 v[28:29], v[4:5]
	v_mov_b64_e32 v[30:31], v[4:5]
	v_mov_b64_e32 v[32:33], v[4:5]
	v_mov_b64_e32 v[34:35], v[4:5]
	v_mov_b64_e32 v[36:37], v[4:5]
	v_mov_b64_e32 v[38:39], v[4:5]
	v_mov_b64_e32 v[40:41], v[4:5]
	v_mov_b64_e32 v[42:43], v[4:5]
	v_mov_b64_e32 v[44:45], v[4:5]
	v_mov_b64_e32 v[46:47], v[4:5]
	v_mov_b64_e32 v[48:49], v[4:5]
	v_mov_b64_e32 v[50:51], v[4:5]
	v_mov_b64_e32 v[52:53], v[4:5]
	v_mov_b64_e32 v[54:55], v[4:5]
	v_mov_b64_e32 v[56:57], v[4:5]
	v_mov_b64_e32 v[58:59], v[4:5]
	v_mov_b64_e32 v[60:61], v[4:5]
	v_mov_b64_e32 v[62:63], v[4:5]
	v_mov_b64_e32 v[64:65], v[4:5]
	v_mov_b64_e32 v[66:67], v[4:5]
	v_mov_b64_e32 v[68:69], v[4:5]
	v_mov_b64_e32 v[70:71], v[4:5]
	v_mov_b64_e32 v[72:73], v[4:5]
	v_mov_b64_e32 v[74:75], v[4:5]
	v_mov_b64_e32 v[76:77], v[4:5]
	v_mov_b64_e32 v[78:79], v[4:5]
	v_mov_b64_e32 v[80:81], v[4:5]
	v_mov_b64_e32 v[82:83], v[4:5]
	v_mov_b64_e32 v[84:85], v[4:5]
	v_mov_b64_e32 v[86:87], v[4:5]
	v_mov_b64_e32 v[88:89], v[4:5]
	v_mov_b64_e32 v[90:91], v[4:5]
	v_mov_b64_e32 v[92:93], v[4:5]
	v_mov_b64_e32 v[94:95], v[4:5]
	v_mov_b64_e32 v[96:97], v[4:5]
	v_mov_b64_e32 v[98:99], v[4:5]
	v_mov_b64_e32 v[100:101], v[4:5]
	v_mov_b64_e32 v[102:103], v[4:5]
	v_mov_b64_e32 v[104:105], v[4:5]
	v_mov_b64_e32 v[106:107], v[4:5]
	v_mov_b64_e32 v[108:109], v[4:5]
	v_mov_b64_e32 v[110:111], v[4:5]
	v_mov_b64_e32 v[112:113], v[4:5]
	v_mov_b64_e32 v[114:115], v[4:5]
	v_mov_b64_e32 v[116:117], v[4:5]
	v_mov_b64_e32 v[118:119], v[4:5]
	v_mov_b64_e32 v[120:121], v[4:5]
	v_mov_b64_e32 v[122:123], v[4:5]
	v_mov_b64_e32 v[124:125], v[4:5]
	v_mov_b64_e32 v[126:127], v[4:5]
	v_mov_b64_e32 v[128:129], v[4:5]
	v_mov_b64_e32 v[130:131], v[4:5]
	s_mov_b64 s[36:37], 0x3020080
	s_mov_b64 s[38:39], 0xc9a0100
	s_mov_b64 s[40:41], 0x3000100
	s_mov_b64 s[42:43], 0xc9c0100
	s_mov_b64 s[44:45], 0x3020100
	s_mov_b64 s[46:47], 0xc9a0180
	s_mov_b64 s[48:49], 0x3000180
	s_mov_b64 s[50:51], 0xc9c0180
	s_barrier
; #define LDA8(dst, b, h) _Pragma("unroll") for (int m = 0; m < 4; ++m) _Pragma("unroll") for (int k = 0; k < 2; ++k) \
;     dst[m][k] = *(const bf16x8*)((const char*)SA8(b, h) + lds_byte8(wr * 64 + m * 16 + fr, k * 32 + fq * 8))
; #define LDB8(dst, b, h) _Pragma("unroll") for (int n = 0; n < 2; ++n) _Pragma("unroll") for (int k = 0; k < 2; ++k) \
;     dst[n][k] = *(const bf16x8*)((const char*)SB8(b, h) + lds_byte8(wc * 32 + n * 16 + fr, k * 32 + fq * 8))
; #define WAIT_V8(n) asm volatile("s_waitcnt vmcnt(" #n ")" ::: "memory")
; #define WAIT_L8(n) asm volatile("s_waitcnt lgkmcnt(" #n ")" ::: "memory")
; #define BAR8 __builtin_amdgcn_s_barrier()
; #define SCHED8 __builtin_amdgcn_sched_barrier(0)
;     ...
;   for (int tt = 0; tt < nt - 2; tt += 2) {
;     LDB8(B0, 0, 0); SCHED8; LDA8(At, 0, 0); STAGE8(SA8(1, 1), A, lda, brow + 128, tt + 1);
;     WAIT_L8(8); BAR8; WAIT_L8(0); MMA8(0, 0, At, B0); BAR8; SCHED8;
;     LDB8(B1, 0, 1); STAGE8(SB8(0, 0), Bt, K, bcol, tt + 2);
;     BAR8; WAIT_L8(0); MMA8(0, 1, At, B1); BAR8;
;     LDA8(At, 0, 1); STAGE8(SA8(0, 0), A, lda, brow, tt + 2);
;     BAR8; WAIT_L8(0); MMA8(1, 0, At, B0); BAR8; SCHED8;
;     STAGE8(SB8(0, 1), Bt, K, bcol + 128, tt + 2);
;     WAIT_V8(6); BAR8; MMA8(1, 1, At, B1); BAR8;
.LBB0_1152:
	ds_read_b128 v[174:177], v171
	ds_read_b128 v[178:181], v171 offset:1024
	ds_read_b128 v[182:185], v171 offset:2048
	ds_read_b128 v[186:189], v171 offset:3072
	v_lshl_add_u64 v[222:223], v[142:143], 0, s[12:13]
	v_lshl_add_u64 v[226:227], v[222:223], 0, s[36:37]
	s_or_b32 m0, s100, 0xc000
	v_lshl_add_u64 v[236:237], v[144:145], 0, s[12:13]
	ds_read_b128 v[190:193], v156
	ds_read_b128 v[194:197], v156 offset:1024
	ds_read_b128 v[198:201], v155
	ds_read_b128 v[202:205], v155 offset:1024
	ds_read_b128 v[206:209], v154
	ds_read_b128 v[210:213], v154 offset:1024
	ds_read_b128 v[214:217], v153
	ds_read_b128 v[218:221], v153 offset:1024
	global_load_lds_dwordx4 v[226:227], off
	v_lshl_add_u64 v[226:227], v[236:237], 0, s[36:37]
	s_or_b32 m0, s100, 0xe000
	s_nop 0
	global_load_lds_dwordx4 v[226:227], off
	s_waitcnt lgkmcnt(8)
	s_barrier
	s_waitcnt lgkmcnt(0)
	v_mfma_f32_16x16x32_bf16 v[128:131], v[190:193], v[174:177], v[128:131]
	v_mfma_f32_16x16x32_bf16 v[124:127], v[190:193], v[182:185], v[124:127]
	v_mfma_f32_16x16x32_bf16 v[120:123], v[198:201], v[174:177], v[120:123]
	v_mfma_f32_16x16x32_bf16 v[116:119], v[198:201], v[182:185], v[116:119]
	v_mfma_f32_16x16x32_bf16 v[112:115], v[206:209], v[174:177], v[112:115]
	v_mfma_f32_16x16x32_bf16 v[108:111], v[206:209], v[182:185], v[108:111]
	v_mfma_f32_16x16x32_bf16 v[104:107], v[214:217], v[174:177], v[104:107]
	v_mfma_f32_16x16x32_bf16 v[100:103], v[214:217], v[182:185], v[100:103]
	v_mfma_f32_16x16x32_bf16 v[128:131], v[194:197], v[178:181], v[128:131]
	v_mfma_f32_16x16x32_bf16 v[124:127], v[194:197], v[186:189], v[124:127]
	v_mfma_f32_16x16x32_bf16 v[120:123], v[202:205], v[178:181], v[120:123]
	v_mfma_f32_16x16x32_bf16 v[116:119], v[202:205], v[186:189], v[116:119]
	v_mfma_f32_16x16x32_bf16 v[112:115], v[210:213], v[178:181], v[112:115]
	v_mfma_f32_16x16x32_bf16 v[108:111], v[210:213], v[186:189], v[108:111]
	v_mfma_f32_16x16x32_bf16 v[104:107], v[218:221], v[178:181], v[104:107]
	v_mfma_f32_16x16x32_bf16 v[100:103], v[218:221], v[186:189], v[100:103]
	s_barrier
	v_lshl_add_u64 v[246:247], v[138:139], 0, s[12:13]
	v_lshl_add_u64 v[248:249], v[246:247], 0, s[38:39]
	s_or_b32 m0, s100, 0x10000
	ds_read_b128 v[226:229], v167
	ds_read_b128 v[230:233], v167 offset:1024
	ds_read_b128 v[238:241], v167 offset:2048
	ds_read_b128 v[242:245], v167 offset:3072
	global_load_lds_dwordx4 v[248:249], off
	v_lshl_add_u64 v[248:249], v[140:141], 0, s[12:13]
	v_lshl_add_u64 v[250:251], v[248:249], 0, s[38:39]
	s_or_b32 m0, s100, 0x12000
	s_nop 0
	global_load_lds_dwordx4 v[250:251], off
	s_barrier
	s_waitcnt lgkmcnt(0)
	v_mfma_f32_16x16x32_bf16 v[96:99], v[190:193], v[226:229], v[96:99]
	v_mfma_f32_16x16x32_bf16 v[92:95], v[190:193], v[238:241], v[92:95]
	v_mfma_f32_16x16x32_bf16 v[88:91], v[198:201], v[226:229], v[88:91]
	v_mfma_f32_16x16x32_bf16 v[84:87], v[198:201], v[238:241], v[84:87]
	v_mfma_f32_16x16x32_bf16 v[80:83], v[206:209], v[226:229], v[80:83]
	v_mfma_f32_16x16x32_bf16 v[76:79], v[206:209], v[238:241], v[76:79]
	v_mfma_f32_16x16x32_bf16 v[72:75], v[214:217], v[226:229], v[72:75]
	v_mfma_f32_16x16x32_bf16 v[68:71], v[214:217], v[238:241], v[68:71]
	v_mfma_f32_16x16x32_bf16 v[96:99], v[194:197], v[230:233], v[96:99]
	v_mfma_f32_16x16x32_bf16 v[92:95], v[194:197], v[242:245], v[92:95]
	v_mfma_f32_16x16x32_bf16 v[88:91], v[202:205], v[230:233], v[88:91]
	v_mfma_f32_16x16x32_bf16 v[84:87], v[202:205], v[242:245], v[84:87]
	v_mfma_f32_16x16x32_bf16 v[80:83], v[210:213], v[230:233], v[80:83]
	v_mfma_f32_16x16x32_bf16 v[76:79], v[210:213], v[242:245], v[76:79]
	v_mfma_f32_16x16x32_bf16 v[72:75], v[218:221], v[230:233], v[72:75]
	v_mfma_f32_16x16x32_bf16 v[68:71], v[218:221], v[242:245], v[68:71]
	v_lshl_add_u64 v[250:251], v[222:223], 0, s[40:41]
	s_mov_b32 m0, s100
	s_barrier
	ds_read_b128 v[190:193], v156 offset:16384
	ds_read_b128 v[194:197], v156 offset:17408
	ds_read_b128 v[198:201], v155 offset:16384
	ds_read_b128 v[202:205], v155 offset:17408
	ds_read_b128 v[206:209], v154 offset:16384
	ds_read_b128 v[210:213], v154 offset:17408
	ds_read_b128 v[214:217], v153 offset:16384
	ds_read_b128 v[218:221], v153 offset:17408
	global_load_lds_dwordx4 v[250:251], off
	v_lshl_add_u64 v[250:251], v[236:237], 0, s[40:41]
	s_or_b32 m0, s100, 0x2000
	s_nop 0
	global_load_lds_dwordx4 v[250:251], off
	s_barrier
	s_waitcnt lgkmcnt(0)
	v_mfma_f32_16x16x32_bf16 v[64:67], v[190:193], v[174:177], v[64:67]
	v_mfma_f32_16x16x32_bf16 v[60:63], v[190:193], v[182:185], v[60:63]
	v_mfma_f32_16x16x32_bf16 v[56:59], v[198:201], v[174:177], v[56:59]
	v_mfma_f32_16x16x32_bf16 v[52:55], v[198:201], v[182:185], v[52:55]
	v_mfma_f32_16x16x32_bf16 v[48:51], v[206:209], v[174:177], v[48:51]
	v_mfma_f32_16x16x32_bf16 v[44:47], v[206:209], v[182:185], v[44:47]
	v_mfma_f32_16x16x32_bf16 v[40:43], v[214:217], v[174:177], v[40:43]
	v_mfma_f32_16x16x32_bf16 v[36:39], v[214:217], v[182:185], v[36:39]
	v_mfma_f32_16x16x32_bf16 v[64:67], v[194:197], v[178:181], v[64:67]
	v_mfma_f32_16x16x32_bf16 v[60:63], v[194:197], v[186:189], v[60:63]
	v_mfma_f32_16x16x32_bf16 v[56:59], v[202:205], v[178:181], v[56:59]
	v_mfma_f32_16x16x32_bf16 v[52:55], v[202:205], v[186:189], v[52:55]
	v_mfma_f32_16x16x32_bf16 v[48:51], v[210:213], v[178:181], v[48:51]
	v_mfma_f32_16x16x32_bf16 v[44:47], v[210:213], v[186:189], v[44:47]
	v_mfma_f32_16x16x32_bf16 v[40:43], v[218:221], v[178:181], v[40:43]
	v_mfma_f32_16x16x32_bf16 v[36:39], v[218:221], v[186:189], v[36:39]
	s_barrier
	v_lshl_add_u64 v[174:175], v[246:247], 0, s[42:43]
	s_or_b32 m0, s100, 0x14000
	s_nop 0
	global_load_lds_dwordx4 v[174:175], off
	v_lshl_add_u64 v[174:175], v[248:249], 0, s[42:43]
	s_or_b32 m0, s100, 0x16000
	s_nop 0
	global_load_lds_dwordx4 v[174:175], off
	s_waitcnt vmcnt(6)
	s_barrier
; #define LDA8(dst, b, h) _Pragma("unroll") for (int m = 0; m < 4; ++m) _Pragma("unroll") for (int k = 0; k < 2; ++k) \
;     dst[m][k] = *(const bf16x8*)((const char*)SA8(b, h) + lds_byte8(wr * 64 + m * 16 + fr, k * 32 + fq * 8))
; #define LDB8(dst, b, h) _Pragma("unroll") for (int n = 0; n < 2; ++n) _Pragma("unroll") for (int k = 0; k < 2; ++k) \
;     dst[n][k] = *(const bf16x8*)((const char*)SB8(b, h) + lds_byte8(wc * 32 + n * 16 + fr, k * 32 + fq * 8))
; #define WAIT_V8(n) asm volatile("s_waitcnt vmcnt(" #n ")" ::: "memory")
; #define WAIT_L8(n) asm volatile("s_waitcnt lgkmcnt(" #n ")" ::: "memory")
; #define BAR8 __builtin_amdgcn_s_barrier()
; #define SCHED8 __builtin_amdgcn_sched_barrier(0)
;     ...
;     WAIT_V8(6); BAR8; MMA8(1, 1, At, B1); BAR8;
;     LDB8(B0, 1, 0); SCHED8; LDA8(At, 1, 0); STAGE8(SA8(0, 1), A, lda, brow + 128, tt + 2);
;     WAIT_L8(8); BAR8; WAIT_L8(0); MMA8(0, 0, At, B0); BAR8; SCHED8;
;     LDB8(B1, 1, 1); STAGE8(SB8(1, 0), Bt, K, bcol, tt + 3);
;     BAR8; WAIT_L8(0); MMA8(0, 1, At, B1); BAR8;
;     LDA8(At, 1, 1); STAGE8(SA8(1, 0), A, lda, brow, tt + 3);
;     BAR8; WAIT_L8(0); MMA8(1, 0, At, B0); BAR8; SCHED8;
	v_mfma_f32_16x16x32_bf16 v[32:35], v[190:193], v[226:229], v[32:35]
	v_mfma_f32_16x16x32_bf16 v[28:31], v[190:193], v[238:241], v[28:31]
	v_mfma_f32_16x16x32_bf16 v[24:27], v[198:201], v[226:229], v[24:27]
	v_mfma_f32_16x16x32_bf16 v[20:23], v[198:201], v[238:241], v[20:23]
	v_mfma_f32_16x16x32_bf16 v[16:19], v[206:209], v[226:229], v[16:19]
	v_mfma_f32_16x16x32_bf16 v[12:15], v[206:209], v[238:241], v[12:15]
	v_mfma_f32_16x16x32_bf16 v[8:11], v[214:217], v[226:229], v[8:11]
	v_mfma_f32_16x16x32_bf16 v[4:7], v[214:217], v[238:241], v[4:7]
	v_mfma_f32_16x16x32_bf16 v[32:35], v[194:197], v[230:233], v[32:35]
	v_mfma_f32_16x16x32_bf16 v[28:31], v[194:197], v[242:245], v[28:31]
	v_mfma_f32_16x16x32_bf16 v[24:27], v[202:205], v[230:233], v[24:27]
	v_mfma_f32_16x16x32_bf16 v[20:23], v[202:205], v[242:245], v[20:23]
	v_mfma_f32_16x16x32_bf16 v[16:19], v[210:213], v[230:233], v[16:19]
	v_mfma_f32_16x16x32_bf16 v[12:15], v[210:213], v[242:245], v[12:15]
	v_mfma_f32_16x16x32_bf16 v[8:11], v[218:221], v[230:233], v[8:11]
	v_mfma_f32_16x16x32_bf16 v[4:7], v[218:221], v[242:245], v[4:7]
	s_barrier
	ds_read_b128 v[174:177], v160
	ds_read_b128 v[178:181], v160 offset:1024
	ds_read_b128 v[182:185], v160 offset:2048
	ds_read_b128 v[186:189], v160 offset:3072
	v_lshl_add_u64 v[226:227], v[222:223], 0, s[44:45]
	s_or_b32 m0, s100, 0x4000
	ds_read_b128 v[190:193], v156 offset:32768
	ds_read_b128 v[194:197], v156 offset:33792
	ds_read_b128 v[198:201], v155 offset:32768
	ds_read_b128 v[202:205], v155 offset:33792
	ds_read_b128 v[206:209], v154 offset:32768
	ds_read_b128 v[210:213], v154 offset:33792
	ds_read_b128 v[214:217], v153 offset:32768
	ds_read_b128 v[218:221], v153 offset:33792
	global_load_lds_dwordx4 v[226:227], off
	v_lshl_add_u64 v[226:227], v[236:237], 0, s[44:45]
	s_or_b32 m0, s100, 0x6000
	s_nop 0
	global_load_lds_dwordx4 v[226:227], off
	s_waitcnt lgkmcnt(8)
	s_barrier
	s_waitcnt lgkmcnt(0)
	v_mfma_f32_16x16x32_bf16 v[128:131], v[190:193], v[174:177], v[128:131]
	v_mfma_f32_16x16x32_bf16 v[124:127], v[190:193], v[182:185], v[124:127]
	v_mfma_f32_16x16x32_bf16 v[120:123], v[198:201], v[174:177], v[120:123]
	v_mfma_f32_16x16x32_bf16 v[116:119], v[198:201], v[182:185], v[116:119]
	v_mfma_f32_16x16x32_bf16 v[112:115], v[206:209], v[174:177], v[112:115]
	v_mfma_f32_16x16x32_bf16 v[108:111], v[206:209], v[182:185], v[108:111]
	v_mfma_f32_16x16x32_bf16 v[104:107], v[214:217], v[174:177], v[104:107]
	v_mfma_f32_16x16x32_bf16 v[100:103], v[214:217], v[182:185], v[100:103]
	v_mfma_f32_16x16x32_bf16 v[128:131], v[194:197], v[178:181], v[128:131]
	v_mfma_f32_16x16x32_bf16 v[124:127], v[194:197], v[186:189], v[124:127]
	v_mfma_f32_16x16x32_bf16 v[120:123], v[202:205], v[178:181], v[120:123]
	v_mfma_f32_16x16x32_bf16 v[116:119], v[202:205], v[186:189], v[116:119]
	v_mfma_f32_16x16x32_bf16 v[112:115], v[210:213], v[178:181], v[112:115]
	v_mfma_f32_16x16x32_bf16 v[108:111], v[210:213], v[186:189], v[108:111]
	v_mfma_f32_16x16x32_bf16 v[104:107], v[218:221], v[178:181], v[104:107]
	v_mfma_f32_16x16x32_bf16 v[100:103], v[218:221], v[186:189], v[100:103]
	s_barrier
	v_lshl_add_u64 v[250:251], v[246:247], 0, s[46:47]
	s_or_b32 m0, s100, 0x18000
	ds_read_b128 v[226:229], v158
	ds_read_b128 v[230:233], v158 offset:1024
	ds_read_b128 v[238:241], v158 offset:2048
	ds_read_b128 v[242:245], v158 offset:3072
	global_load_lds_dwordx4 v[250:251], off
	v_lshl_add_u64 v[250:251], v[248:249], 0, s[46:47]
	s_or_b32 m0, s100, 0x1a000
	s_nop 0
	global_load_lds_dwordx4 v[250:251], off
	s_barrier
	s_waitcnt lgkmcnt(0)
	v_mfma_f32_16x16x32_bf16 v[96:99], v[190:193], v[226:229], v[96:99]
	v_mfma_f32_16x16x32_bf16 v[92:95], v[190:193], v[238:241], v[92:95]
	v_mfma_f32_16x16x32_bf16 v[88:91], v[198:201], v[226:229], v[88:91]
	v_mfma_f32_16x16x32_bf16 v[84:87], v[198:201], v[238:241], v[84:87]
	v_mfma_f32_16x16x32_bf16 v[80:83], v[206:209], v[226:229], v[80:83]
	v_mfma_f32_16x16x32_bf16 v[76:79], v[206:209], v[238:241], v[76:79]
	v_mfma_f32_16x16x32_bf16 v[72:75], v[214:217], v[226:229], v[72:75]
	v_mfma_f32_16x16x32_bf16 v[68:71], v[214:217], v[238:241], v[68:71]
	v_mfma_f32_16x16x32_bf16 v[96:99], v[194:197], v[230:233], v[96:99]
	v_mfma_f32_16x16x32_bf16 v[92:95], v[194:197], v[242:245], v[92:95]
	v_mfma_f32_16x16x32_bf16 v[88:91], v[202:205], v[230:233], v[88:91]
	v_mfma_f32_16x16x32_bf16 v[84:87], v[202:205], v[242:245], v[84:87]
	v_mfma_f32_16x16x32_bf16 v[80:83], v[210:213], v[230:233], v[80:83]
	v_mfma_f32_16x16x32_bf16 v[76:79], v[210:213], v[242:245], v[76:79]
	v_mfma_f32_16x16x32_bf16 v[72:75], v[218:221], v[230:233], v[72:75]
	v_mfma_f32_16x16x32_bf16 v[68:71], v[218:221], v[242:245], v[68:71]
	v_lshl_add_u64 v[222:223], v[222:223], 0, s[48:49]
	s_or_b32 m0, s100, 0x8000
	s_barrier
	ds_read_b128 v[190:193], v156 offset:49152
	ds_read_b128 v[194:197], v156 offset:50176
	ds_read_b128 v[198:201], v155 offset:49152
	ds_read_b128 v[202:205], v155 offset:50176
	ds_read_b128 v[206:209], v154 offset:49152
	ds_read_b128 v[210:213], v154 offset:50176
	ds_read_b128 v[214:217], v153 offset:49152
	ds_read_b128 v[218:221], v153 offset:50176
	global_load_lds_dwordx4 v[222:223], off
	v_lshl_add_u64 v[222:223], v[236:237], 0, s[48:49]
	s_or_b32 m0, s100, 0xa000
	s_nop 0
	global_load_lds_dwordx4 v[222:223], off
	s_barrier
; #define LDA8(dst, b, h) _Pragma("unroll") for (int m = 0; m < 4; ++m) _Pragma("unroll") for (int k = 0; k < 2; ++k) \
;     dst[m][k] = *(const bf16x8*)((const char*)SA8(b, h) + lds_byte8(wr * 64 + m * 16 + fr, k * 32 + fq * 8))
; #define LDB8(dst, b, h) _Pragma("unroll") for (int n = 0; n < 2; ++n) _Pragma("unroll") for (int k = 0; k < 2; ++k) \
;     dst[n][k] = *(const bf16x8*)((const char*)SB8(b, h) + lds_byte8(wc * 32 + n * 16 + fr, k * 32 + fq * 8))
; #define WAIT_V8(n) asm volatile("s_waitcnt vmcnt(" #n ")" ::: "memory")
; #define WAIT_L8(n) asm volatile("s_waitcnt lgkmcnt(" #n ")" ::: "memory")
; #define BAR8 __builtin_amdgcn_s_barrier()
; #define SCHED8 __builtin_amdgcn_sched_barrier(0)
;     ...
;     BAR8; WAIT_L8(0); MMA8(1, 0, At, B0); BAR8; SCHED8;
;     STAGE8(SB8(1, 1), Bt, K, bcol + 128, tt + 3);
;     WAIT_V8(6); BAR8; MMA8(1, 1, At, B1); BAR8;
;   }
;   { LDB8(B0, 0, 0); LDA8(At, 0, 0); STAGE8(SA8(1, 1), A, lda, brow + 128, nt - 1);
;     BAR8; WAIT_L8(0); MMA8(0, 0, At, B0); BAR8;
;     LDB8(B1, 0, 1); BAR8; WAIT_L8(0); MMA8(0, 1, At, B1); BAR8;
;     LDA8(At, 0, 1); WAIT_V8(4); BAR8; WAIT_L8(0); MMA8(1, 0, At, B0); MMA8(1, 1, At, B1); BAR8; }
	s_waitcnt lgkmcnt(0)
	v_mfma_f32_16x16x32_bf16 v[64:67], v[190:193], v[174:177], v[64:67]
	v_mfma_f32_16x16x32_bf16 v[60:63], v[190:193], v[182:185], v[60:63]
	v_mfma_f32_16x16x32_bf16 v[56:59], v[198:201], v[174:177], v[56:59]
	v_mfma_f32_16x16x32_bf16 v[52:55], v[198:201], v[182:185], v[52:55]
	v_mfma_f32_16x16x32_bf16 v[48:51], v[206:209], v[174:177], v[48:51]
	v_mfma_f32_16x16x32_bf16 v[44:47], v[206:209], v[182:185], v[44:47]
	v_mfma_f32_16x16x32_bf16 v[40:43], v[214:217], v[174:177], v[40:43]
	v_mfma_f32_16x16x32_bf16 v[36:39], v[214:217], v[182:185], v[36:39]
	v_mfma_f32_16x16x32_bf16 v[64:67], v[194:197], v[178:181], v[64:67]
	v_mfma_f32_16x16x32_bf16 v[60:63], v[194:197], v[186:189], v[60:63]
	v_mfma_f32_16x16x32_bf16 v[56:59], v[202:205], v[178:181], v[56:59]
	v_mfma_f32_16x16x32_bf16 v[52:55], v[202:205], v[186:189], v[52:55]
	v_mfma_f32_16x16x32_bf16 v[48:51], v[210:213], v[178:181], v[48:51]
	v_mfma_f32_16x16x32_bf16 v[44:47], v[210:213], v[186:189], v[44:47]
	v_mfma_f32_16x16x32_bf16 v[40:43], v[218:221], v[178:181], v[40:43]
	v_mfma_f32_16x16x32_bf16 v[36:39], v[218:221], v[186:189], v[36:39]
	s_barrier
	v_lshl_add_u64 v[174:175], v[246:247], 0, s[50:51]
	s_or_b32 m0, s100, 0x1c000
	s_nop 0
	global_load_lds_dwordx4 v[174:175], off
	v_lshl_add_u64 v[174:175], v[248:249], 0, s[50:51]
	s_or_b32 m0, s100, 0x1e000
	s_nop 0
	global_load_lds_dwordx4 v[174:175], off
	s_waitcnt vmcnt(6)
	s_barrier
	v_mfma_f32_16x16x32_bf16 v[32:35], v[190:193], v[226:229], v[32:35]
	v_mfma_f32_16x16x32_bf16 v[28:31], v[190:193], v[238:241], v[28:31]
	v_mfma_f32_16x16x32_bf16 v[24:27], v[198:201], v[226:229], v[24:27]
	v_mfma_f32_16x16x32_bf16 v[20:23], v[198:201], v[238:241], v[20:23]
	v_mfma_f32_16x16x32_bf16 v[16:19], v[206:209], v[226:229], v[16:19]
	v_mfma_f32_16x16x32_bf16 v[12:15], v[206:209], v[238:241], v[12:15]
	v_mfma_f32_16x16x32_bf16 v[8:11], v[214:217], v[226:229], v[8:11]
	v_mfma_f32_16x16x32_bf16 v[4:7], v[214:217], v[238:241], v[4:7]
	v_mfma_f32_16x16x32_bf16 v[32:35], v[194:197], v[230:233], v[32:35]
	v_mfma_f32_16x16x32_bf16 v[28:31], v[194:197], v[242:245], v[28:31]
	v_mfma_f32_16x16x32_bf16 v[24:27], v[202:205], v[230:233], v[24:27]
	v_mfma_f32_16x16x32_bf16 v[20:23], v[202:205], v[242:245], v[20:23]
	v_mfma_f32_16x16x32_bf16 v[16:19], v[210:213], v[230:233], v[16:19]
	v_mfma_f32_16x16x32_bf16 v[12:15], v[210:213], v[242:245], v[12:15]
	v_mfma_f32_16x16x32_bf16 v[8:11], v[218:221], v[230:233], v[8:11]
	v_mfma_f32_16x16x32_bf16 v[4:7], v[218:221], v[242:245], v[4:7]
	s_add_i32 s29, s29, 2
	s_add_u32 s12, s12, 0x100
	s_addc_u32 s13, s13, 0
	s_cmp_lt_u32 s29, 4
	s_barrier
	s_cbranch_scc1 .LBB0_1152
	s_add_u32 s2, s2, s27
	s_addc_u32 s3, s3, 0
	s_add_u32 s2, s2, 0x3000380
	s_addc_u32 s3, s3, 0
	v_lshl_add_u64 v[136:137], v[136:137], 1, s[2:3]
	v_lshl_add_u64 v[0:1], v[0:1], 1, v[136:137]
	s_or_b32 m0, s100, 0xc000
	ds_read_b128 v[138:141], v171
	ds_read_b128 v[142:145], v171 offset:1024
	ds_read_b128 v[162:165], v171 offset:2048
	ds_read_b128 v[168:171], v171 offset:3072
	ds_read_b128 v[174:177], v156
	ds_read_b128 v[178:181], v156 offset:1024
	ds_read_b128 v[182:185], v155
	ds_read_b128 v[186:189], v155 offset:1024
	ds_read_b128 v[190:193], v154
	ds_read_b128 v[194:197], v154 offset:1024
	ds_read_b128 v[198:201], v153
	ds_read_b128 v[202:205], v153 offset:1024
	global_load_lds_dwordx4 v[0:1], off
	v_lshl_add_u64 v[0:1], v[134:135], 1, s[2:3]
	v_lshl_add_u64 v[0:1], v[132:133], 1, v[0:1]
	s_or_b32 m0, s100, 0xe000
	s_nop 0
	global_load_lds_dwordx4 v[0:1], off
	s_barrier
	s_waitcnt lgkmcnt(0)
	v_mfma_f32_16x16x32_bf16 v[128:131], v[174:177], v[138:141], v[128:131]
	v_mfma_f32_16x16x32_bf16 v[124:127], v[174:177], v[162:165], v[124:127]
	v_mfma_f32_16x16x32_bf16 v[120:123], v[182:185], v[138:141], v[120:123]
	v_mfma_f32_16x16x32_bf16 v[112:115], v[190:193], v[138:141], v[112:115]
	v_mfma_f32_16x16x32_bf16 v[128:131], v[178:181], v[142:145], v[128:131]
	v_mfma_f32_16x16x32_bf16 v[124:127], v[178:181], v[168:171], v[124:127]
	v_mfma_f32_16x16x32_bf16 v[120:123], v[186:189], v[142:145], v[120:123]
	v_mfma_f32_16x16x32_bf16 v[116:119], v[182:185], v[162:165], v[116:119]
	v_mfma_f32_16x16x32_bf16 v[112:115], v[194:197], v[142:145], v[112:115]
	v_mfma_f32_16x16x32_bf16 v[108:111], v[190:193], v[162:165], v[108:111]
	v_mfma_f32_16x16x32_bf16 v[104:107], v[198:201], v[138:141], v[104:107]
	v_mfma_f32_16x16x32_bf16 v[100:103], v[198:201], v[162:165], v[100:103]
	v_mfma_f32_16x16x32_bf16 v[132:135], v[186:189], v[168:171], v[116:119]
	v_mfma_f32_16x16x32_bf16 v[206:209], v[194:197], v[168:171], v[108:111]
	v_mfma_f32_16x16x32_bf16 v[210:213], v[202:205], v[142:145], v[104:107]
	v_mfma_f32_16x16x32_bf16 v[214:217], v[202:205], v[168:171], v[100:103]
	s_barrier
	s_nop 1
	ds_read_b128 v[100:103], v167
	ds_read_b128 v[104:107], v167 offset:1024
	ds_read_b128 v[108:111], v167 offset:2048
	ds_read_b128 v[116:119], v167 offset:3072
	s_barrier
	s_waitcnt lgkmcnt(0)
	v_mfma_f32_16x16x32_bf16 v[80:83], v[190:193], v[100:103], v[80:83]
	v_mfma_f32_16x16x32_bf16 v[76:79], v[190:193], v[108:111], v[76:79]
	v_mfma_f32_16x16x32_bf16 v[72:75], v[198:201], v[100:103], v[72:75]
	v_mfma_f32_16x16x32_bf16 v[68:71], v[198:201], v[108:111], v[68:71]
	v_mfma_f32_16x16x32_bf16 v[96:99], v[174:177], v[100:103], v[96:99]
	v_mfma_f32_16x16x32_bf16 v[92:95], v[174:177], v[108:111], v[92:95]
	v_mfma_f32_16x16x32_bf16 v[88:91], v[182:185], v[100:103], v[88:91]
	v_mfma_f32_16x16x32_bf16 v[84:87], v[182:185], v[108:111], v[84:87]
	v_mfma_f32_16x16x32_bf16 v[80:83], v[194:197], v[104:107], v[80:83]
	v_mfma_f32_16x16x32_bf16 v[76:79], v[194:197], v[116:119], v[76:79]
	v_mfma_f32_16x16x32_bf16 v[72:75], v[202:205], v[104:107], v[72:75]
	v_mfma_f32_16x16x32_bf16 v[68:71], v[202:205], v[116:119], v[68:71]
	v_mfma_f32_16x16x32_bf16 v[218:221], v[178:181], v[104:107], v[96:99]
	v_mfma_f32_16x16x32_bf16 v[172:175], v[178:181], v[116:119], v[92:95]
	v_mfma_f32_16x16x32_bf16 v[176:179], v[186:189], v[104:107], v[88:91]
	v_mfma_f32_16x16x32_bf16 v[180:183], v[186:189], v[116:119], v[84:87]
	s_barrier
; #define LDA8(dst, b, h) _Pragma("unroll") for (int m = 0; m < 4; ++m) _Pragma("unroll") for (int k = 0; k < 2; ++k) \
;     dst[m][k] = *(const bf16x8*)((const char*)SA8(b, h) + lds_byte8(wr * 64 + m * 16 + fr, k * 32 + fq * 8))
; #define LDB8(dst, b, h) _Pragma("unroll") for (int n = 0; n < 2; ++n) _Pragma("unroll") for (int k = 0; k < 2; ++k) \
;     dst[n][k] = *(const bf16x8*)((const char*)SB8(b, h) + lds_byte8(wc * 32 + n * 16 + fr, k * 32 + fq * 8))
; #define WAIT_V8(n) asm volatile("s_waitcnt vmcnt(" #n ")" ::: "memory")
; #define WAIT_L8(n) asm volatile("s_waitcnt lgkmcnt(" #n ")" ::: "memory")
; #define BAR8 __builtin_amdgcn_s_barrier()
;     ...
;     LDA8(At, 0, 1); WAIT_V8(4); BAR8; WAIT_L8(0); MMA8(1, 0, At, B0); MMA8(1, 1, At, B1); BAR8; }
;   { LDB8(B0, 1, 0); LDA8(At, 1, 0); WAIT_V8(2); BAR8; WAIT_L8(0); MMA8(0, 0, At, B0); BAR8;
	s_nop 0
	ds_read_b128 v[84:87], v156 offset:16384
	ds_read_b128 v[88:91], v156 offset:17408
	ds_read_b128 v[92:95], v155 offset:16384
	ds_read_b128 v[96:99], v155 offset:17408
	ds_read_b128 v[184:187], v154 offset:16384
	ds_read_b128 v[188:191], v154 offset:17408
	ds_read_b128 v[192:195], v153 offset:16384
	ds_read_b128 v[196:199], v153 offset:17408
	s_waitcnt vmcnt(4)
	s_barrier
	s_waitcnt lgkmcnt(0)
	v_mfma_f32_16x16x32_bf16 v[64:67], v[84:87], v[138:141], v[64:67]
	v_mfma_f32_16x16x32_bf16 v[60:63], v[84:87], v[162:165], v[60:63]
	v_mfma_f32_16x16x32_bf16 v[56:59], v[92:95], v[138:141], v[56:59]
	v_mfma_f32_16x16x32_bf16 v[52:55], v[92:95], v[162:165], v[52:55]
	v_mfma_f32_16x16x32_bf16 v[48:51], v[184:187], v[138:141], v[48:51]
	v_mfma_f32_16x16x32_bf16 v[44:47], v[184:187], v[162:165], v[44:47]
	v_mfma_f32_16x16x32_bf16 v[40:43], v[192:195], v[138:141], v[40:43]
	v_mfma_f32_16x16x32_bf16 v[36:39], v[192:195], v[162:165], v[36:39]
	v_mfma_f32_16x16x32_bf16 v[64:67], v[88:91], v[142:145], v[64:67]
	v_mfma_f32_16x16x32_bf16 v[60:63], v[88:91], v[168:171], v[60:63]
	v_mfma_f32_16x16x32_bf16 v[56:59], v[96:99], v[142:145], v[56:59]
	v_mfma_f32_16x16x32_bf16 v[52:55], v[96:99], v[168:171], v[52:55]
	v_mfma_f32_16x16x32_bf16 v[48:51], v[188:191], v[142:145], v[48:51]
	v_mfma_f32_16x16x32_bf16 v[44:47], v[188:191], v[168:171], v[44:47]
	v_mfma_f32_16x16x32_bf16 v[40:43], v[196:199], v[142:145], v[40:43]
	v_mfma_f32_16x16x32_bf16 v[36:39], v[196:199], v[168:171], v[36:39]
	v_mfma_f32_16x16x32_bf16 v[32:35], v[84:87], v[100:103], v[32:35]
	v_mfma_f32_16x16x32_bf16 v[28:31], v[84:87], v[108:111], v[28:31]
	v_mfma_f32_16x16x32_bf16 v[24:27], v[92:95], v[100:103], v[24:27]
	v_mfma_f32_16x16x32_bf16 v[20:23], v[92:95], v[108:111], v[20:23]
	v_mfma_f32_16x16x32_bf16 v[16:19], v[184:187], v[100:103], v[16:19]
	v_mfma_f32_16x16x32_bf16 v[12:15], v[184:187], v[108:111], v[12:15]
	v_mfma_f32_16x16x32_bf16 v[8:11], v[192:195], v[100:103], v[8:11]
	v_mfma_f32_16x16x32_bf16 v[4:7], v[192:195], v[108:111], v[4:7]
	v_mfma_f32_16x16x32_bf16 v[136:139], v[88:91], v[104:107], v[32:35]
	v_mfma_f32_16x16x32_bf16 v[140:143], v[88:91], v[116:119], v[28:31]
	v_mfma_f32_16x16x32_bf16 v[162:165], v[96:99], v[104:107], v[24:27]
	v_mfma_f32_16x16x32_bf16 v[166:169], v[96:99], v[116:119], v[20:23]
	v_mfma_f32_16x16x32_bf16 v[200:203], v[188:191], v[104:107], v[16:19]
	v_mfma_f32_16x16x32_bf16 v[184:187], v[188:191], v[116:119], v[12:15]
	v_mfma_f32_16x16x32_bf16 v[188:191], v[196:199], v[104:107], v[8:11]
	v_mfma_f32_16x16x32_bf16 v[192:195], v[196:199], v[116:119], v[4:7]
	s_barrier
	ds_read_b128 v[196:199], v160
	ds_read_b128 v[226:229], v160 offset:1024
	ds_read_b128 v[230:233], v160 offset:2048
	ds_read_b128 v[238:241], v160 offset:3072
	ds_read_b128 v[8:11], v156 offset:32768
	ds_read_b128 v[12:15], v156 offset:33792
	ds_read_b128 v[16:19], v155 offset:32768
	ds_read_b128 v[24:27], v155 offset:33792
	ds_read_b128 v[28:31], v154 offset:32768
	ds_read_b128 v[32:35], v154 offset:33792
	ds_read_b128 v[242:245], v153 offset:32768
	ds_read_b128 v[246:249], v153 offset:33792
	s_waitcnt vmcnt(2)
	s_barrier
	s_waitcnt lgkmcnt(0)
	v_mfma_f32_16x16x32_bf16 v[4:7], v[8:11], v[196:199], v[128:131]
	v_mfma_f32_16x16x32_bf16 v[104:107], v[12:15], v[226:229], v[4:7]
	v_mfma_f32_16x16x32_bf16 v[4:7], v[8:11], v[230:233], v[124:127]
	v_mfma_f32_16x16x32_bf16 v[116:119], v[12:15], v[238:241], v[4:7]
	v_mfma_f32_16x16x32_bf16 v[4:7], v[16:19], v[196:199], v[120:123]
	v_mfma_f32_16x16x32_bf16 v[100:103], v[24:27], v[226:229], v[4:7]
	v_mfma_f32_16x16x32_bf16 v[4:7], v[16:19], v[230:233], v[132:135]
	v_mfma_f32_16x16x32_bf16 v[108:111], v[24:27], v[238:241], v[4:7]
	v_mfma_f32_16x16x32_bf16 v[4:7], v[28:31], v[196:199], v[112:115]
	v_mfma_f32_16x16x32_bf16 v[92:95], v[32:35], v[226:229], v[4:7]
	v_mfma_f32_16x16x32_bf16 v[4:7], v[28:31], v[230:233], v[206:209]
	v_mfma_f32_16x16x32_bf16 v[96:99], v[32:35], v[238:241], v[4:7]
	v_mfma_f32_16x16x32_bf16 v[4:7], v[242:245], v[196:199], v[210:213]
	v_mfma_f32_16x16x32_bf16 v[84:87], v[246:249], v[226:229], v[4:7]
	v_mfma_f32_16x16x32_bf16 v[4:7], v[242:245], v[230:233], v[214:217]
	v_mfma_f32_16x16x32_bf16 v[88:91], v[246:249], v[238:241], v[4:7]
	s_barrier
; #define LDA8(dst, b, h) _Pragma("unroll") for (int m = 0; m < 4; ++m) _Pragma("unroll") for (int k = 0; k < 2; ++k) \
;     dst[m][k] = *(const bf16x8*)((const char*)SA8(b, h) + lds_byte8(wr * 64 + m * 16 + fr, k * 32 + fq * 8))
; #define LDB8(dst, b, h) _Pragma("unroll") for (int n = 0; n < 2; ++n) _Pragma("unroll") for (int k = 0; k < 2; ++k) \
;     dst[n][k] = *(const bf16x8*)((const char*)SB8(b, h) + lds_byte8(wc * 32 + n * 16 + fr, k * 32 + fq * 8))
; #define WAIT_V8(n) asm volatile("s_waitcnt vmcnt(" #n ")" ::: "memory")
; #define WAIT_L8(n) asm volatile("s_waitcnt lgkmcnt(" #n ")" ::: "memory")
; #define BAR8 __builtin_amdgcn_s_barrier()
;     ...
;   { LDB8(B0, 1, 0); LDA8(At, 1, 0); WAIT_V8(2); BAR8; WAIT_L8(0); MMA8(0, 0, At, B0); BAR8;
;     LDB8(B1, 1, 1); WAIT_V8(0); BAR8; WAIT_L8(0); MMA8(0, 1, At, B1); BAR8;
;     LDA8(At, 1, 1); BAR8; WAIT_L8(0); MMA8(1, 0, At, B0); MMA8(1, 1, At, B1); BAR8; }
;   if (wr == 0) BAR8;
;   __syncthreads();
;     ...
;   if (t < 256) {
	ds_read_b128 v[132:135], v158
	ds_read_b128 v[204:207], v158 offset:1024
	ds_read_b128 v[208:211], v158 offset:2048
	ds_read_b128 v[158:161], v158 offset:3072
	s_waitcnt vmcnt(0)
	s_barrier
	s_waitcnt lgkmcnt(0)
	v_mfma_f32_16x16x32_bf16 v[4:7], v[8:11], v[132:135], v[218:221]
	v_mfma_f32_16x16x32_bf16 v[8:11], v[8:11], v[208:211], v[172:175]
	v_mfma_f32_16x16x32_bf16 v[4:7], v[12:15], v[204:207], v[4:7]
	v_mfma_f32_16x16x32_bf16 v[20:23], v[12:15], v[158:161], v[8:11]
	v_mfma_f32_16x16x32_bf16 v[8:11], v[16:19], v[132:135], v[176:179]
	v_mfma_f32_16x16x32_bf16 v[12:15], v[16:19], v[208:211], v[180:183]
	v_mfma_f32_16x16x32_bf16 v[8:11], v[24:27], v[204:207], v[8:11]
	v_mfma_f32_16x16x32_bf16 v[24:27], v[24:27], v[158:161], v[12:15]
	v_mfma_f32_16x16x32_bf16 v[12:15], v[28:31], v[132:135], v[80:83]
	v_mfma_f32_16x16x32_bf16 v[16:19], v[28:31], v[208:211], v[76:79]
	v_mfma_f32_16x16x32_bf16 v[12:15], v[32:35], v[204:207], v[12:15]
	v_mfma_f32_16x16x32_bf16 v[28:31], v[32:35], v[158:161], v[16:19]
	v_mfma_f32_16x16x32_bf16 v[16:19], v[242:245], v[132:135], v[72:75]
	v_mfma_f32_16x16x32_bf16 v[32:35], v[242:245], v[208:211], v[68:71]
	v_mfma_f32_16x16x32_bf16 v[16:19], v[246:249], v[204:207], v[16:19]
	v_mfma_f32_16x16x32_bf16 v[32:35], v[246:249], v[158:161], v[32:35]
	s_barrier
	ds_read_b128 v[170:173], v156 offset:49152
	ds_read_b128 v[174:177], v156 offset:50176
	ds_read_b128 v[178:181], v155 offset:49152
	ds_read_b128 v[212:215], v155 offset:50176
	ds_read_b128 v[216:219], v154 offset:49152
	ds_read_b128 v[154:157], v154 offset:50176
	ds_read_b128 v[220:223], v153 offset:49152
	ds_read_b128 v[150:153], v153 offset:50176
	s_barrier
	s_waitcnt lgkmcnt(0)
	v_mfma_f32_16x16x32_bf16 v[64:67], v[170:173], v[196:199], v[64:67]
	v_mfma_f32_16x16x32_bf16 v[60:63], v[170:173], v[230:233], v[60:63]
	v_mfma_f32_16x16x32_bf16 v[56:59], v[178:181], v[196:199], v[56:59]
	v_mfma_f32_16x16x32_bf16 v[52:55], v[178:181], v[230:233], v[52:55]
	v_mfma_f32_16x16x32_bf16 v[48:51], v[216:219], v[196:199], v[48:51]
	v_mfma_f32_16x16x32_bf16 v[44:47], v[216:219], v[230:233], v[44:47]
	v_mfma_f32_16x16x32_bf16 v[40:43], v[220:223], v[196:199], v[40:43]
	v_mfma_f32_16x16x32_bf16 v[36:39], v[220:223], v[230:233], v[36:39]
	v_mfma_f32_16x16x32_bf16 v[128:131], v[174:177], v[226:229], v[64:67]
	v_mfma_f32_16x16x32_bf16 v[124:127], v[174:177], v[238:241], v[60:63]
	v_mfma_f32_16x16x32_bf16 v[120:123], v[212:215], v[226:229], v[56:59]
	v_mfma_f32_16x16x32_bf16 v[112:115], v[212:215], v[238:241], v[52:55]
	v_mfma_f32_16x16x32_bf16 v[80:83], v[154:157], v[226:229], v[48:51]
	v_mfma_f32_16x16x32_bf16 v[76:79], v[154:157], v[238:241], v[44:47]
	v_mfma_f32_16x16x32_bf16 v[72:75], v[150:153], v[226:229], v[40:43]
	v_mfma_f32_16x16x32_bf16 v[68:71], v[150:153], v[238:241], v[36:39]
	v_mfma_f32_16x16x32_bf16 v[40:43], v[170:173], v[208:211], v[140:143]
	v_mfma_f32_16x16x32_bf16 v[44:47], v[178:181], v[208:211], v[166:169]
	v_mfma_f32_16x16x32_bf16 v[48:51], v[216:219], v[208:211], v[184:187]
	v_mfma_f32_16x16x32_bf16 v[36:39], v[170:173], v[132:135], v[136:139]
	v_mfma_f32_16x16x32_bf16 v[52:55], v[174:177], v[158:161], v[40:43]
	v_mfma_f32_16x16x32_bf16 v[40:43], v[178:181], v[132:135], v[162:165]
	v_mfma_f32_16x16x32_bf16 v[56:59], v[212:215], v[158:161], v[44:47]
	v_mfma_f32_16x16x32_bf16 v[44:47], v[216:219], v[132:135], v[200:203]
	v_mfma_f32_16x16x32_bf16 v[60:63], v[154:157], v[158:161], v[48:51]
	v_mfma_f32_16x16x32_bf16 v[48:51], v[220:223], v[132:135], v[188:191]
	v_mfma_f32_16x16x32_bf16 v[64:67], v[220:223], v[208:211], v[192:195]
	v_mfma_f32_16x16x32_bf16 v[36:39], v[174:177], v[204:207], v[36:39]
	v_mfma_f32_16x16x32_bf16 v[40:43], v[212:215], v[204:207], v[40:43]
	v_mfma_f32_16x16x32_bf16 v[44:47], v[154:157], v[204:207], v[44:47]
	v_mfma_f32_16x16x32_bf16 v[48:51], v[150:153], v[204:207], v[48:51]
	v_mfma_f32_16x16x32_bf16 v[64:67], v[150:153], v[158:161], v[64:67]
	s_movk_i32 s2, 0x100
	v_cmp_gt_u32_e32 vcc, s2, v3
	s_barrier
	s_and_saveexec_b64 s[2:3], vcc
	s_cbranch_execz .LBB0_1155
	s_barrier

;     ...
;   if (!pre) {
;     STAGE8(SB8(0, 0), Bt, K, bcol, 0); STAGE8(SA8(0, 0), A, lda, brow, 0);
;     STAGE8(SB8(0, 1), Bt, K, bcol + 128, 0); STAGE8(SA8(0, 1), A, lda, brow + 128, 0);
;   }
.LBB0_1253:
	s_and_b64 vcc, exec, s[0:1]
	s_cbranch_vccz .LBB0_1266
	s_mov_b32 s0, 25
	s_ashr_i32 s1, s0, 31
	s_xor_b64 s[8:9], s[8:9], -1
	s_lshl_b64 s[0:1], s[0:1], 3
	s_add_u32 s0, s70, s0
	s_addc_u32 s1, s71, s1
	v_readlane_b32 s2, v255, 60
	v_readlane_b32 s3, v255, 61
	s_nop 4
	s_lshl_b32 s0, s25, 8
	v_mov_b32_e32 v3, v224
	s_and_b32 s27, s0, 0x3f00
	s_lshl_b32 s0, s25, 2
	s_and_b32 s0, s0, 0xffffff00
	s_waitcnt vmcnt(10)
	v_lshlrev_b32_e32 v150, 4, v3
	s_nop 0
	v_readfirstlane_b32 s100, v150
	v_ashrrev_i32_e32 v0, 31, v3
	v_bfe_i32 v5, v3, 27, 1
	v_mov_b32_e32 v4, v2
	s_andn2_b64 vcc, exec, s[8:9]
	v_lshrrev_b32_e32 v1, 26, v0
	v_lshrrev_b32_e32 v0, 22, v5
	s_waitcnt vmcnt(9)
	v_add_u32_e32 v152, 0x2000, v150
	s_waitcnt vmcnt(8)
	s_cbranch_vccnz .LBB0_1256
	v_add_u32_e32 v6, v150, v0
	v_and_b32_e32 v6, 0xfffffc00, v6
	v_sub_u32_e32 v6, v150, v6
	v_lshrrev_b32_e32 v7, 4, v6
	v_add_u32_e32 v5, v3, v1
	v_bitop3_b32 v7, v7, v6, 32 bitop3:0x6c
	v_ashrrev_i32_e32 v6, 31, v6
	v_ashrrev_i32_e32 v5, 6, v5
	v_lshrrev_b32_e32 v6, 26, v6
	v_lshlrev_b32_e32 v8, 3, v5
	v_add_u32_e32 v6, v7, v6
	v_and_b32_e32 v8, -16, v8
	v_ashrrev_i32_e32 v9, 6, v6
	v_add_u32_e32 v6, v9, v8
	v_mul_i32_i24_e32 v8, 64, v9
	s_ashr_i32 s1, s0, 31
	v_lshlrev_b32_e32 v5, 5, v5
	v_sub_u32_e32 v7, v7, v8
	v_mov_b32_e32 v14, 1
	s_lshl_b64 s[8:9], s[0:1], 11
	v_and_b32_e32 v5, 32, v5
	v_ashrrev_i16_sdwa v7, v14, sext(v7) dst_sel:DWORD dst_unused:UNUSED_PAD src0_sel:DWORD src1_sel:BYTE_0
	s_add_u32 s8, s4, s8
	v_add_u32_sdwa v8, v5, sext(v7) dst_sel:DWORD dst_unused:UNUSED_PAD src0_sel:DWORD src1_sel:WORD_0
	v_ashrrev_i32_e32 v7, 31, v6
	v_ashrrev_i32_e32 v5, 31, v152
	s_addc_u32 s9, s5, s9
	v_lshlrev_b64 v[6:7], 11, v[6:7]
	v_ashrrev_i32_e32 v9, 31, v8
	v_lshrrev_b32_e32 v5, 22, v5
	v_lshl_add_u64 v[10:11], s[8:9], 0, v[6:7]
	v_lshlrev_b64 v[8:9], 1, v[8:9]
	v_add_u32_e32 v5, v152, v5
	v_lshl_add_u64 v[10:11], v[10:11], 0, v[8:9]
	s_or_b32 m0, s100, 0x10000
	v_ashrrev_i32_e32 v5, 10, v5
	global_load_lds_dwordx4 v[10:11], off
	v_mul_i32_i24_e32 v10, 0x400, v5
	v_sub_u32_e32 v10, v152, v10
	v_lshrrev_b32_e32 v11, 4, v10
	v_bitop3_b32 v11, v11, v10, 32 bitop3:0x6c
	v_ashrrev_i32_e32 v12, 31, v11
	v_lshrrev_b32_e32 v12, 26, v12
	v_add_u32_e32 v12, v11, v12
	v_lshlrev_b32_e32 v10, 3, v5
	v_ashrrev_i32_e32 v13, 6, v12
	v_and_b32_e32 v12, 0xc0, v12
	v_and_b32_e32 v10, -16, v10
	v_lshlrev_b32_e32 v5, 5, v5
	v_sub_u32_e32 v11, v11, v12
	v_add_u32_e32 v10, v13, v10
	v_and_b32_e32 v5, 32, v5
	v_ashrrev_i16_sdwa v11, v14, sext(v11) dst_sel:DWORD dst_unused:UNUSED_PAD src0_sel:DWORD src1_sel:BYTE_0
	v_add_u32_sdwa v12, v5, sext(v11) dst_sel:DWORD dst_unused:UNUSED_PAD src0_sel:DWORD src1_sel:WORD_0
	v_ashrrev_i32_e32 v11, 31, v10
	v_lshlrev_b64 v[10:11], 11, v[10:11]
	v_ashrrev_i32_e32 v13, 31, v12
	s_or_b32 m0, s100, 0x12000
	s_lshl_b32 s1, s27, 11
	v_lshl_add_u64 v[14:15], s[8:9], 0, v[10:11]
	v_lshlrev_b64 v[12:13], 1, v[12:13]
	s_waitcnt lgkmcnt(0)
	s_add_u32 s8, s2, s1
	v_lshl_add_u64 v[14:15], v[14:15], 0, v[12:13]
	s_addc_u32 s9, s3, 0
	s_or_b32 s14, s0, 0x80
	global_load_lds_dwordx4 v[14:15], off
	v_lshl_add_u64 v[14:15], s[8:9], 0, v[6:7]
	s_ashr_i32 s15, s14, 31
	v_lshl_add_u64 v[14:15], v[14:15], 0, v[8:9]
	s_mov_b32 m0, s100
	s_lshl_b64 s[14:15], s[14:15], 11
	global_load_lds_dwordx4 v[14:15], off
	v_lshl_add_u64 v[14:15], s[8:9], 0, v[10:11]
	s_add_u32 s14, s4, s14
	v_lshl_add_u64 v[14:15], v[14:15], 0, v[12:13]
	s_addc_u32 s15, s5, s15
	s_or_b32 m0, s100, 0x2000
	global_load_lds_dwordx4 v[14:15], off
	v_lshl_add_u64 v[14:15], s[14:15], 0, v[6:7]
	v_lshl_add_u64 v[14:15], v[14:15], 0, v[8:9]
	s_or_b32 m0, s100, 0x14000
	s_add_u32 s8, s8, 0x40000
	global_load_lds_dwordx4 v[14:15], off
	v_lshl_add_u64 v[14:15], s[14:15], 0, v[10:11]
	s_addc_u32 s9, s9, 0
	v_lshl_add_u64 v[14:15], v[14:15], 0, v[12:13]
	s_or_b32 m0, s100, 0x16000
	v_lshl_add_u64 v[6:7], s[8:9], 0, v[6:7]
	global_load_lds_dwordx4 v[14:15], off
	v_lshl_add_u64 v[6:7], v[6:7], 0, v[8:9]
	s_or_b32 m0, s100, 0x4000
	s_nop 0
	global_load_lds_dwordx4 v[6:7], off
	v_lshl_add_u64 v[6:7], s[8:9], 0, v[10:11]
	v_lshl_add_u64 v[6:7], v[6:7], 0, v[12:13]
	s_or_b32 m0, s100, 0x6000
	s_nop 0
	global_load_lds_dwordx4 v[6:7], off

; #define WAIT_V8(n) asm volatile("s_waitcnt vmcnt(" #n ")" ::: "memory")
; #define BAR8 __builtin_amdgcn_s_barrier()
;     ...
;   if (wr == 1) BAR8;
;   WAIT_V8(4); BAR8;
;   STAGE8(SB8(1, 0), Bt, K, bcol, 1); STAGE8(SA8(1, 0), A, lda, brow, 1); STAGE8(SB8(1, 1), Bt, K, bcol + 128, 1);
;   WAIT_V8(6); BAR8;
.LBB0_1258:
	s_or_b64 exec, exec, s[8:9]
	v_add_u32_e32 v0, v150, v0
	v_and_b32_e32 v0, 0xfffffc00, v0
	v_sub_u32_e32 v0, v150, v0
	v_lshrrev_b32_e32 v6, 4, v0
	v_add_u32_e32 v1, v3, v1
	v_bitop3_b32 v7, v6, v0, 32 bitop3:0x6c
	v_ashrrev_i32_e32 v0, 31, v0
	v_ashrrev_i32_e32 v1, 6, v1
	v_lshrrev_b32_e32 v0, 26, v0
	v_lshlrev_b32_e32 v6, 3, v1
	v_add_u32_e32 v0, v7, v0
	v_and_b32_e32 v6, -16, v6
	v_ashrrev_i32_e32 v0, 6, v0
	s_and_b32 s1, s12, 63
	s_and_b32 s8, s20, 0xffffff00
	v_add_u32_e32 v6, v0, v6
	v_mul_i32_i24_e32 v0, 64, v0
	s_lshl_b32 s12, s1, 19
	s_ashr_i32 s9, s8, 31
	s_ashr_i32 s1, s0, 31
	v_lshlrev_b32_e32 v1, 5, v1
	v_sub_u32_e32 v0, v7, v0
	v_mov_b32_e32 v13, 1
	s_lshl_b64 s[14:15], s[8:9], 11
	s_lshl_b64 s[8:9], s[0:1], 11
	v_and_b32_e32 v1, 32, v1
	v_ashrrev_i16_sdwa v0, v13, sext(v0) dst_sel:DWORD dst_unused:UNUSED_PAD src0_sel:DWORD src1_sel:BYTE_0
	s_add_u32 s8, s4, s8
	v_add_u32_sdwa v0, v1, sext(v0) dst_sel:DWORD dst_unused:UNUSED_PAD src0_sel:DWORD src1_sel:WORD_0
	v_ashrrev_i32_e32 v7, 31, v6
	v_readlane_b32 s40, v254, 35
	s_addc_u32 s9, s5, s9
	v_lshlrev_b64 v[132:133], 11, v[6:7]
	v_ashrrev_i32_e32 v1, 31, v0
	v_readlane_b32 s41, v254, 36
	v_lshl_add_u64 v[6:7], s[8:9], 0, v[132:133]
	v_lshlrev_b64 v[8:9], 1, v[0:1]
	s_mov_b32 s13, s40
	v_lshl_add_u64 v[6:7], v[6:7], 0, v[8:9]
	s_mov_b64 s[40:41], 0x80
	v_lshl_add_u64 v[6:7], v[6:7], 0, s[40:41]
	s_or_b32 m0, s100, 0x18000
	s_waitcnt vmcnt(4)
	s_barrier
	global_load_lds_dwordx4 v[6:7], off
	v_ashrrev_i32_e32 v6, 31, v152
	v_lshrrev_b32_e32 v6, 22, v6
	v_add_u32_e32 v6, v152, v6
	v_ashrrev_i32_e32 v7, 10, v6
	v_mul_i32_i24_e32 v6, 0x400, v7
	v_sub_u32_e32 v6, v152, v6
	v_lshrrev_b32_e32 v10, 4, v6
	v_bitop3_b32 v10, v10, v6, 32 bitop3:0x6c
	v_ashrrev_i32_e32 v11, 31, v10
	v_lshrrev_b32_e32 v11, 26, v11
	v_add_u32_e32 v11, v10, v11
	v_lshlrev_b32_e32 v6, 3, v7
	v_ashrrev_i32_e32 v12, 6, v11
	v_and_b32_e32 v11, 0xc0, v11
	v_and_b32_e32 v6, -16, v6
	v_lshlrev_b32_e32 v7, 5, v7
	v_sub_u32_e32 v10, v10, v11
	v_add_u32_e32 v6, v12, v6
	v_and_b32_e32 v7, 32, v7
	v_ashrrev_i16_sdwa v10, v13, sext(v10) dst_sel:DWORD dst_unused:UNUSED_PAD src0_sel:DWORD src1_sel:BYTE_0
	v_add_u32_sdwa v134, v7, sext(v10) dst_sel:DWORD dst_unused:UNUSED_PAD src0_sel:DWORD src1_sel:WORD_0
	v_ashrrev_i32_e32 v7, 31, v6
	v_lshlrev_b64 v[136:137], 11, v[6:7]
	v_ashrrev_i32_e32 v135, 31, v134
	v_lshl_add_u64 v[6:7], s[8:9], 0, v[136:137]
	v_lshlrev_b64 v[10:11], 1, v[134:135]
	s_or_b32 m0, s100, 0x1a000
	s_lshl_b32 s1, s27, 11
	v_lshl_add_u64 v[6:7], v[6:7], 0, v[10:11]
	s_waitcnt lgkmcnt(0)
	s_add_u32 s8, s2, s1
	v_lshl_add_u64 v[6:7], v[6:7], 0, s[40:41]
	s_addc_u32 s9, s3, 0
	global_load_lds_dwordx4 v[6:7], off
	v_lshl_add_u64 v[6:7], s[8:9], 0, v[132:133]
	v_lshl_add_u64 v[6:7], v[6:7], 0, v[8:9]
	s_or_b32 s36, s0, 0x80
	v_lshl_add_u64 v[6:7], v[6:7], 0, s[40:41]
	s_or_b32 m0, s100, 0x8000
	s_ashr_i32 s37, s36, 31
	global_load_lds_dwordx4 v[6:7], off
	v_lshl_add_u64 v[6:7], s[8:9], 0, v[136:137]
	s_lshl_b64 s[36:37], s[36:37], 11
	v_lshl_add_u64 v[6:7], v[6:7], 0, v[10:11]
	s_add_u32 s36, s4, s36
	v_lshl_add_u64 v[6:7], v[6:7], 0, s[40:41]
	s_addc_u32 s37, s5, s37
	s_or_b32 m0, s100, 0xa000
	global_load_lds_dwordx4 v[6:7], off
	v_lshl_add_u64 v[6:7], s[36:37], 0, v[132:133]
	v_lshl_add_u64 v[6:7], v[6:7], 0, v[8:9]
	v_lshl_add_u64 v[6:7], v[6:7], 0, s[40:41]
	s_or_b32 m0, s100, 0x1c000
	global_load_lds_dwordx4 v[6:7], off
	v_lshl_add_u64 v[6:7], s[36:37], 0, v[136:137]
	v_lshl_add_u64 v[6:7], v[6:7], 0, v[10:11]
	v_lshl_add_u64 v[6:7], v[6:7], 0, s[40:41]
	s_or_b32 m0, s100, 0x1e000
	v_and_b32_e32 v147, 15, v3
	global_load_lds_dwordx4 v[6:7], off
	v_bfe_u32 v148, v3, 4, 2
	v_lshlrev_b32_e32 v6, 4, v148
	v_lshlrev_b32_e32 v7, 6, v147
	v_lshlrev_b32_e32 v14, 2, v3
	v_or_b32_e32 v13, v6, v7
	v_and_b32_e32 v14, 32, v14
	s_mov_b32 s1, 0x10000
	v_bitop3_b32 v16, v13, s1, v14 bitop3:0xde
	s_mov_b32 s1, 0x14000
	v_bitop3_b32 v15, v6, v14, v7 bitop3:0x36
	v_bitop3_b32 v17, v13, s1, v14 bitop3:0xde
	s_mov_b32 s1, 0x18000
	v_lshlrev_b32_e32 v7, 6, v3
	v_bitop3_b32 v18, v13, s1, v14 bitop3:0xde
	s_mov_b32 s1, 0x1c000
	v_and_b32_e32 v7, 0x3c0, v7
	v_bitop3_b32 v13, v13, s1, v14 bitop3:0xde
	v_bitop3_b32 v14, v7, v14, v6 bitop3:0x36
	v_lshl_add_u64 v[6:7], s[12:13], 0, v[132:133]
	v_lshl_add_u64 v[6:7], v[6:7], 0, v[8:9]
	v_lshl_add_u64 v[138:139], s[2:3], 0, v[6:7]
	v_lshl_add_u64 v[6:7], s[12:13], 0, v[136:137]
	v_lshl_add_u64 v[6:7], v[6:7], 0, v[10:11]
	v_lshl_add_u64 v[140:141], s[2:3], 0, v[6:7]
	v_lshl_add_u64 v[6:7], s[14:15], 0, v[132:133]
	v_lshl_add_u64 v[6:7], v[6:7], 0, v[8:9]
	v_bfe_u32 v146, v3, 6, 2
	s_waitcnt vmcnt(6)
; #define LDA8(dst, b, h) _Pragma("unroll") for (int m = 0; m < 4; ++m) _Pragma("unroll") for (int k = 0; k < 2; ++k) \
;     dst[m][k] = *(const bf16x8*)((const char*)SA8(b, h) + lds_byte8(wr * 64 + m * 16 + fr, k * 32 + fq * 8))
; #define LDB8(dst, b, h) _Pragma("unroll") for (int n = 0; n < 2; ++n) _Pragma("unroll") for (int k = 0; k < 2; ++k) \
;     dst[n][k] = *(const bf16x8*)((const char*)SB8(b, h) + lds_byte8(wc * 32 + n * 16 + fr, k * 32 + fq * 8))
; #define WAIT_V8(n) asm volatile("s_waitcnt vmcnt(" #n ")" ::: "memory")
; #define WAIT_L8(n) asm volatile("s_waitcnt lgkmcnt(" #n ")" ::: "memory")
; #define BAR8 __builtin_amdgcn_s_barrier()
; #define SCHED8 __builtin_amdgcn_sched_barrier(0)
;     ...
;   const int wid = t >> 6, lane = t & 63, wr = wid >> 2, wc = wid & 3, fr = lane & 15, fq = lane >> 4;
;   f32x4 acc[2][2][4][2];
;   {
;     float zinit = 0.f;
;     asm volatile("" : "+v"(zinit));
; #pragma unroll
;     for (int a = 0; a < 2; ++a)
; #pragma unroll
;       for (int b = 0; b < 2; ++b)
; #pragma unroll
;         for (int m = 0; m < 4; ++m)
; #pragma unroll
;           for (int n = 0; n < 2; ++n)
; #pragma unroll
;             for (int j = 0; j < 4; ++j) acc[a][b][m][n][j] = zinit;
;   }
;   bf16x8 At[4][2], B0[2][2], B1[2][2];
;     ...
;   for (int tt = 0; tt < nt - 2; tt += 2) {
;     LDB8(B0, 0, 0); SCHED8; LDA8(At, 0, 0); STAGE8(SA8(1, 1), A, lda, brow + 128, tt + 1);
;     WAIT_L8(8); BAR8; WAIT_L8(0); MMA8(0, 0, At, B0); BAR8; SCHED8;
;     LDB8(B1, 0, 1); STAGE8(SB8(0, 0), Bt, K, bcol, tt + 2);
;     BAR8; WAIT_L8(0); MMA8(0, 1, At, B1); BAR8;
;     LDA8(At, 0, 1); STAGE8(SA8(0, 0), A, lda, brow, tt + 2);
;     BAR8; WAIT_L8(0); MMA8(1, 0, At, B0); BAR8; SCHED8;
;     STAGE8(SB8(0, 1), Bt, K, bcol + 128, tt + 2);
;     WAIT_V8(6); BAR8; MMA8(1, 1, At, B1); BAR8;
	v_lshlrev_b32_e32 v149, 6, v5
	v_lshlrev_b32_e32 v5, 13, v5
	v_lshl_add_u64 v[142:143], s[6:7], 0, v[6:7]
	v_lshl_add_u64 v[6:7], s[14:15], 0, v[136:137]
	v_readlane_b32 s42, v254, 37
	v_readlane_b32 s43, v254, 38
	v_lshlrev_b32_e32 v12, 12, v146
	v_or_b32_e32 v19, 0x800, v5
	v_or_b32_e32 v20, 0x1000, v5
	v_or_b32_e32 v21, 0x1800, v5
	v_lshl_add_u64 v[6:7], v[6:7], 0, v[10:11]
	v_lshl_add_u64 v[144:145], s[6:7], 0, v[6:7]
	s_mov_b32 s1, -2
	s_mov_b64 s[12:13], 0
	v_add_u32_e32 v171, v16, v12
	v_add_u32_e32 v161, v15, v5
	v_add_u32_e32 v160, v14, v19
	v_add_u32_e32 v159, v14, v20
	v_add_u32_e32 v158, v14, v21
	v_add_u32_e32 v169, v17, v12
	v_add_u32_e32 v163, v18, v12
	v_add_u32_e32 v162, v13, v12
	v_mov_b32_e32 v5, v4
	v_mov_b64_e32 v[6:7], v[4:5]
	v_mov_b64_e32 v[8:9], v[4:5]
	v_mov_b64_e32 v[10:11], v[4:5]
	v_mov_b64_e32 v[12:13], v[4:5]
	v_mov_b64_e32 v[14:15], v[4:5]
	v_mov_b64_e32 v[16:17], v[4:5]
	v_mov_b64_e32 v[18:19], v[4:5]
	v_mov_b64_e32 v[20:21], v[4:5]
	v_mov_b64_e32 v[22:23], v[4:5]
	v_mov_b64_e32 v[24:25], v[4:5]
	v_mov_b64_e32 v[26:27], v[4:5]
	v_mov_b64_e32 v[28:29], v[4:5]
	v_mov_b64_e32 v[30:31], v[4:5]
	v_mov_b64_e32 v[32:33], v[4:5]
	v_mov_b64_e32 v[34:35], v[4:5]
	v_mov_b64_e32 v[36:37], v[4:5]
	v_mov_b64_e32 v[38:39], v[4:5]
	v_mov_b64_e32 v[40:41], v[4:5]
	v_mov_b64_e32 v[42:43], v[4:5]
	v_mov_b64_e32 v[44:45], v[4:5]
	v_mov_b64_e32 v[46:47], v[4:5]
	v_mov_b64_e32 v[48:49], v[4:5]
	v_mov_b64_e32 v[50:51], v[4:5]
	v_mov_b64_e32 v[52:53], v[4:5]
	v_mov_b64_e32 v[54:55], v[4:5]
	v_mov_b64_e32 v[56:57], v[4:5]
	v_mov_b64_e32 v[58:59], v[4:5]
	v_mov_b64_e32 v[60:61], v[4:5]
	v_mov_b64_e32 v[62:63], v[4:5]
	v_mov_b64_e32 v[64:65], v[4:5]
	v_mov_b64_e32 v[66:67], v[4:5]
	v_mov_b64_e32 v[68:69], v[4:5]
	v_mov_b64_e32 v[70:71], v[4:5]
	v_mov_b64_e32 v[72:73], v[4:5]
	v_mov_b64_e32 v[74:75], v[4:5]
	v_mov_b64_e32 v[76:77], v[4:5]
	v_mov_b64_e32 v[78:79], v[4:5]
	v_mov_b64_e32 v[80:81], v[4:5]
	v_mov_b64_e32 v[82:83], v[4:5]
	v_mov_b64_e32 v[84:85], v[4:5]
	v_mov_b64_e32 v[86:87], v[4:5]
	v_mov_b64_e32 v[88:89], v[4:5]
	v_mov_b64_e32 v[90:91], v[4:5]
	v_mov_b64_e32 v[92:93], v[4:5]
	v_mov_b64_e32 v[94:95], v[4:5]
	v_mov_b64_e32 v[96:97], v[4:5]
	v_mov_b64_e32 v[98:99], v[4:5]
	v_mov_b64_e32 v[100:101], v[4:5]
	v_mov_b64_e32 v[102:103], v[4:5]
	v_mov_b64_e32 v[104:105], v[4:5]
	v_mov_b64_e32 v[106:107], v[4:5]
	v_mov_b64_e32 v[108:109], v[4:5]
	v_mov_b64_e32 v[110:111], v[4:5]
	v_mov_b64_e32 v[112:113], v[4:5]
	v_mov_b64_e32 v[114:115], v[4:5]
	v_mov_b64_e32 v[116:117], v[4:5]
	v_mov_b64_e32 v[118:119], v[4:5]
	v_mov_b64_e32 v[120:121], v[4:5]
	v_mov_b64_e32 v[122:123], v[4:5]
	v_mov_b64_e32 v[124:125], v[4:5]
	v_mov_b64_e32 v[126:127], v[4:5]
	v_mov_b64_e32 v[128:129], v[4:5]
	v_mov_b64_e32 v[130:131], v[4:5]
	s_mov_b64 s[36:37], 0xcaa0100
	s_mov_b64 s[40:41], 0xcae0100
	s_mov_b64 s[42:43], 0xcaa0180
	s_mov_b64 s[44:45], 0xcae0180
	s_barrier
.LBB0_1259:
	ds_read_b128 v[174:177], v171
	ds_read_b128 v[178:181], v171 offset:1024
	ds_read_b128 v[182:185], v171 offset:2048
	ds_read_b128 v[186:189], v171 offset:3072
	v_lshl_add_u64 v[222:223], v[138:139], 0, s[12:13]
	v_lshl_add_u64 v[226:227], v[222:223], 0, s[34:35]
	s_or_b32 m0, s100, 0xc000
	v_lshl_add_u64 v[236:237], v[140:141], 0, s[12:13]
	ds_read_b128 v[190:193], v161
	ds_read_b128 v[194:197], v161 offset:1024
	ds_read_b128 v[198:201], v160
	ds_read_b128 v[202:205], v160 offset:1024
	ds_read_b128 v[206:209], v159
	ds_read_b128 v[210:213], v159 offset:1024
	ds_read_b128 v[214:217], v158
	ds_read_b128 v[218:221], v158 offset:1024
	global_load_lds_dwordx4 v[226:227], off
	v_lshl_add_u64 v[226:227], v[236:237], 0, s[34:35]
	s_or_b32 m0, s100, 0xe000
	s_nop 0
	global_load_lds_dwordx4 v[226:227], off
	s_waitcnt lgkmcnt(8)
	s_barrier
	s_waitcnt lgkmcnt(0)
	v_mfma_f32_16x16x32_f16 v[128:131], v[190:193], v[174:177], v[128:131]
	v_mfma_f32_16x16x32_f16 v[124:127], v[190:193], v[182:185], v[124:127]
	v_mfma_f32_16x16x32_f16 v[120:123], v[198:201], v[174:177], v[120:123]
	v_mfma_f32_16x16x32_f16 v[116:119], v[198:201], v[182:185], v[116:119]
	v_mfma_f32_16x16x32_f16 v[112:115], v[206:209], v[174:177], v[112:115]
	v_mfma_f32_16x16x32_f16 v[108:111], v[206:209], v[182:185], v[108:111]
	v_mfma_f32_16x16x32_f16 v[104:107], v[214:217], v[174:177], v[104:107]
	v_mfma_f32_16x16x32_f16 v[100:103], v[214:217], v[182:185], v[100:103]
	v_mfma_f32_16x16x32_f16 v[128:131], v[194:197], v[178:181], v[128:131]
	v_mfma_f32_16x16x32_f16 v[124:127], v[194:197], v[186:189], v[124:127]
	v_mfma_f32_16x16x32_f16 v[120:123], v[202:205], v[178:181], v[120:123]
	v_mfma_f32_16x16x32_f16 v[116:119], v[202:205], v[186:189], v[116:119]
	v_mfma_f32_16x16x32_f16 v[112:115], v[210:213], v[178:181], v[112:115]
	v_mfma_f32_16x16x32_f16 v[108:111], v[210:213], v[186:189], v[108:111]
	v_mfma_f32_16x16x32_f16 v[104:107], v[218:221], v[178:181], v[104:107]
	v_mfma_f32_16x16x32_f16 v[100:103], v[218:221], v[186:189], v[100:103]
	s_barrier
	v_lshl_add_u64 v[246:247], v[142:143], 0, s[12:13]
	v_lshl_add_u64 v[248:249], v[246:247], 0, s[36:37]
	s_or_b32 m0, s100, 0x10000
	ds_read_b128 v[226:229], v169
	ds_read_b128 v[230:233], v169 offset:1024
	ds_read_b128 v[238:241], v169 offset:2048
	ds_read_b128 v[242:245], v169 offset:3072
	global_load_lds_dwordx4 v[248:249], off
	v_lshl_add_u64 v[248:249], v[144:145], 0, s[12:13]
	v_lshl_add_u64 v[250:251], v[248:249], 0, s[36:37]
	s_or_b32 m0, s100, 0x12000
	s_nop 0
	global_load_lds_dwordx4 v[250:251], off
	s_barrier
; #define LDA8(dst, b, h) _Pragma("unroll") for (int m = 0; m < 4; ++m) _Pragma("unroll") for (int k = 0; k < 2; ++k) \
;     dst[m][k] = *(const bf16x8*)((const char*)SA8(b, h) + lds_byte8(wr * 64 + m * 16 + fr, k * 32 + fq * 8))
; #define LDB8(dst, b, h) _Pragma("unroll") for (int n = 0; n < 2; ++n) _Pragma("unroll") for (int k = 0; k < 2; ++k) \
;     dst[n][k] = *(const bf16x8*)((const char*)SB8(b, h) + lds_byte8(wc * 32 + n * 16 + fr, k * 32 + fq * 8))
; #define WAIT_V8(n) asm volatile("s_waitcnt vmcnt(" #n ")" ::: "memory")
; #define WAIT_L8(n) asm volatile("s_waitcnt lgkmcnt(" #n ")" ::: "memory")
; #define BAR8 __builtin_amdgcn_s_barrier()
; #define SCHED8 __builtin_amdgcn_sched_barrier(0)
;     ...
;     WAIT_L8(8); BAR8; WAIT_L8(0); MMA8(0, 0, At, B0); BAR8; SCHED8;
;     LDB8(B1, 0, 1); STAGE8(SB8(0, 0), Bt, K, bcol, tt + 2);
;     BAR8; WAIT_L8(0); MMA8(0, 1, At, B1); BAR8;
;     LDA8(At, 0, 1); STAGE8(SA8(0, 0), A, lda, brow, tt + 2);
;     BAR8; WAIT_L8(0); MMA8(1, 0, At, B0); BAR8; SCHED8;
;     STAGE8(SB8(0, 1), Bt, K, bcol + 128, tt + 2);
;     WAIT_V8(6); BAR8; MMA8(1, 1, At, B1); BAR8;
;     LDB8(B0, 1, 0); SCHED8; LDA8(At, 1, 0); STAGE8(SA8(0, 1), A, lda, brow + 128, tt + 2);
;     WAIT_L8(8); BAR8; WAIT_L8(0); MMA8(0, 0, At, B0); BAR8; SCHED8;
	s_waitcnt lgkmcnt(0)
	v_mfma_f32_16x16x32_f16 v[96:99], v[190:193], v[226:229], v[96:99]
	v_mfma_f32_16x16x32_f16 v[92:95], v[190:193], v[238:241], v[92:95]
	v_mfma_f32_16x16x32_f16 v[88:91], v[198:201], v[226:229], v[88:91]
	v_mfma_f32_16x16x32_f16 v[84:87], v[198:201], v[238:241], v[84:87]
	v_mfma_f32_16x16x32_f16 v[80:83], v[206:209], v[226:229], v[80:83]
	v_mfma_f32_16x16x32_f16 v[76:79], v[206:209], v[238:241], v[76:79]
	v_mfma_f32_16x16x32_f16 v[72:75], v[214:217], v[226:229], v[72:75]
	v_mfma_f32_16x16x32_f16 v[68:71], v[214:217], v[238:241], v[68:71]
	v_mfma_f32_16x16x32_f16 v[96:99], v[194:197], v[230:233], v[96:99]
	v_mfma_f32_16x16x32_f16 v[92:95], v[194:197], v[242:245], v[92:95]
	v_mfma_f32_16x16x32_f16 v[88:91], v[202:205], v[230:233], v[88:91]
	v_mfma_f32_16x16x32_f16 v[84:87], v[202:205], v[242:245], v[84:87]
	v_mfma_f32_16x16x32_f16 v[80:83], v[210:213], v[230:233], v[80:83]
	v_mfma_f32_16x16x32_f16 v[76:79], v[210:213], v[242:245], v[76:79]
	v_mfma_f32_16x16x32_f16 v[72:75], v[218:221], v[230:233], v[72:75]
	v_mfma_f32_16x16x32_f16 v[68:71], v[218:221], v[242:245], v[68:71]
	v_lshl_add_u64 v[250:251], v[222:223], 0, s[10:11]
	s_mov_b32 m0, s100
	s_barrier
	ds_read_b128 v[190:193], v161 offset:16384
	ds_read_b128 v[194:197], v161 offset:17408
	ds_read_b128 v[198:201], v160 offset:16384
	ds_read_b128 v[202:205], v160 offset:17408
	ds_read_b128 v[206:209], v159 offset:16384
	ds_read_b128 v[210:213], v159 offset:17408
	ds_read_b128 v[214:217], v158 offset:16384
	ds_read_b128 v[218:221], v158 offset:17408
	global_load_lds_dwordx4 v[250:251], off
	v_lshl_add_u64 v[250:251], v[236:237], 0, s[10:11]
	s_or_b32 m0, s100, 0x2000
	s_nop 0
	global_load_lds_dwordx4 v[250:251], off
	s_barrier
	s_waitcnt lgkmcnt(0)
	v_mfma_f32_16x16x32_f16 v[64:67], v[190:193], v[174:177], v[64:67]
	v_mfma_f32_16x16x32_f16 v[60:63], v[190:193], v[182:185], v[60:63]
	v_mfma_f32_16x16x32_f16 v[56:59], v[198:201], v[174:177], v[56:59]
	v_mfma_f32_16x16x32_f16 v[52:55], v[198:201], v[182:185], v[52:55]
	v_mfma_f32_16x16x32_f16 v[48:51], v[206:209], v[174:177], v[48:51]
	v_mfma_f32_16x16x32_f16 v[44:47], v[206:209], v[182:185], v[44:47]
	v_mfma_f32_16x16x32_f16 v[40:43], v[214:217], v[174:177], v[40:43]
	v_mfma_f32_16x16x32_f16 v[36:39], v[214:217], v[182:185], v[36:39]
	v_mfma_f32_16x16x32_f16 v[64:67], v[194:197], v[178:181], v[64:67]
	v_mfma_f32_16x16x32_f16 v[60:63], v[194:197], v[186:189], v[60:63]
	v_mfma_f32_16x16x32_f16 v[56:59], v[202:205], v[178:181], v[56:59]
	v_mfma_f32_16x16x32_f16 v[52:55], v[202:205], v[186:189], v[52:55]
	v_mfma_f32_16x16x32_f16 v[48:51], v[210:213], v[178:181], v[48:51]
	v_mfma_f32_16x16x32_f16 v[44:47], v[210:213], v[186:189], v[44:47]
	v_mfma_f32_16x16x32_f16 v[40:43], v[218:221], v[178:181], v[40:43]
	v_mfma_f32_16x16x32_f16 v[36:39], v[218:221], v[186:189], v[36:39]
	s_barrier
	v_lshl_add_u64 v[174:175], v[246:247], 0, s[40:41]
	s_or_b32 m0, s100, 0x14000
	s_nop 0
	global_load_lds_dwordx4 v[174:175], off
	v_lshl_add_u64 v[174:175], v[248:249], 0, s[40:41]
	s_or_b32 m0, s100, 0x16000
	s_nop 0
	global_load_lds_dwordx4 v[174:175], off
	s_waitcnt vmcnt(6)
	s_barrier
	v_mfma_f32_16x16x32_f16 v[32:35], v[190:193], v[226:229], v[32:35]
	v_mfma_f32_16x16x32_f16 v[28:31], v[190:193], v[238:241], v[28:31]
	v_mfma_f32_16x16x32_f16 v[24:27], v[198:201], v[226:229], v[24:27]
	v_mfma_f32_16x16x32_f16 v[20:23], v[198:201], v[238:241], v[20:23]
	v_mfma_f32_16x16x32_f16 v[16:19], v[206:209], v[226:229], v[16:19]
	v_mfma_f32_16x16x32_f16 v[12:15], v[206:209], v[238:241], v[12:15]
	v_mfma_f32_16x16x32_f16 v[8:11], v[214:217], v[226:229], v[8:11]
	v_mfma_f32_16x16x32_f16 v[4:7], v[214:217], v[238:241], v[4:7]
	v_mfma_f32_16x16x32_f16 v[32:35], v[194:197], v[230:233], v[32:35]
	v_mfma_f32_16x16x32_f16 v[28:31], v[194:197], v[242:245], v[28:31]
	v_mfma_f32_16x16x32_f16 v[24:27], v[202:205], v[230:233], v[24:27]
	v_mfma_f32_16x16x32_f16 v[20:23], v[202:205], v[242:245], v[20:23]
	v_mfma_f32_16x16x32_f16 v[16:19], v[210:213], v[230:233], v[16:19]
	v_mfma_f32_16x16x32_f16 v[12:15], v[210:213], v[242:245], v[12:15]
	v_mfma_f32_16x16x32_f16 v[8:11], v[218:221], v[230:233], v[8:11]
	v_mfma_f32_16x16x32_f16 v[4:7], v[218:221], v[242:245], v[4:7]
	s_barrier
	ds_read_b128 v[174:177], v163
	ds_read_b128 v[178:181], v163 offset:1024
	ds_read_b128 v[182:185], v163 offset:2048
	ds_read_b128 v[186:189], v163 offset:3072
	v_lshl_add_u64 v[226:227], v[222:223], 0, s[18:19]
	s_or_b32 m0, s100, 0x4000
	ds_read_b128 v[190:193], v161 offset:32768
	ds_read_b128 v[194:197], v161 offset:33792
	ds_read_b128 v[198:201], v160 offset:32768
	ds_read_b128 v[202:205], v160 offset:33792
	ds_read_b128 v[206:209], v159 offset:32768
	ds_read_b128 v[210:213], v159 offset:33792
	ds_read_b128 v[214:217], v158 offset:32768
	ds_read_b128 v[218:221], v158 offset:33792
	global_load_lds_dwordx4 v[226:227], off
	v_lshl_add_u64 v[226:227], v[236:237], 0, s[18:19]
	s_or_b32 m0, s100, 0x6000
	s_nop 0
	global_load_lds_dwordx4 v[226:227], off
	s_waitcnt lgkmcnt(8)
	s_barrier
	s_waitcnt lgkmcnt(0)
	v_mfma_f32_16x16x32_f16 v[128:131], v[190:193], v[174:177], v[128:131]
	v_mfma_f32_16x16x32_f16 v[124:127], v[190:193], v[182:185], v[124:127]
	v_mfma_f32_16x16x32_f16 v[120:123], v[198:201], v[174:177], v[120:123]
	v_mfma_f32_16x16x32_f16 v[116:119], v[198:201], v[182:185], v[116:119]
	v_mfma_f32_16x16x32_f16 v[112:115], v[206:209], v[174:177], v[112:115]
	v_mfma_f32_16x16x32_f16 v[108:111], v[206:209], v[182:185], v[108:111]
	v_mfma_f32_16x16x32_f16 v[104:107], v[214:217], v[174:177], v[104:107]
	v_mfma_f32_16x16x32_f16 v[100:103], v[214:217], v[182:185], v[100:103]
	v_mfma_f32_16x16x32_f16 v[128:131], v[194:197], v[178:181], v[128:131]
	v_mfma_f32_16x16x32_f16 v[124:127], v[194:197], v[186:189], v[124:127]
	v_mfma_f32_16x16x32_f16 v[120:123], v[202:205], v[178:181], v[120:123]
	v_mfma_f32_16x16x32_f16 v[116:119], v[202:205], v[186:189], v[116:119]
	v_mfma_f32_16x16x32_f16 v[112:115], v[210:213], v[178:181], v[112:115]
	v_mfma_f32_16x16x32_f16 v[108:111], v[210:213], v[186:189], v[108:111]
	v_mfma_f32_16x16x32_f16 v[104:107], v[218:221], v[178:181], v[104:107]
	v_mfma_f32_16x16x32_f16 v[100:103], v[218:221], v[186:189], v[100:103]
	s_barrier
; #define LDA8(dst, b, h) _Pragma("unroll") for (int m = 0; m < 4; ++m) _Pragma("unroll") for (int k = 0; k < 2; ++k) \
;     dst[m][k] = *(const bf16x8*)((const char*)SA8(b, h) + lds_byte8(wr * 64 + m * 16 + fr, k * 32 + fq * 8))
; #define LDB8(dst, b, h) _Pragma("unroll") for (int n = 0; n < 2; ++n) _Pragma("unroll") for (int k = 0; k < 2; ++k) \
;     dst[n][k] = *(const bf16x8*)((const char*)SB8(b, h) + lds_byte8(wc * 32 + n * 16 + fr, k * 32 + fq * 8))
; #define WAIT_V8(n) asm volatile("s_waitcnt vmcnt(" #n ")" ::: "memory")
; #define WAIT_L8(n) asm volatile("s_waitcnt lgkmcnt(" #n ")" ::: "memory")
; #define BAR8 __builtin_amdgcn_s_barrier()
; #define SCHED8 __builtin_amdgcn_sched_barrier(0)
;     ...
;     WAIT_L8(8); BAR8; WAIT_L8(0); MMA8(0, 0, At, B0); BAR8; SCHED8;
;     LDB8(B1, 1, 1); STAGE8(SB8(1, 0), Bt, K, bcol, tt + 3);
;     BAR8; WAIT_L8(0); MMA8(0, 1, At, B1); BAR8;
;     LDA8(At, 1, 1); STAGE8(SA8(1, 0), A, lda, brow, tt + 3);
;     BAR8; WAIT_L8(0); MMA8(1, 0, At, B0); BAR8; SCHED8;
;     STAGE8(SB8(1, 1), Bt, K, bcol + 128, tt + 3);
;     WAIT_V8(6); BAR8; MMA8(1, 1, At, B1); BAR8;
;   }
;   { LDB8(B0, 0, 0); LDA8(At, 0, 0); STAGE8(SA8(1, 1), A, lda, brow + 128, nt - 1);
	v_lshl_add_u64 v[250:251], v[246:247], 0, s[42:43]
	s_or_b32 m0, s100, 0x18000
	ds_read_b128 v[226:229], v162
	ds_read_b128 v[230:233], v162 offset:1024
	ds_read_b128 v[238:241], v162 offset:2048
	ds_read_b128 v[242:245], v162 offset:3072
	global_load_lds_dwordx4 v[250:251], off
	v_lshl_add_u64 v[250:251], v[248:249], 0, s[42:43]
	s_or_b32 m0, s100, 0x1a000
	s_nop 0
	global_load_lds_dwordx4 v[250:251], off
	s_barrier
	s_waitcnt lgkmcnt(0)
	v_mfma_f32_16x16x32_f16 v[96:99], v[190:193], v[226:229], v[96:99]
	v_mfma_f32_16x16x32_f16 v[92:95], v[190:193], v[238:241], v[92:95]
	v_mfma_f32_16x16x32_f16 v[88:91], v[198:201], v[226:229], v[88:91]
	v_mfma_f32_16x16x32_f16 v[84:87], v[198:201], v[238:241], v[84:87]
	v_mfma_f32_16x16x32_f16 v[80:83], v[206:209], v[226:229], v[80:83]
	v_mfma_f32_16x16x32_f16 v[76:79], v[206:209], v[238:241], v[76:79]
	v_mfma_f32_16x16x32_f16 v[72:75], v[214:217], v[226:229], v[72:75]
	v_mfma_f32_16x16x32_f16 v[68:71], v[214:217], v[238:241], v[68:71]
	v_mfma_f32_16x16x32_f16 v[96:99], v[194:197], v[230:233], v[96:99]
	v_mfma_f32_16x16x32_f16 v[92:95], v[194:197], v[242:245], v[92:95]
	v_mfma_f32_16x16x32_f16 v[88:91], v[202:205], v[230:233], v[88:91]
	v_mfma_f32_16x16x32_f16 v[84:87], v[202:205], v[242:245], v[84:87]
	v_mfma_f32_16x16x32_f16 v[80:83], v[210:213], v[230:233], v[80:83]
	v_mfma_f32_16x16x32_f16 v[76:79], v[210:213], v[242:245], v[76:79]
	v_mfma_f32_16x16x32_f16 v[72:75], v[218:221], v[230:233], v[72:75]
	v_mfma_f32_16x16x32_f16 v[68:71], v[218:221], v[242:245], v[68:71]
	v_lshl_add_u64 v[222:223], v[222:223], 0, s[22:23]
	s_or_b32 m0, s100, 0x8000
	s_barrier
	ds_read_b128 v[190:193], v161 offset:49152
	ds_read_b128 v[194:197], v161 offset:50176
	ds_read_b128 v[198:201], v160 offset:49152
	ds_read_b128 v[202:205], v160 offset:50176
	ds_read_b128 v[206:209], v159 offset:49152
	ds_read_b128 v[210:213], v159 offset:50176
	ds_read_b128 v[214:217], v158 offset:49152
	ds_read_b128 v[218:221], v158 offset:50176
	global_load_lds_dwordx4 v[222:223], off
	v_lshl_add_u64 v[222:223], v[236:237], 0, s[22:23]
	s_or_b32 m0, s100, 0xa000
	s_nop 0
	global_load_lds_dwordx4 v[222:223], off
	s_barrier
	s_waitcnt lgkmcnt(0)
	v_mfma_f32_16x16x32_f16 v[64:67], v[190:193], v[174:177], v[64:67]
	v_mfma_f32_16x16x32_f16 v[60:63], v[190:193], v[182:185], v[60:63]
	v_mfma_f32_16x16x32_f16 v[56:59], v[198:201], v[174:177], v[56:59]
	v_mfma_f32_16x16x32_f16 v[52:55], v[198:201], v[182:185], v[52:55]
	v_mfma_f32_16x16x32_f16 v[48:51], v[206:209], v[174:177], v[48:51]
	v_mfma_f32_16x16x32_f16 v[44:47], v[206:209], v[182:185], v[44:47]
	v_mfma_f32_16x16x32_f16 v[40:43], v[214:217], v[174:177], v[40:43]
	v_mfma_f32_16x16x32_f16 v[36:39], v[214:217], v[182:185], v[36:39]
	v_mfma_f32_16x16x32_f16 v[64:67], v[194:197], v[178:181], v[64:67]
	v_mfma_f32_16x16x32_f16 v[60:63], v[194:197], v[186:189], v[60:63]
	v_mfma_f32_16x16x32_f16 v[56:59], v[202:205], v[178:181], v[56:59]
	v_mfma_f32_16x16x32_f16 v[52:55], v[202:205], v[186:189], v[52:55]
	v_mfma_f32_16x16x32_f16 v[48:51], v[210:213], v[178:181], v[48:51]
	v_mfma_f32_16x16x32_f16 v[44:47], v[210:213], v[186:189], v[44:47]
	v_mfma_f32_16x16x32_f16 v[40:43], v[218:221], v[178:181], v[40:43]
	v_mfma_f32_16x16x32_f16 v[36:39], v[218:221], v[186:189], v[36:39]
	s_barrier
	v_lshl_add_u64 v[174:175], v[246:247], 0, s[44:45]
	s_or_b32 m0, s100, 0x1c000
	s_nop 0
	global_load_lds_dwordx4 v[174:175], off
	v_lshl_add_u64 v[174:175], v[248:249], 0, s[44:45]
	s_or_b32 m0, s100, 0x1e000
	s_nop 0
	global_load_lds_dwordx4 v[174:175], off
	s_waitcnt vmcnt(6)
	s_barrier
	v_mfma_f32_16x16x32_f16 v[32:35], v[190:193], v[226:229], v[32:35]
	v_mfma_f32_16x16x32_f16 v[28:31], v[190:193], v[238:241], v[28:31]
	v_mfma_f32_16x16x32_f16 v[24:27], v[198:201], v[226:229], v[24:27]
	v_mfma_f32_16x16x32_f16 v[20:23], v[198:201], v[238:241], v[20:23]
	v_mfma_f32_16x16x32_f16 v[16:19], v[206:209], v[226:229], v[16:19]
	v_mfma_f32_16x16x32_f16 v[12:15], v[206:209], v[238:241], v[12:15]
	v_mfma_f32_16x16x32_f16 v[8:11], v[214:217], v[226:229], v[8:11]
	v_mfma_f32_16x16x32_f16 v[4:7], v[214:217], v[238:241], v[4:7]
	v_mfma_f32_16x16x32_f16 v[32:35], v[194:197], v[230:233], v[32:35]
	v_mfma_f32_16x16x32_f16 v[28:31], v[194:197], v[242:245], v[28:31]
	v_mfma_f32_16x16x32_f16 v[24:27], v[202:205], v[230:233], v[24:27]
	v_mfma_f32_16x16x32_f16 v[20:23], v[202:205], v[242:245], v[20:23]
	v_mfma_f32_16x16x32_f16 v[16:19], v[210:213], v[230:233], v[16:19]
	v_mfma_f32_16x16x32_f16 v[12:15], v[210:213], v[242:245], v[12:15]
	v_mfma_f32_16x16x32_f16 v[8:11], v[218:221], v[230:233], v[8:11]
	v_mfma_f32_16x16x32_f16 v[4:7], v[218:221], v[242:245], v[4:7]
	s_add_i32 s1, s1, 2
	s_add_u32 s12, s12, 0x100
	s_addc_u32 s13, s13, 0
	s_cmp_lt_u32 s1, 12
	s_barrier
	s_cbranch_scc1 .LBB0_1259
	s_add_u32 s8, s8, 0x40780
	s_addc_u32 s9, s9, 0
	v_lshl_add_u64 v[132:133], s[8:9], 0, v[132:133]
	v_lshl_add_u64 v[0:1], v[0:1], 1, v[132:133]
	s_or_b32 m0, s100, 0xc000
	ds_read_b128 v[138:141], v171
	ds_read_b128 v[142:145], v171 offset:1024
	ds_read_b128 v[150:153], v171 offset:2048
	ds_read_b128 v[154:157], v171 offset:3072
	ds_read_b128 v[164:167], v161
	ds_read_b128 v[174:177], v161 offset:1024
	ds_read_b128 v[178:181], v160
	ds_read_b128 v[182:185], v160 offset:1024
	ds_read_b128 v[186:189], v159
	ds_read_b128 v[190:193], v159 offset:1024
	ds_read_b128 v[194:197], v158
	ds_read_b128 v[198:201], v158 offset:1024
	global_load_lds_dwordx4 v[0:1], off
	v_lshl_add_u64 v[0:1], s[8:9], 0, v[136:137]
	v_lshl_add_u64 v[0:1], v[134:135], 1, v[0:1]
	s_or_b32 m0, s100, 0xe000
	s_nop 0
	global_load_lds_dwordx4 v[0:1], off
	s_barrier
; #define LDA8(dst, b, h) _Pragma("unroll") for (int m = 0; m < 4; ++m) _Pragma("unroll") for (int k = 0; k < 2; ++k) \
;     dst[m][k] = *(const bf16x8*)((const char*)SA8(b, h) + lds_byte8(wr * 64 + m * 16 + fr, k * 32 + fq * 8))
; #define LDB8(dst, b, h) _Pragma("unroll") for (int n = 0; n < 2; ++n) _Pragma("unroll") for (int k = 0; k < 2; ++k) \
;     dst[n][k] = *(const bf16x8*)((const char*)SB8(b, h) + lds_byte8(wc * 32 + n * 16 + fr, k * 32 + fq * 8))
; #define WAIT_V8(n) asm volatile("s_waitcnt vmcnt(" #n ")" ::: "memory")
; #define WAIT_L8(n) asm volatile("s_waitcnt lgkmcnt(" #n ")" ::: "memory")
; #define BAR8 __builtin_amdgcn_s_barrier()
;     ...
;   { LDB8(B0, 0, 0); LDA8(At, 0, 0); STAGE8(SA8(1, 1), A, lda, brow + 128, nt - 1);
;     BAR8; WAIT_L8(0); MMA8(0, 0, At, B0); BAR8;
;     LDB8(B1, 0, 1); BAR8; WAIT_L8(0); MMA8(0, 1, At, B1); BAR8;
;     LDA8(At, 0, 1); WAIT_V8(4); BAR8; WAIT_L8(0); MMA8(1, 0, At, B0); MMA8(1, 1, At, B1); BAR8; }
;   { LDB8(B0, 1, 0); LDA8(At, 1, 0); WAIT_V8(2); BAR8; WAIT_L8(0); MMA8(0, 0, At, B0); BAR8;
;     LDB8(B1, 1, 1); WAIT_V8(0); BAR8; WAIT_L8(0); MMA8(0, 1, At, B1); BAR8;
;     LDA8(At, 1, 1); BAR8; WAIT_L8(0); MMA8(1, 0, At, B0); MMA8(1, 1, At, B1); BAR8; }
	s_waitcnt lgkmcnt(0)
	v_mfma_f32_16x16x32_f16 v[128:131], v[164:167], v[138:141], v[128:131]
	v_mfma_f32_16x16x32_f16 v[124:127], v[164:167], v[150:153], v[124:127]
	v_mfma_f32_16x16x32_f16 v[120:123], v[178:181], v[138:141], v[120:123]
	v_mfma_f32_16x16x32_f16 v[116:119], v[178:181], v[150:153], v[116:119]
	v_mfma_f32_16x16x32_f16 v[104:107], v[194:197], v[138:141], v[104:107]
	v_mfma_f32_16x16x32_f16 v[100:103], v[194:197], v[150:153], v[100:103]
	v_mfma_f32_16x16x32_f16 v[128:131], v[174:177], v[142:145], v[128:131]
	v_mfma_f32_16x16x32_f16 v[124:127], v[174:177], v[154:157], v[124:127]
	v_mfma_f32_16x16x32_f16 v[120:123], v[182:185], v[142:145], v[120:123]
	v_mfma_f32_16x16x32_f16 v[116:119], v[182:185], v[154:157], v[116:119]
	v_mfma_f32_16x16x32_f16 v[112:115], v[186:189], v[138:141], v[112:115]
	v_mfma_f32_16x16x32_f16 v[108:111], v[186:189], v[150:153], v[108:111]
	v_mfma_f32_16x16x32_f16 v[104:107], v[198:201], v[142:145], v[104:107]
	v_mfma_f32_16x16x32_f16 v[100:103], v[198:201], v[154:157], v[100:103]
	v_mfma_f32_16x16x32_f16 v[132:135], v[190:193], v[142:145], v[112:115]
	v_mfma_f32_16x16x32_f16 v[170:173], v[190:193], v[154:157], v[108:111]
	s_barrier
	s_nop 1
	ds_read_b128 v[108:111], v169
	ds_read_b128 v[112:115], v169 offset:1024
	ds_read_b128 v[202:205], v169 offset:2048
	ds_read_b128 v[206:209], v169 offset:3072
	s_barrier
	s_waitcnt lgkmcnt(0)
	v_mfma_f32_16x16x32_f16 v[88:91], v[178:181], v[108:111], v[88:91]
	v_mfma_f32_16x16x32_f16 v[84:87], v[178:181], v[202:205], v[84:87]
	v_mfma_f32_16x16x32_f16 v[72:75], v[194:197], v[108:111], v[72:75]
	v_mfma_f32_16x16x32_f16 v[68:71], v[194:197], v[202:205], v[68:71]
	v_mfma_f32_16x16x32_f16 v[96:99], v[164:167], v[108:111], v[96:99]
	v_mfma_f32_16x16x32_f16 v[92:95], v[164:167], v[202:205], v[92:95]
	v_mfma_f32_16x16x32_f16 v[88:91], v[182:185], v[112:115], v[88:91]
	v_mfma_f32_16x16x32_f16 v[84:87], v[182:185], v[206:209], v[84:87]
	v_mfma_f32_16x16x32_f16 v[80:83], v[186:189], v[108:111], v[80:83]
	v_mfma_f32_16x16x32_f16 v[76:79], v[186:189], v[202:205], v[76:79]
	v_mfma_f32_16x16x32_f16 v[72:75], v[198:201], v[112:115], v[72:75]
	v_mfma_f32_16x16x32_f16 v[68:71], v[198:201], v[206:209], v[68:71]
	v_mfma_f32_16x16x32_f16 v[210:213], v[174:177], v[112:115], v[96:99]
	v_mfma_f32_16x16x32_f16 v[164:167], v[174:177], v[206:209], v[92:95]
	v_mfma_f32_16x16x32_f16 v[174:177], v[190:193], v[112:115], v[80:83]
	v_mfma_f32_16x16x32_f16 v[178:181], v[190:193], v[206:209], v[76:79]
	s_barrier
	s_nop 0
	ds_read_b128 v[76:79], v161 offset:16384
	ds_read_b128 v[80:83], v161 offset:17408
	ds_read_b128 v[92:95], v160 offset:16384
	ds_read_b128 v[96:99], v160 offset:17408
	ds_read_b128 v[182:185], v159 offset:16384
	ds_read_b128 v[186:189], v159 offset:17408
	ds_read_b128 v[190:193], v158 offset:16384
	ds_read_b128 v[194:197], v158 offset:17408
	s_waitcnt vmcnt(4)
	s_barrier
	s_waitcnt lgkmcnt(0)
	v_mfma_f32_16x16x32_f16 v[64:67], v[76:79], v[138:141], v[64:67]
	v_mfma_f32_16x16x32_f16 v[60:63], v[76:79], v[150:153], v[60:63]
	v_mfma_f32_16x16x32_f16 v[56:59], v[92:95], v[138:141], v[56:59]
	v_mfma_f32_16x16x32_f16 v[52:55], v[92:95], v[150:153], v[52:55]
	v_mfma_f32_16x16x32_f16 v[40:43], v[190:193], v[138:141], v[40:43]
	v_mfma_f32_16x16x32_f16 v[36:39], v[190:193], v[150:153], v[36:39]
	v_mfma_f32_16x16x32_f16 v[64:67], v[80:83], v[142:145], v[64:67]
	v_mfma_f32_16x16x32_f16 v[60:63], v[80:83], v[154:157], v[60:63]
	v_mfma_f32_16x16x32_f16 v[56:59], v[96:99], v[142:145], v[56:59]
	v_mfma_f32_16x16x32_f16 v[52:55], v[96:99], v[154:157], v[52:55]
	v_mfma_f32_16x16x32_f16 v[48:51], v[182:185], v[138:141], v[48:51]
	v_mfma_f32_16x16x32_f16 v[44:47], v[182:185], v[150:153], v[44:47]
	v_mfma_f32_16x16x32_f16 v[40:43], v[194:197], v[142:145], v[40:43]
	v_mfma_f32_16x16x32_f16 v[36:39], v[194:197], v[154:157], v[36:39]
	v_mfma_f32_16x16x32_f16 v[198:201], v[186:189], v[142:145], v[48:51]
	v_mfma_f32_16x16x32_f16 v[214:217], v[186:189], v[154:157], v[44:47]
	v_mfma_f32_16x16x32_f16 v[24:27], v[92:95], v[108:111], v[24:27]
	v_mfma_f32_16x16x32_f16 v[20:23], v[92:95], v[202:205], v[20:23]
	v_mfma_f32_16x16x32_f16 v[8:11], v[190:193], v[108:111], v[8:11]
	v_mfma_f32_16x16x32_f16 v[4:7], v[190:193], v[202:205], v[4:7]
	v_mfma_f32_16x16x32_f16 v[32:35], v[76:79], v[108:111], v[32:35]
	v_mfma_f32_16x16x32_f16 v[28:31], v[76:79], v[202:205], v[28:31]
	v_mfma_f32_16x16x32_f16 v[24:27], v[96:99], v[112:115], v[24:27]
	v_mfma_f32_16x16x32_f16 v[20:23], v[96:99], v[206:209], v[20:23]
	v_mfma_f32_16x16x32_f16 v[16:19], v[182:185], v[108:111], v[16:19]
	v_mfma_f32_16x16x32_f16 v[12:15], v[182:185], v[202:205], v[12:15]
	v_mfma_f32_16x16x32_f16 v[8:11], v[194:197], v[112:115], v[8:11]
	v_mfma_f32_16x16x32_f16 v[4:7], v[194:197], v[206:209], v[4:7]
	v_mfma_f32_16x16x32_f16 v[136:139], v[80:83], v[112:115], v[32:35]
	v_mfma_f32_16x16x32_f16 v[140:143], v[80:83], v[206:209], v[28:31]
	v_mfma_f32_16x16x32_f16 v[150:153], v[186:189], v[112:115], v[16:19]
	v_mfma_f32_16x16x32_f16 v[154:157], v[186:189], v[206:209], v[12:15]
	s_barrier
	s_nop 0
	ds_read_b128 v[12:15], v163
	ds_read_b128 v[16:19], v163 offset:1024
	ds_read_b128 v[182:185], v163 offset:2048
	ds_read_b128 v[186:189], v163 offset:3072
	ds_read_b128 v[28:31], v161 offset:32768
	ds_read_b128 v[32:35], v161 offset:33792
	ds_read_b128 v[44:47], v160 offset:32768
	ds_read_b128 v[48:51], v160 offset:33792
	ds_read_b128 v[190:193], v159 offset:32768
	ds_read_b128 v[194:197], v159 offset:33792
	ds_read_b128 v[202:205], v158 offset:32768
	ds_read_b128 v[206:209], v158 offset:33792
	s_waitcnt vmcnt(2)
	s_barrier
; #define LDA8(dst, b, h) _Pragma("unroll") for (int m = 0; m < 4; ++m) _Pragma("unroll") for (int k = 0; k < 2; ++k) \
;     dst[m][k] = *(const bf16x8*)((const char*)SA8(b, h) + lds_byte8(wr * 64 + m * 16 + fr, k * 32 + fq * 8))
; #define LDB8(dst, b, h) _Pragma("unroll") for (int n = 0; n < 2; ++n) _Pragma("unroll") for (int k = 0; k < 2; ++k) \
;     dst[n][k] = *(const bf16x8*)((const char*)SB8(b, h) + lds_byte8(wc * 32 + n * 16 + fr, k * 32 + fq * 8))
; #define WAIT_V8(n) asm volatile("s_waitcnt vmcnt(" #n ")" ::: "memory")
; #define WAIT_L8(n) asm volatile("s_waitcnt lgkmcnt(" #n ")" ::: "memory")
; #define BAR8 __builtin_amdgcn_s_barrier()
;     ...
;   { LDB8(B0, 1, 0); LDA8(At, 1, 0); WAIT_V8(2); BAR8; WAIT_L8(0); MMA8(0, 0, At, B0); BAR8;
;     LDB8(B1, 1, 1); WAIT_V8(0); BAR8; WAIT_L8(0); MMA8(0, 1, At, B1); BAR8;
;     LDA8(At, 1, 1); BAR8; WAIT_L8(0); MMA8(1, 0, At, B0); MMA8(1, 1, At, B1); BAR8; }
;   if (wr == 0) BAR8;
;   __syncthreads();
;     ...
;   if (t < 256) {
	s_waitcnt lgkmcnt(0)
	v_mfma_f32_16x16x32_f16 v[76:79], v[28:31], v[12:15], v[128:131]
	v_mfma_f32_16x16x32_f16 v[128:131], v[32:35], v[16:19], v[76:79]
	v_mfma_f32_16x16x32_f16 v[76:79], v[28:31], v[182:185], v[124:127]
	v_mfma_f32_16x16x32_f16 v[124:127], v[32:35], v[186:189], v[76:79]
	v_mfma_f32_16x16x32_f16 v[76:79], v[44:47], v[12:15], v[120:123]
	v_mfma_f32_16x16x32_f16 v[112:115], v[48:51], v[16:19], v[76:79]
	v_mfma_f32_16x16x32_f16 v[76:79], v[44:47], v[182:185], v[116:119]
	v_mfma_f32_16x16x32_f16 v[108:111], v[48:51], v[186:189], v[76:79]
	v_mfma_f32_16x16x32_f16 v[76:79], v[190:193], v[12:15], v[132:135]
	v_mfma_f32_16x16x32_f16 v[96:99], v[194:197], v[16:19], v[76:79]
	v_mfma_f32_16x16x32_f16 v[76:79], v[190:193], v[182:185], v[170:173]
	v_mfma_f32_16x16x32_f16 v[92:95], v[194:197], v[186:189], v[76:79]
	v_mfma_f32_16x16x32_f16 v[76:79], v[202:205], v[12:15], v[104:107]
	v_mfma_f32_16x16x32_f16 v[80:83], v[206:209], v[16:19], v[76:79]
	v_mfma_f32_16x16x32_f16 v[76:79], v[202:205], v[182:185], v[100:103]
	v_mfma_f32_16x16x32_f16 v[76:79], v[206:209], v[186:189], v[76:79]
	s_barrier
	ds_read_b128 v[132:135], v162
	ds_read_b128 v[168:171], v162 offset:1024
	ds_read_b128 v[218:221], v162 offset:2048
	ds_read_b128 v[226:229], v162 offset:3072
	s_waitcnt vmcnt(0)
	s_barrier
	s_waitcnt lgkmcnt(0)
	v_mfma_f32_16x16x32_f16 v[100:103], v[28:31], v[132:135], v[210:213]
	v_mfma_f32_16x16x32_f16 v[28:31], v[28:31], v[218:221], v[164:167]
	v_mfma_f32_16x16x32_f16 v[116:119], v[32:35], v[226:229], v[28:31]
	v_mfma_f32_16x16x32_f16 v[28:31], v[44:47], v[132:135], v[88:91]
	v_mfma_f32_16x16x32_f16 v[104:107], v[48:51], v[168:171], v[28:31]
	v_mfma_f32_16x16x32_f16 v[28:31], v[44:47], v[218:221], v[84:87]
	v_mfma_f32_16x16x32_f16 v[120:123], v[32:35], v[168:171], v[100:103]
	v_mfma_f32_16x16x32_f16 v[100:103], v[48:51], v[226:229], v[28:31]
	v_mfma_f32_16x16x32_f16 v[28:31], v[190:193], v[132:135], v[174:177]
	v_mfma_f32_16x16x32_f16 v[88:91], v[194:197], v[168:171], v[28:31]
	v_mfma_f32_16x16x32_f16 v[28:31], v[190:193], v[218:221], v[178:181]
	v_mfma_f32_16x16x32_f16 v[84:87], v[194:197], v[226:229], v[28:31]
	v_mfma_f32_16x16x32_f16 v[28:31], v[202:205], v[132:135], v[72:75]
	v_mfma_f32_16x16x32_f16 v[72:75], v[206:209], v[168:171], v[28:31]
	v_mfma_f32_16x16x32_f16 v[28:31], v[202:205], v[218:221], v[68:71]
	v_mfma_f32_16x16x32_f16 v[68:71], v[206:209], v[226:229], v[28:31]
	s_barrier
	ds_read_b128 v[162:165], v161 offset:49152
	ds_read_b128 v[172:175], v161 offset:50176
	ds_read_b128 v[176:179], v160 offset:49152
	ds_read_b128 v[190:193], v160 offset:50176
	ds_read_b128 v[194:197], v159 offset:49152
	ds_read_b128 v[202:205], v159 offset:50176
	ds_read_b128 v[206:209], v158 offset:49152
	ds_read_b128 v[158:161], v158 offset:50176
	s_barrier
	s_waitcnt lgkmcnt(0)
	v_mfma_f32_16x16x32_f16 v[28:31], v[162:165], v[12:15], v[64:67]
	v_mfma_f32_16x16x32_f16 v[64:67], v[172:175], v[16:19], v[28:31]
	v_mfma_f32_16x16x32_f16 v[28:31], v[162:165], v[182:185], v[60:63]
	v_mfma_f32_16x16x32_f16 v[60:63], v[172:175], v[186:189], v[28:31]
	v_mfma_f32_16x16x32_f16 v[28:31], v[176:179], v[12:15], v[56:59]
	v_mfma_f32_16x16x32_f16 v[48:51], v[190:193], v[16:19], v[28:31]
	v_mfma_f32_16x16x32_f16 v[28:31], v[176:179], v[182:185], v[52:55]
	v_mfma_f32_16x16x32_f16 v[44:47], v[190:193], v[186:189], v[28:31]
	v_mfma_f32_16x16x32_f16 v[28:31], v[194:197], v[12:15], v[198:201]
	v_mfma_f32_16x16x32_f16 v[12:15], v[206:209], v[12:15], v[40:43]
	v_mfma_f32_16x16x32_f16 v[32:35], v[202:205], v[16:19], v[28:31]
	v_mfma_f32_16x16x32_f16 v[28:31], v[194:197], v[182:185], v[214:217]
	v_mfma_f32_16x16x32_f16 v[16:19], v[158:161], v[16:19], v[12:15]
	v_mfma_f32_16x16x32_f16 v[12:15], v[206:209], v[182:185], v[36:39]
	v_mfma_f32_16x16x32_f16 v[28:31], v[202:205], v[186:189], v[28:31]
	v_mfma_f32_16x16x32_f16 v[12:15], v[158:161], v[186:189], v[12:15]
	v_mfma_f32_16x16x32_f16 v[36:39], v[162:165], v[132:135], v[136:139]
	v_mfma_f32_16x16x32_f16 v[56:59], v[172:175], v[168:171], v[36:39]
	v_mfma_f32_16x16x32_f16 v[36:39], v[162:165], v[218:221], v[140:143]
	v_mfma_f32_16x16x32_f16 v[20:23], v[176:179], v[218:221], v[20:23]
	v_mfma_f32_16x16x32_f16 v[52:55], v[172:175], v[226:229], v[36:39]
	v_mfma_f32_16x16x32_f16 v[24:27], v[176:179], v[132:135], v[24:27]
	v_mfma_f32_16x16x32_f16 v[36:39], v[190:193], v[226:229], v[20:23]
	v_mfma_f32_16x16x32_f16 v[20:23], v[194:197], v[132:135], v[150:153]
	v_mfma_f32_16x16x32_f16 v[40:43], v[190:193], v[168:171], v[24:27]
	v_mfma_f32_16x16x32_f16 v[24:27], v[202:205], v[168:171], v[20:23]
	v_mfma_f32_16x16x32_f16 v[20:23], v[194:197], v[218:221], v[154:157]
	v_mfma_f32_16x16x32_f16 v[8:11], v[206:209], v[132:135], v[8:11]
	v_mfma_f32_16x16x32_f16 v[4:7], v[206:209], v[218:221], v[4:7]
	v_mfma_f32_16x16x32_f16 v[20:23], v[202:205], v[226:229], v[20:23]
	v_mfma_f32_16x16x32_f16 v[8:11], v[158:161], v[168:171], v[8:11]
	v_mfma_f32_16x16x32_f16 v[4:7], v[158:161], v[226:229], v[4:7]
	s_movk_i32 s1, 0x100
	v_cmp_gt_u32_e32 vcc, s1, v3
	s_barrier
	s_and_saveexec_b64 s[8:9], vcc
	s_cbranch_execz .LBB0_1262
	s_barrier

; DI int tid_opaque() { int t = threadIdx.x; asm volatile("" : "+v"(t)); return t; }
; #define BAR8 __builtin_amdgcn_s_barrier()
;   constexpr int HT = 128 * 64;
;   bf16_t* shm = (bf16_t*)smem;
;   const int t = tid_opaque();
;     ...
;   if (!pre) {
;     STAGE8(SB8(0, 0), Bt, K, bcol, 0); STAGE8(SA8(0, 0), A, lda, brow, 0);
;     STAGE8(SB8(0, 1), Bt, K, bcol + 128, 0); STAGE8(SA8(0, 1), A, lda, brow + 128, 0);
;   }
;   if (wr == 1) BAR8;
.LBB0_1322:
	s_mov_b32 s0, 24
	s_mov_b32 s0, 25
	s_ashr_i32 s1, s0, 31
	s_lshl_b64 s[0:1], s[0:1], 3
	s_add_u32 s0, s70, s0
	s_addc_u32 s1, s71, s1
	v_readlane_b32 s6, v255, 60
	v_readlane_b32 s7, v255, 61
	s_nop 4
	s_mov_b32 s0, 25
	s_ashr_i32 s1, s0, 31
	s_lshl_b64 s[0:1], s[0:1], 3
	s_add_u32 s0, s70, s0
	s_addc_u32 s1, s71, s1
	s_mov_b32 s2, 25
	v_readlane_b32 s0, v255, 60
	v_readlane_b32 s1, v255, 61
	s_nop 4
	s_ashr_i32 s3, s2, 31
	s_lshl_b64 s[2:3], s[2:3], 3
	s_add_u32 s2, s70, s2
	s_addc_u32 s3, s71, s3
	v_mov_b32_e32 v3, v224
	v_readlane_b32 s2, v255, 60
	v_readlane_b32 s3, v255, 61
	s_nop 4
	s_lshl_b32 s8, s24, 8
	v_bfe_i32 v1, v3, 27, 1
	s_waitcnt vmcnt(10)
	v_lshlrev_b32_e32 v150, 4, v3
	s_nop 0
	v_readfirstlane_b32 s100, v150
	v_lshrrev_b32_e32 v1, 22, v1
	v_add_u32_e32 v1, v150, v1
	v_and_b32_e32 v1, 0xfffffc00, v1
	v_ashrrev_i32_e32 v0, 31, v3
	v_sub_u32_e32 v1, v150, v1
	v_lshrrev_b32_e32 v0, 26, v0
	v_lshrrev_b32_e32 v5, 4, v1
	v_add_u32_e32 v0, v3, v0
	v_bitop3_b32 v6, v5, v1, 32 bitop3:0x6c
	v_ashrrev_i32_e32 v1, 31, v1
	v_ashrrev_i32_e32 v0, 6, v0
	v_lshrrev_b32_e32 v1, 26, v1
	v_lshlrev_b32_e32 v5, 3, v0
	v_add_u32_e32 v1, v6, v1
	v_and_b32_e32 v5, -16, v5
	v_ashrrev_i32_e32 v1, 6, v1
	s_and_b32 s25, s8, 0x3f00
	s_lshl_b32 s8, s24, 2
	v_add_u32_e32 v5, v1, v5
	v_mul_i32_i24_e32 v1, 64, v1
	s_and_b32 s8, s8, 0xffffff00
	v_lshlrev_b32_e32 v0, 5, v0
	v_sub_u32_e32 v1, v6, v1
	v_mov_b32_e32 v15, 1
	s_mul_i32 s12, s8, 0x1600
	v_and_b32_e32 v0, 32, v0
	v_ashrrev_i16_sdwa v1, v15, sext(v1) dst_sel:DWORD dst_unused:UNUSED_PAD src0_sel:DWORD src1_sel:BYTE_0
	s_movk_i32 s27, 0xb00
	s_mul_hi_i32 s9, s8, 0x1600
	s_add_u32 s12, s14, s12
	v_add_u32_sdwa v0, v0, sext(v1) dst_sel:DWORD dst_unused:UNUSED_PAD src0_sel:DWORD src1_sel:WORD_0
	v_mad_i64_i32 v[132:133], s[30:31], v5, s27, 0
	s_addc_u32 s13, s15, s9
	v_lshlrev_b64 v[24:25], 1, v[132:133]
	v_ashrrev_i32_e32 v1, 31, v0
	v_lshl_add_u64 v[8:9], s[12:13], 0, v[24:25]
	v_lshlrev_b64 v[6:7], 1, v[0:1]
	s_waitcnt vmcnt(9)
	v_add_u32_e32 v152, 0x2000, v150
	v_lshl_add_u64 v[10:11], v[8:9], 0, v[6:7]
	v_ashrrev_i32_e32 v8, 31, v152
	v_lshrrev_b32_e32 v8, 22, v8
	v_add_u32_e32 v8, v152, v8
	v_ashrrev_i32_e32 v8, 10, v8
	v_mul_i32_i24_e32 v9, 0x400, v8
	v_sub_u32_e32 v9, v152, v9
	v_lshrrev_b32_e32 v12, 4, v9
	v_bitop3_b32 v9, v12, v9, 32 bitop3:0x6c
	v_ashrrev_i32_e32 v13, 31, v9
	v_lshrrev_b32_e32 v13, 26, v13
	v_lshlrev_b32_e32 v12, 3, v8
	v_add_u32_e32 v13, v9, v13
	s_waitcnt vmcnt(8)
	v_mov_b32_e32 v4, v2
	s_or_b32 m0, s100, 0x10000
	v_and_b32_e32 v12, -16, v12
	v_ashrrev_i32_e32 v14, 6, v13
	global_load_lds_dwordx4 v[10:11], off
	v_add_u32_e32 v22, v14, v12
	v_and_b32_e32 v12, 0xc0, v13
	s_or_b32 m0, s100, 0x12000
	s_mul_i32 s9, s25, 0xb00
	v_lshlrev_b32_e32 v8, 5, v8
	v_sub_u32_e32 v9, v9, v12
	v_mad_i64_i32 v[136:137], s[30:31], v22, s27, 0
	s_lshl_b32 s27, s9, 1
	v_and_b32_e32 v8, 32, v8
	v_ashrrev_i16_sdwa v9, v15, sext(v9) dst_sel:DWORD dst_unused:UNUSED_PAD src0_sel:DWORD src1_sel:BYTE_0
	s_waitcnt lgkmcnt(0)
	s_add_u32 s9, s2, s27
	v_add_u32_sdwa v134, v8, sext(v9) dst_sel:DWORD dst_unused:UNUSED_PAD src0_sel:DWORD src1_sel:WORD_0
	v_lshlrev_b64 v[26:27], 1, v[136:137]
	s_addc_u32 s29, s3, 0
	v_lshl_add_u64 v[12:13], s[12:13], 0, v[26:27]
	v_ashrrev_i32_e32 v135, 31, v134
	s_add_u32 s12, s9, 0x2000000
	v_lshlrev_b64 v[8:9], 1, v[134:135]
	s_addc_u32 s13, s29, 0
	v_lshl_add_u64 v[12:13], v[12:13], 0, v[8:9]
	v_lshl_add_u64 v[14:15], s[12:13], 0, v[24:25]
	global_load_lds_dwordx4 v[12:13], off
	v_lshl_add_u64 v[14:15], v[14:15], 0, v[6:7]
	s_mov_b32 m0, s100
	v_lshl_add_u64 v[16:17], s[12:13], 0, v[26:27]
	s_or_b32 s30, s8, 0x80
	global_load_lds_dwordx4 v[14:15], off
	s_or_b32 m0, s100, 0x2000
	s_mul_i32 s12, s30, 0x1600
	s_mul_hi_i32 s13, s30, 0x1600
	s_add_u32 s12, s14, s12
	s_addc_u32 s13, s15, s13
	v_lshl_add_u64 v[16:17], v[16:17], 0, v[8:9]
	v_lshl_add_u64 v[18:19], s[12:13], 0, v[24:25]
	global_load_lds_dwordx4 v[16:17], off
	v_lshl_add_u64 v[18:19], v[18:19], 0, v[6:7]
	s_or_b32 m0, s100, 0x14000
	v_lshl_add_u64 v[20:21], s[12:13], 0, v[26:27]
	global_load_lds_dwordx4 v[18:19], off
	s_or_b32 m0, s100, 0x16000
	s_add_u32 s12, s9, 0x20b0000
	s_addc_u32 s13, s29, 0
	v_lshl_add_u64 v[20:21], v[20:21], 0, v[8:9]
	v_lshl_add_u64 v[24:25], s[12:13], 0, v[24:25]
	global_load_lds_dwordx4 v[20:21], off
	v_lshl_add_u64 v[24:25], v[24:25], 0, v[6:7]
	s_or_b32 m0, s100, 0x4000
	global_load_lds_dwordx4 v[24:25], off
	v_lshl_add_u64 v[24:25], s[12:13], 0, v[26:27]
	v_lshl_add_u64 v[24:25], v[24:25], 0, v[8:9]
	s_or_b32 m0, s100, 0x6000
	v_ashrrev_i32_e32 v23, 8, v3
	global_load_lds_dwordx4 v[24:25], off
	v_cmp_eq_u32_e32 vcc, 1, v23
	s_and_saveexec_b64 s[12:13], vcc
	s_cbranch_execz .LBB0_1324
	s_barrier
; #define WAIT_V8(n) asm volatile("s_waitcnt vmcnt(" #n ")" ::: "memory")
; #define BAR8 __builtin_amdgcn_s_barrier()
;     ...
;   const int brow = m0, bcol = n0;
;   const int wid = t >> 6, lane = t & 63, wr = wid >> 2, wc = wid & 3, fr = lane & 15, fq = lane >> 4;
;   f32x4 acc[2][2][4][2];
;   {
;     float zinit = 0.f;
;     asm volatile("" : "+v"(zinit));
; #pragma unroll
;     for (int a = 0; a < 2; ++a)
; #pragma unroll
;       for (int b = 0; b < 2; ++b)
; #pragma unroll
;         for (int m = 0; m < 4; ++m)
; #pragma unroll
;           for (int n = 0; n < 2; ++n)
; #pragma unroll
;             for (int j = 0; j < 4; ++j) acc[a][b][m][n][j] = zinit;
;   }
;   bf16x8 At[4][2], B0[2][2], B1[2][2];
;   const int nt = K / 64;
;   if (!pre) {
;     STAGE8(SB8(0, 0), Bt, K, bcol, 0); STAGE8(SA8(0, 0), A, lda, brow, 0);
;     STAGE8(SB8(0, 1), Bt, K, bcol + 128, 0); STAGE8(SA8(0, 1), A, lda, brow + 128, 0);
;   }
;   if (wr == 1) BAR8;
;   WAIT_V8(4); BAR8;
;   STAGE8(SB8(1, 0), Bt, K, bcol, 1); STAGE8(SA8(1, 0), A, lda, brow, 1); STAGE8(SB8(1, 1), Bt, K, bcol + 128, 1);
;   WAIT_V8(6); BAR8;
.LBB0_1324:
	s_or_b64 exec, exec, s[12:13]
	s_mov_b64 s[36:37], 0x80
	v_lshl_add_u64 v[10:11], v[10:11], 0, s[36:37]
	s_or_b32 m0, s100, 0x18000
	s_waitcnt vmcnt(4)
	s_barrier
	global_load_lds_dwordx4 v[10:11], off
	v_lshl_add_u64 v[10:11], v[12:13], 0, s[36:37]
	s_or_b32 m0, s100, 0x1a000
	global_load_lds_dwordx4 v[10:11], off
	v_lshl_add_u64 v[10:11], v[14:15], 0, s[36:37]
	s_or_b32 m0, s100, 0x8000
	global_load_lds_dwordx4 v[10:11], off
	v_lshl_add_u64 v[10:11], v[16:17], 0, s[36:37]
	s_or_b32 m0, s100, 0xa000
	global_load_lds_dwordx4 v[10:11], off
	v_lshl_add_u64 v[10:11], v[18:19], 0, s[36:37]
	s_or_b32 m0, s100, 0x1c000
	s_nop 0
	global_load_lds_dwordx4 v[10:11], off
	v_lshl_add_u64 v[10:11], v[20:21], 0, s[36:37]
	s_or_b32 m0, s100, 0x1e000
	v_and_b32_e32 v147, 15, v3
	global_load_lds_dwordx4 v[10:11], off
	v_bfe_u32 v148, v3, 4, 2
	v_lshlrev_b32_e32 v10, 4, v148
	v_lshlrev_b32_e32 v11, 6, v147
	v_lshlrev_b32_e32 v13, 2, v3
	v_or_b32_e32 v12, v10, v11
	v_and_b32_e32 v13, 32, v13
	s_mov_b32 s12, 0x10000
	v_bitop3_b32 v18, v12, s12, v13 bitop3:0xde
	s_mov_b32 s12, 0x14000
	v_bitop3_b32 v17, v10, v13, v11 bitop3:0x36
	v_bitop3_b32 v19, v12, s12, v13 bitop3:0xde
	s_mov_b32 s12, 0x18000
	v_lshlrev_b32_e32 v11, 6, v3
	v_bitop3_b32 v20, v12, s12, v13 bitop3:0xde
	s_mov_b32 s12, 0x1c000
	v_and_b32_e32 v11, 0x3c0, v11
	s_movk_i32 s31, 0x1600
	s_and_b32 s29, s21, 0xffffff00
	v_bitop3_b32 v21, v12, s12, v13 bitop3:0xde
	v_bitop3_b32 v24, v11, v13, v10 bitop3:0x36
	v_mad_i64_i32 v[10:11], s[12:13], v5, s31, 0
	v_mov_b32_e32 v5, 0x1600
	v_mad_i64_i32 v[12:13], s[12:13], s29, v5, v[10:11]
	v_lshl_add_u64 v[12:13], v[12:13], 0, v[6:7]
	v_lshl_add_u64 v[138:139], s[4:5], 0, v[12:13]
	v_mad_i64_i32 v[12:13], s[12:13], v22, s31, 0
	v_mad_i64_i32 v[14:15], s[12:13], s29, v5, v[12:13]
	s_bfe_u32 s29, s20, 0x60008
	v_mov_b32_e32 v5, 0x160000
	v_mad_u64_u32 v[10:11], s[12:13], s29, v5, v[10:11]
	v_lshl_add_u64 v[6:7], v[10:11], 0, v[6:7]
	v_bfe_u32 v146, v3, 6, 2
	s_waitcnt vmcnt(6)
	v_lshlrev_b32_e32 v149, 6, v23
	v_lshlrev_b32_e32 v23, 13, v23
	v_lshl_add_u64 v[142:143], s[2:3], 0, v[6:7]
	v_mad_u64_u32 v[6:7], s[12:13], s29, v5, v[12:13]
	v_lshlrev_b32_e32 v16, 12, v146
	v_or_b32_e32 v25, 0x800, v23
	v_or_b32_e32 v26, 0x1000, v23
	v_or_b32_e32 v27, 0x1800, v23
	v_lshl_add_u64 v[14:15], v[14:15], 0, v[8:9]
	v_lshl_add_u64 v[6:7], v[6:7], 0, v[8:9]
	s_ashr_i32 s9, s8, 31
	v_lshl_add_u64 v[140:141], s[4:5], 0, v[14:15]
	v_lshl_add_u64 v[144:145], s[2:3], 0, v[6:7]
	s_mov_b32 s29, -2
	s_mov_b64 s[12:13], 0
	v_add_u32_e32 v171, v18, v16
	v_add_u32_e32 v156, v17, v23
	v_add_u32_e32 v155, v24, v25
	v_add_u32_e32 v154, v24, v26
	v_add_u32_e32 v153, v24, v27
	v_add_u32_e32 v169, v19, v16
	v_add_u32_e32 v159, v20, v16
	v_add_u32_e32 v158, v21, v16
	v_mov_b32_e32 v5, v4
	v_mov_b64_e32 v[6:7], v[4:5]
	v_mov_b64_e32 v[8:9], v[4:5]
	v_mov_b64_e32 v[10:11], v[4:5]
	v_mov_b64_e32 v[12:13], v[4:5]
	v_mov_b64_e32 v[14:15], v[4:5]
	v_mov_b64_e32 v[16:17], v[4:5]
	v_mov_b64_e32 v[18:19], v[4:5]
	v_mov_b64_e32 v[20:21], v[4:5]
	v_mov_b64_e32 v[22:23], v[4:5]
	v_mov_b64_e32 v[24:25], v[4:5]
	v_mov_b64_e32 v[26:27], v[4:5]
	v_mov_b64_e32 v[28:29], v[4:5]
	v_mov_b64_e32 v[30:31], v[4:5]
	v_mov_b64_e32 v[32:33], v[4:5]
	v_mov_b64_e32 v[34:35], v[4:5]
	v_mov_b64_e32 v[36:37], v[4:5]
	v_mov_b64_e32 v[38:39], v[4:5]
	v_mov_b64_e32 v[40:41], v[4:5]
	v_mov_b64_e32 v[42:43], v[4:5]
	v_mov_b64_e32 v[44:45], v[4:5]
	v_mov_b64_e32 v[46:47], v[4:5]
	v_mov_b64_e32 v[48:49], v[4:5]
	v_mov_b64_e32 v[50:51], v[4:5]
	v_mov_b64_e32 v[52:53], v[4:5]
	v_mov_b64_e32 v[54:55], v[4:5]
	v_mov_b64_e32 v[56:57], v[4:5]
	v_mov_b64_e32 v[58:59], v[4:5]
	v_mov_b64_e32 v[60:61], v[4:5]
	v_mov_b64_e32 v[62:63], v[4:5]
	v_mov_b64_e32 v[64:65], v[4:5]
	v_mov_b64_e32 v[66:67], v[4:5]
	v_mov_b64_e32 v[68:69], v[4:5]
	v_mov_b64_e32 v[70:71], v[4:5]
	v_mov_b64_e32 v[72:73], v[4:5]
	v_mov_b64_e32 v[74:75], v[4:5]
	v_mov_b64_e32 v[76:77], v[4:5]
	v_mov_b64_e32 v[78:79], v[4:5]
	v_mov_b64_e32 v[80:81], v[4:5]
	v_mov_b64_e32 v[82:83], v[4:5]
	v_mov_b64_e32 v[84:85], v[4:5]
	v_mov_b64_e32 v[86:87], v[4:5]
	v_mov_b64_e32 v[88:89], v[4:5]
	v_mov_b64_e32 v[90:91], v[4:5]
	v_mov_b64_e32 v[92:93], v[4:5]
	v_mov_b64_e32 v[94:95], v[4:5]
	v_mov_b64_e32 v[96:97], v[4:5]
	v_mov_b64_e32 v[98:99], v[4:5]
	v_mov_b64_e32 v[100:101], v[4:5]
	v_mov_b64_e32 v[102:103], v[4:5]
	v_mov_b64_e32 v[104:105], v[4:5]
	v_mov_b64_e32 v[106:107], v[4:5]
	v_mov_b64_e32 v[108:109], v[4:5]
	v_mov_b64_e32 v[110:111], v[4:5]
	v_mov_b64_e32 v[112:113], v[4:5]
	v_mov_b64_e32 v[114:115], v[4:5]
	v_mov_b64_e32 v[116:117], v[4:5]
	v_mov_b64_e32 v[118:119], v[4:5]
	v_mov_b64_e32 v[120:121], v[4:5]
	v_mov_b64_e32 v[122:123], v[4:5]
	v_mov_b64_e32 v[124:125], v[4:5]
	v_mov_b64_e32 v[126:127], v[4:5]
	v_mov_b64_e32 v[128:129], v[4:5]
	v_mov_b64_e32 v[130:131], v[4:5]
	s_mov_b64 s[36:37], 0x20b0080
	s_mov_b64 s[38:39], 0xd5a0100
	s_mov_b64 s[40:41], 0x2000100
	s_mov_b64 s[42:43], 0xd650100
	s_mov_b64 s[44:45], 0x20b0100
	s_mov_b64 s[46:47], 0xd5a0180
	s_mov_b64 s[48:49], 0x2000180
	s_mov_b64 s[50:51], 0xd650180
	s_barrier
; #define LDA8(dst, b, h) _Pragma("unroll") for (int m = 0; m < 4; ++m) _Pragma("unroll") for (int k = 0; k < 2; ++k) \
;     dst[m][k] = *(const bf16x8*)((const char*)SA8(b, h) + lds_byte8(wr * 64 + m * 16 + fr, k * 32 + fq * 8))
; #define LDB8(dst, b, h) _Pragma("unroll") for (int n = 0; n < 2; ++n) _Pragma("unroll") for (int k = 0; k < 2; ++k) \
;     dst[n][k] = *(const bf16x8*)((const char*)SB8(b, h) + lds_byte8(wc * 32 + n * 16 + fr, k * 32 + fq * 8))
; #define WAIT_V8(n) asm volatile("s_waitcnt vmcnt(" #n ")" ::: "memory")
; #define WAIT_L8(n) asm volatile("s_waitcnt lgkmcnt(" #n ")" ::: "memory")
; #define BAR8 __builtin_amdgcn_s_barrier()
; #define SCHED8 __builtin_amdgcn_sched_barrier(0)
;     ...
;   for (int tt = 0; tt < nt - 2; tt += 2) {
;     LDB8(B0, 0, 0); SCHED8; LDA8(At, 0, 0); STAGE8(SA8(1, 1), A, lda, brow + 128, tt + 1);
;     WAIT_L8(8); BAR8; WAIT_L8(0); MMA8(0, 0, At, B0); BAR8; SCHED8;
;     LDB8(B1, 0, 1); STAGE8(SB8(0, 0), Bt, K, bcol, tt + 2);
;     BAR8; WAIT_L8(0); MMA8(0, 1, At, B1); BAR8;
;     LDA8(At, 0, 1); STAGE8(SA8(0, 0), A, lda, brow, tt + 2);
;     BAR8; WAIT_L8(0); MMA8(1, 0, At, B0); BAR8; SCHED8;
;     STAGE8(SB8(0, 1), Bt, K, bcol + 128, tt + 2);
;     WAIT_V8(6); BAR8; MMA8(1, 1, At, B1); BAR8;
.LBB0_1325:
	ds_read_b128 v[174:177], v171
	ds_read_b128 v[178:181], v171 offset:1024
	ds_read_b128 v[182:185], v171 offset:2048
	ds_read_b128 v[186:189], v171 offset:3072
	v_lshl_add_u64 v[222:223], v[142:143], 0, s[12:13]
	v_lshl_add_u64 v[226:227], v[222:223], 0, s[36:37]
	s_or_b32 m0, s100, 0xc000
	v_lshl_add_u64 v[236:237], v[144:145], 0, s[12:13]
	ds_read_b128 v[190:193], v156
	ds_read_b128 v[194:197], v156 offset:1024
	ds_read_b128 v[198:201], v155
	ds_read_b128 v[202:205], v155 offset:1024
	ds_read_b128 v[206:209], v154
	ds_read_b128 v[210:213], v154 offset:1024
	ds_read_b128 v[214:217], v153
	ds_read_b128 v[218:221], v153 offset:1024
	global_load_lds_dwordx4 v[226:227], off
	v_lshl_add_u64 v[226:227], v[236:237], 0, s[36:37]
	s_or_b32 m0, s100, 0xe000
	s_nop 0
	global_load_lds_dwordx4 v[226:227], off
	s_waitcnt lgkmcnt(8)
	s_barrier
	s_waitcnt lgkmcnt(0)
	v_mfma_f32_16x16x32_bf16 v[128:131], v[190:193], v[174:177], v[128:131]
	v_mfma_f32_16x16x32_bf16 v[124:127], v[190:193], v[182:185], v[124:127]
	v_mfma_f32_16x16x32_bf16 v[120:123], v[198:201], v[174:177], v[120:123]
	v_mfma_f32_16x16x32_bf16 v[116:119], v[198:201], v[182:185], v[116:119]
	v_mfma_f32_16x16x32_bf16 v[112:115], v[206:209], v[174:177], v[112:115]
	v_mfma_f32_16x16x32_bf16 v[108:111], v[206:209], v[182:185], v[108:111]
	v_mfma_f32_16x16x32_bf16 v[104:107], v[214:217], v[174:177], v[104:107]
	v_mfma_f32_16x16x32_bf16 v[100:103], v[214:217], v[182:185], v[100:103]
	v_mfma_f32_16x16x32_bf16 v[128:131], v[194:197], v[178:181], v[128:131]
	v_mfma_f32_16x16x32_bf16 v[124:127], v[194:197], v[186:189], v[124:127]
	v_mfma_f32_16x16x32_bf16 v[120:123], v[202:205], v[178:181], v[120:123]
	v_mfma_f32_16x16x32_bf16 v[116:119], v[202:205], v[186:189], v[116:119]
	v_mfma_f32_16x16x32_bf16 v[112:115], v[210:213], v[178:181], v[112:115]
	v_mfma_f32_16x16x32_bf16 v[108:111], v[210:213], v[186:189], v[108:111]
	v_mfma_f32_16x16x32_bf16 v[104:107], v[218:221], v[178:181], v[104:107]
	v_mfma_f32_16x16x32_bf16 v[100:103], v[218:221], v[186:189], v[100:103]
	s_barrier
	v_lshl_add_u64 v[246:247], v[138:139], 0, s[12:13]
	v_lshl_add_u64 v[248:249], v[246:247], 0, s[38:39]
	s_or_b32 m0, s100, 0x10000
	ds_read_b128 v[226:229], v169
	ds_read_b128 v[230:233], v169 offset:1024
	ds_read_b128 v[238:241], v169 offset:2048
	ds_read_b128 v[242:245], v169 offset:3072
	global_load_lds_dwordx4 v[248:249], off
	v_lshl_add_u64 v[248:249], v[140:141], 0, s[12:13]
	v_lshl_add_u64 v[250:251], v[248:249], 0, s[38:39]
	s_or_b32 m0, s100, 0x12000
	s_nop 0
	global_load_lds_dwordx4 v[250:251], off
	s_barrier
	s_waitcnt lgkmcnt(0)
	v_mfma_f32_16x16x32_bf16 v[96:99], v[190:193], v[226:229], v[96:99]
	v_mfma_f32_16x16x32_bf16 v[92:95], v[190:193], v[238:241], v[92:95]
	v_mfma_f32_16x16x32_bf16 v[88:91], v[198:201], v[226:229], v[88:91]
	v_mfma_f32_16x16x32_bf16 v[84:87], v[198:201], v[238:241], v[84:87]
	v_mfma_f32_16x16x32_bf16 v[80:83], v[206:209], v[226:229], v[80:83]
	v_mfma_f32_16x16x32_bf16 v[76:79], v[206:209], v[238:241], v[76:79]
	v_mfma_f32_16x16x32_bf16 v[72:75], v[214:217], v[226:229], v[72:75]
	v_mfma_f32_16x16x32_bf16 v[68:71], v[214:217], v[238:241], v[68:71]
	v_mfma_f32_16x16x32_bf16 v[96:99], v[194:197], v[230:233], v[96:99]
	v_mfma_f32_16x16x32_bf16 v[92:95], v[194:197], v[242:245], v[92:95]
	v_mfma_f32_16x16x32_bf16 v[88:91], v[202:205], v[230:233], v[88:91]
	v_mfma_f32_16x16x32_bf16 v[84:87], v[202:205], v[242:245], v[84:87]
	v_mfma_f32_16x16x32_bf16 v[80:83], v[210:213], v[230:233], v[80:83]
	v_mfma_f32_16x16x32_bf16 v[76:79], v[210:213], v[242:245], v[76:79]
	v_mfma_f32_16x16x32_bf16 v[72:75], v[218:221], v[230:233], v[72:75]
	v_mfma_f32_16x16x32_bf16 v[68:71], v[218:221], v[242:245], v[68:71]
	v_lshl_add_u64 v[250:251], v[222:223], 0, s[40:41]
	s_mov_b32 m0, s100
	s_barrier
	ds_read_b128 v[190:193], v156 offset:16384
	ds_read_b128 v[194:197], v156 offset:17408
	ds_read_b128 v[198:201], v155 offset:16384
	ds_read_b128 v[202:205], v155 offset:17408
	ds_read_b128 v[206:209], v154 offset:16384
	ds_read_b128 v[210:213], v154 offset:17408
	ds_read_b128 v[214:217], v153 offset:16384
	ds_read_b128 v[218:221], v153 offset:17408
	global_load_lds_dwordx4 v[250:251], off
	v_lshl_add_u64 v[250:251], v[236:237], 0, s[40:41]
	s_or_b32 m0, s100, 0x2000
	s_nop 0
	global_load_lds_dwordx4 v[250:251], off
	s_barrier
	s_waitcnt lgkmcnt(0)
	v_mfma_f32_16x16x32_bf16 v[64:67], v[190:193], v[174:177], v[64:67]
	v_mfma_f32_16x16x32_bf16 v[60:63], v[190:193], v[182:185], v[60:63]
	v_mfma_f32_16x16x32_bf16 v[56:59], v[198:201], v[174:177], v[56:59]
	v_mfma_f32_16x16x32_bf16 v[52:55], v[198:201], v[182:185], v[52:55]
	v_mfma_f32_16x16x32_bf16 v[48:51], v[206:209], v[174:177], v[48:51]
	v_mfma_f32_16x16x32_bf16 v[44:47], v[206:209], v[182:185], v[44:47]
	v_mfma_f32_16x16x32_bf16 v[40:43], v[214:217], v[174:177], v[40:43]
	v_mfma_f32_16x16x32_bf16 v[36:39], v[214:217], v[182:185], v[36:39]
	v_mfma_f32_16x16x32_bf16 v[64:67], v[194:197], v[178:181], v[64:67]
	v_mfma_f32_16x16x32_bf16 v[60:63], v[194:197], v[186:189], v[60:63]
	v_mfma_f32_16x16x32_bf16 v[56:59], v[202:205], v[178:181], v[56:59]
	v_mfma_f32_16x16x32_bf16 v[52:55], v[202:205], v[186:189], v[52:55]
	v_mfma_f32_16x16x32_bf16 v[48:51], v[210:213], v[178:181], v[48:51]
	v_mfma_f32_16x16x32_bf16 v[44:47], v[210:213], v[186:189], v[44:47]
	v_mfma_f32_16x16x32_bf16 v[40:43], v[218:221], v[178:181], v[40:43]
	v_mfma_f32_16x16x32_bf16 v[36:39], v[218:221], v[186:189], v[36:39]
	s_barrier
	v_lshl_add_u64 v[174:175], v[246:247], 0, s[42:43]
	s_or_b32 m0, s100, 0x14000
	s_nop 0
	global_load_lds_dwordx4 v[174:175], off
	v_lshl_add_u64 v[174:175], v[248:249], 0, s[42:43]
	s_or_b32 m0, s100, 0x16000
	s_nop 0
	global_load_lds_dwordx4 v[174:175], off
	s_waitcnt vmcnt(6)
	s_barrier
; #define LDA8(dst, b, h) _Pragma("unroll") for (int m = 0; m < 4; ++m) _Pragma("unroll") for (int k = 0; k < 2; ++k) \
;     dst[m][k] = *(const bf16x8*)((const char*)SA8(b, h) + lds_byte8(wr * 64 + m * 16 + fr, k * 32 + fq * 8))
; #define LDB8(dst, b, h) _Pragma("unroll") for (int n = 0; n < 2; ++n) _Pragma("unroll") for (int k = 0; k < 2; ++k) \
;     dst[n][k] = *(const bf16x8*)((const char*)SB8(b, h) + lds_byte8(wc * 32 + n * 16 + fr, k * 32 + fq * 8))
; #define WAIT_V8(n) asm volatile("s_waitcnt vmcnt(" #n ")" ::: "memory")
; #define WAIT_L8(n) asm volatile("s_waitcnt lgkmcnt(" #n ")" ::: "memory")
; #define BAR8 __builtin_amdgcn_s_barrier()
; #define SCHED8 __builtin_amdgcn_sched_barrier(0)
;     ...
;     WAIT_V8(6); BAR8; MMA8(1, 1, At, B1); BAR8;
;     LDB8(B0, 1, 0); SCHED8; LDA8(At, 1, 0); STAGE8(SA8(0, 1), A, lda, brow + 128, tt + 2);
;     WAIT_L8(8); BAR8; WAIT_L8(0); MMA8(0, 0, At, B0); BAR8; SCHED8;
;     LDB8(B1, 1, 1); STAGE8(SB8(1, 0), Bt, K, bcol, tt + 3);
;     BAR8; WAIT_L8(0); MMA8(0, 1, At, B1); BAR8;
;     LDA8(At, 1, 1); STAGE8(SA8(1, 0), A, lda, brow, tt + 3);
;     BAR8; WAIT_L8(0); MMA8(1, 0, At, B0); BAR8; SCHED8;
;     STAGE8(SB8(1, 1), Bt, K, bcol + 128, tt + 3);
;     WAIT_V8(6); BAR8; MMA8(1, 1, At, B1); BAR8;
	v_mfma_f32_16x16x32_bf16 v[32:35], v[190:193], v[226:229], v[32:35]
	v_mfma_f32_16x16x32_bf16 v[28:31], v[190:193], v[238:241], v[28:31]
	v_mfma_f32_16x16x32_bf16 v[24:27], v[198:201], v[226:229], v[24:27]
	v_mfma_f32_16x16x32_bf16 v[20:23], v[198:201], v[238:241], v[20:23]
	v_mfma_f32_16x16x32_bf16 v[16:19], v[206:209], v[226:229], v[16:19]
	v_mfma_f32_16x16x32_bf16 v[12:15], v[206:209], v[238:241], v[12:15]
	v_mfma_f32_16x16x32_bf16 v[8:11], v[214:217], v[226:229], v[8:11]
	v_mfma_f32_16x16x32_bf16 v[4:7], v[214:217], v[238:241], v[4:7]
	v_mfma_f32_16x16x32_bf16 v[32:35], v[194:197], v[230:233], v[32:35]
	v_mfma_f32_16x16x32_bf16 v[28:31], v[194:197], v[242:245], v[28:31]
	v_mfma_f32_16x16x32_bf16 v[24:27], v[202:205], v[230:233], v[24:27]
	v_mfma_f32_16x16x32_bf16 v[20:23], v[202:205], v[242:245], v[20:23]
	v_mfma_f32_16x16x32_bf16 v[16:19], v[210:213], v[230:233], v[16:19]
	v_mfma_f32_16x16x32_bf16 v[12:15], v[210:213], v[242:245], v[12:15]
	v_mfma_f32_16x16x32_bf16 v[8:11], v[218:221], v[230:233], v[8:11]
	v_mfma_f32_16x16x32_bf16 v[4:7], v[218:221], v[242:245], v[4:7]
	s_barrier
	ds_read_b128 v[174:177], v159
	ds_read_b128 v[178:181], v159 offset:1024
	ds_read_b128 v[182:185], v159 offset:2048
	ds_read_b128 v[186:189], v159 offset:3072
	v_lshl_add_u64 v[226:227], v[222:223], 0, s[44:45]
	s_or_b32 m0, s100, 0x4000
	ds_read_b128 v[190:193], v156 offset:32768
	ds_read_b128 v[194:197], v156 offset:33792
	ds_read_b128 v[198:201], v155 offset:32768
	ds_read_b128 v[202:205], v155 offset:33792
	ds_read_b128 v[206:209], v154 offset:32768
	ds_read_b128 v[210:213], v154 offset:33792
	ds_read_b128 v[214:217], v153 offset:32768
	ds_read_b128 v[218:221], v153 offset:33792
	global_load_lds_dwordx4 v[226:227], off
	v_lshl_add_u64 v[226:227], v[236:237], 0, s[44:45]
	s_or_b32 m0, s100, 0x6000
	s_nop 0
	global_load_lds_dwordx4 v[226:227], off
	s_waitcnt lgkmcnt(8)
	s_barrier
	s_waitcnt lgkmcnt(0)
	v_mfma_f32_16x16x32_bf16 v[128:131], v[190:193], v[174:177], v[128:131]
	v_mfma_f32_16x16x32_bf16 v[124:127], v[190:193], v[182:185], v[124:127]
	v_mfma_f32_16x16x32_bf16 v[120:123], v[198:201], v[174:177], v[120:123]
	v_mfma_f32_16x16x32_bf16 v[116:119], v[198:201], v[182:185], v[116:119]
	v_mfma_f32_16x16x32_bf16 v[112:115], v[206:209], v[174:177], v[112:115]
	v_mfma_f32_16x16x32_bf16 v[108:111], v[206:209], v[182:185], v[108:111]
	v_mfma_f32_16x16x32_bf16 v[104:107], v[214:217], v[174:177], v[104:107]
	v_mfma_f32_16x16x32_bf16 v[100:103], v[214:217], v[182:185], v[100:103]
	v_mfma_f32_16x16x32_bf16 v[128:131], v[194:197], v[178:181], v[128:131]
	v_mfma_f32_16x16x32_bf16 v[124:127], v[194:197], v[186:189], v[124:127]
	v_mfma_f32_16x16x32_bf16 v[120:123], v[202:205], v[178:181], v[120:123]
	v_mfma_f32_16x16x32_bf16 v[116:119], v[202:205], v[186:189], v[116:119]
	v_mfma_f32_16x16x32_bf16 v[112:115], v[210:213], v[178:181], v[112:115]
	v_mfma_f32_16x16x32_bf16 v[108:111], v[210:213], v[186:189], v[108:111]
	v_mfma_f32_16x16x32_bf16 v[104:107], v[218:221], v[178:181], v[104:107]
	v_mfma_f32_16x16x32_bf16 v[100:103], v[218:221], v[186:189], v[100:103]
	s_barrier
	v_lshl_add_u64 v[250:251], v[246:247], 0, s[46:47]
	s_or_b32 m0, s100, 0x18000
	ds_read_b128 v[226:229], v158
	ds_read_b128 v[230:233], v158 offset:1024
	ds_read_b128 v[238:241], v158 offset:2048
	ds_read_b128 v[242:245], v158 offset:3072
	global_load_lds_dwordx4 v[250:251], off
	v_lshl_add_u64 v[250:251], v[248:249], 0, s[46:47]
	s_or_b32 m0, s100, 0x1a000
	s_nop 0
	global_load_lds_dwordx4 v[250:251], off
	s_barrier
	s_waitcnt lgkmcnt(0)
	v_mfma_f32_16x16x32_bf16 v[96:99], v[190:193], v[226:229], v[96:99]
	v_mfma_f32_16x16x32_bf16 v[92:95], v[190:193], v[238:241], v[92:95]
	v_mfma_f32_16x16x32_bf16 v[88:91], v[198:201], v[226:229], v[88:91]
	v_mfma_f32_16x16x32_bf16 v[84:87], v[198:201], v[238:241], v[84:87]
	v_mfma_f32_16x16x32_bf16 v[80:83], v[206:209], v[226:229], v[80:83]
	v_mfma_f32_16x16x32_bf16 v[76:79], v[206:209], v[238:241], v[76:79]
	v_mfma_f32_16x16x32_bf16 v[72:75], v[214:217], v[226:229], v[72:75]
	v_mfma_f32_16x16x32_bf16 v[68:71], v[214:217], v[238:241], v[68:71]
	v_mfma_f32_16x16x32_bf16 v[96:99], v[194:197], v[230:233], v[96:99]
	v_mfma_f32_16x16x32_bf16 v[92:95], v[194:197], v[242:245], v[92:95]
	v_mfma_f32_16x16x32_bf16 v[88:91], v[202:205], v[230:233], v[88:91]
	v_mfma_f32_16x16x32_bf16 v[84:87], v[202:205], v[242:245], v[84:87]
	v_mfma_f32_16x16x32_bf16 v[80:83], v[210:213], v[230:233], v[80:83]
	v_mfma_f32_16x16x32_bf16 v[76:79], v[210:213], v[242:245], v[76:79]
	v_mfma_f32_16x16x32_bf16 v[72:75], v[218:221], v[230:233], v[72:75]
	v_mfma_f32_16x16x32_bf16 v[68:71], v[218:221], v[242:245], v[68:71]
	v_lshl_add_u64 v[222:223], v[222:223], 0, s[48:49]
	s_or_b32 m0, s100, 0x8000
	s_barrier
	ds_read_b128 v[190:193], v156 offset:49152
	ds_read_b128 v[194:197], v156 offset:50176
	ds_read_b128 v[198:201], v155 offset:49152
	ds_read_b128 v[202:205], v155 offset:50176
	ds_read_b128 v[206:209], v154 offset:49152
	ds_read_b128 v[210:213], v154 offset:50176
	ds_read_b128 v[214:217], v153 offset:49152
	ds_read_b128 v[218:221], v153 offset:50176
	global_load_lds_dwordx4 v[222:223], off
	v_lshl_add_u64 v[222:223], v[236:237], 0, s[48:49]
	s_or_b32 m0, s100, 0xa000
	s_nop 0
	global_load_lds_dwordx4 v[222:223], off
	s_barrier
; #define LDA8(dst, b, h) _Pragma("unroll") for (int m = 0; m < 4; ++m) _Pragma("unroll") for (int k = 0; k < 2; ++k) \
;     dst[m][k] = *(const bf16x8*)((const char*)SA8(b, h) + lds_byte8(wr * 64 + m * 16 + fr, k * 32 + fq * 8))
; #define LDB8(dst, b, h) _Pragma("unroll") for (int n = 0; n < 2; ++n) _Pragma("unroll") for (int k = 0; k < 2; ++k) \
;     dst[n][k] = *(const bf16x8*)((const char*)SB8(b, h) + lds_byte8(wc * 32 + n * 16 + fr, k * 32 + fq * 8))
; #define WAIT_V8(n) asm volatile("s_waitcnt vmcnt(" #n ")" ::: "memory")
; #define WAIT_L8(n) asm volatile("s_waitcnt lgkmcnt(" #n ")" ::: "memory")
; #define BAR8 __builtin_amdgcn_s_barrier()
; #define SCHED8 __builtin_amdgcn_sched_barrier(0)
;     ...
;     BAR8; WAIT_L8(0); MMA8(1, 0, At, B0); BAR8; SCHED8;
;     STAGE8(SB8(1, 1), Bt, K, bcol + 128, tt + 3);
;     WAIT_V8(6); BAR8; MMA8(1, 1, At, B1); BAR8;
;   }
;   { LDB8(B0, 0, 0); LDA8(At, 0, 0); STAGE8(SA8(1, 1), A, lda, brow + 128, nt - 1);
;     BAR8; WAIT_L8(0); MMA8(0, 0, At, B0); BAR8;
;     LDB8(B1, 0, 1); BAR8; WAIT_L8(0); MMA8(0, 1, At, B1); BAR8;
;     LDA8(At, 0, 1); WAIT_V8(4); BAR8; WAIT_L8(0); MMA8(1, 0, At, B0); MMA8(1, 1, At, B1); BAR8; }
	s_waitcnt lgkmcnt(0)
	v_mfma_f32_16x16x32_bf16 v[64:67], v[190:193], v[174:177], v[64:67]
	v_mfma_f32_16x16x32_bf16 v[60:63], v[190:193], v[182:185], v[60:63]
	v_mfma_f32_16x16x32_bf16 v[56:59], v[198:201], v[174:177], v[56:59]
	v_mfma_f32_16x16x32_bf16 v[52:55], v[198:201], v[182:185], v[52:55]
	v_mfma_f32_16x16x32_bf16 v[48:51], v[206:209], v[174:177], v[48:51]
	v_mfma_f32_16x16x32_bf16 v[44:47], v[206:209], v[182:185], v[44:47]
	v_mfma_f32_16x16x32_bf16 v[40:43], v[214:217], v[174:177], v[40:43]
	v_mfma_f32_16x16x32_bf16 v[36:39], v[214:217], v[182:185], v[36:39]
	v_mfma_f32_16x16x32_bf16 v[64:67], v[194:197], v[178:181], v[64:67]
	v_mfma_f32_16x16x32_bf16 v[60:63], v[194:197], v[186:189], v[60:63]
	v_mfma_f32_16x16x32_bf16 v[56:59], v[202:205], v[178:181], v[56:59]
	v_mfma_f32_16x16x32_bf16 v[52:55], v[202:205], v[186:189], v[52:55]
	v_mfma_f32_16x16x32_bf16 v[48:51], v[210:213], v[178:181], v[48:51]
	v_mfma_f32_16x16x32_bf16 v[44:47], v[210:213], v[186:189], v[44:47]
	v_mfma_f32_16x16x32_bf16 v[40:43], v[218:221], v[178:181], v[40:43]
	v_mfma_f32_16x16x32_bf16 v[36:39], v[218:221], v[186:189], v[36:39]
	s_barrier
	v_lshl_add_u64 v[174:175], v[246:247], 0, s[50:51]
	s_or_b32 m0, s100, 0x1c000
	s_nop 0
	global_load_lds_dwordx4 v[174:175], off
	v_lshl_add_u64 v[174:175], v[248:249], 0, s[50:51]
	s_or_b32 m0, s100, 0x1e000
	s_nop 0
	global_load_lds_dwordx4 v[174:175], off
	s_waitcnt vmcnt(6)
	s_barrier
	v_mfma_f32_16x16x32_bf16 v[32:35], v[190:193], v[226:229], v[32:35]
	v_mfma_f32_16x16x32_bf16 v[28:31], v[190:193], v[238:241], v[28:31]
	v_mfma_f32_16x16x32_bf16 v[24:27], v[198:201], v[226:229], v[24:27]
	v_mfma_f32_16x16x32_bf16 v[20:23], v[198:201], v[238:241], v[20:23]
	v_mfma_f32_16x16x32_bf16 v[16:19], v[206:209], v[226:229], v[16:19]
	v_mfma_f32_16x16x32_bf16 v[12:15], v[206:209], v[238:241], v[12:15]
	v_mfma_f32_16x16x32_bf16 v[8:11], v[214:217], v[226:229], v[8:11]
	v_mfma_f32_16x16x32_bf16 v[4:7], v[214:217], v[238:241], v[4:7]
	v_mfma_f32_16x16x32_bf16 v[32:35], v[194:197], v[230:233], v[32:35]
	v_mfma_f32_16x16x32_bf16 v[28:31], v[194:197], v[242:245], v[28:31]
	v_mfma_f32_16x16x32_bf16 v[24:27], v[202:205], v[230:233], v[24:27]
	v_mfma_f32_16x16x32_bf16 v[20:23], v[202:205], v[242:245], v[20:23]
	v_mfma_f32_16x16x32_bf16 v[16:19], v[210:213], v[230:233], v[16:19]
	v_mfma_f32_16x16x32_bf16 v[12:15], v[210:213], v[242:245], v[12:15]
	v_mfma_f32_16x16x32_bf16 v[8:11], v[218:221], v[230:233], v[8:11]
	v_mfma_f32_16x16x32_bf16 v[4:7], v[218:221], v[242:245], v[4:7]
	s_add_i32 s29, s29, 2
	s_add_u32 s12, s12, 0x100
	s_addc_u32 s13, s13, 0
	s_cmp_lt_u32 s29, 40
	s_barrier
	s_cbranch_scc1 .LBB0_1325
	s_add_i32 s27, s27, 0xb0000
	s_add_u32 s2, s2, s27
	s_addc_u32 s3, s3, 0
	s_add_u32 s2, s2, 0x2001580
	s_addc_u32 s3, s3, 0
	v_lshl_add_u64 v[132:133], v[132:133], 1, s[2:3]
	v_lshl_add_u64 v[0:1], v[0:1], 1, v[132:133]
	s_or_b32 m0, s100, 0xc000
	ds_read_b128 v[138:141], v171
	ds_read_b128 v[142:145], v171 offset:1024
	ds_read_b128 v[160:163], v171 offset:2048
	ds_read_b128 v[164:167], v171 offset:3072
	ds_read_b128 v[174:177], v156
	ds_read_b128 v[178:181], v156 offset:1024
	ds_read_b128 v[182:185], v155
	ds_read_b128 v[186:189], v155 offset:1024
	ds_read_b128 v[190:193], v154
	ds_read_b128 v[194:197], v154 offset:1024
	ds_read_b128 v[198:201], v153
	ds_read_b128 v[202:205], v153 offset:1024
	global_load_lds_dwordx4 v[0:1], off
	v_lshl_add_u64 v[0:1], v[136:137], 1, s[2:3]
	v_lshl_add_u64 v[0:1], v[134:135], 1, v[0:1]
	s_or_b32 m0, s100, 0xe000
	s_nop 0
	global_load_lds_dwordx4 v[0:1], off
	s_barrier
	s_waitcnt lgkmcnt(0)
	v_mfma_f32_16x16x32_bf16 v[128:131], v[174:177], v[138:141], v[128:131]
	v_mfma_f32_16x16x32_bf16 v[124:127], v[174:177], v[160:163], v[124:127]
	v_mfma_f32_16x16x32_bf16 v[120:123], v[182:185], v[138:141], v[120:123]
	v_mfma_f32_16x16x32_bf16 v[112:115], v[190:193], v[138:141], v[112:115]
	v_mfma_f32_16x16x32_bf16 v[128:131], v[178:181], v[142:145], v[128:131]
	v_mfma_f32_16x16x32_bf16 v[124:127], v[178:181], v[164:167], v[124:127]
	v_mfma_f32_16x16x32_bf16 v[120:123], v[186:189], v[142:145], v[120:123]
	v_mfma_f32_16x16x32_bf16 v[116:119], v[182:185], v[160:163], v[116:119]
	v_mfma_f32_16x16x32_bf16 v[112:115], v[194:197], v[142:145], v[112:115]
	v_mfma_f32_16x16x32_bf16 v[108:111], v[190:193], v[160:163], v[108:111]
	v_mfma_f32_16x16x32_bf16 v[104:107], v[198:201], v[138:141], v[104:107]
	v_mfma_f32_16x16x32_bf16 v[100:103], v[198:201], v[160:163], v[100:103]
	v_mfma_f32_16x16x32_bf16 v[132:135], v[186:189], v[164:167], v[116:119]
	v_mfma_f32_16x16x32_bf16 v[170:173], v[194:197], v[164:167], v[108:111]
	v_mfma_f32_16x16x32_bf16 v[206:209], v[202:205], v[142:145], v[104:107]
	v_mfma_f32_16x16x32_bf16 v[210:213], v[202:205], v[164:167], v[100:103]
	s_barrier
	s_nop 1
	ds_read_b128 v[100:103], v169
	ds_read_b128 v[104:107], v169 offset:1024
	ds_read_b128 v[108:111], v169 offset:2048
	ds_read_b128 v[116:119], v169 offset:3072
	s_barrier
	s_waitcnt lgkmcnt(0)
	v_mfma_f32_16x16x32_bf16 v[80:83], v[190:193], v[100:103], v[80:83]
	v_mfma_f32_16x16x32_bf16 v[76:79], v[190:193], v[108:111], v[76:79]
	v_mfma_f32_16x16x32_bf16 v[72:75], v[198:201], v[100:103], v[72:75]
	v_mfma_f32_16x16x32_bf16 v[68:71], v[198:201], v[108:111], v[68:71]
	v_mfma_f32_16x16x32_bf16 v[96:99], v[174:177], v[100:103], v[96:99]
	v_mfma_f32_16x16x32_bf16 v[92:95], v[174:177], v[108:111], v[92:95]
	v_mfma_f32_16x16x32_bf16 v[88:91], v[182:185], v[100:103], v[88:91]
	v_mfma_f32_16x16x32_bf16 v[84:87], v[182:185], v[108:111], v[84:87]
	v_mfma_f32_16x16x32_bf16 v[80:83], v[194:197], v[104:107], v[80:83]
	v_mfma_f32_16x16x32_bf16 v[76:79], v[194:197], v[116:119], v[76:79]
	v_mfma_f32_16x16x32_bf16 v[72:75], v[202:205], v[104:107], v[72:75]
	v_mfma_f32_16x16x32_bf16 v[68:71], v[202:205], v[116:119], v[68:71]
	v_mfma_f32_16x16x32_bf16 v[214:217], v[178:181], v[104:107], v[96:99]
	v_mfma_f32_16x16x32_bf16 v[174:177], v[178:181], v[116:119], v[92:95]
	v_mfma_f32_16x16x32_bf16 v[178:181], v[186:189], v[104:107], v[88:91]
	v_mfma_f32_16x16x32_bf16 v[182:185], v[186:189], v[116:119], v[84:87]
	s_barrier
; #define LDA8(dst, b, h) _Pragma("unroll") for (int m = 0; m < 4; ++m) _Pragma("unroll") for (int k = 0; k < 2; ++k) \
;     dst[m][k] = *(const bf16x8*)((const char*)SA8(b, h) + lds_byte8(wr * 64 + m * 16 + fr, k * 32 + fq * 8))
; #define LDB8(dst, b, h) _Pragma("unroll") for (int n = 0; n < 2; ++n) _Pragma("unroll") for (int k = 0; k < 2; ++k) \
;     dst[n][k] = *(const bf16x8*)((const char*)SB8(b, h) + lds_byte8(wc * 32 + n * 16 + fr, k * 32 + fq * 8))
; #define WAIT_V8(n) asm volatile("s_waitcnt vmcnt(" #n ")" ::: "memory")
; #define WAIT_L8(n) asm volatile("s_waitcnt lgkmcnt(" #n ")" ::: "memory")
; #define BAR8 __builtin_amdgcn_s_barrier()
;     ...
;     BAR8; WAIT_L8(0); MMA8(0, 0, At, B0); BAR8;
;     LDB8(B1, 0, 1); BAR8; WAIT_L8(0); MMA8(0, 1, At, B1); BAR8;
;     LDA8(At, 0, 1); WAIT_V8(4); BAR8; WAIT_L8(0); MMA8(1, 0, At, B0); MMA8(1, 1, At, B1); BAR8; }
;   { LDB8(B0, 1, 0); LDA8(At, 1, 0); WAIT_V8(2); BAR8; WAIT_L8(0); MMA8(0, 0, At, B0); BAR8;
;     LDB8(B1, 1, 1); WAIT_V8(0); BAR8; WAIT_L8(0); MMA8(0, 1, At, B1); BAR8;
	s_nop 0
	ds_read_b128 v[84:87], v156 offset:16384
	ds_read_b128 v[88:91], v156 offset:17408
	ds_read_b128 v[92:95], v155 offset:16384
	ds_read_b128 v[96:99], v155 offset:17408
	ds_read_b128 v[186:189], v154 offset:16384
	ds_read_b128 v[190:193], v154 offset:17408
	ds_read_b128 v[194:197], v153 offset:16384
	ds_read_b128 v[198:201], v153 offset:17408
	s_waitcnt vmcnt(4)
	s_barrier
	s_waitcnt lgkmcnt(0)
	v_mfma_f32_16x16x32_bf16 v[64:67], v[84:87], v[138:141], v[64:67]
	v_mfma_f32_16x16x32_bf16 v[60:63], v[84:87], v[160:163], v[60:63]
	v_mfma_f32_16x16x32_bf16 v[56:59], v[92:95], v[138:141], v[56:59]
	v_mfma_f32_16x16x32_bf16 v[52:55], v[92:95], v[160:163], v[52:55]
	v_mfma_f32_16x16x32_bf16 v[48:51], v[186:189], v[138:141], v[48:51]
	v_mfma_f32_16x16x32_bf16 v[44:47], v[186:189], v[160:163], v[44:47]
	v_mfma_f32_16x16x32_bf16 v[40:43], v[194:197], v[138:141], v[40:43]
	v_mfma_f32_16x16x32_bf16 v[36:39], v[194:197], v[160:163], v[36:39]
	v_mfma_f32_16x16x32_bf16 v[64:67], v[88:91], v[142:145], v[64:67]
	v_mfma_f32_16x16x32_bf16 v[60:63], v[88:91], v[164:167], v[60:63]
	v_mfma_f32_16x16x32_bf16 v[56:59], v[96:99], v[142:145], v[56:59]
	v_mfma_f32_16x16x32_bf16 v[52:55], v[96:99], v[164:167], v[52:55]
	v_mfma_f32_16x16x32_bf16 v[48:51], v[190:193], v[142:145], v[48:51]
	v_mfma_f32_16x16x32_bf16 v[44:47], v[190:193], v[164:167], v[44:47]
	v_mfma_f32_16x16x32_bf16 v[40:43], v[198:201], v[142:145], v[40:43]
	v_mfma_f32_16x16x32_bf16 v[36:39], v[198:201], v[164:167], v[36:39]
	v_mfma_f32_16x16x32_bf16 v[32:35], v[84:87], v[100:103], v[32:35]
	v_mfma_f32_16x16x32_bf16 v[28:31], v[84:87], v[108:111], v[28:31]
	v_mfma_f32_16x16x32_bf16 v[24:27], v[92:95], v[100:103], v[24:27]
	v_mfma_f32_16x16x32_bf16 v[20:23], v[92:95], v[108:111], v[20:23]
	v_mfma_f32_16x16x32_bf16 v[16:19], v[186:189], v[100:103], v[16:19]
	v_mfma_f32_16x16x32_bf16 v[12:15], v[186:189], v[108:111], v[12:15]
	v_mfma_f32_16x16x32_bf16 v[8:11], v[194:197], v[100:103], v[8:11]
	v_mfma_f32_16x16x32_bf16 v[4:7], v[194:197], v[108:111], v[4:7]
	v_mfma_f32_16x16x32_bf16 v[136:139], v[88:91], v[104:107], v[32:35]
	v_mfma_f32_16x16x32_bf16 v[140:143], v[88:91], v[116:119], v[28:31]
	v_mfma_f32_16x16x32_bf16 v[160:163], v[96:99], v[104:107], v[24:27]
	v_mfma_f32_16x16x32_bf16 v[164:167], v[96:99], v[116:119], v[20:23]
	v_mfma_f32_16x16x32_bf16 v[202:205], v[190:193], v[104:107], v[16:19]
	v_mfma_f32_16x16x32_bf16 v[186:189], v[190:193], v[116:119], v[12:15]
	v_mfma_f32_16x16x32_bf16 v[190:193], v[198:201], v[104:107], v[8:11]
	v_mfma_f32_16x16x32_bf16 v[194:197], v[198:201], v[116:119], v[4:7]
	s_barrier
	ds_read_b128 v[198:201], v159
	ds_read_b128 v[218:221], v159 offset:1024
	ds_read_b128 v[226:229], v159 offset:2048
	ds_read_b128 v[230:233], v159 offset:3072
	ds_read_b128 v[8:11], v156 offset:32768
	ds_read_b128 v[12:15], v156 offset:33792
	ds_read_b128 v[16:19], v155 offset:32768
	ds_read_b128 v[24:27], v155 offset:33792
	ds_read_b128 v[28:31], v154 offset:32768
	ds_read_b128 v[32:35], v154 offset:33792
	ds_read_b128 v[238:241], v153 offset:32768
	ds_read_b128 v[242:245], v153 offset:33792
	s_waitcnt vmcnt(2)
	s_barrier
	s_waitcnt lgkmcnt(0)
	v_mfma_f32_16x16x32_bf16 v[4:7], v[8:11], v[198:201], v[128:131]
	v_mfma_f32_16x16x32_bf16 v[104:107], v[12:15], v[218:221], v[4:7]
	v_mfma_f32_16x16x32_bf16 v[4:7], v[8:11], v[226:229], v[124:127]
	v_mfma_f32_16x16x32_bf16 v[116:119], v[12:15], v[230:233], v[4:7]
	v_mfma_f32_16x16x32_bf16 v[4:7], v[16:19], v[198:201], v[120:123]
	v_mfma_f32_16x16x32_bf16 v[100:103], v[24:27], v[218:221], v[4:7]
	v_mfma_f32_16x16x32_bf16 v[4:7], v[16:19], v[226:229], v[132:135]
	v_mfma_f32_16x16x32_bf16 v[108:111], v[24:27], v[230:233], v[4:7]
	v_mfma_f32_16x16x32_bf16 v[4:7], v[28:31], v[198:201], v[112:115]
	v_mfma_f32_16x16x32_bf16 v[92:95], v[32:35], v[218:221], v[4:7]
	v_mfma_f32_16x16x32_bf16 v[4:7], v[28:31], v[226:229], v[170:173]
	v_mfma_f32_16x16x32_bf16 v[96:99], v[32:35], v[230:233], v[4:7]
	v_mfma_f32_16x16x32_bf16 v[4:7], v[238:241], v[198:201], v[206:209]
	v_mfma_f32_16x16x32_bf16 v[84:87], v[242:245], v[218:221], v[4:7]
	v_mfma_f32_16x16x32_bf16 v[4:7], v[238:241], v[226:229], v[210:213]
	v_mfma_f32_16x16x32_bf16 v[88:91], v[242:245], v[230:233], v[4:7]
	s_barrier
; #define LDA8(dst, b, h) _Pragma("unroll") for (int m = 0; m < 4; ++m) _Pragma("unroll") for (int k = 0; k < 2; ++k) \
;     dst[m][k] = *(const bf16x8*)((const char*)SA8(b, h) + lds_byte8(wr * 64 + m * 16 + fr, k * 32 + fq * 8))
; #define LDB8(dst, b, h) _Pragma("unroll") for (int n = 0; n < 2; ++n) _Pragma("unroll") for (int k = 0; k < 2; ++k) \
;     dst[n][k] = *(const bf16x8*)((const char*)SB8(b, h) + lds_byte8(wc * 32 + n * 16 + fr, k * 32 + fq * 8))
; #define WAIT_V8(n) asm volatile("s_waitcnt vmcnt(" #n ")" ::: "memory")
; #define WAIT_L8(n) asm volatile("s_waitcnt lgkmcnt(" #n ")" ::: "memory")
; #define BAR8 __builtin_amdgcn_s_barrier()
;     ...
;   { LDB8(B0, 1, 0); LDA8(At, 1, 0); WAIT_V8(2); BAR8; WAIT_L8(0); MMA8(0, 0, At, B0); BAR8;
;     LDB8(B1, 1, 1); WAIT_V8(0); BAR8; WAIT_L8(0); MMA8(0, 1, At, B1); BAR8;
;     LDA8(At, 1, 1); BAR8; WAIT_L8(0); MMA8(1, 0, At, B0); MMA8(1, 1, At, B1); BAR8; }
;   if (wr == 0) BAR8;
;   __syncthreads();
;     ...
;   if (t < 256) {
	ds_read_b128 v[132:135], v158
	ds_read_b128 v[168:171], v158 offset:1024
	ds_read_b128 v[206:209], v158 offset:2048
	ds_read_b128 v[210:213], v158 offset:3072
	s_waitcnt vmcnt(0)
	s_barrier
	s_waitcnt lgkmcnt(0)
	v_mfma_f32_16x16x32_bf16 v[4:7], v[8:11], v[132:135], v[214:217]
	v_mfma_f32_16x16x32_bf16 v[8:11], v[8:11], v[206:209], v[174:177]
	v_mfma_f32_16x16x32_bf16 v[4:7], v[12:15], v[168:171], v[4:7]
	v_mfma_f32_16x16x32_bf16 v[20:23], v[12:15], v[210:213], v[8:11]
	v_mfma_f32_16x16x32_bf16 v[8:11], v[16:19], v[132:135], v[178:181]
	v_mfma_f32_16x16x32_bf16 v[12:15], v[16:19], v[206:209], v[182:185]
	v_mfma_f32_16x16x32_bf16 v[8:11], v[24:27], v[168:171], v[8:11]
	v_mfma_f32_16x16x32_bf16 v[24:27], v[24:27], v[210:213], v[12:15]
	v_mfma_f32_16x16x32_bf16 v[12:15], v[28:31], v[132:135], v[80:83]
	v_mfma_f32_16x16x32_bf16 v[16:19], v[28:31], v[206:209], v[76:79]
	v_mfma_f32_16x16x32_bf16 v[12:15], v[32:35], v[168:171], v[12:15]
	v_mfma_f32_16x16x32_bf16 v[28:31], v[32:35], v[210:213], v[16:19]
	v_mfma_f32_16x16x32_bf16 v[16:19], v[238:241], v[132:135], v[72:75]
	v_mfma_f32_16x16x32_bf16 v[32:35], v[238:241], v[206:209], v[68:71]
	v_mfma_f32_16x16x32_bf16 v[16:19], v[242:245], v[168:171], v[16:19]
	v_mfma_f32_16x16x32_bf16 v[32:35], v[242:245], v[210:213], v[32:35]
	s_barrier
	ds_read_b128 v[172:175], v156 offset:49152
	ds_read_b128 v[156:159], v156 offset:50176
	ds_read_b128 v[176:179], v155 offset:49152
	ds_read_b128 v[180:183], v155 offset:50176
	ds_read_b128 v[214:217], v154 offset:49152
	ds_read_b128 v[238:241], v154 offset:50176
	ds_read_b128 v[242:245], v153 offset:49152
	ds_read_b128 v[150:153], v153 offset:50176
	s_barrier
	s_waitcnt lgkmcnt(0)
	v_mfma_f32_16x16x32_bf16 v[64:67], v[172:175], v[198:201], v[64:67]
	v_mfma_f32_16x16x32_bf16 v[60:63], v[172:175], v[226:229], v[60:63]
	v_mfma_f32_16x16x32_bf16 v[56:59], v[176:179], v[198:201], v[56:59]
	v_mfma_f32_16x16x32_bf16 v[52:55], v[176:179], v[226:229], v[52:55]
	v_mfma_f32_16x16x32_bf16 v[48:51], v[214:217], v[198:201], v[48:51]
	v_mfma_f32_16x16x32_bf16 v[44:47], v[214:217], v[226:229], v[44:47]
	v_mfma_f32_16x16x32_bf16 v[40:43], v[242:245], v[198:201], v[40:43]
	v_mfma_f32_16x16x32_bf16 v[36:39], v[242:245], v[226:229], v[36:39]
	v_mfma_f32_16x16x32_bf16 v[128:131], v[156:159], v[218:221], v[64:67]
	v_mfma_f32_16x16x32_bf16 v[124:127], v[156:159], v[230:233], v[60:63]
	v_mfma_f32_16x16x32_bf16 v[120:123], v[180:183], v[218:221], v[56:59]
	v_mfma_f32_16x16x32_bf16 v[112:115], v[180:183], v[230:233], v[52:55]
	v_mfma_f32_16x16x32_bf16 v[80:83], v[238:241], v[218:221], v[48:51]
	v_mfma_f32_16x16x32_bf16 v[76:79], v[238:241], v[230:233], v[44:47]
	v_mfma_f32_16x16x32_bf16 v[72:75], v[150:153], v[218:221], v[40:43]
	v_mfma_f32_16x16x32_bf16 v[68:71], v[150:153], v[230:233], v[36:39]
	v_mfma_f32_16x16x32_bf16 v[40:43], v[172:175], v[206:209], v[140:143]
	v_mfma_f32_16x16x32_bf16 v[44:47], v[176:179], v[206:209], v[164:167]
	v_mfma_f32_16x16x32_bf16 v[48:51], v[214:217], v[206:209], v[186:189]
	v_mfma_f32_16x16x32_bf16 v[36:39], v[172:175], v[132:135], v[136:139]
	v_mfma_f32_16x16x32_bf16 v[52:55], v[156:159], v[210:213], v[40:43]
	v_mfma_f32_16x16x32_bf16 v[40:43], v[176:179], v[132:135], v[160:163]
	v_mfma_f32_16x16x32_bf16 v[56:59], v[180:183], v[210:213], v[44:47]
	v_mfma_f32_16x16x32_bf16 v[44:47], v[214:217], v[132:135], v[202:205]
	v_mfma_f32_16x16x32_bf16 v[60:63], v[238:241], v[210:213], v[48:51]
	v_mfma_f32_16x16x32_bf16 v[48:51], v[242:245], v[132:135], v[190:193]
	v_mfma_f32_16x16x32_bf16 v[64:67], v[242:245], v[206:209], v[194:197]
	v_mfma_f32_16x16x32_bf16 v[36:39], v[156:159], v[168:171], v[36:39]
	v_mfma_f32_16x16x32_bf16 v[40:43], v[180:183], v[168:171], v[40:43]
	v_mfma_f32_16x16x32_bf16 v[44:47], v[238:241], v[168:171], v[44:47]
	v_mfma_f32_16x16x32_bf16 v[48:51], v[150:153], v[168:171], v[48:51]
	v_mfma_f32_16x16x32_bf16 v[64:67], v[150:153], v[210:213], v[64:67]
	s_movk_i32 s2, 0x100
	v_cmp_gt_u32_e32 vcc, s2, v3
	s_barrier
	s_and_saveexec_b64 s[2:3], vcc
	s_cbranch_execz .LBB0_1328
	s_barrier
